# GEMM MFMA blocks: dropped the back-to-back setprio 0/1 pair in the middle of each 32-MFMA block
# speedup vs baseline: 1.0028x; 1.0028x over previous
; template <class Epi, class Sched, bool ALIGN_EPI = false, bool SP2 = false>
; __device__ __forceinline__ void gemm_phase(PG8_LAS unsigned char* lds, const Gemm g, const Sched& S, const Epi& E) {
;     ...
;         const bool has_next = S.next(ui + 1, nxt);
;         const char* nA = has_next ? (const char*)g.A + (size_t)nxt.pm * tstep : cA; const char* nB = has_next ? (const char*)g.Bt + (size_t)nxt.pn * tstep : cB;
;         for (int t = 0; t < nt; t += 2) {
;             const bool last = (t == nt - 2);
;             const char* a1 = cA + (size_t)(t + 1) * kstep;
;             const char* a2 = last ? nA : cA + (size_t)(t + 2) * kstep; const char* b2 = last ? nB : cB + (size_t)(t + 2) * kstep;
;             const char* a3 = a2 + kstep; const char* b3 = b2 + kstep;
.LBB0_241:
	s_ashr_i32 s51, s50, 31
	s_lshl_b64 s[30:31], s[50:51], 19
	s_add_u32 s56, s96, s30
	s_addc_u32 s57, s97, s31
	s_and_b64 s[30:31], s[54:55], exec
	s_cselect_b32 s1, s57, s19
	s_cselect_b32 s30, s56, s18
	s_ashr_i32 s49, s48, 31
	s_lshl_b64 s[34:35], s[48:49], 19
	s_add_u32 s58, s25, s34
	s_addc_u32 s59, s26, s35
	s_and_b64 s[34:35], s[54:55], exec
	s_cselect_b32 s31, s59, s37
	s_cselect_b32 s34, s58, s36
	s_add_u32 s18, s18, 0x40080
	s_addc_u32 s19, s19, 0
	s_add_u32 s35, s36, 0x100

; template <class Epi, class Sched, bool ALIGN_EPI = false, bool SP2 = false>
; __device__ __forceinline__ void gemm_phase(PG8_LAS unsigned char* lds, const Gemm g, const Sched& S, const Epi& E) {
;     ...
;         for (int t = 0; t < nt; t += 2) {
;             const bool last = (t == nt - 2);
;             const char* a1 = cA + (size_t)(t + 1) * kstep;
;             const char* a2 = last ? nA : cA + (size_t)(t + 2) * kstep; const char* b2 = last ? nB : cB + (size_t)(t + 2) * kstep;
	s_addc_u32 s49, s37, 0
	s_mov_b32 s51, -2


; #define PG8_STAGE(bufoff, gbase, voff) do { _Pragma("unroll") for (int _i = 0; _i < 2; ++_i) \
;         __builtin_amdgcn_global_load_lds((const unsigned*)((const char*)(gbase) + (voff)[_i]), (PG8_LAS unsigned*)(lds + (bufoff) + ldsw + _i * 8192), 16, 0, 0); } while (0)
; #define PG8_LDA(dst, b, h) do { _Pragma("unroll") for (int m = 0; m < 4; ++m) _Pragma("unroll") for (int k = 0; k < 2; ++k) dst[m][k] = *(const PG8_LAS bf16x8*)(lds + PG8_SA(b, h) + aoff + m * 2048 + k * 1024); } while (0)
; #define PG8_LDB(dst, b, h) do { _Pragma("unroll") for (int n = 0; n < 2; ++n) _Pragma("unroll") for (int k = 0; k < 2; ++k) dst[n][k] = *(const PG8_LAS bf16x8*)(lds + PG8_SB(b, h) + boff + n * 2048 + k * 1024); } while (0)
; #define PG8_MMA(ai, bj, At, Bt) do { __builtin_amdgcn_s_setprio(1); _Pragma("unroll") for (int m = 0; m < 4; ++m) _Pragma("unroll") for (int n = 0; n < 2; ++n) _Pragma("unroll") for (int k = 0; k < 2; ++k) \
;         acc[ai][bj][m][n] = __builtin_amdgcn_mfma_f32_16x16x32_bf16(Bt[n][k], At[m][k], acc[ai][bj][m][n], 0, 0, 0); __builtin_amdgcn_s_setprio(0); } while (0)
; #define PG8_WAIT_V(n) asm volatile("s_waitcnt vmcnt(" #n ")" ::: "memory")
; #define PG8_WAIT_L(n) asm volatile("s_waitcnt lgkmcnt(" #n ")" ::: "memory")
; #define PG8_BAR __builtin_amdgcn_s_barrier()
; #define PG8_SCHED __builtin_amdgcn_sched_barrier(0)
; template <class Epi, class Sched, bool ALIGN_EPI = false, bool SP2 = false>
; __device__ __forceinline__ void gemm_phase(PG8_LAS unsigned char* lds, const Gemm g, const Sched& S, const Epi& E) {
;     ...
;             const bool last = (t == nt - 2);
;             const char* a1 = cA + (size_t)(t + 1) * kstep;
;             const char* a2 = last ? nA : cA + (size_t)(t + 2) * kstep; const char* b2 = last ? nB : cB + (size_t)(t + 2) * kstep;
;             const char* a3 = a2 + kstep; const char* b3 = b2 + kstep;
;             if (last && has_next) S.a_ready(nxt);
;             if constexpr (SP2) {
;             PG8_LDB(B0, 0, 0); PG8_LDB(B1, 0, 1); PG8_SCHED; PG8_LDA(At, 0, 0); PG8_STAGE(PG8_SA(1, 1), a1 + hstep, voffA);
;             PG8_WAIT_V(8); PG8_WAIT_L(0); PG8_BAR; PG8_MMA(0, 0, At, B0); PG8_MMA(0, 1, At, B1); PG8_BAR; PG8_SCHED;
	s_add_u32 s36, s18, 0xfffc0080
	s_addc_u32 s37, s19, -1
	s_add_i32 s52, 0, 0x10000
	s_cmp_eq_u32 s51, 12
	s_cselect_b32 s63, s1, s37
	s_cselect_b32 s62, s30, s36
	s_cselect_b32 s37, s31, s49
	s_cselect_b32 s36, s34, s35
	s_add_i32 s67, 0, 0x14000
	v_add_u32_e32 v110, s52, v180
	v_add_u32_e32 v170, s67, v180
	ds_read_b128 v[98:101], v110
	ds_read_b128 v[102:105], v110 offset:1024
	ds_read_b128 v[106:109], v110 offset:2048
	ds_read_b128 v[110:113], v110 offset:3072
	ds_read_b128 v[158:161], v170
	ds_read_b128 v[162:165], v170 offset:1024
	ds_read_b128 v[166:169], v170 offset:2048
	ds_read_b128 v[170:173], v170 offset:3072
	v_lshl_add_u64 v[174:175], s[18:19], 0, v[154:155]
	s_add_i32 m0, s27, 0xc000
	ds_read_b128 v[184:187], v182
	ds_read_b128 v[194:197], v182 offset:1024
	ds_read_b128 v[198:201], v182 offset:2048
	ds_read_b128 v[202:205], v182 offset:3072
	ds_read_b128 v[206:209], v182 offset:4096
	ds_read_b128 v[210:213], v182 offset:5120
	ds_read_b128 v[214:217], v182 offset:6144
	ds_read_b128 v[218:221], v182 offset:7168
	global_load_lds_dwordx4 v[174:175], off
	v_lshl_add_u64 v[174:175], s[18:19], 0, v[156:157]
	s_add_i32 m0, s27, 0xe000
	s_nop 0
	global_load_lds_dwordx4 v[174:175], off
	s_waitcnt vmcnt(8)
	s_waitcnt lgkmcnt(0)
	s_barrier
	s_setprio 1
	s_waitcnt lgkmcnt(0)
	v_mfma_f32_16x16x32_bf16 v[142:145], v[98:101], v[184:187], 0
	v_mfma_f32_16x16x32_bf16 v[138:141], v[106:109], v[184:187], 0
	v_mfma_f32_16x16x32_bf16 v[126:129], v[98:101], v[198:201], 0
	v_mfma_f32_16x16x32_bf16 v[122:125], v[106:109], v[198:201], 0
	v_mfma_f32_16x16x32_bf16 v[94:97], v[98:101], v[206:209], 0
	v_mfma_f32_16x16x32_bf16 v[90:93], v[106:109], v[206:209], 0
	v_mfma_f32_16x16x32_bf16 v[78:81], v[98:101], v[214:217], 0
	v_mfma_f32_16x16x32_bf16 v[74:77], v[106:109], v[214:217], 0
	v_mfma_f32_16x16x32_bf16 v[142:145], v[102:105], v[194:197], v[142:145]
	v_mfma_f32_16x16x32_bf16 v[138:141], v[110:113], v[194:197], v[138:141]
	v_mfma_f32_16x16x32_bf16 v[126:129], v[102:105], v[202:205], v[126:129]
	v_mfma_f32_16x16x32_bf16 v[122:125], v[110:113], v[202:205], v[122:125]
	v_mfma_f32_16x16x32_bf16 v[94:97], v[102:105], v[210:213], v[94:97]
	v_mfma_f32_16x16x32_bf16 v[90:93], v[110:113], v[210:213], v[90:93]
	v_mfma_f32_16x16x32_bf16 v[78:81], v[102:105], v[218:221], v[78:81]
	v_mfma_f32_16x16x32_bf16 v[74:77], v[110:113], v[218:221], v[74:77]


; #define PG8_STAGE(bufoff, gbase, voff) do { _Pragma("unroll") for (int _i = 0; _i < 2; ++_i) \
;         __builtin_amdgcn_global_load_lds((const unsigned*)((const char*)(gbase) + (voff)[_i]), (PG8_LAS unsigned*)(lds + (bufoff) + ldsw + _i * 8192), 16, 0, 0); } while (0)
; #define PG8_LDA(dst, b, h) do { _Pragma("unroll") for (int m = 0; m < 4; ++m) _Pragma("unroll") for (int k = 0; k < 2; ++k) dst[m][k] = *(const PG8_LAS bf16x8*)(lds + PG8_SA(b, h) + aoff + m * 2048 + k * 1024); } while (0)
; #define PG8_MMA(ai, bj, At, Bt) do { __builtin_amdgcn_s_setprio(1); _Pragma("unroll") for (int m = 0; m < 4; ++m) _Pragma("unroll") for (int n = 0; n < 2; ++n) _Pragma("unroll") for (int k = 0; k < 2; ++k) \
;         acc[ai][bj][m][n] = __builtin_amdgcn_mfma_f32_16x16x32_bf16(Bt[n][k], At[m][k], acc[ai][bj][m][n], 0, 0, 0); __builtin_amdgcn_s_setprio(0); } while (0)
; #define PG8_WAIT_V(n) asm volatile("s_waitcnt vmcnt(" #n ")" ::: "memory")
; #define PG8_WAIT_L(n) asm volatile("s_waitcnt lgkmcnt(" #n ")" ::: "memory")
; #define PG8_BAR __builtin_amdgcn_s_barrier()
; #define PG8_SCHED __builtin_amdgcn_sched_barrier(0)
; template <class Epi, class Sched, bool ALIGN_EPI = false, bool SP2 = false>
; __device__ __forceinline__ void gemm_phase(PG8_LAS unsigned char* lds, const Gemm g, const Sched& S, const Epi& E) {
;     ...
;             PG8_WAIT_V(8); PG8_WAIT_L(0); PG8_BAR; PG8_MMA(0, 0, At, B0); PG8_MMA(0, 1, At, B1); PG8_BAR; PG8_SCHED;
;             PG8_LDA(At, 0, 1); PG8_STAGE(PG8_SB(0, 0), b2, voffB); PG8_STAGE(PG8_SB(0, 1), b2 + hstep, voffB); PG8_STAGE(PG8_SA(0, 0), a2, voffA);
;             PG8_WAIT_V(8); PG8_WAIT_L(0); PG8_BAR; PG8_MMA(1, 0, At, B0); PG8_MMA(1, 1, At, B1); PG8_BAR; PG8_SCHED;
	v_mfma_f32_16x16x32_bf16 v[134:137], v[158:161], v[184:187], 0
	v_mfma_f32_16x16x32_bf16 v[130:133], v[166:169], v[184:187], 0
	v_mfma_f32_16x16x32_bf16 v[118:121], v[158:161], v[198:201], 0
	v_mfma_f32_16x16x32_bf16 v[114:117], v[166:169], v[198:201], 0
	v_mfma_f32_16x16x32_bf16 v[86:89], v[158:161], v[206:209], 0
	v_mfma_f32_16x16x32_bf16 v[82:85], v[166:169], v[206:209], 0
	v_mfma_f32_16x16x32_bf16 v[70:73], v[158:161], v[214:217], 0
	v_mfma_f32_16x16x32_bf16 v[66:69], v[166:169], v[214:217], 0
	v_mfma_f32_16x16x32_bf16 v[134:137], v[162:165], v[194:197], v[134:137]
	v_mfma_f32_16x16x32_bf16 v[130:133], v[170:173], v[194:197], v[130:133]
	v_mfma_f32_16x16x32_bf16 v[118:121], v[162:165], v[202:205], v[118:121]
	v_mfma_f32_16x16x32_bf16 v[114:117], v[170:173], v[202:205], v[114:117]
	v_mfma_f32_16x16x32_bf16 v[86:89], v[162:165], v[210:213], v[86:89]
	v_mfma_f32_16x16x32_bf16 v[82:85], v[170:173], v[210:213], v[82:85]
	v_mfma_f32_16x16x32_bf16 v[70:73], v[162:165], v[218:221], v[70:73]
	v_mfma_f32_16x16x32_bf16 v[66:69], v[170:173], v[218:221], v[66:69]
	s_setprio 0
	s_barrier
	s_add_i32 s52, s52, s24
	v_lshl_add_u64 v[174:175], s[36:37], 0, v[0:1]
	s_mov_b32 m0, s52
	ds_read_b128 v[184:187], v182 offset:16384
	ds_read_b128 v[194:197], v182 offset:17408
	ds_read_b128 v[198:201], v182 offset:18432
	ds_read_b128 v[202:205], v182 offset:19456
	ds_read_b128 v[206:209], v182 offset:20480
	ds_read_b128 v[210:213], v182 offset:21504
	ds_read_b128 v[214:217], v182 offset:22528
	ds_read_b128 v[218:221], v182 offset:23552
	global_load_lds_dwordx4 v[174:175], off
	s_add_i32 m0, s52, 0x2000
	s_add_u32 s52, s36, 0x40000
	v_lshl_add_u64 v[178:179], s[36:37], 0, v[150:151]
	s_addc_u32 s53, s37, 0
	s_add_i32 s67, s67, s24
	global_load_lds_dwordx4 v[178:179], off
	v_lshl_add_u64 v[188:189], s[52:53], 0, v[0:1]
	s_mov_b32 m0, s67
	v_lshl_add_u64 v[222:223], s[62:63], 0, v[148:149]
	global_load_lds_dwordx4 v[188:189], off
	v_lshl_add_u64 v[188:189], s[52:53], 0, v[150:151]
	s_add_i32 m0, s67, 0x2000
	s_nop 0
	global_load_lds_dwordx4 v[188:189], off
	v_lshl_add_u64 v[188:189], s[62:63], 0, v[146:147]
	s_mov_b32 m0, s27
	s_nop 0
	global_load_lds_dwordx4 v[188:189], off
	s_mov_b32 m0, s28
	s_nop 0
	global_load_lds_dwordx4 v[222:223], off
	s_waitcnt vmcnt(8)
	s_waitcnt lgkmcnt(0)
	s_barrier
	s_setprio 1
	s_waitcnt lgkmcnt(0)
	v_mfma_f32_16x16x32_bf16 v[62:65], v[98:101], v[184:187], 0
	v_mfma_f32_16x16x32_bf16 v[58:61], v[106:109], v[184:187], 0
	v_mfma_f32_16x16x32_bf16 v[46:49], v[98:101], v[198:201], 0
	v_mfma_f32_16x16x32_bf16 v[42:45], v[106:109], v[198:201], 0
	v_mfma_f32_16x16x32_bf16 v[30:33], v[98:101], v[206:209], 0
	v_mfma_f32_16x16x32_bf16 v[26:29], v[106:109], v[206:209], 0
	v_mfma_f32_16x16x32_bf16 v[14:17], v[98:101], v[214:217], 0
	v_mfma_f32_16x16x32_bf16 v[10:13], v[106:109], v[214:217], 0
	v_mfma_f32_16x16x32_bf16 v[62:65], v[102:105], v[194:197], v[62:65]
	v_mfma_f32_16x16x32_bf16 v[58:61], v[110:113], v[194:197], v[58:61]
	v_mfma_f32_16x16x32_bf16 v[46:49], v[102:105], v[202:205], v[46:49]
	v_mfma_f32_16x16x32_bf16 v[42:45], v[110:113], v[202:205], v[42:45]
	v_mfma_f32_16x16x32_bf16 v[30:33], v[102:105], v[210:213], v[30:33]
	v_mfma_f32_16x16x32_bf16 v[26:29], v[110:113], v[210:213], v[26:29]
	v_mfma_f32_16x16x32_bf16 v[14:17], v[102:105], v[218:221], v[14:17]
	v_mfma_f32_16x16x32_bf16 v[10:13], v[110:113], v[218:221], v[10:13]


; #define PG8_STAGE(bufoff, gbase, voff) do { _Pragma("unroll") for (int _i = 0; _i < 2; ++_i) \
;         __builtin_amdgcn_global_load_lds((const unsigned*)((const char*)(gbase) + (voff)[_i]), (PG8_LAS unsigned*)(lds + (bufoff) + ldsw + _i * 8192), 16, 0, 0); } while (0)
; #define PG8_LDA(dst, b, h) do { _Pragma("unroll") for (int m = 0; m < 4; ++m) _Pragma("unroll") for (int k = 0; k < 2; ++k) dst[m][k] = *(const PG8_LAS bf16x8*)(lds + PG8_SA(b, h) + aoff + m * 2048 + k * 1024); } while (0)
; #define PG8_LDB(dst, b, h) do { _Pragma("unroll") for (int n = 0; n < 2; ++n) _Pragma("unroll") for (int k = 0; k < 2; ++k) dst[n][k] = *(const PG8_LAS bf16x8*)(lds + PG8_SB(b, h) + boff + n * 2048 + k * 1024); } while (0)
; #define PG8_MMA(ai, bj, At, Bt) do { __builtin_amdgcn_s_setprio(1); _Pragma("unroll") for (int m = 0; m < 4; ++m) _Pragma("unroll") for (int n = 0; n < 2; ++n) _Pragma("unroll") for (int k = 0; k < 2; ++k) \
;         acc[ai][bj][m][n] = __builtin_amdgcn_mfma_f32_16x16x32_bf16(Bt[n][k], At[m][k], acc[ai][bj][m][n], 0, 0, 0); __builtin_amdgcn_s_setprio(0); } while (0)
; #define PG8_WAIT_V(n) asm volatile("s_waitcnt vmcnt(" #n ")" ::: "memory")
; #define PG8_WAIT_L(n) asm volatile("s_waitcnt lgkmcnt(" #n ")" ::: "memory")
; #define PG8_BAR __builtin_amdgcn_s_barrier()
; #define PG8_SCHED __builtin_amdgcn_sched_barrier(0)
; template <class Epi, class Sched, bool ALIGN_EPI = false, bool SP2 = false>
; __device__ __forceinline__ void gemm_phase(PG8_LAS unsigned char* lds, const Gemm g, const Sched& S, const Epi& E) {
;     ...
;             PG8_WAIT_V(8); PG8_WAIT_L(0); PG8_BAR; PG8_MMA(1, 0, At, B0); PG8_MMA(1, 1, At, B1); PG8_BAR; PG8_SCHED;
;             PG8_LDB(B0, 1, 0); PG8_LDB(B1, 1, 1); PG8_SCHED; PG8_LDA(At, 1, 0); PG8_STAGE(PG8_SA(0, 1), a2 + hstep, voffA);
;             PG8_WAIT_V(8); PG8_WAIT_L(0); PG8_BAR; PG8_MMA(0, 0, At, B0); PG8_MMA(0, 1, At, B1); PG8_BAR; PG8_SCHED;
	v_mfma_f32_16x16x32_bf16 v[54:57], v[158:161], v[184:187], 0
	v_mfma_f32_16x16x32_bf16 v[50:53], v[166:169], v[184:187], 0
	v_mfma_f32_16x16x32_bf16 v[38:41], v[158:161], v[198:201], 0
	v_mfma_f32_16x16x32_bf16 v[34:37], v[166:169], v[198:201], 0
	v_mfma_f32_16x16x32_bf16 v[22:25], v[158:161], v[206:209], 0
	v_mfma_f32_16x16x32_bf16 v[18:21], v[166:169], v[206:209], 0
	v_mfma_f32_16x16x32_bf16 v[6:9], v[158:161], v[214:217], 0
	v_mfma_f32_16x16x32_bf16 v[2:5], v[166:169], v[214:217], 0
	v_mfma_f32_16x16x32_bf16 v[54:57], v[162:165], v[194:197], v[54:57]
	v_mfma_f32_16x16x32_bf16 v[50:53], v[170:173], v[194:197], v[50:53]
	v_mfma_f32_16x16x32_bf16 v[38:41], v[162:165], v[202:205], v[38:41]
	v_mfma_f32_16x16x32_bf16 v[34:37], v[170:173], v[202:205], v[34:37]
	v_mfma_f32_16x16x32_bf16 v[22:25], v[162:165], v[210:213], v[22:25]
	v_mfma_f32_16x16x32_bf16 v[18:21], v[170:173], v[210:213], v[18:21]
	v_mfma_f32_16x16x32_bf16 v[6:9], v[162:165], v[218:221], v[6:9]
	v_mfma_f32_16x16x32_bf16 v[2:5], v[170:173], v[218:221], v[2:5]
	s_setprio 0
	s_barrier
	s_add_i32 s67, 0, 0x18000
	s_add_i32 s68, 0, 0x1c000
	v_add_u32_e32 v110, s67, v180
	v_add_u32_e32 v170, s68, v180
	ds_read_b128 v[98:101], v110
	ds_read_b128 v[102:105], v110 offset:1024
	ds_read_b128 v[106:109], v110 offset:2048
	ds_read_b128 v[110:113], v110 offset:3072
	ds_read_b128 v[158:161], v170
	ds_read_b128 v[162:165], v170 offset:1024
	ds_read_b128 v[166:169], v170 offset:2048
	ds_read_b128 v[170:173], v170 offset:3072
	s_add_u32 s52, s62, 0x40000
	s_addc_u32 s53, s63, 0
	s_mov_b32 m0, s29
	v_lshl_add_u64 v[224:225], s[52:53], 0, v[146:147]
	ds_read_b128 v[184:187], v182 offset:32768
	ds_read_b128 v[194:197], v182 offset:33792
	ds_read_b128 v[198:201], v182 offset:34816
	ds_read_b128 v[202:205], v182 offset:35840
	ds_read_b128 v[206:209], v182 offset:36864
	ds_read_b128 v[210:213], v182 offset:37888
	ds_read_b128 v[214:217], v182 offset:38912
	ds_read_b128 v[218:221], v182 offset:39936
	global_load_lds_dwordx4 v[224:225], off
	v_lshl_add_u64 v[224:225], s[52:53], 0, v[148:149]
	s_mov_b32 m0, s61
	s_nop 0
	global_load_lds_dwordx4 v[224:225], off
	s_waitcnt vmcnt(8)
	s_waitcnt lgkmcnt(0)
	s_barrier
	s_setprio 1
	s_waitcnt lgkmcnt(0)
	v_mfma_f32_16x16x32_bf16 v[142:145], v[98:101], v[184:187], v[142:145]
	v_mfma_f32_16x16x32_bf16 v[138:141], v[106:109], v[184:187], v[138:141]
	v_mfma_f32_16x16x32_bf16 v[126:129], v[98:101], v[198:201], v[126:129]
	v_mfma_f32_16x16x32_bf16 v[122:125], v[106:109], v[198:201], v[122:125]
	v_mfma_f32_16x16x32_bf16 v[94:97], v[98:101], v[206:209], v[94:97]
	v_mfma_f32_16x16x32_bf16 v[90:93], v[106:109], v[206:209], v[90:93]
	v_mfma_f32_16x16x32_bf16 v[78:81], v[98:101], v[214:217], v[78:81]
	v_mfma_f32_16x16x32_bf16 v[74:77], v[106:109], v[214:217], v[74:77]
	v_mfma_f32_16x16x32_bf16 v[142:145], v[102:105], v[194:197], v[142:145]
	v_mfma_f32_16x16x32_bf16 v[138:141], v[110:113], v[194:197], v[138:141]
	v_mfma_f32_16x16x32_bf16 v[126:129], v[102:105], v[202:205], v[126:129]
	v_mfma_f32_16x16x32_bf16 v[122:125], v[110:113], v[202:205], v[122:125]
	v_mfma_f32_16x16x32_bf16 v[94:97], v[102:105], v[210:213], v[94:97]
	v_mfma_f32_16x16x32_bf16 v[90:93], v[110:113], v[210:213], v[90:93]
	v_mfma_f32_16x16x32_bf16 v[78:81], v[102:105], v[218:221], v[78:81]
	v_mfma_f32_16x16x32_bf16 v[74:77], v[110:113], v[218:221], v[74:77]


; #define PG8_STAGE(bufoff, gbase, voff) do { _Pragma("unroll") for (int _i = 0; _i < 2; ++_i) \
;         __builtin_amdgcn_global_load_lds((const unsigned*)((const char*)(gbase) + (voff)[_i]), (PG8_LAS unsigned*)(lds + (bufoff) + ldsw + _i * 8192), 16, 0, 0); } while (0)
; #define PG8_LDA(dst, b, h) do { _Pragma("unroll") for (int m = 0; m < 4; ++m) _Pragma("unroll") for (int k = 0; k < 2; ++k) dst[m][k] = *(const PG8_LAS bf16x8*)(lds + PG8_SA(b, h) + aoff + m * 2048 + k * 1024); } while (0)
; #define PG8_MMA(ai, bj, At, Bt) do { __builtin_amdgcn_s_setprio(1); _Pragma("unroll") for (int m = 0; m < 4; ++m) _Pragma("unroll") for (int n = 0; n < 2; ++n) _Pragma("unroll") for (int k = 0; k < 2; ++k) \
;         acc[ai][bj][m][n] = __builtin_amdgcn_mfma_f32_16x16x32_bf16(Bt[n][k], At[m][k], acc[ai][bj][m][n], 0, 0, 0); __builtin_amdgcn_s_setprio(0); } while (0)
; #define PG8_WAIT_V(n) asm volatile("s_waitcnt vmcnt(" #n ")" ::: "memory")
; #define PG8_WAIT_L(n) asm volatile("s_waitcnt lgkmcnt(" #n ")" ::: "memory")
; #define PG8_BAR __builtin_amdgcn_s_barrier()
; #define PG8_SCHED __builtin_amdgcn_sched_barrier(0)
; template <class Epi, class Sched, bool ALIGN_EPI = false, bool SP2 = false>
; __device__ __forceinline__ void gemm_phase(PG8_LAS unsigned char* lds, const Gemm g, const Sched& S, const Epi& E) {
;     ...
;             PG8_WAIT_V(8); PG8_WAIT_L(0); PG8_BAR; PG8_MMA(0, 0, At, B0); PG8_MMA(0, 1, At, B1); PG8_BAR; PG8_SCHED;
;             PG8_LDA(At, 1, 1); PG8_STAGE(PG8_SB(1, 0), b3, voffB); PG8_STAGE(PG8_SB(1, 1), b3 + hstep, voffB); PG8_STAGE(PG8_SA(1, 0), a3, voffA);
;             PG8_WAIT_V(8); PG8_WAIT_L(0); PG8_BAR; PG8_MMA(1, 0, At, B0); PG8_MMA(1, 1, At, B1); PG8_BAR; PG8_SCHED;
	v_mfma_f32_16x16x32_bf16 v[134:137], v[158:161], v[184:187], v[134:137]
	v_mfma_f32_16x16x32_bf16 v[130:133], v[166:169], v[184:187], v[130:133]
	v_mfma_f32_16x16x32_bf16 v[118:121], v[158:161], v[198:201], v[118:121]
	v_mfma_f32_16x16x32_bf16 v[114:117], v[166:169], v[198:201], v[114:117]
	v_mfma_f32_16x16x32_bf16 v[86:89], v[158:161], v[206:209], v[86:89]
	v_mfma_f32_16x16x32_bf16 v[82:85], v[166:169], v[206:209], v[82:85]
	v_mfma_f32_16x16x32_bf16 v[70:73], v[158:161], v[214:217], v[70:73]
	v_mfma_f32_16x16x32_bf16 v[66:69], v[166:169], v[214:217], v[66:69]
	v_mfma_f32_16x16x32_bf16 v[134:137], v[162:165], v[194:197], v[134:137]
	v_mfma_f32_16x16x32_bf16 v[130:133], v[170:173], v[194:197], v[130:133]
	v_mfma_f32_16x16x32_bf16 v[118:121], v[162:165], v[202:205], v[118:121]
	v_mfma_f32_16x16x32_bf16 v[114:117], v[170:173], v[202:205], v[114:117]
	v_mfma_f32_16x16x32_bf16 v[86:89], v[162:165], v[210:213], v[86:89]
	v_mfma_f32_16x16x32_bf16 v[82:85], v[170:173], v[210:213], v[82:85]
	v_mfma_f32_16x16x32_bf16 v[70:73], v[162:165], v[218:221], v[70:73]
	v_mfma_f32_16x16x32_bf16 v[66:69], v[170:173], v[218:221], v[66:69]
	s_setprio 0
	s_barrier
	s_add_i32 s52, s67, s24
	v_lshl_add_u64 v[174:175], v[174:175], 0, s[8:9]
	s_mov_b32 m0, s52
	ds_read_b128 v[184:187], v182 offset:49152
	ds_read_b128 v[194:197], v182 offset:50176
	ds_read_b128 v[198:201], v182 offset:51200
	ds_read_b128 v[202:205], v182 offset:52224
	ds_read_b128 v[206:209], v182 offset:53248
	ds_read_b128 v[210:213], v182 offset:54272
	ds_read_b128 v[214:217], v182 offset:55296
	ds_read_b128 v[218:221], v182 offset:56320
	global_load_lds_dwordx4 v[174:175], off
	s_add_i32 m0, s52, 0x2000
	s_add_u32 s36, s36, 0x40080
	v_lshl_add_u64 v[174:175], v[178:179], 0, s[8:9]
	s_addc_u32 s37, s37, 0
	s_add_i32 s52, s68, s24
	global_load_lds_dwordx4 v[174:175], off
	v_lshl_add_u64 v[174:175], s[36:37], 0, v[0:1]
	s_mov_b32 m0, s52
	s_nop 0
	global_load_lds_dwordx4 v[174:175], off
	v_lshl_add_u64 v[174:175], s[36:37], 0, v[150:151]
	s_add_i32 m0, s52, 0x2000
	s_nop 0
	global_load_lds_dwordx4 v[174:175], off
	v_lshl_add_u64 v[174:175], v[188:189], 0, s[8:9]
	s_mov_b32 m0, s64
	s_nop 0
	global_load_lds_dwordx4 v[174:175], off
	v_lshl_add_u64 v[174:175], v[222:223], 0, s[8:9]
	s_mov_b32 m0, s65
	s_nop 0
	global_load_lds_dwordx4 v[174:175], off
	s_waitcnt vmcnt(8)
	s_waitcnt lgkmcnt(0)
	s_barrier
	s_setprio 1
	s_waitcnt lgkmcnt(0)
	v_mfma_f32_16x16x32_bf16 v[62:65], v[98:101], v[184:187], v[62:65]
	v_mfma_f32_16x16x32_bf16 v[58:61], v[106:109], v[184:187], v[58:61]
	v_mfma_f32_16x16x32_bf16 v[46:49], v[98:101], v[198:201], v[46:49]
	v_mfma_f32_16x16x32_bf16 v[42:45], v[106:109], v[198:201], v[42:45]
	v_mfma_f32_16x16x32_bf16 v[30:33], v[98:101], v[206:209], v[30:33]
	v_mfma_f32_16x16x32_bf16 v[26:29], v[106:109], v[206:209], v[26:29]
	v_mfma_f32_16x16x32_bf16 v[14:17], v[98:101], v[214:217], v[14:17]
	v_mfma_f32_16x16x32_bf16 v[10:13], v[106:109], v[214:217], v[10:13]
	v_mfma_f32_16x16x32_bf16 v[62:65], v[102:105], v[194:197], v[62:65]
	v_mfma_f32_16x16x32_bf16 v[58:61], v[110:113], v[194:197], v[58:61]
	v_mfma_f32_16x16x32_bf16 v[46:49], v[102:105], v[202:205], v[46:49]
	v_mfma_f32_16x16x32_bf16 v[42:45], v[110:113], v[202:205], v[42:45]
	v_mfma_f32_16x16x32_bf16 v[30:33], v[102:105], v[210:213], v[30:33]
	v_mfma_f32_16x16x32_bf16 v[26:29], v[110:113], v[210:213], v[26:29]
	v_mfma_f32_16x16x32_bf16 v[14:17], v[102:105], v[218:221], v[14:17]
	v_mfma_f32_16x16x32_bf16 v[10:13], v[110:113], v[218:221], v[10:13]


; #define PG8_STAGE(bufoff, gbase, voff) do { _Pragma("unroll") for (int _i = 0; _i < 2; ++_i) \
;         __builtin_amdgcn_global_load_lds((const unsigned*)((const char*)(gbase) + (voff)[_i]), (PG8_LAS unsigned*)(lds + (bufoff) + ldsw + _i * 8192), 16, 0, 0); } while (0)
; #define PG8_LDA(dst, b, h) do { _Pragma("unroll") for (int m = 0; m < 4; ++m) _Pragma("unroll") for (int k = 0; k < 2; ++k) dst[m][k] = *(const PG8_LAS bf16x8*)(lds + PG8_SA(b, h) + aoff + m * 2048 + k * 1024); } while (0)
; #define PG8_LDB(dst, b, h) do { _Pragma("unroll") for (int n = 0; n < 2; ++n) _Pragma("unroll") for (int k = 0; k < 2; ++k) dst[n][k] = *(const PG8_LAS bf16x8*)(lds + PG8_SB(b, h) + boff + n * 2048 + k * 1024); } while (0)
; template <class Epi, class Sched, bool ALIGN_EPI = false, bool SP2 = false>
; __device__ __forceinline__ void gemm_phase(PG8_LAS unsigned char* lds, const Gemm g, const Sched& S, const Epi& E) {
;     ...
;         for (int t = 0; t < nt; t += 2) {
;             const bool last = (t == nt - 2);
;             const char* a1 = cA + (size_t)(t + 1) * kstep;
;             const char* a2 = last ? nA : cA + (size_t)(t + 2) * kstep; const char* b2 = last ? nB : cB + (size_t)(t + 2) * kstep;
;             const char* a3 = a2 + kstep; const char* b3 = b2 + kstep;
;             if (last && has_next) S.a_ready(nxt);
;             if constexpr (SP2) {
;             PG8_LDB(B0, 0, 0); PG8_LDB(B1, 0, 1); PG8_SCHED; PG8_LDA(At, 0, 0); PG8_STAGE(PG8_SA(1, 1), a1 + hstep, voffA);
;             PG8_WAIT_V(8); PG8_WAIT_L(0); PG8_BAR; PG8_MMA(0, 0, At, B0); PG8_MMA(0, 1, At, B1); PG8_BAR; PG8_SCHED;
;             PG8_LDA(At, 0, 1); PG8_STAGE(PG8_SB(0, 0), b2, voffB); PG8_STAGE(PG8_SB(0, 1), b2 + hstep, voffB); PG8_STAGE(PG8_SA(0, 0), a2, voffA);
;             PG8_WAIT_V(8); PG8_WAIT_L(0); PG8_BAR; PG8_MMA(1, 0, At, B0); PG8_MMA(1, 1, At, B1); PG8_BAR; PG8_SCHED;
;             PG8_LDB(B0, 1, 0); PG8_LDB(B1, 1, 1); PG8_SCHED; PG8_LDA(At, 1, 0); PG8_STAGE(PG8_SA(0, 1), a2 + hstep, voffA);
;             PG8_WAIT_V(8); PG8_WAIT_L(0); PG8_BAR; PG8_MMA(0, 0, At, B0); PG8_MMA(0, 1, At, B1); PG8_BAR; PG8_SCHED;
;             PG8_LDA(At, 1, 1); PG8_STAGE(PG8_SB(1, 0), b3, voffB); PG8_STAGE(PG8_SB(1, 1), b3 + hstep, voffB); PG8_STAGE(PG8_SA(1, 0), a3, voffA);
;             PG8_WAIT_V(8); PG8_WAIT_L(0); PG8_BAR; PG8_MMA(1, 0, At, B0); PG8_MMA(1, 1, At, B1); PG8_BAR; PG8_SCHED;
	v_mfma_f32_16x16x32_bf16 v[54:57], v[158:161], v[184:187], v[54:57]
	v_mfma_f32_16x16x32_bf16 v[50:53], v[166:169], v[184:187], v[50:53]
	v_mfma_f32_16x16x32_bf16 v[38:41], v[158:161], v[198:201], v[38:41]
	v_mfma_f32_16x16x32_bf16 v[34:37], v[166:169], v[198:201], v[34:37]
	v_mfma_f32_16x16x32_bf16 v[22:25], v[158:161], v[206:209], v[22:25]
	v_mfma_f32_16x16x32_bf16 v[18:21], v[166:169], v[206:209], v[18:21]
	v_mfma_f32_16x16x32_bf16 v[6:9], v[158:161], v[214:217], v[6:9]
	v_mfma_f32_16x16x32_bf16 v[2:5], v[166:169], v[214:217], v[2:5]
	v_mfma_f32_16x16x32_bf16 v[54:57], v[162:165], v[194:197], v[54:57]
	v_mfma_f32_16x16x32_bf16 v[50:53], v[170:173], v[194:197], v[50:53]
	v_mfma_f32_16x16x32_bf16 v[38:41], v[162:165], v[202:205], v[38:41]
	v_mfma_f32_16x16x32_bf16 v[34:37], v[170:173], v[202:205], v[34:37]
	v_mfma_f32_16x16x32_bf16 v[22:25], v[162:165], v[210:213], v[22:25]
	v_mfma_f32_16x16x32_bf16 v[18:21], v[170:173], v[210:213], v[18:21]
	v_mfma_f32_16x16x32_bf16 v[6:9], v[162:165], v[218:221], v[6:9]
	v_mfma_f32_16x16x32_bf16 v[2:5], v[170:173], v[218:221], v[2:5]
	s_setprio 0
	s_barrier
	s_add_i32 s51, s51, 2
	s_add_u32 s18, s18, 0x100
	s_addc_u32 s19, s19, 0
	s_add_u32 s35, s35, 0x100
	s_addc_u32 s49, s49, 0
	s_cmp_gt_u32 s51, 13
.LBB0_242:
	s_add_u32 s36, s18, 0xfffc0080
	s_addc_u32 s37, s19, -1
	s_add_i32 s52, 0, 0x10000
	s_cmp_eq_u32 s51, 12
	s_cselect_b32 s63, s1, s37
	s_cselect_b32 s62, s30, s36
	s_cselect_b32 s37, s31, s49
	s_cselect_b32 s36, s34, s35
	s_add_i32 s67, 0, 0x14000
	v_add_u32_e32 v110, s52, v180
	v_add_u32_e32 v170, s67, v180
	ds_read_b128 v[98:101], v110
	ds_read_b128 v[102:105], v110 offset:1024
	ds_read_b128 v[106:109], v110 offset:2048
	ds_read_b128 v[110:113], v110 offset:3072
	ds_read_b128 v[158:161], v170
	ds_read_b128 v[162:165], v170 offset:1024
	ds_read_b128 v[166:169], v170 offset:2048
	ds_read_b128 v[170:173], v170 offset:3072
	v_lshl_add_u64 v[174:175], s[18:19], 0, v[154:155]
	s_add_i32 m0, s27, 0xc000
	ds_read_b128 v[184:187], v182
	ds_read_b128 v[194:197], v182 offset:1024
	ds_read_b128 v[198:201], v182 offset:2048
	ds_read_b128 v[202:205], v182 offset:3072
	ds_read_b128 v[206:209], v182 offset:4096
	ds_read_b128 v[210:213], v182 offset:5120
	ds_read_b128 v[214:217], v182 offset:6144
	ds_read_b128 v[218:221], v182 offset:7168
	global_load_lds_dwordx4 v[174:175], off
	v_lshl_add_u64 v[174:175], s[18:19], 0, v[156:157]
	s_add_i32 m0, s27, 0xe000
	s_nop 0
	global_load_lds_dwordx4 v[174:175], off
	s_waitcnt vmcnt(8)
	s_waitcnt lgkmcnt(0)
	s_barrier
	s_setprio 1
	s_waitcnt lgkmcnt(0)
	v_mfma_f32_16x16x32_bf16 v[142:145], v[98:101], v[184:187], v[142:145]
	v_mfma_f32_16x16x32_bf16 v[138:141], v[106:109], v[184:187], v[138:141]
	v_mfma_f32_16x16x32_bf16 v[126:129], v[98:101], v[198:201], v[126:129]
	v_mfma_f32_16x16x32_bf16 v[122:125], v[106:109], v[198:201], v[122:125]
	v_mfma_f32_16x16x32_bf16 v[94:97], v[98:101], v[206:209], v[94:97]
	v_mfma_f32_16x16x32_bf16 v[90:93], v[106:109], v[206:209], v[90:93]
	v_mfma_f32_16x16x32_bf16 v[78:81], v[98:101], v[214:217], v[78:81]
	v_mfma_f32_16x16x32_bf16 v[74:77], v[106:109], v[214:217], v[74:77]
	v_mfma_f32_16x16x32_bf16 v[142:145], v[102:105], v[194:197], v[142:145]
	v_mfma_f32_16x16x32_bf16 v[138:141], v[110:113], v[194:197], v[138:141]
	v_mfma_f32_16x16x32_bf16 v[126:129], v[102:105], v[202:205], v[126:129]
	v_mfma_f32_16x16x32_bf16 v[122:125], v[110:113], v[202:205], v[122:125]
	v_mfma_f32_16x16x32_bf16 v[94:97], v[102:105], v[210:213], v[94:97]
	v_mfma_f32_16x16x32_bf16 v[90:93], v[110:113], v[210:213], v[90:93]
	v_mfma_f32_16x16x32_bf16 v[78:81], v[102:105], v[218:221], v[78:81]
	v_mfma_f32_16x16x32_bf16 v[74:77], v[110:113], v[218:221], v[74:77]


; #define PG8_STAGE(bufoff, gbase, voff) do { _Pragma("unroll") for (int _i = 0; _i < 2; ++_i) \
;         __builtin_amdgcn_global_load_lds((const unsigned*)((const char*)(gbase) + (voff)[_i]), (PG8_LAS unsigned*)(lds + (bufoff) + ldsw + _i * 8192), 16, 0, 0); } while (0)
; #define PG8_LDA(dst, b, h) do { _Pragma("unroll") for (int m = 0; m < 4; ++m) _Pragma("unroll") for (int k = 0; k < 2; ++k) dst[m][k] = *(const PG8_LAS bf16x8*)(lds + PG8_SA(b, h) + aoff + m * 2048 + k * 1024); } while (0)
; #define PG8_MMA(ai, bj, At, Bt) do { __builtin_amdgcn_s_setprio(1); _Pragma("unroll") for (int m = 0; m < 4; ++m) _Pragma("unroll") for (int n = 0; n < 2; ++n) _Pragma("unroll") for (int k = 0; k < 2; ++k) \
;         acc[ai][bj][m][n] = __builtin_amdgcn_mfma_f32_16x16x32_bf16(Bt[n][k], At[m][k], acc[ai][bj][m][n], 0, 0, 0); __builtin_amdgcn_s_setprio(0); } while (0)
; #define PG8_WAIT_V(n) asm volatile("s_waitcnt vmcnt(" #n ")" ::: "memory")
; #define PG8_WAIT_L(n) asm volatile("s_waitcnt lgkmcnt(" #n ")" ::: "memory")
; #define PG8_BAR __builtin_amdgcn_s_barrier()
; #define PG8_SCHED __builtin_amdgcn_sched_barrier(0)
; template <class Epi, class Sched, bool ALIGN_EPI = false, bool SP2 = false>
; __device__ __forceinline__ void gemm_phase(PG8_LAS unsigned char* lds, const Gemm g, const Sched& S, const Epi& E) {
;     ...
;             PG8_WAIT_V(8); PG8_WAIT_L(0); PG8_BAR; PG8_MMA(0, 0, At, B0); PG8_MMA(0, 1, At, B1); PG8_BAR; PG8_SCHED;
;             PG8_LDA(At, 0, 1); PG8_STAGE(PG8_SB(0, 0), b2, voffB); PG8_STAGE(PG8_SB(0, 1), b2 + hstep, voffB); PG8_STAGE(PG8_SA(0, 0), a2, voffA);
;             PG8_WAIT_V(8); PG8_WAIT_L(0); PG8_BAR; PG8_MMA(1, 0, At, B0); PG8_MMA(1, 1, At, B1); PG8_BAR; PG8_SCHED;
	v_mfma_f32_16x16x32_bf16 v[134:137], v[158:161], v[184:187], v[134:137]
	v_mfma_f32_16x16x32_bf16 v[130:133], v[166:169], v[184:187], v[130:133]
	v_mfma_f32_16x16x32_bf16 v[118:121], v[158:161], v[198:201], v[118:121]
	v_mfma_f32_16x16x32_bf16 v[114:117], v[166:169], v[198:201], v[114:117]
	v_mfma_f32_16x16x32_bf16 v[86:89], v[158:161], v[206:209], v[86:89]
	v_mfma_f32_16x16x32_bf16 v[82:85], v[166:169], v[206:209], v[82:85]
	v_mfma_f32_16x16x32_bf16 v[70:73], v[158:161], v[214:217], v[70:73]
	v_mfma_f32_16x16x32_bf16 v[66:69], v[166:169], v[214:217], v[66:69]
	v_mfma_f32_16x16x32_bf16 v[134:137], v[162:165], v[194:197], v[134:137]
	v_mfma_f32_16x16x32_bf16 v[130:133], v[170:173], v[194:197], v[130:133]
	v_mfma_f32_16x16x32_bf16 v[118:121], v[162:165], v[202:205], v[118:121]
	v_mfma_f32_16x16x32_bf16 v[114:117], v[170:173], v[202:205], v[114:117]
	v_mfma_f32_16x16x32_bf16 v[86:89], v[162:165], v[210:213], v[86:89]
	v_mfma_f32_16x16x32_bf16 v[82:85], v[170:173], v[210:213], v[82:85]
	v_mfma_f32_16x16x32_bf16 v[70:73], v[162:165], v[218:221], v[70:73]
	v_mfma_f32_16x16x32_bf16 v[66:69], v[170:173], v[218:221], v[66:69]
	s_setprio 0
	s_barrier
	s_add_i32 s52, s52, s24
	v_lshl_add_u64 v[174:175], s[36:37], 0, v[0:1]
	s_mov_b32 m0, s52
	ds_read_b128 v[184:187], v182 offset:16384
	ds_read_b128 v[194:197], v182 offset:17408
	ds_read_b128 v[198:201], v182 offset:18432
	ds_read_b128 v[202:205], v182 offset:19456
	ds_read_b128 v[206:209], v182 offset:20480
	ds_read_b128 v[210:213], v182 offset:21504
	ds_read_b128 v[214:217], v182 offset:22528
	ds_read_b128 v[218:221], v182 offset:23552
	global_load_lds_dwordx4 v[174:175], off
	s_add_i32 m0, s52, 0x2000
	s_add_u32 s52, s36, 0x40000
	v_lshl_add_u64 v[178:179], s[36:37], 0, v[150:151]
	s_addc_u32 s53, s37, 0
	s_add_i32 s67, s67, s24
	global_load_lds_dwordx4 v[178:179], off
	v_lshl_add_u64 v[188:189], s[52:53], 0, v[0:1]
	s_mov_b32 m0, s67
	v_lshl_add_u64 v[222:223], s[62:63], 0, v[148:149]
	global_load_lds_dwordx4 v[188:189], off
	v_lshl_add_u64 v[188:189], s[52:53], 0, v[150:151]
	s_add_i32 m0, s67, 0x2000
	s_nop 0
	global_load_lds_dwordx4 v[188:189], off
	v_lshl_add_u64 v[188:189], s[62:63], 0, v[146:147]
	s_mov_b32 m0, s27
	s_nop 0
	global_load_lds_dwordx4 v[188:189], off
	s_mov_b32 m0, s28
	s_nop 0
	global_load_lds_dwordx4 v[222:223], off
	s_waitcnt vmcnt(8)
	s_waitcnt lgkmcnt(0)
	s_barrier
	s_setprio 1
	s_waitcnt lgkmcnt(0)
	v_mfma_f32_16x16x32_bf16 v[62:65], v[98:101], v[184:187], v[62:65]
	v_mfma_f32_16x16x32_bf16 v[58:61], v[106:109], v[184:187], v[58:61]
	v_mfma_f32_16x16x32_bf16 v[46:49], v[98:101], v[198:201], v[46:49]
	v_mfma_f32_16x16x32_bf16 v[42:45], v[106:109], v[198:201], v[42:45]
	v_mfma_f32_16x16x32_bf16 v[30:33], v[98:101], v[206:209], v[30:33]
	v_mfma_f32_16x16x32_bf16 v[26:29], v[106:109], v[206:209], v[26:29]
	v_mfma_f32_16x16x32_bf16 v[14:17], v[98:101], v[214:217], v[14:17]
	v_mfma_f32_16x16x32_bf16 v[10:13], v[106:109], v[214:217], v[10:13]
	v_mfma_f32_16x16x32_bf16 v[62:65], v[102:105], v[194:197], v[62:65]
	v_mfma_f32_16x16x32_bf16 v[58:61], v[110:113], v[194:197], v[58:61]
	v_mfma_f32_16x16x32_bf16 v[46:49], v[102:105], v[202:205], v[46:49]
	v_mfma_f32_16x16x32_bf16 v[42:45], v[110:113], v[202:205], v[42:45]
	v_mfma_f32_16x16x32_bf16 v[30:33], v[102:105], v[210:213], v[30:33]
	v_mfma_f32_16x16x32_bf16 v[26:29], v[110:113], v[210:213], v[26:29]
	v_mfma_f32_16x16x32_bf16 v[14:17], v[102:105], v[218:221], v[14:17]
	v_mfma_f32_16x16x32_bf16 v[10:13], v[110:113], v[218:221], v[10:13]


; #define PG8_STAGE(bufoff, gbase, voff) do { _Pragma("unroll") for (int _i = 0; _i < 2; ++_i) \
;         __builtin_amdgcn_global_load_lds((const unsigned*)((const char*)(gbase) + (voff)[_i]), (PG8_LAS unsigned*)(lds + (bufoff) + ldsw + _i * 8192), 16, 0, 0); } while (0)
; #define PG8_LDA(dst, b, h) do { _Pragma("unroll") for (int m = 0; m < 4; ++m) _Pragma("unroll") for (int k = 0; k < 2; ++k) dst[m][k] = *(const PG8_LAS bf16x8*)(lds + PG8_SA(b, h) + aoff + m * 2048 + k * 1024); } while (0)
; #define PG8_LDB(dst, b, h) do { _Pragma("unroll") for (int n = 0; n < 2; ++n) _Pragma("unroll") for (int k = 0; k < 2; ++k) dst[n][k] = *(const PG8_LAS bf16x8*)(lds + PG8_SB(b, h) + boff + n * 2048 + k * 1024); } while (0)
; #define PG8_MMA(ai, bj, At, Bt) do { __builtin_amdgcn_s_setprio(1); _Pragma("unroll") for (int m = 0; m < 4; ++m) _Pragma("unroll") for (int n = 0; n < 2; ++n) _Pragma("unroll") for (int k = 0; k < 2; ++k) \
;         acc[ai][bj][m][n] = __builtin_amdgcn_mfma_f32_16x16x32_bf16(Bt[n][k], At[m][k], acc[ai][bj][m][n], 0, 0, 0); __builtin_amdgcn_s_setprio(0); } while (0)
; #define PG8_WAIT_V(n) asm volatile("s_waitcnt vmcnt(" #n ")" ::: "memory")
; #define PG8_WAIT_L(n) asm volatile("s_waitcnt lgkmcnt(" #n ")" ::: "memory")
; #define PG8_BAR __builtin_amdgcn_s_barrier()
; #define PG8_SCHED __builtin_amdgcn_sched_barrier(0)
; template <class Epi, class Sched, bool ALIGN_EPI = false, bool SP2 = false>
; __device__ __forceinline__ void gemm_phase(PG8_LAS unsigned char* lds, const Gemm g, const Sched& S, const Epi& E) {
;     ...
;             PG8_WAIT_V(8); PG8_WAIT_L(0); PG8_BAR; PG8_MMA(1, 0, At, B0); PG8_MMA(1, 1, At, B1); PG8_BAR; PG8_SCHED;
;             PG8_LDB(B0, 1, 0); PG8_LDB(B1, 1, 1); PG8_SCHED; PG8_LDA(At, 1, 0); PG8_STAGE(PG8_SA(0, 1), a2 + hstep, voffA);
;             PG8_WAIT_V(8); PG8_WAIT_L(0); PG8_BAR; PG8_MMA(0, 0, At, B0); PG8_MMA(0, 1, At, B1); PG8_BAR; PG8_SCHED;
	v_mfma_f32_16x16x32_bf16 v[54:57], v[158:161], v[184:187], v[54:57]
	v_mfma_f32_16x16x32_bf16 v[50:53], v[166:169], v[184:187], v[50:53]
	v_mfma_f32_16x16x32_bf16 v[38:41], v[158:161], v[198:201], v[38:41]
	v_mfma_f32_16x16x32_bf16 v[34:37], v[166:169], v[198:201], v[34:37]
	v_mfma_f32_16x16x32_bf16 v[22:25], v[158:161], v[206:209], v[22:25]
	v_mfma_f32_16x16x32_bf16 v[18:21], v[166:169], v[206:209], v[18:21]
	v_mfma_f32_16x16x32_bf16 v[6:9], v[158:161], v[214:217], v[6:9]
	v_mfma_f32_16x16x32_bf16 v[2:5], v[166:169], v[214:217], v[2:5]
	v_mfma_f32_16x16x32_bf16 v[54:57], v[162:165], v[194:197], v[54:57]
	v_mfma_f32_16x16x32_bf16 v[50:53], v[170:173], v[194:197], v[50:53]
	v_mfma_f32_16x16x32_bf16 v[38:41], v[162:165], v[202:205], v[38:41]
	v_mfma_f32_16x16x32_bf16 v[34:37], v[170:173], v[202:205], v[34:37]
	v_mfma_f32_16x16x32_bf16 v[22:25], v[162:165], v[210:213], v[22:25]
	v_mfma_f32_16x16x32_bf16 v[18:21], v[170:173], v[210:213], v[18:21]
	v_mfma_f32_16x16x32_bf16 v[6:9], v[162:165], v[218:221], v[6:9]
	v_mfma_f32_16x16x32_bf16 v[2:5], v[170:173], v[218:221], v[2:5]
	s_setprio 0
	s_barrier
	s_add_i32 s67, 0, 0x18000
	s_add_i32 s68, 0, 0x1c000
	v_add_u32_e32 v110, s67, v180
	v_add_u32_e32 v170, s68, v180
	ds_read_b128 v[98:101], v110
	ds_read_b128 v[102:105], v110 offset:1024
	ds_read_b128 v[106:109], v110 offset:2048
	ds_read_b128 v[110:113], v110 offset:3072
	ds_read_b128 v[158:161], v170
	ds_read_b128 v[162:165], v170 offset:1024
	ds_read_b128 v[166:169], v170 offset:2048
	ds_read_b128 v[170:173], v170 offset:3072
	s_add_u32 s52, s62, 0x40000
	s_addc_u32 s53, s63, 0
	s_mov_b32 m0, s29
	v_lshl_add_u64 v[224:225], s[52:53], 0, v[146:147]
	ds_read_b128 v[184:187], v182 offset:32768
	ds_read_b128 v[194:197], v182 offset:33792
	ds_read_b128 v[198:201], v182 offset:34816
	ds_read_b128 v[202:205], v182 offset:35840
	ds_read_b128 v[206:209], v182 offset:36864
	ds_read_b128 v[210:213], v182 offset:37888
	ds_read_b128 v[214:217], v182 offset:38912
	ds_read_b128 v[218:221], v182 offset:39936
	global_load_lds_dwordx4 v[224:225], off
	v_lshl_add_u64 v[224:225], s[52:53], 0, v[148:149]
	s_mov_b32 m0, s61
	s_nop 0
	global_load_lds_dwordx4 v[224:225], off
	s_waitcnt vmcnt(8)
	s_waitcnt lgkmcnt(0)
	s_barrier
	s_setprio 1
	s_waitcnt lgkmcnt(0)
	v_mfma_f32_16x16x32_bf16 v[142:145], v[98:101], v[184:187], v[142:145]
	v_mfma_f32_16x16x32_bf16 v[138:141], v[106:109], v[184:187], v[138:141]
	v_mfma_f32_16x16x32_bf16 v[126:129], v[98:101], v[198:201], v[126:129]
	v_mfma_f32_16x16x32_bf16 v[122:125], v[106:109], v[198:201], v[122:125]
	v_mfma_f32_16x16x32_bf16 v[94:97], v[98:101], v[206:209], v[94:97]
	v_mfma_f32_16x16x32_bf16 v[90:93], v[106:109], v[206:209], v[90:93]
	v_mfma_f32_16x16x32_bf16 v[78:81], v[98:101], v[214:217], v[78:81]
	v_mfma_f32_16x16x32_bf16 v[74:77], v[106:109], v[214:217], v[74:77]
	v_mfma_f32_16x16x32_bf16 v[142:145], v[102:105], v[194:197], v[142:145]
	v_mfma_f32_16x16x32_bf16 v[138:141], v[110:113], v[194:197], v[138:141]
	v_mfma_f32_16x16x32_bf16 v[126:129], v[102:105], v[202:205], v[126:129]
	v_mfma_f32_16x16x32_bf16 v[122:125], v[110:113], v[202:205], v[122:125]
	v_mfma_f32_16x16x32_bf16 v[94:97], v[102:105], v[210:213], v[94:97]
	v_mfma_f32_16x16x32_bf16 v[90:93], v[110:113], v[210:213], v[90:93]
	v_mfma_f32_16x16x32_bf16 v[78:81], v[102:105], v[218:221], v[78:81]
	v_mfma_f32_16x16x32_bf16 v[74:77], v[110:113], v[218:221], v[74:77]


; #define PG8_STAGE(bufoff, gbase, voff) do { _Pragma("unroll") for (int _i = 0; _i < 2; ++_i) \
;         __builtin_amdgcn_global_load_lds((const unsigned*)((const char*)(gbase) + (voff)[_i]), (PG8_LAS unsigned*)(lds + (bufoff) + ldsw + _i * 8192), 16, 0, 0); } while (0)
; #define PG8_LDA(dst, b, h) do { _Pragma("unroll") for (int m = 0; m < 4; ++m) _Pragma("unroll") for (int k = 0; k < 2; ++k) dst[m][k] = *(const PG8_LAS bf16x8*)(lds + PG8_SA(b, h) + aoff + m * 2048 + k * 1024); } while (0)
; #define PG8_MMA(ai, bj, At, Bt) do { __builtin_amdgcn_s_setprio(1); _Pragma("unroll") for (int m = 0; m < 4; ++m) _Pragma("unroll") for (int n = 0; n < 2; ++n) _Pragma("unroll") for (int k = 0; k < 2; ++k) \
;         acc[ai][bj][m][n] = __builtin_amdgcn_mfma_f32_16x16x32_bf16(Bt[n][k], At[m][k], acc[ai][bj][m][n], 0, 0, 0); __builtin_amdgcn_s_setprio(0); } while (0)
; #define PG8_WAIT_V(n) asm volatile("s_waitcnt vmcnt(" #n ")" ::: "memory")
; #define PG8_WAIT_L(n) asm volatile("s_waitcnt lgkmcnt(" #n ")" ::: "memory")
; #define PG8_BAR __builtin_amdgcn_s_barrier()
; #define PG8_SCHED __builtin_amdgcn_sched_barrier(0)
; template <class Epi, class Sched, bool ALIGN_EPI = false, bool SP2 = false>
; __device__ __forceinline__ void gemm_phase(PG8_LAS unsigned char* lds, const Gemm g, const Sched& S, const Epi& E) {
;     ...
;             PG8_WAIT_V(8); PG8_WAIT_L(0); PG8_BAR; PG8_MMA(0, 0, At, B0); PG8_MMA(0, 1, At, B1); PG8_BAR; PG8_SCHED;
;             PG8_LDA(At, 1, 1); PG8_STAGE(PG8_SB(1, 0), b3, voffB); PG8_STAGE(PG8_SB(1, 1), b3 + hstep, voffB); PG8_STAGE(PG8_SA(1, 0), a3, voffA);
;             PG8_WAIT_V(8); PG8_WAIT_L(0); PG8_BAR; PG8_MMA(1, 0, At, B0); PG8_MMA(1, 1, At, B1); PG8_BAR; PG8_SCHED;
	v_mfma_f32_16x16x32_bf16 v[134:137], v[158:161], v[184:187], v[134:137]
	v_mfma_f32_16x16x32_bf16 v[130:133], v[166:169], v[184:187], v[130:133]
	v_mfma_f32_16x16x32_bf16 v[118:121], v[158:161], v[198:201], v[118:121]
	v_mfma_f32_16x16x32_bf16 v[114:117], v[166:169], v[198:201], v[114:117]
	v_mfma_f32_16x16x32_bf16 v[86:89], v[158:161], v[206:209], v[86:89]
	v_mfma_f32_16x16x32_bf16 v[82:85], v[166:169], v[206:209], v[82:85]
	v_mfma_f32_16x16x32_bf16 v[70:73], v[158:161], v[214:217], v[70:73]
	v_mfma_f32_16x16x32_bf16 v[66:69], v[166:169], v[214:217], v[66:69]
	v_mfma_f32_16x16x32_bf16 v[134:137], v[162:165], v[194:197], v[134:137]
	v_mfma_f32_16x16x32_bf16 v[130:133], v[170:173], v[194:197], v[130:133]
	v_mfma_f32_16x16x32_bf16 v[118:121], v[162:165], v[202:205], v[118:121]
	v_mfma_f32_16x16x32_bf16 v[114:117], v[170:173], v[202:205], v[114:117]
	v_mfma_f32_16x16x32_bf16 v[86:89], v[162:165], v[210:213], v[86:89]
	v_mfma_f32_16x16x32_bf16 v[82:85], v[170:173], v[210:213], v[82:85]
	v_mfma_f32_16x16x32_bf16 v[70:73], v[162:165], v[218:221], v[70:73]
	v_mfma_f32_16x16x32_bf16 v[66:69], v[170:173], v[218:221], v[66:69]
	s_setprio 0
	s_barrier
	s_add_i32 s52, s67, s24
	v_lshl_add_u64 v[174:175], v[174:175], 0, s[8:9]
	s_mov_b32 m0, s52
	ds_read_b128 v[184:187], v182 offset:49152
	ds_read_b128 v[194:197], v182 offset:50176
	ds_read_b128 v[198:201], v182 offset:51200
	ds_read_b128 v[202:205], v182 offset:52224
	ds_read_b128 v[206:209], v182 offset:53248
	ds_read_b128 v[210:213], v182 offset:54272
	ds_read_b128 v[214:217], v182 offset:55296
	ds_read_b128 v[218:221], v182 offset:56320
	global_load_lds_dwordx4 v[174:175], off
	s_add_i32 m0, s52, 0x2000
	s_add_u32 s36, s36, 0x40080
	v_lshl_add_u64 v[174:175], v[178:179], 0, s[8:9]
	s_addc_u32 s37, s37, 0
	s_add_i32 s52, s68, s24
	global_load_lds_dwordx4 v[174:175], off
	v_lshl_add_u64 v[174:175], s[36:37], 0, v[0:1]
	s_mov_b32 m0, s52
	s_nop 0
	global_load_lds_dwordx4 v[174:175], off
	v_lshl_add_u64 v[174:175], s[36:37], 0, v[150:151]
	s_add_i32 m0, s52, 0x2000
	s_nop 0
	global_load_lds_dwordx4 v[174:175], off
	v_lshl_add_u64 v[174:175], v[188:189], 0, s[8:9]
	s_mov_b32 m0, s64
	s_nop 0
	global_load_lds_dwordx4 v[174:175], off
	v_lshl_add_u64 v[174:175], v[222:223], 0, s[8:9]
	s_mov_b32 m0, s65
	s_nop 0
	global_load_lds_dwordx4 v[174:175], off
	s_waitcnt vmcnt(8)
	s_waitcnt lgkmcnt(0)
	s_barrier
	s_setprio 1
	s_waitcnt lgkmcnt(0)
	v_mfma_f32_16x16x32_bf16 v[62:65], v[98:101], v[184:187], v[62:65]
	v_mfma_f32_16x16x32_bf16 v[58:61], v[106:109], v[184:187], v[58:61]
	v_mfma_f32_16x16x32_bf16 v[46:49], v[98:101], v[198:201], v[46:49]
	v_mfma_f32_16x16x32_bf16 v[42:45], v[106:109], v[198:201], v[42:45]
	v_mfma_f32_16x16x32_bf16 v[30:33], v[98:101], v[206:209], v[30:33]
	v_mfma_f32_16x16x32_bf16 v[26:29], v[106:109], v[206:209], v[26:29]
	v_mfma_f32_16x16x32_bf16 v[14:17], v[98:101], v[214:217], v[14:17]
	v_mfma_f32_16x16x32_bf16 v[10:13], v[106:109], v[214:217], v[10:13]
	v_mfma_f32_16x16x32_bf16 v[62:65], v[102:105], v[194:197], v[62:65]
	v_mfma_f32_16x16x32_bf16 v[58:61], v[110:113], v[194:197], v[58:61]
	v_mfma_f32_16x16x32_bf16 v[46:49], v[102:105], v[202:205], v[46:49]
	v_mfma_f32_16x16x32_bf16 v[42:45], v[110:113], v[202:205], v[42:45]
	v_mfma_f32_16x16x32_bf16 v[30:33], v[102:105], v[210:213], v[30:33]
	v_mfma_f32_16x16x32_bf16 v[26:29], v[110:113], v[210:213], v[26:29]
	v_mfma_f32_16x16x32_bf16 v[14:17], v[102:105], v[218:221], v[14:17]
	v_mfma_f32_16x16x32_bf16 v[10:13], v[110:113], v[218:221], v[10:13]


; #define PG8_STAGE(bufoff, gbase, voff) do { _Pragma("unroll") for (int _i = 0; _i < 2; ++_i) \
;         __builtin_amdgcn_global_load_lds((const unsigned*)((const char*)(gbase) + (voff)[_i]), (PG8_LAS unsigned*)(lds + (bufoff) + ldsw + _i * 8192), 16, 0, 0); } while (0)
; #define PG8_LDA(dst, b, h) do { _Pragma("unroll") for (int m = 0; m < 4; ++m) _Pragma("unroll") for (int k = 0; k < 2; ++k) dst[m][k] = *(const PG8_LAS bf16x8*)(lds + PG8_SA(b, h) + aoff + m * 2048 + k * 1024); } while (0)
; #define PG8_LDB(dst, b, h) do { _Pragma("unroll") for (int n = 0; n < 2; ++n) _Pragma("unroll") for (int k = 0; k < 2; ++k) dst[n][k] = *(const PG8_LAS bf16x8*)(lds + PG8_SB(b, h) + boff + n * 2048 + k * 1024); } while (0)
; template <class Epi, class Sched, bool ALIGN_EPI = false, bool SP2 = false>
; __device__ __forceinline__ void gemm_phase(PG8_LAS unsigned char* lds, const Gemm g, const Sched& S, const Epi& E) {
;     ...
;         for (int t = 0; t < nt; t += 2) {
;             const bool last = (t == nt - 2);
;             const char* a1 = cA + (size_t)(t + 1) * kstep;
;             const char* a2 = last ? nA : cA + (size_t)(t + 2) * kstep; const char* b2 = last ? nB : cB + (size_t)(t + 2) * kstep;
;             const char* a3 = a2 + kstep; const char* b3 = b2 + kstep;
;             if (last && has_next) S.a_ready(nxt);
;             if constexpr (SP2) {
;             PG8_LDB(B0, 0, 0); PG8_LDB(B1, 0, 1); PG8_SCHED; PG8_LDA(At, 0, 0); PG8_STAGE(PG8_SA(1, 1), a1 + hstep, voffA);
;             PG8_WAIT_V(8); PG8_WAIT_L(0); PG8_BAR; PG8_MMA(0, 0, At, B0); PG8_MMA(0, 1, At, B1); PG8_BAR; PG8_SCHED;
;             PG8_LDA(At, 0, 1); PG8_STAGE(PG8_SB(0, 0), b2, voffB); PG8_STAGE(PG8_SB(0, 1), b2 + hstep, voffB); PG8_STAGE(PG8_SA(0, 0), a2, voffA);
;             PG8_WAIT_V(8); PG8_WAIT_L(0); PG8_BAR; PG8_MMA(1, 0, At, B0); PG8_MMA(1, 1, At, B1); PG8_BAR; PG8_SCHED;
;             PG8_LDB(B0, 1, 0); PG8_LDB(B1, 1, 1); PG8_SCHED; PG8_LDA(At, 1, 0); PG8_STAGE(PG8_SA(0, 1), a2 + hstep, voffA);
;             PG8_WAIT_V(8); PG8_WAIT_L(0); PG8_BAR; PG8_MMA(0, 0, At, B0); PG8_MMA(0, 1, At, B1); PG8_BAR; PG8_SCHED;
;             PG8_LDA(At, 1, 1); PG8_STAGE(PG8_SB(1, 0), b3, voffB); PG8_STAGE(PG8_SB(1, 1), b3 + hstep, voffB); PG8_STAGE(PG8_SA(1, 0), a3, voffA);
;             PG8_WAIT_V(8); PG8_WAIT_L(0); PG8_BAR; PG8_MMA(1, 0, At, B0); PG8_MMA(1, 1, At, B1); PG8_BAR; PG8_SCHED;
	v_mfma_f32_16x16x32_bf16 v[54:57], v[158:161], v[184:187], v[54:57]
	v_mfma_f32_16x16x32_bf16 v[50:53], v[166:169], v[184:187], v[50:53]
	v_mfma_f32_16x16x32_bf16 v[38:41], v[158:161], v[198:201], v[38:41]
	v_mfma_f32_16x16x32_bf16 v[34:37], v[166:169], v[198:201], v[34:37]
	v_mfma_f32_16x16x32_bf16 v[22:25], v[158:161], v[206:209], v[22:25]
	v_mfma_f32_16x16x32_bf16 v[18:21], v[166:169], v[206:209], v[18:21]
	v_mfma_f32_16x16x32_bf16 v[6:9], v[158:161], v[214:217], v[6:9]
	v_mfma_f32_16x16x32_bf16 v[2:5], v[166:169], v[214:217], v[2:5]
	v_mfma_f32_16x16x32_bf16 v[54:57], v[162:165], v[194:197], v[54:57]
	v_mfma_f32_16x16x32_bf16 v[50:53], v[170:173], v[194:197], v[50:53]
	v_mfma_f32_16x16x32_bf16 v[38:41], v[162:165], v[202:205], v[38:41]
	v_mfma_f32_16x16x32_bf16 v[34:37], v[170:173], v[202:205], v[34:37]
	v_mfma_f32_16x16x32_bf16 v[22:25], v[162:165], v[210:213], v[22:25]
	v_mfma_f32_16x16x32_bf16 v[18:21], v[170:173], v[210:213], v[18:21]
	v_mfma_f32_16x16x32_bf16 v[6:9], v[162:165], v[218:221], v[6:9]
	v_mfma_f32_16x16x32_bf16 v[2:5], v[170:173], v[218:221], v[2:5]
	s_setprio 0
	s_barrier
	s_add_i32 s51, s51, 2
	s_add_u32 s18, s18, 0x100
	s_addc_u32 s19, s19, 0
	s_add_u32 s35, s35, 0x100
	s_addc_u32 s49, s49, 0
	s_cmp_gt_u32 s51, 13
	s_cbranch_scc0 .LBB0_242



; template <class Epi, class Sched, bool ALIGN_EPI = false, bool SP2 = false>
; __device__ __forceinline__ void gemm_phase(PG8_LAS unsigned char* lds, const Gemm g, const Sched& S, const Epi& E) {
;     ...
;         const bool has_next = S.next(ui + 1, nxt);
;         const char* nA = has_next ? (const char*)g.A + (size_t)nxt.pm * tstep : cA; const char* nB = has_next ? (const char*)g.Bt + (size_t)nxt.pn * tstep : cB;
;         for (int t = 0; t < nt; t += 2) {
;             const bool last = (t == nt - 2);
;             const char* a1 = cA + (size_t)(t + 1) * kstep;
;             const char* a2 = last ? nA : cA + (size_t)(t + 2) * kstep; const char* b2 = last ? nB : cB + (size_t)(t + 2) * kstep;
;             const char* a3 = a2 + kstep; const char* b3 = b2 + kstep;
.LBB0_290:
	s_ashr_i32 s45, s44, 31
	s_lshl_b64 s[30:31], s[44:45], 19
	s_add_u32 s50, s25, s30
	s_addc_u32 s51, s26, s31
	s_and_b64 s[30:31], s[48:49], exec
	s_cselect_b32 s30, s51, s19
	s_cselect_b32 s31, s50, s18
	s_ashr_i32 s43, s42, 31
	s_lshl_b64 s[34:35], s[42:43], 19
	s_add_u32 s54, s96, s34
	s_addc_u32 s55, s97, s35
	s_and_b64 s[34:35], s[48:49], exec
	s_cselect_b32 s34, s55, s59
	s_cselect_b32 s35, s54, s58
	s_add_u32 s18, s18, 0x40080
	s_addc_u32 s19, s19, 0
	s_add_u32 s43, s58, 0x100

; template <class Epi, class Sched, bool ALIGN_EPI = false, bool SP2 = false>
; __device__ __forceinline__ void gemm_phase(PG8_LAS unsigned char* lds, const Gemm g, const Sched& S, const Epi& E) {
;     ...
;         for (int t = 0; t < nt; t += 2) {
;             const bool last = (t == nt - 2);
;             const char* a1 = cA + (size_t)(t + 1) * kstep;
;             const char* a2 = last ? nA : cA + (size_t)(t + 2) * kstep; const char* b2 = last ? nB : cB + (size_t)(t + 2) * kstep;
	s_addc_u32 s45, s59, 0
	s_mov_b32 s52, -2


; #define PG8_STAGE(bufoff, gbase, voff) do { _Pragma("unroll") for (int _i = 0; _i < 2; ++_i) \
;         __builtin_amdgcn_global_load_lds((const unsigned*)((const char*)(gbase) + (voff)[_i]), (PG8_LAS unsigned*)(lds + (bufoff) + ldsw + _i * 8192), 16, 0, 0); } while (0)
; #define PG8_LDA(dst, b, h) do { _Pragma("unroll") for (int m = 0; m < 4; ++m) _Pragma("unroll") for (int k = 0; k < 2; ++k) dst[m][k] = *(const PG8_LAS bf16x8*)(lds + PG8_SA(b, h) + aoff + m * 2048 + k * 1024); } while (0)
; #define PG8_LDB(dst, b, h) do { _Pragma("unroll") for (int n = 0; n < 2; ++n) _Pragma("unroll") for (int k = 0; k < 2; ++k) dst[n][k] = *(const PG8_LAS bf16x8*)(lds + PG8_SB(b, h) + boff + n * 2048 + k * 1024); } while (0)
; #define PG8_MMA(ai, bj, At, Bt) do { __builtin_amdgcn_s_setprio(1); _Pragma("unroll") for (int m = 0; m < 4; ++m) _Pragma("unroll") for (int n = 0; n < 2; ++n) _Pragma("unroll") for (int k = 0; k < 2; ++k) \
;         acc[ai][bj][m][n] = __builtin_amdgcn_mfma_f32_16x16x32_bf16(Bt[n][k], At[m][k], acc[ai][bj][m][n], 0, 0, 0); __builtin_amdgcn_s_setprio(0); } while (0)
; #define PG8_WAIT_V(n) asm volatile("s_waitcnt vmcnt(" #n ")" ::: "memory")
; #define PG8_WAIT_L(n) asm volatile("s_waitcnt lgkmcnt(" #n ")" ::: "memory")
; #define PG8_BAR __builtin_amdgcn_s_barrier()
; #define PG8_SCHED __builtin_amdgcn_sched_barrier(0)
; template <class Epi, class Sched, bool ALIGN_EPI = false, bool SP2 = false>
; __device__ __forceinline__ void gemm_phase(PG8_LAS unsigned char* lds, const Gemm g, const Sched& S, const Epi& E) {
;     ...
;             const bool last = (t == nt - 2);
;             const char* a1 = cA + (size_t)(t + 1) * kstep;
;             const char* a2 = last ? nA : cA + (size_t)(t + 2) * kstep; const char* b2 = last ? nB : cB + (size_t)(t + 2) * kstep;
;             const char* a3 = a2 + kstep; const char* b3 = b2 + kstep;
;             if (last && has_next) S.a_ready(nxt);
;             if constexpr (SP2) {
;             PG8_LDB(B0, 0, 0); PG8_LDB(B1, 0, 1); PG8_SCHED; PG8_LDA(At, 0, 0); PG8_STAGE(PG8_SA(1, 1), a1 + hstep, voffA);
;             PG8_WAIT_V(8); PG8_WAIT_L(0); PG8_BAR; PG8_MMA(0, 0, At, B0); PG8_MMA(0, 1, At, B1); PG8_BAR; PG8_SCHED;
	s_add_u32 s53, s18, 0xfffc0080
	s_addc_u32 s58, s19, -1
	s_add_i32 s64, 0, 0x10000
	s_cmp_eq_u32 s52, 12
	s_cselect_b32 s61, s30, s58
	s_cselect_b32 s60, s31, s53
	s_cselect_b32 s59, s34, s45
	s_cselect_b32 s58, s35, s43
	s_add_i32 s53, 0, 0x14000
	v_add_u32_e32 v142, s64, v167
	v_add_u32_e32 v164, s53, v167
	ds_read_b128 v[130:133], v142
	ds_read_b128 v[134:137], v142 offset:1024
	ds_read_b128 v[138:141], v142 offset:2048
	ds_read_b128 v[142:145], v142 offset:3072
	ds_read_b128 v[156:159], v164
	ds_read_b128 v[160:163], v164 offset:1024
	ds_read_b128 v[170:173], v164 offset:2048
	ds_read_b128 v[174:177], v164 offset:3072
	v_lshl_add_u64 v[164:165], s[18:19], 0, v[152:153]
	s_add_i32 m0, s27, 0xc000
	ds_read_b128 v[178:181], v169
	ds_read_b128 v[182:185], v169 offset:1024
	ds_read_b128 v[186:189], v169 offset:2048
	ds_read_b128 v[194:197], v169 offset:3072
	ds_read_b128 v[198:201], v169 offset:4096
	ds_read_b128 v[202:205], v169 offset:5120
	ds_read_b128 v[206:209], v169 offset:6144
	ds_read_b128 v[210:213], v169 offset:7168
	global_load_lds_dwordx4 v[164:165], off
	v_lshl_add_u64 v[164:165], s[18:19], 0, v[154:155]
	s_add_i32 m0, s27, 0xe000
	s_nop 0
	global_load_lds_dwordx4 v[164:165], off
	s_waitcnt vmcnt(8)
	s_waitcnt lgkmcnt(0)
	s_barrier
	s_setprio 1
	s_waitcnt lgkmcnt(0)
	v_mfma_f32_16x16x32_bf16 v[126:129], v[130:133], v[178:181], 0
	v_mfma_f32_16x16x32_bf16 v[122:125], v[138:141], v[178:181], 0
	v_mfma_f32_16x16x32_bf16 v[114:117], v[130:133], v[186:189], 0
	v_mfma_f32_16x16x32_bf16 v[110:113], v[138:141], v[186:189], 0
	v_mfma_f32_16x16x32_bf16 v[102:105], v[130:133], v[198:201], 0
	v_mfma_f32_16x16x32_bf16 v[94:97], v[138:141], v[198:201], 0
	v_mfma_f32_16x16x32_bf16 v[86:89], v[130:133], v[206:209], 0
	v_mfma_f32_16x16x32_bf16 v[78:81], v[138:141], v[206:209], 0
	v_mfma_f32_16x16x32_bf16 v[126:129], v[134:137], v[182:185], v[126:129]
	v_mfma_f32_16x16x32_bf16 v[122:125], v[142:145], v[182:185], v[122:125]
	v_mfma_f32_16x16x32_bf16 v[114:117], v[134:137], v[194:197], v[114:117]
	v_mfma_f32_16x16x32_bf16 v[110:113], v[142:145], v[194:197], v[110:113]
	v_mfma_f32_16x16x32_bf16 v[102:105], v[134:137], v[202:205], v[102:105]
	v_mfma_f32_16x16x32_bf16 v[94:97], v[142:145], v[202:205], v[94:97]
	v_mfma_f32_16x16x32_bf16 v[86:89], v[134:137], v[210:213], v[86:89]
	v_mfma_f32_16x16x32_bf16 v[78:81], v[142:145], v[210:213], v[78:81]


; #define PG8_STAGE(bufoff, gbase, voff) do { _Pragma("unroll") for (int _i = 0; _i < 2; ++_i) \
;         __builtin_amdgcn_global_load_lds((const unsigned*)((const char*)(gbase) + (voff)[_i]), (PG8_LAS unsigned*)(lds + (bufoff) + ldsw + _i * 8192), 16, 0, 0); } while (0)
; #define PG8_LDA(dst, b, h) do { _Pragma("unroll") for (int m = 0; m < 4; ++m) _Pragma("unroll") for (int k = 0; k < 2; ++k) dst[m][k] = *(const PG8_LAS bf16x8*)(lds + PG8_SA(b, h) + aoff + m * 2048 + k * 1024); } while (0)
; #define PG8_MMA(ai, bj, At, Bt) do { __builtin_amdgcn_s_setprio(1); _Pragma("unroll") for (int m = 0; m < 4; ++m) _Pragma("unroll") for (int n = 0; n < 2; ++n) _Pragma("unroll") for (int k = 0; k < 2; ++k) \
;         acc[ai][bj][m][n] = __builtin_amdgcn_mfma_f32_16x16x32_bf16(Bt[n][k], At[m][k], acc[ai][bj][m][n], 0, 0, 0); __builtin_amdgcn_s_setprio(0); } while (0)
; #define PG8_WAIT_V(n) asm volatile("s_waitcnt vmcnt(" #n ")" ::: "memory")
; #define PG8_WAIT_L(n) asm volatile("s_waitcnt lgkmcnt(" #n ")" ::: "memory")
; #define PG8_BAR __builtin_amdgcn_s_barrier()
; #define PG8_SCHED __builtin_amdgcn_sched_barrier(0)
; template <class Epi, class Sched, bool ALIGN_EPI = false, bool SP2 = false>
; __device__ __forceinline__ void gemm_phase(PG8_LAS unsigned char* lds, const Gemm g, const Sched& S, const Epi& E) {
;     ...
;             PG8_WAIT_V(8); PG8_WAIT_L(0); PG8_BAR; PG8_MMA(0, 0, At, B0); PG8_MMA(0, 1, At, B1); PG8_BAR; PG8_SCHED;
;             PG8_LDA(At, 0, 1); PG8_STAGE(PG8_SB(0, 0), b2, voffB); PG8_STAGE(PG8_SB(0, 1), b2 + hstep, voffB); PG8_STAGE(PG8_SA(0, 0), a2, voffA);
;             PG8_WAIT_V(8); PG8_WAIT_L(0); PG8_BAR; PG8_MMA(1, 0, At, B0); PG8_MMA(1, 1, At, B1); PG8_BAR; PG8_SCHED;
	v_mfma_f32_16x16x32_bf16 v[118:121], v[156:159], v[178:181], 0
	v_mfma_f32_16x16x32_bf16 v[106:109], v[170:173], v[178:181], 0
	v_mfma_f32_16x16x32_bf16 v[98:101], v[156:159], v[186:189], 0
	v_mfma_f32_16x16x32_bf16 v[90:93], v[170:173], v[186:189], 0
	v_mfma_f32_16x16x32_bf16 v[82:85], v[156:159], v[198:201], 0
	v_mfma_f32_16x16x32_bf16 v[74:77], v[170:173], v[198:201], 0
	v_mfma_f32_16x16x32_bf16 v[70:73], v[156:159], v[206:209], 0
	v_mfma_f32_16x16x32_bf16 v[66:69], v[170:173], v[206:209], 0
	v_mfma_f32_16x16x32_bf16 v[118:121], v[160:163], v[182:185], v[118:121]
	v_mfma_f32_16x16x32_bf16 v[106:109], v[174:177], v[182:185], v[106:109]
	v_mfma_f32_16x16x32_bf16 v[98:101], v[160:163], v[194:197], v[98:101]
	v_mfma_f32_16x16x32_bf16 v[90:93], v[174:177], v[194:197], v[90:93]
	v_mfma_f32_16x16x32_bf16 v[82:85], v[160:163], v[202:205], v[82:85]
	v_mfma_f32_16x16x32_bf16 v[74:77], v[174:177], v[202:205], v[74:77]
	v_mfma_f32_16x16x32_bf16 v[70:73], v[160:163], v[210:213], v[70:73]
	v_mfma_f32_16x16x32_bf16 v[66:69], v[174:177], v[210:213], v[66:69]
	s_setprio 0
	s_barrier
	s_add_i32 s64, s64, s24
	v_lshl_add_u64 v[164:165], s[58:59], 0, v[0:1]
	s_mov_b32 m0, s64
	ds_read_b128 v[178:181], v169 offset:16384
	ds_read_b128 v[182:185], v169 offset:17408
	ds_read_b128 v[186:189], v169 offset:18432
	ds_read_b128 v[194:197], v169 offset:19456
	ds_read_b128 v[198:201], v169 offset:20480
	ds_read_b128 v[202:205], v169 offset:21504
	ds_read_b128 v[206:209], v169 offset:22528
	ds_read_b128 v[210:213], v169 offset:23552
	global_load_lds_dwordx4 v[164:165], off
	s_add_i32 m0, s64, 0x2000
	s_add_u32 s64, s58, 0x40000
	v_lshl_add_u64 v[214:215], s[58:59], 0, v[150:151]
	s_addc_u32 s65, s59, 0
	s_add_i32 s53, s53, s24
	global_load_lds_dwordx4 v[214:215], off
	v_lshl_add_u64 v[216:217], s[64:65], 0, v[0:1]
	s_mov_b32 m0, s53
	v_lshl_add_u64 v[218:219], s[60:61], 0, v[148:149]
	global_load_lds_dwordx4 v[216:217], off
	v_lshl_add_u64 v[216:217], s[64:65], 0, v[150:151]
	s_add_i32 m0, s53, 0x2000
	s_nop 0
	global_load_lds_dwordx4 v[216:217], off
	v_lshl_add_u64 v[216:217], s[60:61], 0, v[146:147]
	s_mov_b32 m0, s27
	s_nop 0
	global_load_lds_dwordx4 v[216:217], off
	s_mov_b32 m0, s28
	s_nop 0
	global_load_lds_dwordx4 v[218:219], off
	s_waitcnt vmcnt(8)
	s_waitcnt lgkmcnt(0)
	s_barrier
	s_setprio 1
	s_waitcnt lgkmcnt(0)
	v_mfma_f32_16x16x32_bf16 v[62:65], v[130:133], v[178:181], 0
	v_mfma_f32_16x16x32_bf16 v[58:61], v[138:141], v[178:181], 0
	v_mfma_f32_16x16x32_bf16 v[54:57], v[130:133], v[186:189], 0
	v_mfma_f32_16x16x32_bf16 v[46:49], v[138:141], v[186:189], 0
	v_mfma_f32_16x16x32_bf16 v[38:41], v[130:133], v[198:201], 0
	v_mfma_f32_16x16x32_bf16 v[30:33], v[138:141], v[198:201], 0
	v_mfma_f32_16x16x32_bf16 v[22:25], v[130:133], v[206:209], 0
	v_mfma_f32_16x16x32_bf16 v[14:17], v[138:141], v[206:209], 0
	v_mfma_f32_16x16x32_bf16 v[62:65], v[134:137], v[182:185], v[62:65]
	v_mfma_f32_16x16x32_bf16 v[58:61], v[142:145], v[182:185], v[58:61]
	v_mfma_f32_16x16x32_bf16 v[54:57], v[134:137], v[194:197], v[54:57]
	v_mfma_f32_16x16x32_bf16 v[46:49], v[142:145], v[194:197], v[46:49]
	v_mfma_f32_16x16x32_bf16 v[38:41], v[134:137], v[202:205], v[38:41]
	v_mfma_f32_16x16x32_bf16 v[30:33], v[142:145], v[202:205], v[30:33]
	v_mfma_f32_16x16x32_bf16 v[22:25], v[134:137], v[210:213], v[22:25]
	v_mfma_f32_16x16x32_bf16 v[14:17], v[142:145], v[210:213], v[14:17]


; #define PG8_STAGE(bufoff, gbase, voff) do { _Pragma("unroll") for (int _i = 0; _i < 2; ++_i) \
;         __builtin_amdgcn_global_load_lds((const unsigned*)((const char*)(gbase) + (voff)[_i]), (PG8_LAS unsigned*)(lds + (bufoff) + ldsw + _i * 8192), 16, 0, 0); } while (0)
; #define PG8_LDA(dst, b, h) do { _Pragma("unroll") for (int m = 0; m < 4; ++m) _Pragma("unroll") for (int k = 0; k < 2; ++k) dst[m][k] = *(const PG8_LAS bf16x8*)(lds + PG8_SA(b, h) + aoff + m * 2048 + k * 1024); } while (0)
; #define PG8_LDB(dst, b, h) do { _Pragma("unroll") for (int n = 0; n < 2; ++n) _Pragma("unroll") for (int k = 0; k < 2; ++k) dst[n][k] = *(const PG8_LAS bf16x8*)(lds + PG8_SB(b, h) + boff + n * 2048 + k * 1024); } while (0)
; #define PG8_MMA(ai, bj, At, Bt) do { __builtin_amdgcn_s_setprio(1); _Pragma("unroll") for (int m = 0; m < 4; ++m) _Pragma("unroll") for (int n = 0; n < 2; ++n) _Pragma("unroll") for (int k = 0; k < 2; ++k) \
;         acc[ai][bj][m][n] = __builtin_amdgcn_mfma_f32_16x16x32_bf16(Bt[n][k], At[m][k], acc[ai][bj][m][n], 0, 0, 0); __builtin_amdgcn_s_setprio(0); } while (0)
; #define PG8_WAIT_V(n) asm volatile("s_waitcnt vmcnt(" #n ")" ::: "memory")
; #define PG8_WAIT_L(n) asm volatile("s_waitcnt lgkmcnt(" #n ")" ::: "memory")
; #define PG8_BAR __builtin_amdgcn_s_barrier()
; #define PG8_SCHED __builtin_amdgcn_sched_barrier(0)
; template <class Epi, class Sched, bool ALIGN_EPI = false, bool SP2 = false>
; __device__ __forceinline__ void gemm_phase(PG8_LAS unsigned char* lds, const Gemm g, const Sched& S, const Epi& E) {
;     ...
;             PG8_WAIT_V(8); PG8_WAIT_L(0); PG8_BAR; PG8_MMA(1, 0, At, B0); PG8_MMA(1, 1, At, B1); PG8_BAR; PG8_SCHED;
;             PG8_LDB(B0, 1, 0); PG8_LDB(B1, 1, 1); PG8_SCHED; PG8_LDA(At, 1, 0); PG8_STAGE(PG8_SA(0, 1), a2 + hstep, voffA);
;             PG8_WAIT_V(8); PG8_WAIT_L(0); PG8_BAR; PG8_MMA(0, 0, At, B0); PG8_MMA(0, 1, At, B1); PG8_BAR; PG8_SCHED;
	v_mfma_f32_16x16x32_bf16 v[50:53], v[156:159], v[178:181], 0
	v_mfma_f32_16x16x32_bf16 v[42:45], v[170:173], v[178:181], 0
	v_mfma_f32_16x16x32_bf16 v[34:37], v[156:159], v[186:189], 0
	v_mfma_f32_16x16x32_bf16 v[26:29], v[170:173], v[186:189], 0
	v_mfma_f32_16x16x32_bf16 v[18:21], v[156:159], v[198:201], 0
	v_mfma_f32_16x16x32_bf16 v[10:13], v[170:173], v[198:201], 0
	v_mfma_f32_16x16x32_bf16 v[6:9], v[156:159], v[206:209], 0
	v_mfma_f32_16x16x32_bf16 v[2:5], v[170:173], v[206:209], 0
	v_mfma_f32_16x16x32_bf16 v[50:53], v[160:163], v[182:185], v[50:53]
	v_mfma_f32_16x16x32_bf16 v[42:45], v[174:177], v[182:185], v[42:45]
	v_mfma_f32_16x16x32_bf16 v[34:37], v[160:163], v[194:197], v[34:37]
	v_mfma_f32_16x16x32_bf16 v[26:29], v[174:177], v[194:197], v[26:29]
	v_mfma_f32_16x16x32_bf16 v[18:21], v[160:163], v[202:205], v[18:21]
	v_mfma_f32_16x16x32_bf16 v[10:13], v[174:177], v[202:205], v[10:13]
	v_mfma_f32_16x16x32_bf16 v[6:9], v[160:163], v[210:213], v[6:9]
	v_mfma_f32_16x16x32_bf16 v[2:5], v[174:177], v[210:213], v[2:5]
	s_setprio 0
	s_barrier
	s_add_i32 s53, 0, 0x18000
	s_add_i32 s64, 0, 0x1c000
	v_add_u32_e32 v142, s53, v167
	v_add_u32_e32 v174, s64, v167
	ds_read_b128 v[130:133], v142
	ds_read_b128 v[134:137], v142 offset:1024
	ds_read_b128 v[138:141], v142 offset:2048
	ds_read_b128 v[142:145], v142 offset:3072
	ds_read_b128 v[156:159], v174
	ds_read_b128 v[160:163], v174 offset:1024
	ds_read_b128 v[170:173], v174 offset:2048
	ds_read_b128 v[174:177], v174 offset:3072
	s_add_u32 s60, s60, 0x40000
	s_addc_u32 s61, s61, 0
	s_mov_b32 m0, s29
	v_lshl_add_u64 v[220:221], s[60:61], 0, v[146:147]
	ds_read_b128 v[178:181], v169 offset:32768
	ds_read_b128 v[182:185], v169 offset:33792
	ds_read_b128 v[186:189], v169 offset:34816
	ds_read_b128 v[194:197], v169 offset:35840
	ds_read_b128 v[198:201], v169 offset:36864
	ds_read_b128 v[202:205], v169 offset:37888
	ds_read_b128 v[206:209], v169 offset:38912
	ds_read_b128 v[210:213], v169 offset:39936
	global_load_lds_dwordx4 v[220:221], off
	v_lshl_add_u64 v[220:221], s[60:61], 0, v[148:149]
	s_mov_b32 m0, s47
	s_nop 0
	global_load_lds_dwordx4 v[220:221], off
	s_waitcnt vmcnt(8)
	s_waitcnt lgkmcnt(0)
	s_barrier
	s_setprio 1
	s_waitcnt lgkmcnt(0)
	v_mfma_f32_16x16x32_bf16 v[126:129], v[130:133], v[178:181], v[126:129]
	v_mfma_f32_16x16x32_bf16 v[122:125], v[138:141], v[178:181], v[122:125]
	v_mfma_f32_16x16x32_bf16 v[114:117], v[130:133], v[186:189], v[114:117]
	v_mfma_f32_16x16x32_bf16 v[110:113], v[138:141], v[186:189], v[110:113]
	v_mfma_f32_16x16x32_bf16 v[102:105], v[130:133], v[198:201], v[102:105]
	v_mfma_f32_16x16x32_bf16 v[94:97], v[138:141], v[198:201], v[94:97]
	v_mfma_f32_16x16x32_bf16 v[86:89], v[130:133], v[206:209], v[86:89]
	v_mfma_f32_16x16x32_bf16 v[78:81], v[138:141], v[206:209], v[78:81]
	v_mfma_f32_16x16x32_bf16 v[126:129], v[134:137], v[182:185], v[126:129]
	v_mfma_f32_16x16x32_bf16 v[122:125], v[142:145], v[182:185], v[122:125]
	v_mfma_f32_16x16x32_bf16 v[114:117], v[134:137], v[194:197], v[114:117]
	v_mfma_f32_16x16x32_bf16 v[110:113], v[142:145], v[194:197], v[110:113]
	v_mfma_f32_16x16x32_bf16 v[102:105], v[134:137], v[202:205], v[102:105]
	v_mfma_f32_16x16x32_bf16 v[94:97], v[142:145], v[202:205], v[94:97]
	v_mfma_f32_16x16x32_bf16 v[86:89], v[134:137], v[210:213], v[86:89]
	v_mfma_f32_16x16x32_bf16 v[78:81], v[142:145], v[210:213], v[78:81]


; #define PG8_STAGE(bufoff, gbase, voff) do { _Pragma("unroll") for (int _i = 0; _i < 2; ++_i) \
;         __builtin_amdgcn_global_load_lds((const unsigned*)((const char*)(gbase) + (voff)[_i]), (PG8_LAS unsigned*)(lds + (bufoff) + ldsw + _i * 8192), 16, 0, 0); } while (0)
; #define PG8_LDA(dst, b, h) do { _Pragma("unroll") for (int m = 0; m < 4; ++m) _Pragma("unroll") for (int k = 0; k < 2; ++k) dst[m][k] = *(const PG8_LAS bf16x8*)(lds + PG8_SA(b, h) + aoff + m * 2048 + k * 1024); } while (0)
; #define PG8_MMA(ai, bj, At, Bt) do { __builtin_amdgcn_s_setprio(1); _Pragma("unroll") for (int m = 0; m < 4; ++m) _Pragma("unroll") for (int n = 0; n < 2; ++n) _Pragma("unroll") for (int k = 0; k < 2; ++k) \
;         acc[ai][bj][m][n] = __builtin_amdgcn_mfma_f32_16x16x32_bf16(Bt[n][k], At[m][k], acc[ai][bj][m][n], 0, 0, 0); __builtin_amdgcn_s_setprio(0); } while (0)
; #define PG8_WAIT_V(n) asm volatile("s_waitcnt vmcnt(" #n ")" ::: "memory")
; #define PG8_WAIT_L(n) asm volatile("s_waitcnt lgkmcnt(" #n ")" ::: "memory")
; #define PG8_BAR __builtin_amdgcn_s_barrier()
; #define PG8_SCHED __builtin_amdgcn_sched_barrier(0)
; template <class Epi, class Sched, bool ALIGN_EPI = false, bool SP2 = false>
; __device__ __forceinline__ void gemm_phase(PG8_LAS unsigned char* lds, const Gemm g, const Sched& S, const Epi& E) {
;     ...
;             PG8_WAIT_V(8); PG8_WAIT_L(0); PG8_BAR; PG8_MMA(0, 0, At, B0); PG8_MMA(0, 1, At, B1); PG8_BAR; PG8_SCHED;
;             PG8_LDA(At, 1, 1); PG8_STAGE(PG8_SB(1, 0), b3, voffB); PG8_STAGE(PG8_SB(1, 1), b3 + hstep, voffB); PG8_STAGE(PG8_SA(1, 0), a3, voffA);
;             PG8_WAIT_V(8); PG8_WAIT_L(0); PG8_BAR; PG8_MMA(1, 0, At, B0); PG8_MMA(1, 1, At, B1); PG8_BAR; PG8_SCHED;
	v_mfma_f32_16x16x32_bf16 v[118:121], v[156:159], v[178:181], v[118:121]
	v_mfma_f32_16x16x32_bf16 v[106:109], v[170:173], v[178:181], v[106:109]
	v_mfma_f32_16x16x32_bf16 v[98:101], v[156:159], v[186:189], v[98:101]
	v_mfma_f32_16x16x32_bf16 v[90:93], v[170:173], v[186:189], v[90:93]
	v_mfma_f32_16x16x32_bf16 v[82:85], v[156:159], v[198:201], v[82:85]
	v_mfma_f32_16x16x32_bf16 v[74:77], v[170:173], v[198:201], v[74:77]
	v_mfma_f32_16x16x32_bf16 v[70:73], v[156:159], v[206:209], v[70:73]
	v_mfma_f32_16x16x32_bf16 v[66:69], v[170:173], v[206:209], v[66:69]
	v_mfma_f32_16x16x32_bf16 v[118:121], v[160:163], v[182:185], v[118:121]
	v_mfma_f32_16x16x32_bf16 v[106:109], v[174:177], v[182:185], v[106:109]
	v_mfma_f32_16x16x32_bf16 v[98:101], v[160:163], v[194:197], v[98:101]
	v_mfma_f32_16x16x32_bf16 v[90:93], v[174:177], v[194:197], v[90:93]
	v_mfma_f32_16x16x32_bf16 v[82:85], v[160:163], v[202:205], v[82:85]
	v_mfma_f32_16x16x32_bf16 v[74:77], v[174:177], v[202:205], v[74:77]
	v_mfma_f32_16x16x32_bf16 v[70:73], v[160:163], v[210:213], v[70:73]
	v_mfma_f32_16x16x32_bf16 v[66:69], v[174:177], v[210:213], v[66:69]
	s_setprio 0
	s_barrier
	s_add_i32 s53, s53, s24
	v_lshl_add_u64 v[164:165], v[164:165], 0, s[8:9]
	s_mov_b32 m0, s53
	ds_read_b128 v[178:181], v169 offset:49152
	ds_read_b128 v[182:185], v169 offset:50176
	ds_read_b128 v[186:189], v169 offset:51200
	ds_read_b128 v[194:197], v169 offset:52224
	ds_read_b128 v[198:201], v169 offset:53248
	ds_read_b128 v[202:205], v169 offset:54272
	ds_read_b128 v[206:209], v169 offset:55296
	ds_read_b128 v[210:213], v169 offset:56320
	global_load_lds_dwordx4 v[164:165], off
	s_add_i32 m0, s53, 0x2000
	s_add_u32 s58, s58, 0x40080
	v_lshl_add_u64 v[164:165], v[214:215], 0, s[8:9]
	s_addc_u32 s59, s59, 0
	s_add_i32 s53, s64, s24
	global_load_lds_dwordx4 v[164:165], off
	v_lshl_add_u64 v[164:165], s[58:59], 0, v[0:1]
	s_mov_b32 m0, s53
	s_nop 0
	global_load_lds_dwordx4 v[164:165], off
	v_lshl_add_u64 v[164:165], s[58:59], 0, v[150:151]
	s_add_i32 m0, s53, 0x2000
	s_nop 0
	global_load_lds_dwordx4 v[164:165], off
	v_lshl_add_u64 v[164:165], v[216:217], 0, s[8:9]
	s_mov_b32 m0, s57
	s_nop 0
	global_load_lds_dwordx4 v[164:165], off
	v_lshl_add_u64 v[164:165], v[218:219], 0, s[8:9]
	s_mov_b32 m0, s62
	s_nop 0
	global_load_lds_dwordx4 v[164:165], off
	s_waitcnt vmcnt(8)
	s_waitcnt lgkmcnt(0)
	s_barrier
	s_setprio 1
	s_waitcnt lgkmcnt(0)
	v_mfma_f32_16x16x32_bf16 v[62:65], v[130:133], v[178:181], v[62:65]
	v_mfma_f32_16x16x32_bf16 v[58:61], v[138:141], v[178:181], v[58:61]
	v_mfma_f32_16x16x32_bf16 v[54:57], v[130:133], v[186:189], v[54:57]
	v_mfma_f32_16x16x32_bf16 v[46:49], v[138:141], v[186:189], v[46:49]
	v_mfma_f32_16x16x32_bf16 v[38:41], v[130:133], v[198:201], v[38:41]
	v_mfma_f32_16x16x32_bf16 v[30:33], v[138:141], v[198:201], v[30:33]
	v_mfma_f32_16x16x32_bf16 v[22:25], v[130:133], v[206:209], v[22:25]
	v_mfma_f32_16x16x32_bf16 v[14:17], v[138:141], v[206:209], v[14:17]
	v_mfma_f32_16x16x32_bf16 v[62:65], v[134:137], v[182:185], v[62:65]
	v_mfma_f32_16x16x32_bf16 v[58:61], v[142:145], v[182:185], v[58:61]
	v_mfma_f32_16x16x32_bf16 v[54:57], v[134:137], v[194:197], v[54:57]
	v_mfma_f32_16x16x32_bf16 v[46:49], v[142:145], v[194:197], v[46:49]
	v_mfma_f32_16x16x32_bf16 v[38:41], v[134:137], v[202:205], v[38:41]
	v_mfma_f32_16x16x32_bf16 v[30:33], v[142:145], v[202:205], v[30:33]
	v_mfma_f32_16x16x32_bf16 v[22:25], v[134:137], v[210:213], v[22:25]
	v_mfma_f32_16x16x32_bf16 v[14:17], v[142:145], v[210:213], v[14:17]


; #define PG8_STAGE(bufoff, gbase, voff) do { _Pragma("unroll") for (int _i = 0; _i < 2; ++_i) \
;         __builtin_amdgcn_global_load_lds((const unsigned*)((const char*)(gbase) + (voff)[_i]), (PG8_LAS unsigned*)(lds + (bufoff) + ldsw + _i * 8192), 16, 0, 0); } while (0)
; #define PG8_LDA(dst, b, h) do { _Pragma("unroll") for (int m = 0; m < 4; ++m) _Pragma("unroll") for (int k = 0; k < 2; ++k) dst[m][k] = *(const PG8_LAS bf16x8*)(lds + PG8_SA(b, h) + aoff + m * 2048 + k * 1024); } while (0)
; #define PG8_LDB(dst, b, h) do { _Pragma("unroll") for (int n = 0; n < 2; ++n) _Pragma("unroll") for (int k = 0; k < 2; ++k) dst[n][k] = *(const PG8_LAS bf16x8*)(lds + PG8_SB(b, h) + boff + n * 2048 + k * 1024); } while (0)
; template <class Epi, class Sched, bool ALIGN_EPI = false, bool SP2 = false>
; __device__ __forceinline__ void gemm_phase(PG8_LAS unsigned char* lds, const Gemm g, const Sched& S, const Epi& E) {
;     ...
;         for (int t = 0; t < nt; t += 2) {
;             const bool last = (t == nt - 2);
;             const char* a1 = cA + (size_t)(t + 1) * kstep;
;             const char* a2 = last ? nA : cA + (size_t)(t + 2) * kstep; const char* b2 = last ? nB : cB + (size_t)(t + 2) * kstep;
;             const char* a3 = a2 + kstep; const char* b3 = b2 + kstep;
;             if (last && has_next) S.a_ready(nxt);
;             if constexpr (SP2) {
;             PG8_LDB(B0, 0, 0); PG8_LDB(B1, 0, 1); PG8_SCHED; PG8_LDA(At, 0, 0); PG8_STAGE(PG8_SA(1, 1), a1 + hstep, voffA);
;             PG8_WAIT_V(8); PG8_WAIT_L(0); PG8_BAR; PG8_MMA(0, 0, At, B0); PG8_MMA(0, 1, At, B1); PG8_BAR; PG8_SCHED;
;             PG8_LDA(At, 0, 1); PG8_STAGE(PG8_SB(0, 0), b2, voffB); PG8_STAGE(PG8_SB(0, 1), b2 + hstep, voffB); PG8_STAGE(PG8_SA(0, 0), a2, voffA);
;             PG8_WAIT_V(8); PG8_WAIT_L(0); PG8_BAR; PG8_MMA(1, 0, At, B0); PG8_MMA(1, 1, At, B1); PG8_BAR; PG8_SCHED;
;             PG8_LDB(B0, 1, 0); PG8_LDB(B1, 1, 1); PG8_SCHED; PG8_LDA(At, 1, 0); PG8_STAGE(PG8_SA(0, 1), a2 + hstep, voffA);
;             PG8_WAIT_V(8); PG8_WAIT_L(0); PG8_BAR; PG8_MMA(0, 0, At, B0); PG8_MMA(0, 1, At, B1); PG8_BAR; PG8_SCHED;
;             PG8_LDA(At, 1, 1); PG8_STAGE(PG8_SB(1, 0), b3, voffB); PG8_STAGE(PG8_SB(1, 1), b3 + hstep, voffB); PG8_STAGE(PG8_SA(1, 0), a3, voffA);
;             PG8_WAIT_V(8); PG8_WAIT_L(0); PG8_BAR; PG8_MMA(1, 0, At, B0); PG8_MMA(1, 1, At, B1); PG8_BAR; PG8_SCHED;
	v_mfma_f32_16x16x32_bf16 v[50:53], v[156:159], v[178:181], v[50:53]
	v_mfma_f32_16x16x32_bf16 v[42:45], v[170:173], v[178:181], v[42:45]
	v_mfma_f32_16x16x32_bf16 v[34:37], v[156:159], v[186:189], v[34:37]
	v_mfma_f32_16x16x32_bf16 v[26:29], v[170:173], v[186:189], v[26:29]
	v_mfma_f32_16x16x32_bf16 v[18:21], v[156:159], v[198:201], v[18:21]
	v_mfma_f32_16x16x32_bf16 v[10:13], v[170:173], v[198:201], v[10:13]
	v_mfma_f32_16x16x32_bf16 v[6:9], v[156:159], v[206:209], v[6:9]
	v_mfma_f32_16x16x32_bf16 v[2:5], v[170:173], v[206:209], v[2:5]
	v_mfma_f32_16x16x32_bf16 v[50:53], v[160:163], v[182:185], v[50:53]
	v_mfma_f32_16x16x32_bf16 v[42:45], v[174:177], v[182:185], v[42:45]
	v_mfma_f32_16x16x32_bf16 v[34:37], v[160:163], v[194:197], v[34:37]
	v_mfma_f32_16x16x32_bf16 v[26:29], v[174:177], v[194:197], v[26:29]
	v_mfma_f32_16x16x32_bf16 v[18:21], v[160:163], v[202:205], v[18:21]
	v_mfma_f32_16x16x32_bf16 v[10:13], v[174:177], v[202:205], v[10:13]
	v_mfma_f32_16x16x32_bf16 v[6:9], v[160:163], v[210:213], v[6:9]
	v_mfma_f32_16x16x32_bf16 v[2:5], v[174:177], v[210:213], v[2:5]
	s_setprio 0
	s_barrier
	s_add_i32 s52, s52, 2
	s_add_u32 s18, s18, 0x100
	s_addc_u32 s19, s19, 0
	s_add_u32 s43, s43, 0x100
	s_addc_u32 s45, s45, 0
	s_cmp_gt_u32 s52, 13
.LBB0_291:
	s_add_u32 s53, s18, 0xfffc0080
	s_addc_u32 s58, s19, -1
	s_add_i32 s64, 0, 0x10000
	s_cmp_eq_u32 s52, 12
	s_cselect_b32 s61, s30, s58
	s_cselect_b32 s60, s31, s53
	s_cselect_b32 s59, s34, s45
	s_cselect_b32 s58, s35, s43
	s_add_i32 s53, 0, 0x14000
	v_add_u32_e32 v142, s64, v167
	v_add_u32_e32 v164, s53, v167
	ds_read_b128 v[130:133], v142
	ds_read_b128 v[134:137], v142 offset:1024
	ds_read_b128 v[138:141], v142 offset:2048
	ds_read_b128 v[142:145], v142 offset:3072
	ds_read_b128 v[156:159], v164
	ds_read_b128 v[160:163], v164 offset:1024
	ds_read_b128 v[170:173], v164 offset:2048
	ds_read_b128 v[174:177], v164 offset:3072
	v_lshl_add_u64 v[164:165], s[18:19], 0, v[152:153]
	s_add_i32 m0, s27, 0xc000
	ds_read_b128 v[178:181], v169
	ds_read_b128 v[182:185], v169 offset:1024
	ds_read_b128 v[186:189], v169 offset:2048
	ds_read_b128 v[194:197], v169 offset:3072
	ds_read_b128 v[198:201], v169 offset:4096
	ds_read_b128 v[202:205], v169 offset:5120
	ds_read_b128 v[206:209], v169 offset:6144
	ds_read_b128 v[210:213], v169 offset:7168
	global_load_lds_dwordx4 v[164:165], off
	v_lshl_add_u64 v[164:165], s[18:19], 0, v[154:155]
	s_add_i32 m0, s27, 0xe000
	s_nop 0
	global_load_lds_dwordx4 v[164:165], off
	s_waitcnt vmcnt(8)
	s_waitcnt lgkmcnt(0)
	s_barrier
	s_setprio 1
	s_waitcnt lgkmcnt(0)
	v_mfma_f32_16x16x32_bf16 v[126:129], v[130:133], v[178:181], v[126:129]
	v_mfma_f32_16x16x32_bf16 v[122:125], v[138:141], v[178:181], v[122:125]
	v_mfma_f32_16x16x32_bf16 v[114:117], v[130:133], v[186:189], v[114:117]
	v_mfma_f32_16x16x32_bf16 v[110:113], v[138:141], v[186:189], v[110:113]
	v_mfma_f32_16x16x32_bf16 v[102:105], v[130:133], v[198:201], v[102:105]
	v_mfma_f32_16x16x32_bf16 v[94:97], v[138:141], v[198:201], v[94:97]
	v_mfma_f32_16x16x32_bf16 v[86:89], v[130:133], v[206:209], v[86:89]
	v_mfma_f32_16x16x32_bf16 v[78:81], v[138:141], v[206:209], v[78:81]
	v_mfma_f32_16x16x32_bf16 v[126:129], v[134:137], v[182:185], v[126:129]
	v_mfma_f32_16x16x32_bf16 v[122:125], v[142:145], v[182:185], v[122:125]
	v_mfma_f32_16x16x32_bf16 v[114:117], v[134:137], v[194:197], v[114:117]
	v_mfma_f32_16x16x32_bf16 v[110:113], v[142:145], v[194:197], v[110:113]
	v_mfma_f32_16x16x32_bf16 v[102:105], v[134:137], v[202:205], v[102:105]
	v_mfma_f32_16x16x32_bf16 v[94:97], v[142:145], v[202:205], v[94:97]
	v_mfma_f32_16x16x32_bf16 v[86:89], v[134:137], v[210:213], v[86:89]
	v_mfma_f32_16x16x32_bf16 v[78:81], v[142:145], v[210:213], v[78:81]


; #define PG8_STAGE(bufoff, gbase, voff) do { _Pragma("unroll") for (int _i = 0; _i < 2; ++_i) \
;         __builtin_amdgcn_global_load_lds((const unsigned*)((const char*)(gbase) + (voff)[_i]), (PG8_LAS unsigned*)(lds + (bufoff) + ldsw + _i * 8192), 16, 0, 0); } while (0)
; #define PG8_LDA(dst, b, h) do { _Pragma("unroll") for (int m = 0; m < 4; ++m) _Pragma("unroll") for (int k = 0; k < 2; ++k) dst[m][k] = *(const PG8_LAS bf16x8*)(lds + PG8_SA(b, h) + aoff + m * 2048 + k * 1024); } while (0)
; #define PG8_MMA(ai, bj, At, Bt) do { __builtin_amdgcn_s_setprio(1); _Pragma("unroll") for (int m = 0; m < 4; ++m) _Pragma("unroll") for (int n = 0; n < 2; ++n) _Pragma("unroll") for (int k = 0; k < 2; ++k) \
;         acc[ai][bj][m][n] = __builtin_amdgcn_mfma_f32_16x16x32_bf16(Bt[n][k], At[m][k], acc[ai][bj][m][n], 0, 0, 0); __builtin_amdgcn_s_setprio(0); } while (0)
; #define PG8_WAIT_V(n) asm volatile("s_waitcnt vmcnt(" #n ")" ::: "memory")
; #define PG8_WAIT_L(n) asm volatile("s_waitcnt lgkmcnt(" #n ")" ::: "memory")
; #define PG8_BAR __builtin_amdgcn_s_barrier()
; #define PG8_SCHED __builtin_amdgcn_sched_barrier(0)
; template <class Epi, class Sched, bool ALIGN_EPI = false, bool SP2 = false>
; __device__ __forceinline__ void gemm_phase(PG8_LAS unsigned char* lds, const Gemm g, const Sched& S, const Epi& E) {
;     ...
;             PG8_WAIT_V(8); PG8_WAIT_L(0); PG8_BAR; PG8_MMA(0, 0, At, B0); PG8_MMA(0, 1, At, B1); PG8_BAR; PG8_SCHED;
;             PG8_LDA(At, 0, 1); PG8_STAGE(PG8_SB(0, 0), b2, voffB); PG8_STAGE(PG8_SB(0, 1), b2 + hstep, voffB); PG8_STAGE(PG8_SA(0, 0), a2, voffA);
;             PG8_WAIT_V(8); PG8_WAIT_L(0); PG8_BAR; PG8_MMA(1, 0, At, B0); PG8_MMA(1, 1, At, B1); PG8_BAR; PG8_SCHED;
	v_mfma_f32_16x16x32_bf16 v[118:121], v[156:159], v[178:181], v[118:121]
	v_mfma_f32_16x16x32_bf16 v[106:109], v[170:173], v[178:181], v[106:109]
	v_mfma_f32_16x16x32_bf16 v[98:101], v[156:159], v[186:189], v[98:101]
	v_mfma_f32_16x16x32_bf16 v[90:93], v[170:173], v[186:189], v[90:93]
	v_mfma_f32_16x16x32_bf16 v[82:85], v[156:159], v[198:201], v[82:85]
	v_mfma_f32_16x16x32_bf16 v[74:77], v[170:173], v[198:201], v[74:77]
	v_mfma_f32_16x16x32_bf16 v[70:73], v[156:159], v[206:209], v[70:73]
	v_mfma_f32_16x16x32_bf16 v[66:69], v[170:173], v[206:209], v[66:69]
	v_mfma_f32_16x16x32_bf16 v[118:121], v[160:163], v[182:185], v[118:121]
	v_mfma_f32_16x16x32_bf16 v[106:109], v[174:177], v[182:185], v[106:109]
	v_mfma_f32_16x16x32_bf16 v[98:101], v[160:163], v[194:197], v[98:101]
	v_mfma_f32_16x16x32_bf16 v[90:93], v[174:177], v[194:197], v[90:93]
	v_mfma_f32_16x16x32_bf16 v[82:85], v[160:163], v[202:205], v[82:85]
	v_mfma_f32_16x16x32_bf16 v[74:77], v[174:177], v[202:205], v[74:77]
	v_mfma_f32_16x16x32_bf16 v[70:73], v[160:163], v[210:213], v[70:73]
	v_mfma_f32_16x16x32_bf16 v[66:69], v[174:177], v[210:213], v[66:69]
	s_setprio 0
	s_barrier
	s_add_i32 s64, s64, s24
	v_lshl_add_u64 v[164:165], s[58:59], 0, v[0:1]
	s_mov_b32 m0, s64
	ds_read_b128 v[178:181], v169 offset:16384
	ds_read_b128 v[182:185], v169 offset:17408
	ds_read_b128 v[186:189], v169 offset:18432
	ds_read_b128 v[194:197], v169 offset:19456
	ds_read_b128 v[198:201], v169 offset:20480
	ds_read_b128 v[202:205], v169 offset:21504
	ds_read_b128 v[206:209], v169 offset:22528
	ds_read_b128 v[210:213], v169 offset:23552
	global_load_lds_dwordx4 v[164:165], off
	s_add_i32 m0, s64, 0x2000
	s_add_u32 s64, s58, 0x40000
	v_lshl_add_u64 v[214:215], s[58:59], 0, v[150:151]
	s_addc_u32 s65, s59, 0
	s_add_i32 s53, s53, s24
	global_load_lds_dwordx4 v[214:215], off
	v_lshl_add_u64 v[216:217], s[64:65], 0, v[0:1]
	s_mov_b32 m0, s53
	v_lshl_add_u64 v[218:219], s[60:61], 0, v[148:149]
	global_load_lds_dwordx4 v[216:217], off
	v_lshl_add_u64 v[216:217], s[64:65], 0, v[150:151]
	s_add_i32 m0, s53, 0x2000
	s_nop 0
	global_load_lds_dwordx4 v[216:217], off
	v_lshl_add_u64 v[216:217], s[60:61], 0, v[146:147]
	s_mov_b32 m0, s27
	s_nop 0
	global_load_lds_dwordx4 v[216:217], off
	s_mov_b32 m0, s28
	s_nop 0
	global_load_lds_dwordx4 v[218:219], off
	s_waitcnt vmcnt(8)
	s_waitcnt lgkmcnt(0)
	s_barrier
	s_setprio 1
	s_waitcnt lgkmcnt(0)
	v_mfma_f32_16x16x32_bf16 v[62:65], v[130:133], v[178:181], v[62:65]
	v_mfma_f32_16x16x32_bf16 v[58:61], v[138:141], v[178:181], v[58:61]
	v_mfma_f32_16x16x32_bf16 v[54:57], v[130:133], v[186:189], v[54:57]
	v_mfma_f32_16x16x32_bf16 v[46:49], v[138:141], v[186:189], v[46:49]
	v_mfma_f32_16x16x32_bf16 v[38:41], v[130:133], v[198:201], v[38:41]
	v_mfma_f32_16x16x32_bf16 v[30:33], v[138:141], v[198:201], v[30:33]
	v_mfma_f32_16x16x32_bf16 v[22:25], v[130:133], v[206:209], v[22:25]
	v_mfma_f32_16x16x32_bf16 v[14:17], v[138:141], v[206:209], v[14:17]
	v_mfma_f32_16x16x32_bf16 v[62:65], v[134:137], v[182:185], v[62:65]
	v_mfma_f32_16x16x32_bf16 v[58:61], v[142:145], v[182:185], v[58:61]
	v_mfma_f32_16x16x32_bf16 v[54:57], v[134:137], v[194:197], v[54:57]
	v_mfma_f32_16x16x32_bf16 v[46:49], v[142:145], v[194:197], v[46:49]
	v_mfma_f32_16x16x32_bf16 v[38:41], v[134:137], v[202:205], v[38:41]
	v_mfma_f32_16x16x32_bf16 v[30:33], v[142:145], v[202:205], v[30:33]
	v_mfma_f32_16x16x32_bf16 v[22:25], v[134:137], v[210:213], v[22:25]
	v_mfma_f32_16x16x32_bf16 v[14:17], v[142:145], v[210:213], v[14:17]


; #define PG8_STAGE(bufoff, gbase, voff) do { _Pragma("unroll") for (int _i = 0; _i < 2; ++_i) \
;         __builtin_amdgcn_global_load_lds((const unsigned*)((const char*)(gbase) + (voff)[_i]), (PG8_LAS unsigned*)(lds + (bufoff) + ldsw + _i * 8192), 16, 0, 0); } while (0)
; #define PG8_LDA(dst, b, h) do { _Pragma("unroll") for (int m = 0; m < 4; ++m) _Pragma("unroll") for (int k = 0; k < 2; ++k) dst[m][k] = *(const PG8_LAS bf16x8*)(lds + PG8_SA(b, h) + aoff + m * 2048 + k * 1024); } while (0)
; #define PG8_LDB(dst, b, h) do { _Pragma("unroll") for (int n = 0; n < 2; ++n) _Pragma("unroll") for (int k = 0; k < 2; ++k) dst[n][k] = *(const PG8_LAS bf16x8*)(lds + PG8_SB(b, h) + boff + n * 2048 + k * 1024); } while (0)
; #define PG8_MMA(ai, bj, At, Bt) do { __builtin_amdgcn_s_setprio(1); _Pragma("unroll") for (int m = 0; m < 4; ++m) _Pragma("unroll") for (int n = 0; n < 2; ++n) _Pragma("unroll") for (int k = 0; k < 2; ++k) \
;         acc[ai][bj][m][n] = __builtin_amdgcn_mfma_f32_16x16x32_bf16(Bt[n][k], At[m][k], acc[ai][bj][m][n], 0, 0, 0); __builtin_amdgcn_s_setprio(0); } while (0)
; #define PG8_WAIT_V(n) asm volatile("s_waitcnt vmcnt(" #n ")" ::: "memory")
; #define PG8_WAIT_L(n) asm volatile("s_waitcnt lgkmcnt(" #n ")" ::: "memory")
; #define PG8_BAR __builtin_amdgcn_s_barrier()
; #define PG8_SCHED __builtin_amdgcn_sched_barrier(0)
; template <class Epi, class Sched, bool ALIGN_EPI = false, bool SP2 = false>
; __device__ __forceinline__ void gemm_phase(PG8_LAS unsigned char* lds, const Gemm g, const Sched& S, const Epi& E) {
;     ...
;             PG8_WAIT_V(8); PG8_WAIT_L(0); PG8_BAR; PG8_MMA(1, 0, At, B0); PG8_MMA(1, 1, At, B1); PG8_BAR; PG8_SCHED;
;             PG8_LDB(B0, 1, 0); PG8_LDB(B1, 1, 1); PG8_SCHED; PG8_LDA(At, 1, 0); PG8_STAGE(PG8_SA(0, 1), a2 + hstep, voffA);
;             PG8_WAIT_V(8); PG8_WAIT_L(0); PG8_BAR; PG8_MMA(0, 0, At, B0); PG8_MMA(0, 1, At, B1); PG8_BAR; PG8_SCHED;
	v_mfma_f32_16x16x32_bf16 v[50:53], v[156:159], v[178:181], v[50:53]
	v_mfma_f32_16x16x32_bf16 v[42:45], v[170:173], v[178:181], v[42:45]
	v_mfma_f32_16x16x32_bf16 v[34:37], v[156:159], v[186:189], v[34:37]
	v_mfma_f32_16x16x32_bf16 v[26:29], v[170:173], v[186:189], v[26:29]
	v_mfma_f32_16x16x32_bf16 v[18:21], v[156:159], v[198:201], v[18:21]
	v_mfma_f32_16x16x32_bf16 v[10:13], v[170:173], v[198:201], v[10:13]
	v_mfma_f32_16x16x32_bf16 v[6:9], v[156:159], v[206:209], v[6:9]
	v_mfma_f32_16x16x32_bf16 v[2:5], v[170:173], v[206:209], v[2:5]
	v_mfma_f32_16x16x32_bf16 v[50:53], v[160:163], v[182:185], v[50:53]
	v_mfma_f32_16x16x32_bf16 v[42:45], v[174:177], v[182:185], v[42:45]
	v_mfma_f32_16x16x32_bf16 v[34:37], v[160:163], v[194:197], v[34:37]
	v_mfma_f32_16x16x32_bf16 v[26:29], v[174:177], v[194:197], v[26:29]
	v_mfma_f32_16x16x32_bf16 v[18:21], v[160:163], v[202:205], v[18:21]
	v_mfma_f32_16x16x32_bf16 v[10:13], v[174:177], v[202:205], v[10:13]
	v_mfma_f32_16x16x32_bf16 v[6:9], v[160:163], v[210:213], v[6:9]
	v_mfma_f32_16x16x32_bf16 v[2:5], v[174:177], v[210:213], v[2:5]
	s_setprio 0
	s_barrier
	s_add_i32 s53, 0, 0x18000
	s_add_i32 s64, 0, 0x1c000
	v_add_u32_e32 v142, s53, v167
	v_add_u32_e32 v174, s64, v167
	ds_read_b128 v[130:133], v142
	ds_read_b128 v[134:137], v142 offset:1024
	ds_read_b128 v[138:141], v142 offset:2048
	ds_read_b128 v[142:145], v142 offset:3072
	ds_read_b128 v[156:159], v174
	ds_read_b128 v[160:163], v174 offset:1024
	ds_read_b128 v[170:173], v174 offset:2048
	ds_read_b128 v[174:177], v174 offset:3072
	s_add_u32 s60, s60, 0x40000
	s_addc_u32 s61, s61, 0
	s_mov_b32 m0, s29
	v_lshl_add_u64 v[220:221], s[60:61], 0, v[146:147]
	ds_read_b128 v[178:181], v169 offset:32768
	ds_read_b128 v[182:185], v169 offset:33792
	ds_read_b128 v[186:189], v169 offset:34816
	ds_read_b128 v[194:197], v169 offset:35840
	ds_read_b128 v[198:201], v169 offset:36864
	ds_read_b128 v[202:205], v169 offset:37888
	ds_read_b128 v[206:209], v169 offset:38912
	ds_read_b128 v[210:213], v169 offset:39936
	global_load_lds_dwordx4 v[220:221], off
	v_lshl_add_u64 v[220:221], s[60:61], 0, v[148:149]
	s_mov_b32 m0, s47
	s_nop 0
	global_load_lds_dwordx4 v[220:221], off
	s_waitcnt vmcnt(8)
	s_waitcnt lgkmcnt(0)
	s_barrier
	s_setprio 1
	s_waitcnt lgkmcnt(0)
	v_mfma_f32_16x16x32_bf16 v[126:129], v[130:133], v[178:181], v[126:129]
	v_mfma_f32_16x16x32_bf16 v[122:125], v[138:141], v[178:181], v[122:125]
	v_mfma_f32_16x16x32_bf16 v[114:117], v[130:133], v[186:189], v[114:117]
	v_mfma_f32_16x16x32_bf16 v[110:113], v[138:141], v[186:189], v[110:113]
	v_mfma_f32_16x16x32_bf16 v[102:105], v[130:133], v[198:201], v[102:105]
	v_mfma_f32_16x16x32_bf16 v[94:97], v[138:141], v[198:201], v[94:97]
	v_mfma_f32_16x16x32_bf16 v[86:89], v[130:133], v[206:209], v[86:89]
	v_mfma_f32_16x16x32_bf16 v[78:81], v[138:141], v[206:209], v[78:81]
	v_mfma_f32_16x16x32_bf16 v[126:129], v[134:137], v[182:185], v[126:129]
	v_mfma_f32_16x16x32_bf16 v[122:125], v[142:145], v[182:185], v[122:125]
	v_mfma_f32_16x16x32_bf16 v[114:117], v[134:137], v[194:197], v[114:117]
	v_mfma_f32_16x16x32_bf16 v[110:113], v[142:145], v[194:197], v[110:113]
	v_mfma_f32_16x16x32_bf16 v[102:105], v[134:137], v[202:205], v[102:105]
	v_mfma_f32_16x16x32_bf16 v[94:97], v[142:145], v[202:205], v[94:97]
	v_mfma_f32_16x16x32_bf16 v[86:89], v[134:137], v[210:213], v[86:89]
	v_mfma_f32_16x16x32_bf16 v[78:81], v[142:145], v[210:213], v[78:81]


; #define PG8_STAGE(bufoff, gbase, voff) do { _Pragma("unroll") for (int _i = 0; _i < 2; ++_i) \
;         __builtin_amdgcn_global_load_lds((const unsigned*)((const char*)(gbase) + (voff)[_i]), (PG8_LAS unsigned*)(lds + (bufoff) + ldsw + _i * 8192), 16, 0, 0); } while (0)
; #define PG8_LDA(dst, b, h) do { _Pragma("unroll") for (int m = 0; m < 4; ++m) _Pragma("unroll") for (int k = 0; k < 2; ++k) dst[m][k] = *(const PG8_LAS bf16x8*)(lds + PG8_SA(b, h) + aoff + m * 2048 + k * 1024); } while (0)
; #define PG8_MMA(ai, bj, At, Bt) do { __builtin_amdgcn_s_setprio(1); _Pragma("unroll") for (int m = 0; m < 4; ++m) _Pragma("unroll") for (int n = 0; n < 2; ++n) _Pragma("unroll") for (int k = 0; k < 2; ++k) \
;         acc[ai][bj][m][n] = __builtin_amdgcn_mfma_f32_16x16x32_bf16(Bt[n][k], At[m][k], acc[ai][bj][m][n], 0, 0, 0); __builtin_amdgcn_s_setprio(0); } while (0)
; #define PG8_WAIT_V(n) asm volatile("s_waitcnt vmcnt(" #n ")" ::: "memory")
; #define PG8_WAIT_L(n) asm volatile("s_waitcnt lgkmcnt(" #n ")" ::: "memory")
; #define PG8_BAR __builtin_amdgcn_s_barrier()
; #define PG8_SCHED __builtin_amdgcn_sched_barrier(0)
; template <class Epi, class Sched, bool ALIGN_EPI = false, bool SP2 = false>
; __device__ __forceinline__ void gemm_phase(PG8_LAS unsigned char* lds, const Gemm g, const Sched& S, const Epi& E) {
;     ...
;             PG8_WAIT_V(8); PG8_WAIT_L(0); PG8_BAR; PG8_MMA(0, 0, At, B0); PG8_MMA(0, 1, At, B1); PG8_BAR; PG8_SCHED;
;             PG8_LDA(At, 1, 1); PG8_STAGE(PG8_SB(1, 0), b3, voffB); PG8_STAGE(PG8_SB(1, 1), b3 + hstep, voffB); PG8_STAGE(PG8_SA(1, 0), a3, voffA);
;             PG8_WAIT_V(8); PG8_WAIT_L(0); PG8_BAR; PG8_MMA(1, 0, At, B0); PG8_MMA(1, 1, At, B1); PG8_BAR; PG8_SCHED;
	v_mfma_f32_16x16x32_bf16 v[118:121], v[156:159], v[178:181], v[118:121]
	v_mfma_f32_16x16x32_bf16 v[106:109], v[170:173], v[178:181], v[106:109]
	v_mfma_f32_16x16x32_bf16 v[98:101], v[156:159], v[186:189], v[98:101]
	v_mfma_f32_16x16x32_bf16 v[90:93], v[170:173], v[186:189], v[90:93]
	v_mfma_f32_16x16x32_bf16 v[82:85], v[156:159], v[198:201], v[82:85]
	v_mfma_f32_16x16x32_bf16 v[74:77], v[170:173], v[198:201], v[74:77]
	v_mfma_f32_16x16x32_bf16 v[70:73], v[156:159], v[206:209], v[70:73]
	v_mfma_f32_16x16x32_bf16 v[66:69], v[170:173], v[206:209], v[66:69]
	v_mfma_f32_16x16x32_bf16 v[118:121], v[160:163], v[182:185], v[118:121]
	v_mfma_f32_16x16x32_bf16 v[106:109], v[174:177], v[182:185], v[106:109]
	v_mfma_f32_16x16x32_bf16 v[98:101], v[160:163], v[194:197], v[98:101]
	v_mfma_f32_16x16x32_bf16 v[90:93], v[174:177], v[194:197], v[90:93]
	v_mfma_f32_16x16x32_bf16 v[82:85], v[160:163], v[202:205], v[82:85]
	v_mfma_f32_16x16x32_bf16 v[74:77], v[174:177], v[202:205], v[74:77]
	v_mfma_f32_16x16x32_bf16 v[70:73], v[160:163], v[210:213], v[70:73]
	v_mfma_f32_16x16x32_bf16 v[66:69], v[174:177], v[210:213], v[66:69]
	s_setprio 0
	s_barrier
	s_add_i32 s53, s53, s24
	v_lshl_add_u64 v[164:165], v[164:165], 0, s[8:9]
	s_mov_b32 m0, s53
	ds_read_b128 v[178:181], v169 offset:49152
	ds_read_b128 v[182:185], v169 offset:50176
	ds_read_b128 v[186:189], v169 offset:51200
	ds_read_b128 v[194:197], v169 offset:52224
	ds_read_b128 v[198:201], v169 offset:53248
	ds_read_b128 v[202:205], v169 offset:54272
	ds_read_b128 v[206:209], v169 offset:55296
	ds_read_b128 v[210:213], v169 offset:56320
	global_load_lds_dwordx4 v[164:165], off
	s_add_i32 m0, s53, 0x2000
	s_add_u32 s58, s58, 0x40080
	v_lshl_add_u64 v[164:165], v[214:215], 0, s[8:9]
	s_addc_u32 s59, s59, 0
	s_add_i32 s53, s64, s24
	global_load_lds_dwordx4 v[164:165], off
	v_lshl_add_u64 v[164:165], s[58:59], 0, v[0:1]
	s_mov_b32 m0, s53
	s_nop 0
	global_load_lds_dwordx4 v[164:165], off
	v_lshl_add_u64 v[164:165], s[58:59], 0, v[150:151]
	s_add_i32 m0, s53, 0x2000
	s_nop 0
	global_load_lds_dwordx4 v[164:165], off
	v_lshl_add_u64 v[164:165], v[216:217], 0, s[8:9]
	s_mov_b32 m0, s57
	s_nop 0
	global_load_lds_dwordx4 v[164:165], off
	v_lshl_add_u64 v[164:165], v[218:219], 0, s[8:9]
	s_mov_b32 m0, s62
	s_nop 0
	global_load_lds_dwordx4 v[164:165], off
	s_waitcnt vmcnt(8)
	s_waitcnt lgkmcnt(0)
	s_barrier
	s_setprio 1
	s_waitcnt lgkmcnt(0)
	v_mfma_f32_16x16x32_bf16 v[62:65], v[130:133], v[178:181], v[62:65]
	v_mfma_f32_16x16x32_bf16 v[58:61], v[138:141], v[178:181], v[58:61]
	v_mfma_f32_16x16x32_bf16 v[54:57], v[130:133], v[186:189], v[54:57]
	v_mfma_f32_16x16x32_bf16 v[46:49], v[138:141], v[186:189], v[46:49]
	v_mfma_f32_16x16x32_bf16 v[38:41], v[130:133], v[198:201], v[38:41]
	v_mfma_f32_16x16x32_bf16 v[30:33], v[138:141], v[198:201], v[30:33]
	v_mfma_f32_16x16x32_bf16 v[22:25], v[130:133], v[206:209], v[22:25]
	v_mfma_f32_16x16x32_bf16 v[14:17], v[138:141], v[206:209], v[14:17]
	v_mfma_f32_16x16x32_bf16 v[62:65], v[134:137], v[182:185], v[62:65]
	v_mfma_f32_16x16x32_bf16 v[58:61], v[142:145], v[182:185], v[58:61]
	v_mfma_f32_16x16x32_bf16 v[54:57], v[134:137], v[194:197], v[54:57]
	v_mfma_f32_16x16x32_bf16 v[46:49], v[142:145], v[194:197], v[46:49]
	v_mfma_f32_16x16x32_bf16 v[38:41], v[134:137], v[202:205], v[38:41]
	v_mfma_f32_16x16x32_bf16 v[30:33], v[142:145], v[202:205], v[30:33]
	v_mfma_f32_16x16x32_bf16 v[22:25], v[134:137], v[210:213], v[22:25]
	v_mfma_f32_16x16x32_bf16 v[14:17], v[142:145], v[210:213], v[14:17]


; #define PG8_STAGE(bufoff, gbase, voff) do { _Pragma("unroll") for (int _i = 0; _i < 2; ++_i) \
;         __builtin_amdgcn_global_load_lds((const unsigned*)((const char*)(gbase) + (voff)[_i]), (PG8_LAS unsigned*)(lds + (bufoff) + ldsw + _i * 8192), 16, 0, 0); } while (0)
; #define PG8_LDA(dst, b, h) do { _Pragma("unroll") for (int m = 0; m < 4; ++m) _Pragma("unroll") for (int k = 0; k < 2; ++k) dst[m][k] = *(const PG8_LAS bf16x8*)(lds + PG8_SA(b, h) + aoff + m * 2048 + k * 1024); } while (0)
; #define PG8_LDB(dst, b, h) do { _Pragma("unroll") for (int n = 0; n < 2; ++n) _Pragma("unroll") for (int k = 0; k < 2; ++k) dst[n][k] = *(const PG8_LAS bf16x8*)(lds + PG8_SB(b, h) + boff + n * 2048 + k * 1024); } while (0)
; template <class Epi, class Sched, bool ALIGN_EPI = false, bool SP2 = false>
; __device__ __forceinline__ void gemm_phase(PG8_LAS unsigned char* lds, const Gemm g, const Sched& S, const Epi& E) {
;     ...
;         for (int t = 0; t < nt; t += 2) {
;             const bool last = (t == nt - 2);
;             const char* a1 = cA + (size_t)(t + 1) * kstep;
;             const char* a2 = last ? nA : cA + (size_t)(t + 2) * kstep; const char* b2 = last ? nB : cB + (size_t)(t + 2) * kstep;
;             const char* a3 = a2 + kstep; const char* b3 = b2 + kstep;
;             if (last && has_next) S.a_ready(nxt);
;             if constexpr (SP2) {
;             PG8_LDB(B0, 0, 0); PG8_LDB(B1, 0, 1); PG8_SCHED; PG8_LDA(At, 0, 0); PG8_STAGE(PG8_SA(1, 1), a1 + hstep, voffA);
;             PG8_WAIT_V(8); PG8_WAIT_L(0); PG8_BAR; PG8_MMA(0, 0, At, B0); PG8_MMA(0, 1, At, B1); PG8_BAR; PG8_SCHED;
;             PG8_LDA(At, 0, 1); PG8_STAGE(PG8_SB(0, 0), b2, voffB); PG8_STAGE(PG8_SB(0, 1), b2 + hstep, voffB); PG8_STAGE(PG8_SA(0, 0), a2, voffA);
;             PG8_WAIT_V(8); PG8_WAIT_L(0); PG8_BAR; PG8_MMA(1, 0, At, B0); PG8_MMA(1, 1, At, B1); PG8_BAR; PG8_SCHED;
;             PG8_LDB(B0, 1, 0); PG8_LDB(B1, 1, 1); PG8_SCHED; PG8_LDA(At, 1, 0); PG8_STAGE(PG8_SA(0, 1), a2 + hstep, voffA);
;             PG8_WAIT_V(8); PG8_WAIT_L(0); PG8_BAR; PG8_MMA(0, 0, At, B0); PG8_MMA(0, 1, At, B1); PG8_BAR; PG8_SCHED;
;             PG8_LDA(At, 1, 1); PG8_STAGE(PG8_SB(1, 0), b3, voffB); PG8_STAGE(PG8_SB(1, 1), b3 + hstep, voffB); PG8_STAGE(PG8_SA(1, 0), a3, voffA);
;             PG8_WAIT_V(8); PG8_WAIT_L(0); PG8_BAR; PG8_MMA(1, 0, At, B0); PG8_MMA(1, 1, At, B1); PG8_BAR; PG8_SCHED;
	v_mfma_f32_16x16x32_bf16 v[50:53], v[156:159], v[178:181], v[50:53]
	v_mfma_f32_16x16x32_bf16 v[42:45], v[170:173], v[178:181], v[42:45]
	v_mfma_f32_16x16x32_bf16 v[34:37], v[156:159], v[186:189], v[34:37]
	v_mfma_f32_16x16x32_bf16 v[26:29], v[170:173], v[186:189], v[26:29]
	v_mfma_f32_16x16x32_bf16 v[18:21], v[156:159], v[198:201], v[18:21]
	v_mfma_f32_16x16x32_bf16 v[10:13], v[170:173], v[198:201], v[10:13]
	v_mfma_f32_16x16x32_bf16 v[6:9], v[156:159], v[206:209], v[6:9]
	v_mfma_f32_16x16x32_bf16 v[2:5], v[170:173], v[206:209], v[2:5]
	v_mfma_f32_16x16x32_bf16 v[50:53], v[160:163], v[182:185], v[50:53]
	v_mfma_f32_16x16x32_bf16 v[42:45], v[174:177], v[182:185], v[42:45]
	v_mfma_f32_16x16x32_bf16 v[34:37], v[160:163], v[194:197], v[34:37]
	v_mfma_f32_16x16x32_bf16 v[26:29], v[174:177], v[194:197], v[26:29]
	v_mfma_f32_16x16x32_bf16 v[18:21], v[160:163], v[202:205], v[18:21]
	v_mfma_f32_16x16x32_bf16 v[10:13], v[174:177], v[202:205], v[10:13]
	v_mfma_f32_16x16x32_bf16 v[6:9], v[160:163], v[210:213], v[6:9]
	v_mfma_f32_16x16x32_bf16 v[2:5], v[174:177], v[210:213], v[2:5]
	s_setprio 0
	s_barrier
	s_add_i32 s52, s52, 2
	s_add_u32 s18, s18, 0x100
	s_addc_u32 s19, s19, 0
	s_add_u32 s43, s43, 0x100
	s_addc_u32 s45, s45, 0
	s_cmp_gt_u32 s52, 13
	s_cbranch_scc0 .LBB0_291



; template <class Epi, class Sched, bool ALIGN_EPI = false, bool SP2 = false>
; __device__ __forceinline__ void gemm_phase(PG8_LAS unsigned char* lds, const Gemm g, const Sched& S, const Epi& E) {
;     ...
;         const bool has_next = S.next(ui + 1, nxt);
;         const char* nA = has_next ? (const char*)g.A + (size_t)nxt.pm * tstep : cA; const char* nB = has_next ? (const char*)g.Bt + (size_t)nxt.pn * tstep : cB;
;         for (int t = 0; t < nt; t += 2) {
;             const bool last = (t == nt - 2);
;             const char* a1 = cA + (size_t)(t + 1) * kstep;
;             const char* a2 = last ? nA : cA + (size_t)(t + 2) * kstep; const char* b2 = last ? nB : cB + (size_t)(t + 2) * kstep;
;             const char* a3 = a2 + kstep; const char* b3 = b2 + kstep;
.LBB0_452:
	s_ashr_i32 s51, s50, 31
	s_lshl_b64 s[30:31], s[50:51], 19
	s_add_u32 s56, s98, s30
	s_addc_u32 s57, s99, s31
	s_and_b64 s[30:31], s[54:55], exec
	s_cselect_b32 s30, s57, s19
	s_cselect_b32 s31, s56, s18
	s_ashr_i32 s49, s48, 31
	s_lshl_b64 s[34:35], s[48:49], 19
	s_add_u32 s58, s68, s34
	s_addc_u32 s59, s69, s35
	s_and_b64 s[34:35], s[54:55], exec
	s_cselect_b32 s34, s59, s65
	s_cselect_b32 s35, s58, s64
	s_add_u32 s18, s18, 0x40080
	s_addc_u32 s19, s19, 0
	s_add_u32 s49, s64, 0x100

; template <class Epi, class Sched, bool ALIGN_EPI = false, bool SP2 = false>
; __device__ __forceinline__ void gemm_phase(PG8_LAS unsigned char* lds, const Gemm g, const Sched& S, const Epi& E) {
;     ...
;         for (int t = 0; t < nt; t += 2) {
;             const bool last = (t == nt - 2);
;             const char* a1 = cA + (size_t)(t + 1) * kstep;
;             const char* a2 = last ? nA : cA + (size_t)(t + 2) * kstep; const char* b2 = last ? nB : cB + (size_t)(t + 2) * kstep;
	s_addc_u32 s51, s65, 0
	s_mov_b32 s52, -2


; #define PG8_STAGE(bufoff, gbase, voff) do { _Pragma("unroll") for (int _i = 0; _i < 2; ++_i) \
;         __builtin_amdgcn_global_load_lds((const unsigned*)((const char*)(gbase) + (voff)[_i]), (PG8_LAS unsigned*)(lds + (bufoff) + ldsw + _i * 8192), 16, 0, 0); } while (0)
; #define PG8_LDA(dst, b, h) do { _Pragma("unroll") for (int m = 0; m < 4; ++m) _Pragma("unroll") for (int k = 0; k < 2; ++k) dst[m][k] = *(const PG8_LAS bf16x8*)(lds + PG8_SA(b, h) + aoff + m * 2048 + k * 1024); } while (0)
; #define PG8_LDB(dst, b, h) do { _Pragma("unroll") for (int n = 0; n < 2; ++n) _Pragma("unroll") for (int k = 0; k < 2; ++k) dst[n][k] = *(const PG8_LAS bf16x8*)(lds + PG8_SB(b, h) + boff + n * 2048 + k * 1024); } while (0)
; #define PG8_MMA(ai, bj, At, Bt) do { __builtin_amdgcn_s_setprio(1); _Pragma("unroll") for (int m = 0; m < 4; ++m) _Pragma("unroll") for (int n = 0; n < 2; ++n) _Pragma("unroll") for (int k = 0; k < 2; ++k) \
;         acc[ai][bj][m][n] = __builtin_amdgcn_mfma_f32_16x16x32_bf16(Bt[n][k], At[m][k], acc[ai][bj][m][n], 0, 0, 0); __builtin_amdgcn_s_setprio(0); } while (0)
; #define PG8_WAIT_V(n) asm volatile("s_waitcnt vmcnt(" #n ")" ::: "memory")
; #define PG8_WAIT_L(n) asm volatile("s_waitcnt lgkmcnt(" #n ")" ::: "memory")
; #define PG8_BAR __builtin_amdgcn_s_barrier()
; #define PG8_SCHED __builtin_amdgcn_sched_barrier(0)
; template <class Epi, class Sched, bool ALIGN_EPI = false, bool SP2 = false>
; __device__ __forceinline__ void gemm_phase(PG8_LAS unsigned char* lds, const Gemm g, const Sched& S, const Epi& E) {
;     ...
;             const bool last = (t == nt - 2);
;             const char* a1 = cA + (size_t)(t + 1) * kstep;
;             const char* a2 = last ? nA : cA + (size_t)(t + 2) * kstep; const char* b2 = last ? nB : cB + (size_t)(t + 2) * kstep;
;             const char* a3 = a2 + kstep; const char* b3 = b2 + kstep;
;             if (last && has_next) S.a_ready(nxt);
;             if constexpr (SP2) {
;             PG8_LDB(B0, 0, 0); PG8_LDB(B1, 0, 1); PG8_SCHED; PG8_LDA(At, 0, 0); PG8_STAGE(PG8_SA(1, 1), a1 + hstep, voffA);
;             PG8_WAIT_V(8); PG8_WAIT_L(0); PG8_BAR; PG8_MMA(0, 0, At, B0); PG8_MMA(0, 1, At, B1); PG8_BAR; PG8_SCHED;
	s_add_u32 s53, s18, 0xfffc0080
	s_addc_u32 s64, s19, -1
	s_add_i32 s70, 0, 0x10000
	s_cmp_eq_u32 s52, 12
	s_cselect_b32 s67, s30, s64
	s_cselect_b32 s66, s31, s53
	s_cselect_b32 s65, s34, s51
	s_cselect_b32 s64, s35, s49
	s_add_i32 s53, 0, 0x14000
	v_add_u32_e32 v142, s70, v223
	v_add_u32_e32 v158, s53, v223
	ds_read_b128 v[130:133], v142
	ds_read_b128 v[134:137], v142 offset:1024
	ds_read_b128 v[138:141], v142 offset:2048
	ds_read_b128 v[142:145], v142 offset:3072
	ds_read_b128 v[146:149], v158
	ds_read_b128 v[150:153], v158 offset:1024
	ds_read_b128 v[154:157], v158 offset:2048
	ds_read_b128 v[158:161], v158 offset:3072
	v_lshl_add_u64 v[208:209], s[18:19], 0, v[200:201]
	s_add_i32 m0, s25, 0xc000
	ds_read_b128 v[162:165], v225
	ds_read_b128 v[166:169], v225 offset:1024
	ds_read_b128 v[170:173], v225 offset:2048
	ds_read_b128 v[174:177], v225 offset:3072
	ds_read_b128 v[178:181], v225 offset:4096
	ds_read_b128 v[182:185], v225 offset:5120
	ds_read_b128 v[186:189], v225 offset:6144
	ds_read_b128 v[204:207], v225 offset:7168
	global_load_lds_dwordx4 v[208:209], off
	v_lshl_add_u64 v[208:209], s[18:19], 0, v[202:203]
	s_add_i32 m0, s25, 0xe000
	s_nop 0
	global_load_lds_dwordx4 v[208:209], off
	s_waitcnt vmcnt(8)
	s_waitcnt lgkmcnt(0)
	s_barrier
	s_setprio 1
	s_waitcnt lgkmcnt(0)
	v_mfma_f32_16x16x32_bf16 v[126:129], v[130:133], v[162:165], 0
	v_mfma_f32_16x16x32_bf16 v[122:125], v[138:141], v[162:165], 0
	v_mfma_f32_16x16x32_bf16 v[110:113], v[130:133], v[170:173], 0
	v_mfma_f32_16x16x32_bf16 v[106:109], v[138:141], v[170:173], 0
	v_mfma_f32_16x16x32_bf16 v[98:101], v[130:133], v[178:181], 0
	v_mfma_f32_16x16x32_bf16 v[90:93], v[138:141], v[178:181], 0
	v_mfma_f32_16x16x32_bf16 v[82:85], v[130:133], v[186:189], 0
	v_mfma_f32_16x16x32_bf16 v[74:77], v[138:141], v[186:189], 0
	v_mfma_f32_16x16x32_bf16 v[126:129], v[134:137], v[166:169], v[126:129]
	v_mfma_f32_16x16x32_bf16 v[122:125], v[142:145], v[166:169], v[122:125]
	v_mfma_f32_16x16x32_bf16 v[110:113], v[134:137], v[174:177], v[110:113]
	v_mfma_f32_16x16x32_bf16 v[106:109], v[142:145], v[174:177], v[106:109]
	v_mfma_f32_16x16x32_bf16 v[98:101], v[134:137], v[182:185], v[98:101]
	v_mfma_f32_16x16x32_bf16 v[90:93], v[142:145], v[182:185], v[90:93]
	v_mfma_f32_16x16x32_bf16 v[82:85], v[134:137], v[204:207], v[82:85]
	v_mfma_f32_16x16x32_bf16 v[74:77], v[142:145], v[204:207], v[74:77]


; #define PG8_STAGE(bufoff, gbase, voff) do { _Pragma("unroll") for (int _i = 0; _i < 2; ++_i) \
;         __builtin_amdgcn_global_load_lds((const unsigned*)((const char*)(gbase) + (voff)[_i]), (PG8_LAS unsigned*)(lds + (bufoff) + ldsw + _i * 8192), 16, 0, 0); } while (0)
; #define PG8_LDA(dst, b, h) do { _Pragma("unroll") for (int m = 0; m < 4; ++m) _Pragma("unroll") for (int k = 0; k < 2; ++k) dst[m][k] = *(const PG8_LAS bf16x8*)(lds + PG8_SA(b, h) + aoff + m * 2048 + k * 1024); } while (0)
; #define PG8_MMA(ai, bj, At, Bt) do { __builtin_amdgcn_s_setprio(1); _Pragma("unroll") for (int m = 0; m < 4; ++m) _Pragma("unroll") for (int n = 0; n < 2; ++n) _Pragma("unroll") for (int k = 0; k < 2; ++k) \
;         acc[ai][bj][m][n] = __builtin_amdgcn_mfma_f32_16x16x32_bf16(Bt[n][k], At[m][k], acc[ai][bj][m][n], 0, 0, 0); __builtin_amdgcn_s_setprio(0); } while (0)
; #define PG8_WAIT_V(n) asm volatile("s_waitcnt vmcnt(" #n ")" ::: "memory")
; #define PG8_WAIT_L(n) asm volatile("s_waitcnt lgkmcnt(" #n ")" ::: "memory")
; #define PG8_BAR __builtin_amdgcn_s_barrier()
; #define PG8_SCHED __builtin_amdgcn_sched_barrier(0)
; template <class Epi, class Sched, bool ALIGN_EPI = false, bool SP2 = false>
; __device__ __forceinline__ void gemm_phase(PG8_LAS unsigned char* lds, const Gemm g, const Sched& S, const Epi& E) {
;     ...
;             PG8_WAIT_V(8); PG8_WAIT_L(0); PG8_BAR; PG8_MMA(0, 0, At, B0); PG8_MMA(0, 1, At, B1); PG8_BAR; PG8_SCHED;
;             PG8_LDA(At, 0, 1); PG8_STAGE(PG8_SB(0, 0), b2, voffB); PG8_STAGE(PG8_SB(0, 1), b2 + hstep, voffB); PG8_STAGE(PG8_SA(0, 0), a2, voffA);
;             PG8_WAIT_V(8); PG8_WAIT_L(0); PG8_BAR; PG8_MMA(1, 0, At, B0); PG8_MMA(1, 1, At, B1); PG8_BAR; PG8_SCHED;
	v_mfma_f32_16x16x32_bf16 v[118:121], v[146:149], v[162:165], 0
	v_mfma_f32_16x16x32_bf16 v[114:117], v[154:157], v[162:165], 0
	v_mfma_f32_16x16x32_bf16 v[102:105], v[146:149], v[170:173], 0
	v_mfma_f32_16x16x32_bf16 v[94:97], v[154:157], v[170:173], 0
	v_mfma_f32_16x16x32_bf16 v[86:89], v[146:149], v[178:181], 0
	v_mfma_f32_16x16x32_bf16 v[78:81], v[154:157], v[178:181], 0
	v_mfma_f32_16x16x32_bf16 v[70:73], v[146:149], v[186:189], 0
	v_mfma_f32_16x16x32_bf16 v[66:69], v[154:157], v[186:189], 0
	v_mfma_f32_16x16x32_bf16 v[118:121], v[150:153], v[166:169], v[118:121]
	v_mfma_f32_16x16x32_bf16 v[114:117], v[158:161], v[166:169], v[114:117]
	v_mfma_f32_16x16x32_bf16 v[102:105], v[150:153], v[174:177], v[102:105]
	v_mfma_f32_16x16x32_bf16 v[94:97], v[158:161], v[174:177], v[94:97]
	v_mfma_f32_16x16x32_bf16 v[86:89], v[150:153], v[182:185], v[86:89]
	v_mfma_f32_16x16x32_bf16 v[78:81], v[158:161], v[182:185], v[78:81]
	v_mfma_f32_16x16x32_bf16 v[70:73], v[150:153], v[204:207], v[70:73]
	v_mfma_f32_16x16x32_bf16 v[66:69], v[158:161], v[204:207], v[66:69]
	s_setprio 0
	s_barrier
	s_add_i32 s70, s70, s24
	v_lshl_add_u64 v[208:209], s[64:65], 0, v[0:1]
	s_mov_b32 m0, s70
	ds_read_b128 v[162:165], v225 offset:16384
	ds_read_b128 v[166:169], v225 offset:17408
	ds_read_b128 v[170:173], v225 offset:18432
	ds_read_b128 v[174:177], v225 offset:19456
	ds_read_b128 v[178:181], v225 offset:20480
	ds_read_b128 v[182:185], v225 offset:21504
	ds_read_b128 v[186:189], v225 offset:22528
	ds_read_b128 v[204:207], v225 offset:23552
	global_load_lds_dwordx4 v[208:209], off
	s_add_i32 m0, s70, 0x2000
	s_add_u32 s70, s64, 0x40000
	v_lshl_add_u64 v[210:211], s[64:65], 0, v[198:199]
	s_addc_u32 s71, s65, 0
	s_add_i32 s53, s53, s24
	global_load_lds_dwordx4 v[210:211], off
	v_lshl_add_u64 v[212:213], s[70:71], 0, v[0:1]
	s_mov_b32 m0, s53
	v_lshl_add_u64 v[214:215], s[66:67], 0, v[196:197]
	global_load_lds_dwordx4 v[212:213], off
	v_lshl_add_u64 v[212:213], s[70:71], 0, v[198:199]
	s_add_i32 m0, s53, 0x2000
	s_nop 0
	global_load_lds_dwordx4 v[212:213], off
	v_lshl_add_u64 v[212:213], s[66:67], 0, v[194:195]
	s_mov_b32 m0, s25
	s_nop 0
	global_load_lds_dwordx4 v[212:213], off
	s_mov_b32 m0, s26
	s_nop 0
	global_load_lds_dwordx4 v[214:215], off
	s_waitcnt vmcnt(8)
	s_waitcnt lgkmcnt(0)
	s_barrier
	s_setprio 1
	s_waitcnt lgkmcnt(0)
	v_mfma_f32_16x16x32_bf16 v[62:65], v[130:133], v[162:165], 0
	v_mfma_f32_16x16x32_bf16 v[58:61], v[138:141], v[162:165], 0
	v_mfma_f32_16x16x32_bf16 v[50:53], v[130:133], v[170:173], 0
	v_mfma_f32_16x16x32_bf16 v[42:45], v[138:141], v[170:173], 0
	v_mfma_f32_16x16x32_bf16 v[34:37], v[130:133], v[178:181], 0
	v_mfma_f32_16x16x32_bf16 v[26:29], v[138:141], v[178:181], 0
	v_mfma_f32_16x16x32_bf16 v[18:21], v[130:133], v[186:189], 0
	v_mfma_f32_16x16x32_bf16 v[10:13], v[138:141], v[186:189], 0
	v_mfma_f32_16x16x32_bf16 v[62:65], v[134:137], v[166:169], v[62:65]
	v_mfma_f32_16x16x32_bf16 v[58:61], v[142:145], v[166:169], v[58:61]
	v_mfma_f32_16x16x32_bf16 v[50:53], v[134:137], v[174:177], v[50:53]
	v_mfma_f32_16x16x32_bf16 v[42:45], v[142:145], v[174:177], v[42:45]
	v_mfma_f32_16x16x32_bf16 v[34:37], v[134:137], v[182:185], v[34:37]
	v_mfma_f32_16x16x32_bf16 v[26:29], v[142:145], v[182:185], v[26:29]
	v_mfma_f32_16x16x32_bf16 v[18:21], v[134:137], v[204:207], v[18:21]
	v_mfma_f32_16x16x32_bf16 v[10:13], v[142:145], v[204:207], v[10:13]


; #define PG8_STAGE(bufoff, gbase, voff) do { _Pragma("unroll") for (int _i = 0; _i < 2; ++_i) \
;         __builtin_amdgcn_global_load_lds((const unsigned*)((const char*)(gbase) + (voff)[_i]), (PG8_LAS unsigned*)(lds + (bufoff) + ldsw + _i * 8192), 16, 0, 0); } while (0)
; #define PG8_LDA(dst, b, h) do { _Pragma("unroll") for (int m = 0; m < 4; ++m) _Pragma("unroll") for (int k = 0; k < 2; ++k) dst[m][k] = *(const PG8_LAS bf16x8*)(lds + PG8_SA(b, h) + aoff + m * 2048 + k * 1024); } while (0)
; #define PG8_LDB(dst, b, h) do { _Pragma("unroll") for (int n = 0; n < 2; ++n) _Pragma("unroll") for (int k = 0; k < 2; ++k) dst[n][k] = *(const PG8_LAS bf16x8*)(lds + PG8_SB(b, h) + boff + n * 2048 + k * 1024); } while (0)
; #define PG8_MMA(ai, bj, At, Bt) do { __builtin_amdgcn_s_setprio(1); _Pragma("unroll") for (int m = 0; m < 4; ++m) _Pragma("unroll") for (int n = 0; n < 2; ++n) _Pragma("unroll") for (int k = 0; k < 2; ++k) \
;         acc[ai][bj][m][n] = __builtin_amdgcn_mfma_f32_16x16x32_bf16(Bt[n][k], At[m][k], acc[ai][bj][m][n], 0, 0, 0); __builtin_amdgcn_s_setprio(0); } while (0)
; #define PG8_WAIT_V(n) asm volatile("s_waitcnt vmcnt(" #n ")" ::: "memory")
; #define PG8_WAIT_L(n) asm volatile("s_waitcnt lgkmcnt(" #n ")" ::: "memory")
; #define PG8_BAR __builtin_amdgcn_s_barrier()
; #define PG8_SCHED __builtin_amdgcn_sched_barrier(0)
; template <class Epi, class Sched, bool ALIGN_EPI = false, bool SP2 = false>
; __device__ __forceinline__ void gemm_phase(PG8_LAS unsigned char* lds, const Gemm g, const Sched& S, const Epi& E) {
;     ...
;             PG8_WAIT_V(8); PG8_WAIT_L(0); PG8_BAR; PG8_MMA(1, 0, At, B0); PG8_MMA(1, 1, At, B1); PG8_BAR; PG8_SCHED;
;             PG8_LDB(B0, 1, 0); PG8_LDB(B1, 1, 1); PG8_SCHED; PG8_LDA(At, 1, 0); PG8_STAGE(PG8_SA(0, 1), a2 + hstep, voffA);
;             PG8_WAIT_V(8); PG8_WAIT_L(0); PG8_BAR; PG8_MMA(0, 0, At, B0); PG8_MMA(0, 1, At, B1); PG8_BAR; PG8_SCHED;
	v_mfma_f32_16x16x32_bf16 v[54:57], v[146:149], v[162:165], 0
	v_mfma_f32_16x16x32_bf16 v[46:49], v[154:157], v[162:165], 0
	v_mfma_f32_16x16x32_bf16 v[38:41], v[146:149], v[170:173], 0
	v_mfma_f32_16x16x32_bf16 v[30:33], v[154:157], v[170:173], 0
	v_mfma_f32_16x16x32_bf16 v[22:25], v[146:149], v[178:181], 0
	v_mfma_f32_16x16x32_bf16 v[14:17], v[154:157], v[178:181], 0
	v_mfma_f32_16x16x32_bf16 v[6:9], v[146:149], v[186:189], 0
	v_mfma_f32_16x16x32_bf16 v[2:5], v[154:157], v[186:189], 0
	v_mfma_f32_16x16x32_bf16 v[54:57], v[150:153], v[166:169], v[54:57]
	v_mfma_f32_16x16x32_bf16 v[46:49], v[158:161], v[166:169], v[46:49]
	v_mfma_f32_16x16x32_bf16 v[38:41], v[150:153], v[174:177], v[38:41]
	v_mfma_f32_16x16x32_bf16 v[30:33], v[158:161], v[174:177], v[30:33]
	v_mfma_f32_16x16x32_bf16 v[22:25], v[150:153], v[182:185], v[22:25]
	v_mfma_f32_16x16x32_bf16 v[14:17], v[158:161], v[182:185], v[14:17]
	v_mfma_f32_16x16x32_bf16 v[6:9], v[150:153], v[204:207], v[6:9]
	v_mfma_f32_16x16x32_bf16 v[2:5], v[158:161], v[204:207], v[2:5]
	s_setprio 0
	s_barrier
	s_add_i32 s53, 0, 0x18000
	s_add_i32 s70, 0, 0x1c000
	v_add_u32_e32 v142, s53, v223
	v_add_u32_e32 v158, s70, v223
	ds_read_b128 v[130:133], v142
	ds_read_b128 v[134:137], v142 offset:1024
	ds_read_b128 v[138:141], v142 offset:2048
	ds_read_b128 v[142:145], v142 offset:3072
	ds_read_b128 v[146:149], v158
	ds_read_b128 v[150:153], v158 offset:1024
	ds_read_b128 v[154:157], v158 offset:2048
	ds_read_b128 v[158:161], v158 offset:3072
	s_add_u32 s66, s66, 0x40000
	s_addc_u32 s67, s67, 0
	s_mov_b32 m0, s27
	v_lshl_add_u64 v[216:217], s[66:67], 0, v[194:195]
	ds_read_b128 v[162:165], v225 offset:32768
	ds_read_b128 v[166:169], v225 offset:33792
	ds_read_b128 v[170:173], v225 offset:34816
	ds_read_b128 v[174:177], v225 offset:35840
	ds_read_b128 v[178:181], v225 offset:36864
	ds_read_b128 v[182:185], v225 offset:37888
	ds_read_b128 v[186:189], v225 offset:38912
	ds_read_b128 v[204:207], v225 offset:39936
	global_load_lds_dwordx4 v[216:217], off
	v_lshl_add_u64 v[216:217], s[66:67], 0, v[196:197]
	s_mov_b32 m0, s28
	s_nop 0
	global_load_lds_dwordx4 v[216:217], off
	s_waitcnt vmcnt(8)
	s_waitcnt lgkmcnt(0)
	s_barrier
	s_setprio 1
	s_waitcnt lgkmcnt(0)
	v_mfma_f32_16x16x32_bf16 v[126:129], v[130:133], v[162:165], v[126:129]
	v_mfma_f32_16x16x32_bf16 v[122:125], v[138:141], v[162:165], v[122:125]
	v_mfma_f32_16x16x32_bf16 v[110:113], v[130:133], v[170:173], v[110:113]
	v_mfma_f32_16x16x32_bf16 v[106:109], v[138:141], v[170:173], v[106:109]
	v_mfma_f32_16x16x32_bf16 v[98:101], v[130:133], v[178:181], v[98:101]
	v_mfma_f32_16x16x32_bf16 v[90:93], v[138:141], v[178:181], v[90:93]
	v_mfma_f32_16x16x32_bf16 v[82:85], v[130:133], v[186:189], v[82:85]
	v_mfma_f32_16x16x32_bf16 v[74:77], v[138:141], v[186:189], v[74:77]
	v_mfma_f32_16x16x32_bf16 v[126:129], v[134:137], v[166:169], v[126:129]
	v_mfma_f32_16x16x32_bf16 v[122:125], v[142:145], v[166:169], v[122:125]
	v_mfma_f32_16x16x32_bf16 v[110:113], v[134:137], v[174:177], v[110:113]
	v_mfma_f32_16x16x32_bf16 v[106:109], v[142:145], v[174:177], v[106:109]
	v_mfma_f32_16x16x32_bf16 v[98:101], v[134:137], v[182:185], v[98:101]
	v_mfma_f32_16x16x32_bf16 v[90:93], v[142:145], v[182:185], v[90:93]
	v_mfma_f32_16x16x32_bf16 v[82:85], v[134:137], v[204:207], v[82:85]
	v_mfma_f32_16x16x32_bf16 v[74:77], v[142:145], v[204:207], v[74:77]


; #define PG8_STAGE(bufoff, gbase, voff) do { _Pragma("unroll") for (int _i = 0; _i < 2; ++_i) \
;         __builtin_amdgcn_global_load_lds((const unsigned*)((const char*)(gbase) + (voff)[_i]), (PG8_LAS unsigned*)(lds + (bufoff) + ldsw + _i * 8192), 16, 0, 0); } while (0)
; #define PG8_LDA(dst, b, h) do { _Pragma("unroll") for (int m = 0; m < 4; ++m) _Pragma("unroll") for (int k = 0; k < 2; ++k) dst[m][k] = *(const PG8_LAS bf16x8*)(lds + PG8_SA(b, h) + aoff + m * 2048 + k * 1024); } while (0)
; #define PG8_MMA(ai, bj, At, Bt) do { __builtin_amdgcn_s_setprio(1); _Pragma("unroll") for (int m = 0; m < 4; ++m) _Pragma("unroll") for (int n = 0; n < 2; ++n) _Pragma("unroll") for (int k = 0; k < 2; ++k) \
;         acc[ai][bj][m][n] = __builtin_amdgcn_mfma_f32_16x16x32_bf16(Bt[n][k], At[m][k], acc[ai][bj][m][n], 0, 0, 0); __builtin_amdgcn_s_setprio(0); } while (0)
; #define PG8_WAIT_V(n) asm volatile("s_waitcnt vmcnt(" #n ")" ::: "memory")
; #define PG8_WAIT_L(n) asm volatile("s_waitcnt lgkmcnt(" #n ")" ::: "memory")
; #define PG8_BAR __builtin_amdgcn_s_barrier()
; #define PG8_SCHED __builtin_amdgcn_sched_barrier(0)
; template <class Epi, class Sched, bool ALIGN_EPI = false, bool SP2 = false>
; __device__ __forceinline__ void gemm_phase(PG8_LAS unsigned char* lds, const Gemm g, const Sched& S, const Epi& E) {
;     ...
;             PG8_WAIT_V(8); PG8_WAIT_L(0); PG8_BAR; PG8_MMA(0, 0, At, B0); PG8_MMA(0, 1, At, B1); PG8_BAR; PG8_SCHED;
;             PG8_LDA(At, 1, 1); PG8_STAGE(PG8_SB(1, 0), b3, voffB); PG8_STAGE(PG8_SB(1, 1), b3 + hstep, voffB); PG8_STAGE(PG8_SA(1, 0), a3, voffA);
;             PG8_WAIT_V(8); PG8_WAIT_L(0); PG8_BAR; PG8_MMA(1, 0, At, B0); PG8_MMA(1, 1, At, B1); PG8_BAR; PG8_SCHED;
	v_mfma_f32_16x16x32_bf16 v[118:121], v[146:149], v[162:165], v[118:121]
	v_mfma_f32_16x16x32_bf16 v[114:117], v[154:157], v[162:165], v[114:117]
	v_mfma_f32_16x16x32_bf16 v[102:105], v[146:149], v[170:173], v[102:105]
	v_mfma_f32_16x16x32_bf16 v[94:97], v[154:157], v[170:173], v[94:97]
	v_mfma_f32_16x16x32_bf16 v[86:89], v[146:149], v[178:181], v[86:89]
	v_mfma_f32_16x16x32_bf16 v[78:81], v[154:157], v[178:181], v[78:81]
	v_mfma_f32_16x16x32_bf16 v[70:73], v[146:149], v[186:189], v[70:73]
	v_mfma_f32_16x16x32_bf16 v[66:69], v[154:157], v[186:189], v[66:69]
	v_mfma_f32_16x16x32_bf16 v[118:121], v[150:153], v[166:169], v[118:121]
	v_mfma_f32_16x16x32_bf16 v[114:117], v[158:161], v[166:169], v[114:117]
	v_mfma_f32_16x16x32_bf16 v[102:105], v[150:153], v[174:177], v[102:105]
	v_mfma_f32_16x16x32_bf16 v[94:97], v[158:161], v[174:177], v[94:97]
	v_mfma_f32_16x16x32_bf16 v[86:89], v[150:153], v[182:185], v[86:89]
	v_mfma_f32_16x16x32_bf16 v[78:81], v[158:161], v[182:185], v[78:81]
	v_mfma_f32_16x16x32_bf16 v[70:73], v[150:153], v[204:207], v[70:73]
	v_mfma_f32_16x16x32_bf16 v[66:69], v[158:161], v[204:207], v[66:69]
	s_setprio 0
	s_barrier
	s_add_i32 s53, s53, s24
	v_lshl_add_u64 v[208:209], v[208:209], 0, s[8:9]
	s_mov_b32 m0, s53
	ds_read_b128 v[162:165], v225 offset:49152
	ds_read_b128 v[166:169], v225 offset:50176
	ds_read_b128 v[170:173], v225 offset:51200
	ds_read_b128 v[174:177], v225 offset:52224
	ds_read_b128 v[178:181], v225 offset:53248
	ds_read_b128 v[182:185], v225 offset:54272
	ds_read_b128 v[186:189], v225 offset:55296
	ds_read_b128 v[204:207], v225 offset:56320
	global_load_lds_dwordx4 v[208:209], off
	s_add_i32 m0, s53, 0x2000
	s_add_u32 s64, s64, 0x40080
	v_lshl_add_u64 v[208:209], v[210:211], 0, s[8:9]
	s_addc_u32 s65, s65, 0
	s_add_i32 s53, s70, s24
	global_load_lds_dwordx4 v[208:209], off
	v_lshl_add_u64 v[208:209], s[64:65], 0, v[0:1]
	s_mov_b32 m0, s53
	s_nop 0
	global_load_lds_dwordx4 v[208:209], off
	v_lshl_add_u64 v[208:209], s[64:65], 0, v[198:199]
	s_add_i32 m0, s53, 0x2000
	s_nop 0
	global_load_lds_dwordx4 v[208:209], off
	v_lshl_add_u64 v[208:209], v[212:213], 0, s[8:9]
	s_mov_b32 m0, s29
	s_nop 0
	global_load_lds_dwordx4 v[208:209], off
	v_lshl_add_u64 v[208:209], v[214:215], 0, s[8:9]
	s_mov_b32 m0, s61
	s_nop 0
	global_load_lds_dwordx4 v[208:209], off
	s_waitcnt vmcnt(8)
	s_waitcnt lgkmcnt(0)
	s_barrier
	s_setprio 1
	s_waitcnt lgkmcnt(0)
	v_mfma_f32_16x16x32_bf16 v[62:65], v[130:133], v[162:165], v[62:65]
	v_mfma_f32_16x16x32_bf16 v[58:61], v[138:141], v[162:165], v[58:61]
	v_mfma_f32_16x16x32_bf16 v[50:53], v[130:133], v[170:173], v[50:53]
	v_mfma_f32_16x16x32_bf16 v[42:45], v[138:141], v[170:173], v[42:45]
	v_mfma_f32_16x16x32_bf16 v[34:37], v[130:133], v[178:181], v[34:37]
	v_mfma_f32_16x16x32_bf16 v[26:29], v[138:141], v[178:181], v[26:29]
	v_mfma_f32_16x16x32_bf16 v[18:21], v[130:133], v[186:189], v[18:21]
	v_mfma_f32_16x16x32_bf16 v[10:13], v[138:141], v[186:189], v[10:13]
	v_mfma_f32_16x16x32_bf16 v[62:65], v[134:137], v[166:169], v[62:65]
	v_mfma_f32_16x16x32_bf16 v[58:61], v[142:145], v[166:169], v[58:61]
	v_mfma_f32_16x16x32_bf16 v[50:53], v[134:137], v[174:177], v[50:53]
	v_mfma_f32_16x16x32_bf16 v[42:45], v[142:145], v[174:177], v[42:45]
	v_mfma_f32_16x16x32_bf16 v[34:37], v[134:137], v[182:185], v[34:37]
	v_mfma_f32_16x16x32_bf16 v[26:29], v[142:145], v[182:185], v[26:29]
	v_mfma_f32_16x16x32_bf16 v[18:21], v[134:137], v[204:207], v[18:21]
	v_mfma_f32_16x16x32_bf16 v[10:13], v[142:145], v[204:207], v[10:13]


; #define PG8_STAGE(bufoff, gbase, voff) do { _Pragma("unroll") for (int _i = 0; _i < 2; ++_i) \
;         __builtin_amdgcn_global_load_lds((const unsigned*)((const char*)(gbase) + (voff)[_i]), (PG8_LAS unsigned*)(lds + (bufoff) + ldsw + _i * 8192), 16, 0, 0); } while (0)
; #define PG8_LDA(dst, b, h) do { _Pragma("unroll") for (int m = 0; m < 4; ++m) _Pragma("unroll") for (int k = 0; k < 2; ++k) dst[m][k] = *(const PG8_LAS bf16x8*)(lds + PG8_SA(b, h) + aoff + m * 2048 + k * 1024); } while (0)
; #define PG8_LDB(dst, b, h) do { _Pragma("unroll") for (int n = 0; n < 2; ++n) _Pragma("unroll") for (int k = 0; k < 2; ++k) dst[n][k] = *(const PG8_LAS bf16x8*)(lds + PG8_SB(b, h) + boff + n * 2048 + k * 1024); } while (0)
; template <class Epi, class Sched, bool ALIGN_EPI = false, bool SP2 = false>
; __device__ __forceinline__ void gemm_phase(PG8_LAS unsigned char* lds, const Gemm g, const Sched& S, const Epi& E) {
;     ...
;         for (int t = 0; t < nt; t += 2) {
;             const bool last = (t == nt - 2);
;             const char* a1 = cA + (size_t)(t + 1) * kstep;
;             const char* a2 = last ? nA : cA + (size_t)(t + 2) * kstep; const char* b2 = last ? nB : cB + (size_t)(t + 2) * kstep;
;             const char* a3 = a2 + kstep; const char* b3 = b2 + kstep;
;             if (last && has_next) S.a_ready(nxt);
;             if constexpr (SP2) {
;             PG8_LDB(B0, 0, 0); PG8_LDB(B1, 0, 1); PG8_SCHED; PG8_LDA(At, 0, 0); PG8_STAGE(PG8_SA(1, 1), a1 + hstep, voffA);
;             PG8_WAIT_V(8); PG8_WAIT_L(0); PG8_BAR; PG8_MMA(0, 0, At, B0); PG8_MMA(0, 1, At, B1); PG8_BAR; PG8_SCHED;
;             PG8_LDA(At, 0, 1); PG8_STAGE(PG8_SB(0, 0), b2, voffB); PG8_STAGE(PG8_SB(0, 1), b2 + hstep, voffB); PG8_STAGE(PG8_SA(0, 0), a2, voffA);
;             PG8_WAIT_V(8); PG8_WAIT_L(0); PG8_BAR; PG8_MMA(1, 0, At, B0); PG8_MMA(1, 1, At, B1); PG8_BAR; PG8_SCHED;
;             PG8_LDB(B0, 1, 0); PG8_LDB(B1, 1, 1); PG8_SCHED; PG8_LDA(At, 1, 0); PG8_STAGE(PG8_SA(0, 1), a2 + hstep, voffA);
;             PG8_WAIT_V(8); PG8_WAIT_L(0); PG8_BAR; PG8_MMA(0, 0, At, B0); PG8_MMA(0, 1, At, B1); PG8_BAR; PG8_SCHED;
;             PG8_LDA(At, 1, 1); PG8_STAGE(PG8_SB(1, 0), b3, voffB); PG8_STAGE(PG8_SB(1, 1), b3 + hstep, voffB); PG8_STAGE(PG8_SA(1, 0), a3, voffA);
;             PG8_WAIT_V(8); PG8_WAIT_L(0); PG8_BAR; PG8_MMA(1, 0, At, B0); PG8_MMA(1, 1, At, B1); PG8_BAR; PG8_SCHED;
	v_mfma_f32_16x16x32_bf16 v[54:57], v[146:149], v[162:165], v[54:57]
	v_mfma_f32_16x16x32_bf16 v[46:49], v[154:157], v[162:165], v[46:49]
	v_mfma_f32_16x16x32_bf16 v[38:41], v[146:149], v[170:173], v[38:41]
	v_mfma_f32_16x16x32_bf16 v[30:33], v[154:157], v[170:173], v[30:33]
	v_mfma_f32_16x16x32_bf16 v[22:25], v[146:149], v[178:181], v[22:25]
	v_mfma_f32_16x16x32_bf16 v[14:17], v[154:157], v[178:181], v[14:17]
	v_mfma_f32_16x16x32_bf16 v[6:9], v[146:149], v[186:189], v[6:9]
	v_mfma_f32_16x16x32_bf16 v[2:5], v[154:157], v[186:189], v[2:5]
	v_mfma_f32_16x16x32_bf16 v[54:57], v[150:153], v[166:169], v[54:57]
	v_mfma_f32_16x16x32_bf16 v[46:49], v[158:161], v[166:169], v[46:49]
	v_mfma_f32_16x16x32_bf16 v[38:41], v[150:153], v[174:177], v[38:41]
	v_mfma_f32_16x16x32_bf16 v[30:33], v[158:161], v[174:177], v[30:33]
	v_mfma_f32_16x16x32_bf16 v[22:25], v[150:153], v[182:185], v[22:25]
	v_mfma_f32_16x16x32_bf16 v[14:17], v[158:161], v[182:185], v[14:17]
	v_mfma_f32_16x16x32_bf16 v[6:9], v[150:153], v[204:207], v[6:9]
	v_mfma_f32_16x16x32_bf16 v[2:5], v[158:161], v[204:207], v[2:5]
	s_setprio 0
	s_barrier
	s_add_i32 s52, s52, 2
	s_add_u32 s18, s18, 0x100
	s_addc_u32 s19, s19, 0
	s_add_u32 s49, s49, 0x100
	s_addc_u32 s51, s51, 0
	s_cmp_gt_u32 s52, 13
.LBB0_453:
	s_add_u32 s53, s18, 0xfffc0080
	s_addc_u32 s64, s19, -1
	s_add_i32 s70, 0, 0x10000
	s_cmp_eq_u32 s52, 12
	s_cselect_b32 s67, s30, s64
	s_cselect_b32 s66, s31, s53
	s_cselect_b32 s65, s34, s51
	s_cselect_b32 s64, s35, s49
	s_add_i32 s53, 0, 0x14000
	v_add_u32_e32 v142, s70, v223
	v_add_u32_e32 v158, s53, v223
	ds_read_b128 v[130:133], v142
	ds_read_b128 v[134:137], v142 offset:1024
	ds_read_b128 v[138:141], v142 offset:2048
	ds_read_b128 v[142:145], v142 offset:3072
	ds_read_b128 v[146:149], v158
	ds_read_b128 v[150:153], v158 offset:1024
	ds_read_b128 v[154:157], v158 offset:2048
	ds_read_b128 v[158:161], v158 offset:3072
	v_lshl_add_u64 v[208:209], s[18:19], 0, v[200:201]
	s_add_i32 m0, s25, 0xc000
	ds_read_b128 v[162:165], v225
	ds_read_b128 v[166:169], v225 offset:1024
	ds_read_b128 v[170:173], v225 offset:2048
	ds_read_b128 v[174:177], v225 offset:3072
	ds_read_b128 v[178:181], v225 offset:4096
	ds_read_b128 v[182:185], v225 offset:5120
	ds_read_b128 v[186:189], v225 offset:6144
	ds_read_b128 v[204:207], v225 offset:7168
	global_load_lds_dwordx4 v[208:209], off
	v_lshl_add_u64 v[208:209], s[18:19], 0, v[202:203]
	s_add_i32 m0, s25, 0xe000
	s_nop 0
	global_load_lds_dwordx4 v[208:209], off
	s_waitcnt vmcnt(8)
	s_waitcnt lgkmcnt(0)
	s_barrier
	s_setprio 1
	s_waitcnt lgkmcnt(0)
	v_mfma_f32_16x16x32_bf16 v[126:129], v[130:133], v[162:165], v[126:129]
	v_mfma_f32_16x16x32_bf16 v[122:125], v[138:141], v[162:165], v[122:125]
	v_mfma_f32_16x16x32_bf16 v[110:113], v[130:133], v[170:173], v[110:113]
	v_mfma_f32_16x16x32_bf16 v[106:109], v[138:141], v[170:173], v[106:109]
	v_mfma_f32_16x16x32_bf16 v[98:101], v[130:133], v[178:181], v[98:101]
	v_mfma_f32_16x16x32_bf16 v[90:93], v[138:141], v[178:181], v[90:93]
	v_mfma_f32_16x16x32_bf16 v[82:85], v[130:133], v[186:189], v[82:85]
	v_mfma_f32_16x16x32_bf16 v[74:77], v[138:141], v[186:189], v[74:77]
	v_mfma_f32_16x16x32_bf16 v[126:129], v[134:137], v[166:169], v[126:129]
	v_mfma_f32_16x16x32_bf16 v[122:125], v[142:145], v[166:169], v[122:125]
	v_mfma_f32_16x16x32_bf16 v[110:113], v[134:137], v[174:177], v[110:113]
	v_mfma_f32_16x16x32_bf16 v[106:109], v[142:145], v[174:177], v[106:109]
	v_mfma_f32_16x16x32_bf16 v[98:101], v[134:137], v[182:185], v[98:101]
	v_mfma_f32_16x16x32_bf16 v[90:93], v[142:145], v[182:185], v[90:93]
	v_mfma_f32_16x16x32_bf16 v[82:85], v[134:137], v[204:207], v[82:85]
	v_mfma_f32_16x16x32_bf16 v[74:77], v[142:145], v[204:207], v[74:77]


; #define PG8_STAGE(bufoff, gbase, voff) do { _Pragma("unroll") for (int _i = 0; _i < 2; ++_i) \
;         __builtin_amdgcn_global_load_lds((const unsigned*)((const char*)(gbase) + (voff)[_i]), (PG8_LAS unsigned*)(lds + (bufoff) + ldsw + _i * 8192), 16, 0, 0); } while (0)
; #define PG8_LDA(dst, b, h) do { _Pragma("unroll") for (int m = 0; m < 4; ++m) _Pragma("unroll") for (int k = 0; k < 2; ++k) dst[m][k] = *(const PG8_LAS bf16x8*)(lds + PG8_SA(b, h) + aoff + m * 2048 + k * 1024); } while (0)
; #define PG8_MMA(ai, bj, At, Bt) do { __builtin_amdgcn_s_setprio(1); _Pragma("unroll") for (int m = 0; m < 4; ++m) _Pragma("unroll") for (int n = 0; n < 2; ++n) _Pragma("unroll") for (int k = 0; k < 2; ++k) \
;         acc[ai][bj][m][n] = __builtin_amdgcn_mfma_f32_16x16x32_bf16(Bt[n][k], At[m][k], acc[ai][bj][m][n], 0, 0, 0); __builtin_amdgcn_s_setprio(0); } while (0)
; #define PG8_WAIT_V(n) asm volatile("s_waitcnt vmcnt(" #n ")" ::: "memory")
; #define PG8_WAIT_L(n) asm volatile("s_waitcnt lgkmcnt(" #n ")" ::: "memory")
; #define PG8_BAR __builtin_amdgcn_s_barrier()
; #define PG8_SCHED __builtin_amdgcn_sched_barrier(0)
; template <class Epi, class Sched, bool ALIGN_EPI = false, bool SP2 = false>
; __device__ __forceinline__ void gemm_phase(PG8_LAS unsigned char* lds, const Gemm g, const Sched& S, const Epi& E) {
;     ...
;             PG8_WAIT_V(8); PG8_WAIT_L(0); PG8_BAR; PG8_MMA(0, 0, At, B0); PG8_MMA(0, 1, At, B1); PG8_BAR; PG8_SCHED;
;             PG8_LDA(At, 0, 1); PG8_STAGE(PG8_SB(0, 0), b2, voffB); PG8_STAGE(PG8_SB(0, 1), b2 + hstep, voffB); PG8_STAGE(PG8_SA(0, 0), a2, voffA);
;             PG8_WAIT_V(8); PG8_WAIT_L(0); PG8_BAR; PG8_MMA(1, 0, At, B0); PG8_MMA(1, 1, At, B1); PG8_BAR; PG8_SCHED;
	v_mfma_f32_16x16x32_bf16 v[118:121], v[146:149], v[162:165], v[118:121]
	v_mfma_f32_16x16x32_bf16 v[114:117], v[154:157], v[162:165], v[114:117]
	v_mfma_f32_16x16x32_bf16 v[102:105], v[146:149], v[170:173], v[102:105]
	v_mfma_f32_16x16x32_bf16 v[94:97], v[154:157], v[170:173], v[94:97]
	v_mfma_f32_16x16x32_bf16 v[86:89], v[146:149], v[178:181], v[86:89]
	v_mfma_f32_16x16x32_bf16 v[78:81], v[154:157], v[178:181], v[78:81]
	v_mfma_f32_16x16x32_bf16 v[70:73], v[146:149], v[186:189], v[70:73]
	v_mfma_f32_16x16x32_bf16 v[66:69], v[154:157], v[186:189], v[66:69]
	v_mfma_f32_16x16x32_bf16 v[118:121], v[150:153], v[166:169], v[118:121]
	v_mfma_f32_16x16x32_bf16 v[114:117], v[158:161], v[166:169], v[114:117]
	v_mfma_f32_16x16x32_bf16 v[102:105], v[150:153], v[174:177], v[102:105]
	v_mfma_f32_16x16x32_bf16 v[94:97], v[158:161], v[174:177], v[94:97]
	v_mfma_f32_16x16x32_bf16 v[86:89], v[150:153], v[182:185], v[86:89]
	v_mfma_f32_16x16x32_bf16 v[78:81], v[158:161], v[182:185], v[78:81]
	v_mfma_f32_16x16x32_bf16 v[70:73], v[150:153], v[204:207], v[70:73]
	v_mfma_f32_16x16x32_bf16 v[66:69], v[158:161], v[204:207], v[66:69]
	s_setprio 0
	s_barrier
	s_add_i32 s70, s70, s24
	v_lshl_add_u64 v[208:209], s[64:65], 0, v[0:1]
	s_mov_b32 m0, s70
	ds_read_b128 v[162:165], v225 offset:16384
	ds_read_b128 v[166:169], v225 offset:17408
	ds_read_b128 v[170:173], v225 offset:18432
	ds_read_b128 v[174:177], v225 offset:19456
	ds_read_b128 v[178:181], v225 offset:20480
	ds_read_b128 v[182:185], v225 offset:21504
	ds_read_b128 v[186:189], v225 offset:22528
	ds_read_b128 v[204:207], v225 offset:23552
	global_load_lds_dwordx4 v[208:209], off
	s_add_i32 m0, s70, 0x2000
	s_add_u32 s70, s64, 0x40000
	v_lshl_add_u64 v[210:211], s[64:65], 0, v[198:199]
	s_addc_u32 s71, s65, 0
	s_add_i32 s53, s53, s24
	global_load_lds_dwordx4 v[210:211], off
	v_lshl_add_u64 v[212:213], s[70:71], 0, v[0:1]
	s_mov_b32 m0, s53
	v_lshl_add_u64 v[214:215], s[66:67], 0, v[196:197]
	global_load_lds_dwordx4 v[212:213], off
	v_lshl_add_u64 v[212:213], s[70:71], 0, v[198:199]
	s_add_i32 m0, s53, 0x2000
	s_nop 0
	global_load_lds_dwordx4 v[212:213], off
	v_lshl_add_u64 v[212:213], s[66:67], 0, v[194:195]
	s_mov_b32 m0, s25
	s_nop 0
	global_load_lds_dwordx4 v[212:213], off
	s_mov_b32 m0, s26
	s_nop 0
	global_load_lds_dwordx4 v[214:215], off
	s_waitcnt vmcnt(8)
	s_waitcnt lgkmcnt(0)
	s_barrier
	s_setprio 1
	s_waitcnt lgkmcnt(0)
	v_mfma_f32_16x16x32_bf16 v[62:65], v[130:133], v[162:165], v[62:65]
	v_mfma_f32_16x16x32_bf16 v[58:61], v[138:141], v[162:165], v[58:61]
	v_mfma_f32_16x16x32_bf16 v[50:53], v[130:133], v[170:173], v[50:53]
	v_mfma_f32_16x16x32_bf16 v[42:45], v[138:141], v[170:173], v[42:45]
	v_mfma_f32_16x16x32_bf16 v[34:37], v[130:133], v[178:181], v[34:37]
	v_mfma_f32_16x16x32_bf16 v[26:29], v[138:141], v[178:181], v[26:29]
	v_mfma_f32_16x16x32_bf16 v[18:21], v[130:133], v[186:189], v[18:21]
	v_mfma_f32_16x16x32_bf16 v[10:13], v[138:141], v[186:189], v[10:13]
	v_mfma_f32_16x16x32_bf16 v[62:65], v[134:137], v[166:169], v[62:65]
	v_mfma_f32_16x16x32_bf16 v[58:61], v[142:145], v[166:169], v[58:61]
	v_mfma_f32_16x16x32_bf16 v[50:53], v[134:137], v[174:177], v[50:53]
	v_mfma_f32_16x16x32_bf16 v[42:45], v[142:145], v[174:177], v[42:45]
	v_mfma_f32_16x16x32_bf16 v[34:37], v[134:137], v[182:185], v[34:37]
	v_mfma_f32_16x16x32_bf16 v[26:29], v[142:145], v[182:185], v[26:29]
	v_mfma_f32_16x16x32_bf16 v[18:21], v[134:137], v[204:207], v[18:21]
	v_mfma_f32_16x16x32_bf16 v[10:13], v[142:145], v[204:207], v[10:13]


; #define PG8_STAGE(bufoff, gbase, voff) do { _Pragma("unroll") for (int _i = 0; _i < 2; ++_i) \
;         __builtin_amdgcn_global_load_lds((const unsigned*)((const char*)(gbase) + (voff)[_i]), (PG8_LAS unsigned*)(lds + (bufoff) + ldsw + _i * 8192), 16, 0, 0); } while (0)
; #define PG8_LDA(dst, b, h) do { _Pragma("unroll") for (int m = 0; m < 4; ++m) _Pragma("unroll") for (int k = 0; k < 2; ++k) dst[m][k] = *(const PG8_LAS bf16x8*)(lds + PG8_SA(b, h) + aoff + m * 2048 + k * 1024); } while (0)
; #define PG8_LDB(dst, b, h) do { _Pragma("unroll") for (int n = 0; n < 2; ++n) _Pragma("unroll") for (int k = 0; k < 2; ++k) dst[n][k] = *(const PG8_LAS bf16x8*)(lds + PG8_SB(b, h) + boff + n * 2048 + k * 1024); } while (0)
; #define PG8_MMA(ai, bj, At, Bt) do { __builtin_amdgcn_s_setprio(1); _Pragma("unroll") for (int m = 0; m < 4; ++m) _Pragma("unroll") for (int n = 0; n < 2; ++n) _Pragma("unroll") for (int k = 0; k < 2; ++k) \
;         acc[ai][bj][m][n] = __builtin_amdgcn_mfma_f32_16x16x32_bf16(Bt[n][k], At[m][k], acc[ai][bj][m][n], 0, 0, 0); __builtin_amdgcn_s_setprio(0); } while (0)
; #define PG8_WAIT_V(n) asm volatile("s_waitcnt vmcnt(" #n ")" ::: "memory")
; #define PG8_WAIT_L(n) asm volatile("s_waitcnt lgkmcnt(" #n ")" ::: "memory")
; #define PG8_BAR __builtin_amdgcn_s_barrier()
; #define PG8_SCHED __builtin_amdgcn_sched_barrier(0)
; template <class Epi, class Sched, bool ALIGN_EPI = false, bool SP2 = false>
; __device__ __forceinline__ void gemm_phase(PG8_LAS unsigned char* lds, const Gemm g, const Sched& S, const Epi& E) {
;     ...
;             PG8_WAIT_V(8); PG8_WAIT_L(0); PG8_BAR; PG8_MMA(1, 0, At, B0); PG8_MMA(1, 1, At, B1); PG8_BAR; PG8_SCHED;
;             PG8_LDB(B0, 1, 0); PG8_LDB(B1, 1, 1); PG8_SCHED; PG8_LDA(At, 1, 0); PG8_STAGE(PG8_SA(0, 1), a2 + hstep, voffA);
;             PG8_WAIT_V(8); PG8_WAIT_L(0); PG8_BAR; PG8_MMA(0, 0, At, B0); PG8_MMA(0, 1, At, B1); PG8_BAR; PG8_SCHED;
	v_mfma_f32_16x16x32_bf16 v[54:57], v[146:149], v[162:165], v[54:57]
	v_mfma_f32_16x16x32_bf16 v[46:49], v[154:157], v[162:165], v[46:49]
	v_mfma_f32_16x16x32_bf16 v[38:41], v[146:149], v[170:173], v[38:41]
	v_mfma_f32_16x16x32_bf16 v[30:33], v[154:157], v[170:173], v[30:33]
	v_mfma_f32_16x16x32_bf16 v[22:25], v[146:149], v[178:181], v[22:25]
	v_mfma_f32_16x16x32_bf16 v[14:17], v[154:157], v[178:181], v[14:17]
	v_mfma_f32_16x16x32_bf16 v[6:9], v[146:149], v[186:189], v[6:9]
	v_mfma_f32_16x16x32_bf16 v[2:5], v[154:157], v[186:189], v[2:5]
	v_mfma_f32_16x16x32_bf16 v[54:57], v[150:153], v[166:169], v[54:57]
	v_mfma_f32_16x16x32_bf16 v[46:49], v[158:161], v[166:169], v[46:49]
	v_mfma_f32_16x16x32_bf16 v[38:41], v[150:153], v[174:177], v[38:41]
	v_mfma_f32_16x16x32_bf16 v[30:33], v[158:161], v[174:177], v[30:33]
	v_mfma_f32_16x16x32_bf16 v[22:25], v[150:153], v[182:185], v[22:25]
	v_mfma_f32_16x16x32_bf16 v[14:17], v[158:161], v[182:185], v[14:17]
	v_mfma_f32_16x16x32_bf16 v[6:9], v[150:153], v[204:207], v[6:9]
	v_mfma_f32_16x16x32_bf16 v[2:5], v[158:161], v[204:207], v[2:5]
	s_setprio 0
	s_barrier
	s_add_i32 s53, 0, 0x18000
	s_add_i32 s70, 0, 0x1c000
	v_add_u32_e32 v142, s53, v223
	v_add_u32_e32 v158, s70, v223
	ds_read_b128 v[130:133], v142
	ds_read_b128 v[134:137], v142 offset:1024
	ds_read_b128 v[138:141], v142 offset:2048
	ds_read_b128 v[142:145], v142 offset:3072
	ds_read_b128 v[146:149], v158
	ds_read_b128 v[150:153], v158 offset:1024
	ds_read_b128 v[154:157], v158 offset:2048
	ds_read_b128 v[158:161], v158 offset:3072
	s_add_u32 s66, s66, 0x40000
	s_addc_u32 s67, s67, 0
	s_mov_b32 m0, s27
	v_lshl_add_u64 v[216:217], s[66:67], 0, v[194:195]
	ds_read_b128 v[162:165], v225 offset:32768
	ds_read_b128 v[166:169], v225 offset:33792
	ds_read_b128 v[170:173], v225 offset:34816
	ds_read_b128 v[174:177], v225 offset:35840
	ds_read_b128 v[178:181], v225 offset:36864
	ds_read_b128 v[182:185], v225 offset:37888
	ds_read_b128 v[186:189], v225 offset:38912
	ds_read_b128 v[204:207], v225 offset:39936
	global_load_lds_dwordx4 v[216:217], off
	v_lshl_add_u64 v[216:217], s[66:67], 0, v[196:197]
	s_mov_b32 m0, s28
	s_nop 0
	global_load_lds_dwordx4 v[216:217], off
	s_waitcnt vmcnt(8)
	s_waitcnt lgkmcnt(0)
	s_barrier
	s_setprio 1
	s_waitcnt lgkmcnt(0)
	v_mfma_f32_16x16x32_bf16 v[126:129], v[130:133], v[162:165], v[126:129]
	v_mfma_f32_16x16x32_bf16 v[122:125], v[138:141], v[162:165], v[122:125]
	v_mfma_f32_16x16x32_bf16 v[110:113], v[130:133], v[170:173], v[110:113]
	v_mfma_f32_16x16x32_bf16 v[106:109], v[138:141], v[170:173], v[106:109]
	v_mfma_f32_16x16x32_bf16 v[98:101], v[130:133], v[178:181], v[98:101]
	v_mfma_f32_16x16x32_bf16 v[90:93], v[138:141], v[178:181], v[90:93]
	v_mfma_f32_16x16x32_bf16 v[82:85], v[130:133], v[186:189], v[82:85]
	v_mfma_f32_16x16x32_bf16 v[74:77], v[138:141], v[186:189], v[74:77]
	v_mfma_f32_16x16x32_bf16 v[126:129], v[134:137], v[166:169], v[126:129]
	v_mfma_f32_16x16x32_bf16 v[122:125], v[142:145], v[166:169], v[122:125]
	v_mfma_f32_16x16x32_bf16 v[110:113], v[134:137], v[174:177], v[110:113]
	v_mfma_f32_16x16x32_bf16 v[106:109], v[142:145], v[174:177], v[106:109]
	v_mfma_f32_16x16x32_bf16 v[98:101], v[134:137], v[182:185], v[98:101]
	v_mfma_f32_16x16x32_bf16 v[90:93], v[142:145], v[182:185], v[90:93]
	v_mfma_f32_16x16x32_bf16 v[82:85], v[134:137], v[204:207], v[82:85]
	v_mfma_f32_16x16x32_bf16 v[74:77], v[142:145], v[204:207], v[74:77]


; #define PG8_STAGE(bufoff, gbase, voff) do { _Pragma("unroll") for (int _i = 0; _i < 2; ++_i) \
;         __builtin_amdgcn_global_load_lds((const unsigned*)((const char*)(gbase) + (voff)[_i]), (PG8_LAS unsigned*)(lds + (bufoff) + ldsw + _i * 8192), 16, 0, 0); } while (0)
; #define PG8_LDA(dst, b, h) do { _Pragma("unroll") for (int m = 0; m < 4; ++m) _Pragma("unroll") for (int k = 0; k < 2; ++k) dst[m][k] = *(const PG8_LAS bf16x8*)(lds + PG8_SA(b, h) + aoff + m * 2048 + k * 1024); } while (0)
; #define PG8_MMA(ai, bj, At, Bt) do { __builtin_amdgcn_s_setprio(1); _Pragma("unroll") for (int m = 0; m < 4; ++m) _Pragma("unroll") for (int n = 0; n < 2; ++n) _Pragma("unroll") for (int k = 0; k < 2; ++k) \
;         acc[ai][bj][m][n] = __builtin_amdgcn_mfma_f32_16x16x32_bf16(Bt[n][k], At[m][k], acc[ai][bj][m][n], 0, 0, 0); __builtin_amdgcn_s_setprio(0); } while (0)
; #define PG8_WAIT_V(n) asm volatile("s_waitcnt vmcnt(" #n ")" ::: "memory")
; #define PG8_WAIT_L(n) asm volatile("s_waitcnt lgkmcnt(" #n ")" ::: "memory")
; #define PG8_BAR __builtin_amdgcn_s_barrier()
; #define PG8_SCHED __builtin_amdgcn_sched_barrier(0)
; template <class Epi, class Sched, bool ALIGN_EPI = false, bool SP2 = false>
; __device__ __forceinline__ void gemm_phase(PG8_LAS unsigned char* lds, const Gemm g, const Sched& S, const Epi& E) {
;     ...
;             PG8_WAIT_V(8); PG8_WAIT_L(0); PG8_BAR; PG8_MMA(0, 0, At, B0); PG8_MMA(0, 1, At, B1); PG8_BAR; PG8_SCHED;
;             PG8_LDA(At, 1, 1); PG8_STAGE(PG8_SB(1, 0), b3, voffB); PG8_STAGE(PG8_SB(1, 1), b3 + hstep, voffB); PG8_STAGE(PG8_SA(1, 0), a3, voffA);
;             PG8_WAIT_V(8); PG8_WAIT_L(0); PG8_BAR; PG8_MMA(1, 0, At, B0); PG8_MMA(1, 1, At, B1); PG8_BAR; PG8_SCHED;
	v_mfma_f32_16x16x32_bf16 v[118:121], v[146:149], v[162:165], v[118:121]
	v_mfma_f32_16x16x32_bf16 v[114:117], v[154:157], v[162:165], v[114:117]
	v_mfma_f32_16x16x32_bf16 v[102:105], v[146:149], v[170:173], v[102:105]
	v_mfma_f32_16x16x32_bf16 v[94:97], v[154:157], v[170:173], v[94:97]
	v_mfma_f32_16x16x32_bf16 v[86:89], v[146:149], v[178:181], v[86:89]
	v_mfma_f32_16x16x32_bf16 v[78:81], v[154:157], v[178:181], v[78:81]
	v_mfma_f32_16x16x32_bf16 v[70:73], v[146:149], v[186:189], v[70:73]
	v_mfma_f32_16x16x32_bf16 v[66:69], v[154:157], v[186:189], v[66:69]
	v_mfma_f32_16x16x32_bf16 v[118:121], v[150:153], v[166:169], v[118:121]
	v_mfma_f32_16x16x32_bf16 v[114:117], v[158:161], v[166:169], v[114:117]
	v_mfma_f32_16x16x32_bf16 v[102:105], v[150:153], v[174:177], v[102:105]
	v_mfma_f32_16x16x32_bf16 v[94:97], v[158:161], v[174:177], v[94:97]
	v_mfma_f32_16x16x32_bf16 v[86:89], v[150:153], v[182:185], v[86:89]
	v_mfma_f32_16x16x32_bf16 v[78:81], v[158:161], v[182:185], v[78:81]
	v_mfma_f32_16x16x32_bf16 v[70:73], v[150:153], v[204:207], v[70:73]
	v_mfma_f32_16x16x32_bf16 v[66:69], v[158:161], v[204:207], v[66:69]
	s_setprio 0
	s_barrier
	s_add_i32 s53, s53, s24
	v_lshl_add_u64 v[208:209], v[208:209], 0, s[8:9]
	s_mov_b32 m0, s53
	ds_read_b128 v[162:165], v225 offset:49152
	ds_read_b128 v[166:169], v225 offset:50176
	ds_read_b128 v[170:173], v225 offset:51200
	ds_read_b128 v[174:177], v225 offset:52224
	ds_read_b128 v[178:181], v225 offset:53248
	ds_read_b128 v[182:185], v225 offset:54272
	ds_read_b128 v[186:189], v225 offset:55296
	ds_read_b128 v[204:207], v225 offset:56320
	global_load_lds_dwordx4 v[208:209], off
	s_add_i32 m0, s53, 0x2000
	s_add_u32 s64, s64, 0x40080
	v_lshl_add_u64 v[208:209], v[210:211], 0, s[8:9]
	s_addc_u32 s65, s65, 0
	s_add_i32 s53, s70, s24
	global_load_lds_dwordx4 v[208:209], off
	v_lshl_add_u64 v[208:209], s[64:65], 0, v[0:1]
	s_mov_b32 m0, s53
	s_nop 0
	global_load_lds_dwordx4 v[208:209], off
	v_lshl_add_u64 v[208:209], s[64:65], 0, v[198:199]
	s_add_i32 m0, s53, 0x2000
	s_nop 0
	global_load_lds_dwordx4 v[208:209], off
	v_lshl_add_u64 v[208:209], v[212:213], 0, s[8:9]
	s_mov_b32 m0, s29
	s_nop 0
	global_load_lds_dwordx4 v[208:209], off
	v_lshl_add_u64 v[208:209], v[214:215], 0, s[8:9]
	s_mov_b32 m0, s61
	s_nop 0
	global_load_lds_dwordx4 v[208:209], off
	s_waitcnt vmcnt(8)
	s_waitcnt lgkmcnt(0)
	s_barrier
	s_setprio 1
	s_waitcnt lgkmcnt(0)
	v_mfma_f32_16x16x32_bf16 v[62:65], v[130:133], v[162:165], v[62:65]
	v_mfma_f32_16x16x32_bf16 v[58:61], v[138:141], v[162:165], v[58:61]
	v_mfma_f32_16x16x32_bf16 v[50:53], v[130:133], v[170:173], v[50:53]
	v_mfma_f32_16x16x32_bf16 v[42:45], v[138:141], v[170:173], v[42:45]
	v_mfma_f32_16x16x32_bf16 v[34:37], v[130:133], v[178:181], v[34:37]
	v_mfma_f32_16x16x32_bf16 v[26:29], v[138:141], v[178:181], v[26:29]
	v_mfma_f32_16x16x32_bf16 v[18:21], v[130:133], v[186:189], v[18:21]
	v_mfma_f32_16x16x32_bf16 v[10:13], v[138:141], v[186:189], v[10:13]
	v_mfma_f32_16x16x32_bf16 v[62:65], v[134:137], v[166:169], v[62:65]
	v_mfma_f32_16x16x32_bf16 v[58:61], v[142:145], v[166:169], v[58:61]
	v_mfma_f32_16x16x32_bf16 v[50:53], v[134:137], v[174:177], v[50:53]
	v_mfma_f32_16x16x32_bf16 v[42:45], v[142:145], v[174:177], v[42:45]
	v_mfma_f32_16x16x32_bf16 v[34:37], v[134:137], v[182:185], v[34:37]
	v_mfma_f32_16x16x32_bf16 v[26:29], v[142:145], v[182:185], v[26:29]
	v_mfma_f32_16x16x32_bf16 v[18:21], v[134:137], v[204:207], v[18:21]
	v_mfma_f32_16x16x32_bf16 v[10:13], v[142:145], v[204:207], v[10:13]


; #define PG8_STAGE(bufoff, gbase, voff) do { _Pragma("unroll") for (int _i = 0; _i < 2; ++_i) \
;         __builtin_amdgcn_global_load_lds((const unsigned*)((const char*)(gbase) + (voff)[_i]), (PG8_LAS unsigned*)(lds + (bufoff) + ldsw + _i * 8192), 16, 0, 0); } while (0)
; #define PG8_LDA(dst, b, h) do { _Pragma("unroll") for (int m = 0; m < 4; ++m) _Pragma("unroll") for (int k = 0; k < 2; ++k) dst[m][k] = *(const PG8_LAS bf16x8*)(lds + PG8_SA(b, h) + aoff + m * 2048 + k * 1024); } while (0)
; #define PG8_LDB(dst, b, h) do { _Pragma("unroll") for (int n = 0; n < 2; ++n) _Pragma("unroll") for (int k = 0; k < 2; ++k) dst[n][k] = *(const PG8_LAS bf16x8*)(lds + PG8_SB(b, h) + boff + n * 2048 + k * 1024); } while (0)
; template <class Epi, class Sched, bool ALIGN_EPI = false, bool SP2 = false>
; __device__ __forceinline__ void gemm_phase(PG8_LAS unsigned char* lds, const Gemm g, const Sched& S, const Epi& E) {
;     ...
;         for (int t = 0; t < nt; t += 2) {
;             const bool last = (t == nt - 2);
;             const char* a1 = cA + (size_t)(t + 1) * kstep;
;             const char* a2 = last ? nA : cA + (size_t)(t + 2) * kstep; const char* b2 = last ? nB : cB + (size_t)(t + 2) * kstep;
;             const char* a3 = a2 + kstep; const char* b3 = b2 + kstep;
;             if (last && has_next) S.a_ready(nxt);
;             if constexpr (SP2) {
;             PG8_LDB(B0, 0, 0); PG8_LDB(B1, 0, 1); PG8_SCHED; PG8_LDA(At, 0, 0); PG8_STAGE(PG8_SA(1, 1), a1 + hstep, voffA);
;             PG8_WAIT_V(8); PG8_WAIT_L(0); PG8_BAR; PG8_MMA(0, 0, At, B0); PG8_MMA(0, 1, At, B1); PG8_BAR; PG8_SCHED;
;             PG8_LDA(At, 0, 1); PG8_STAGE(PG8_SB(0, 0), b2, voffB); PG8_STAGE(PG8_SB(0, 1), b2 + hstep, voffB); PG8_STAGE(PG8_SA(0, 0), a2, voffA);
;             PG8_WAIT_V(8); PG8_WAIT_L(0); PG8_BAR; PG8_MMA(1, 0, At, B0); PG8_MMA(1, 1, At, B1); PG8_BAR; PG8_SCHED;
;             PG8_LDB(B0, 1, 0); PG8_LDB(B1, 1, 1); PG8_SCHED; PG8_LDA(At, 1, 0); PG8_STAGE(PG8_SA(0, 1), a2 + hstep, voffA);
;             PG8_WAIT_V(8); PG8_WAIT_L(0); PG8_BAR; PG8_MMA(0, 0, At, B0); PG8_MMA(0, 1, At, B1); PG8_BAR; PG8_SCHED;
;             PG8_LDA(At, 1, 1); PG8_STAGE(PG8_SB(1, 0), b3, voffB); PG8_STAGE(PG8_SB(1, 1), b3 + hstep, voffB); PG8_STAGE(PG8_SA(1, 0), a3, voffA);
;             PG8_WAIT_V(8); PG8_WAIT_L(0); PG8_BAR; PG8_MMA(1, 0, At, B0); PG8_MMA(1, 1, At, B1); PG8_BAR; PG8_SCHED;
	v_mfma_f32_16x16x32_bf16 v[54:57], v[146:149], v[162:165], v[54:57]
	v_mfma_f32_16x16x32_bf16 v[46:49], v[154:157], v[162:165], v[46:49]
	v_mfma_f32_16x16x32_bf16 v[38:41], v[146:149], v[170:173], v[38:41]
	v_mfma_f32_16x16x32_bf16 v[30:33], v[154:157], v[170:173], v[30:33]
	v_mfma_f32_16x16x32_bf16 v[22:25], v[146:149], v[178:181], v[22:25]
	v_mfma_f32_16x16x32_bf16 v[14:17], v[154:157], v[178:181], v[14:17]
	v_mfma_f32_16x16x32_bf16 v[6:9], v[146:149], v[186:189], v[6:9]
	v_mfma_f32_16x16x32_bf16 v[2:5], v[154:157], v[186:189], v[2:5]
	v_mfma_f32_16x16x32_bf16 v[54:57], v[150:153], v[166:169], v[54:57]
	v_mfma_f32_16x16x32_bf16 v[46:49], v[158:161], v[166:169], v[46:49]
	v_mfma_f32_16x16x32_bf16 v[38:41], v[150:153], v[174:177], v[38:41]
	v_mfma_f32_16x16x32_bf16 v[30:33], v[158:161], v[174:177], v[30:33]
	v_mfma_f32_16x16x32_bf16 v[22:25], v[150:153], v[182:185], v[22:25]
	v_mfma_f32_16x16x32_bf16 v[14:17], v[158:161], v[182:185], v[14:17]
	v_mfma_f32_16x16x32_bf16 v[6:9], v[150:153], v[204:207], v[6:9]
	v_mfma_f32_16x16x32_bf16 v[2:5], v[158:161], v[204:207], v[2:5]
	s_setprio 0
	s_barrier
	s_add_i32 s52, s52, 2
	s_add_u32 s18, s18, 0x100
	s_addc_u32 s19, s19, 0
	s_add_u32 s49, s49, 0x100
	s_addc_u32 s51, s51, 0
	s_cmp_gt_u32 s52, 13
	s_cbranch_scc0 .LBB0_453



; template <class Epi, class Sched, bool ALIGN_EPI = false, bool SP2 = false>
; __device__ __forceinline__ void gemm_phase(PG8_LAS unsigned char* lds, const Gemm g, const Sched& S, const Epi& E) {
;     ...
;         const bool has_next = S.next(ui + 1, nxt);
;         const char* nA = has_next ? (const char*)g.A + (size_t)nxt.pm * tstep : cA; const char* nB = has_next ? (const char*)g.Bt + (size_t)nxt.pn * tstep : cB;
;         for (int t = 0; t < nt; t += 2) {
;             const bool last = (t == nt - 2);
;             const char* a1 = cA + (size_t)(t + 1) * kstep;
;             const char* a2 = last ? nA : cA + (size_t)(t + 2) * kstep; const char* b2 = last ? nB : cB + (size_t)(t + 2) * kstep;
;             const char* a3 = a2 + kstep; const char* b3 = b2 + kstep;
.LBB0_486:
	s_ashr_i32 s47, s46, 31
	s_lshl_b64 s[30:31], s[46:47], 19
	s_add_u32 s50, s98, s30
	s_addc_u32 s51, s99, s31
	s_and_b64 s[30:31], s[48:49], exec
	s_cselect_b32 s30, s51, s19
	s_cselect_b32 s31, s50, s18
	s_ashr_i32 s45, s44, 31
	s_lshl_b64 s[34:35], s[44:45], 19
	s_add_u32 s54, s68, s34
	s_addc_u32 s55, s69, s35
	s_and_b64 s[34:35], s[48:49], exec
	s_cselect_b32 s34, s55, s61
	s_cselect_b32 s35, s54, s60
	s_add_u32 s18, s18, 0x40080
	s_addc_u32 s19, s19, 0
	s_add_u32 s45, s60, 0x100

; template <class Epi, class Sched, bool ALIGN_EPI = false, bool SP2 = false>
; __device__ __forceinline__ void gemm_phase(PG8_LAS unsigned char* lds, const Gemm g, const Sched& S, const Epi& E) {
;     ...
;         for (int t = 0; t < nt; t += 2) {
;             const bool last = (t == nt - 2);
;             const char* a1 = cA + (size_t)(t + 1) * kstep;
;             const char* a2 = last ? nA : cA + (size_t)(t + 2) * kstep; const char* b2 = last ? nB : cB + (size_t)(t + 2) * kstep;
	s_addc_u32 s47, s61, 0
	s_mov_b32 s52, -2


; #define PG8_STAGE(bufoff, gbase, voff) do { _Pragma("unroll") for (int _i = 0; _i < 2; ++_i) \
;         __builtin_amdgcn_global_load_lds((const unsigned*)((const char*)(gbase) + (voff)[_i]), (PG8_LAS unsigned*)(lds + (bufoff) + ldsw + _i * 8192), 16, 0, 0); } while (0)
; #define PG8_LDA(dst, b, h) do { _Pragma("unroll") for (int m = 0; m < 4; ++m) _Pragma("unroll") for (int k = 0; k < 2; ++k) dst[m][k] = *(const PG8_LAS bf16x8*)(lds + PG8_SA(b, h) + aoff + m * 2048 + k * 1024); } while (0)
; #define PG8_LDB(dst, b, h) do { _Pragma("unroll") for (int n = 0; n < 2; ++n) _Pragma("unroll") for (int k = 0; k < 2; ++k) dst[n][k] = *(const PG8_LAS bf16x8*)(lds + PG8_SB(b, h) + boff + n * 2048 + k * 1024); } while (0)
; #define PG8_SCHED __builtin_amdgcn_sched_barrier(0)
; template <class Epi, class Sched, bool ALIGN_EPI = false, bool SP2 = false>
; __device__ __forceinline__ void gemm_phase(PG8_LAS unsigned char* lds, const Gemm g, const Sched& S, const Epi& E) {
;     ...
;         for (int t = 0; t < nt; t += 2) {
;             const bool last = (t == nt - 2);
;             const char* a1 = cA + (size_t)(t + 1) * kstep;
;             const char* a2 = last ? nA : cA + (size_t)(t + 2) * kstep; const char* b2 = last ? nB : cB + (size_t)(t + 2) * kstep;
;             const char* a3 = a2 + kstep; const char* b3 = b2 + kstep;
;             if (last && has_next) S.a_ready(nxt);
;             if constexpr (SP2) {
;             PG8_LDB(B0, 0, 0); PG8_LDB(B1, 0, 1); PG8_SCHED; PG8_LDA(At, 0, 0); PG8_STAGE(PG8_SA(1, 1), a1 + hstep, voffA);
	s_waitcnt lgkmcnt(0)


; #define PG8_STAGE(bufoff, gbase, voff) do { _Pragma("unroll") for (int _i = 0; _i < 2; ++_i) \
;         __builtin_amdgcn_global_load_lds((const unsigned*)((const char*)(gbase) + (voff)[_i]), (PG8_LAS unsigned*)(lds + (bufoff) + ldsw + _i * 8192), 16, 0, 0); } while (0)
; #define PG8_LDA(dst, b, h) do { _Pragma("unroll") for (int m = 0; m < 4; ++m) _Pragma("unroll") for (int k = 0; k < 2; ++k) dst[m][k] = *(const PG8_LAS bf16x8*)(lds + PG8_SA(b, h) + aoff + m * 2048 + k * 1024); } while (0)
; #define PG8_LDB(dst, b, h) do { _Pragma("unroll") for (int n = 0; n < 2; ++n) _Pragma("unroll") for (int k = 0; k < 2; ++k) dst[n][k] = *(const PG8_LAS bf16x8*)(lds + PG8_SB(b, h) + boff + n * 2048 + k * 1024); } while (0)
; #define PG8_MMA(ai, bj, At, Bt) do { __builtin_amdgcn_s_setprio(1); _Pragma("unroll") for (int m = 0; m < 4; ++m) _Pragma("unroll") for (int n = 0; n < 2; ++n) _Pragma("unroll") for (int k = 0; k < 2; ++k) \
;         acc[ai][bj][m][n] = __builtin_amdgcn_mfma_f32_16x16x32_bf16(Bt[n][k], At[m][k], acc[ai][bj][m][n], 0, 0, 0); __builtin_amdgcn_s_setprio(0); } while (0)
; #define PG8_WAIT_V(n) asm volatile("s_waitcnt vmcnt(" #n ")" ::: "memory")
; #define PG8_WAIT_L(n) asm volatile("s_waitcnt lgkmcnt(" #n ")" ::: "memory")
; #define PG8_BAR __builtin_amdgcn_s_barrier()
; #define PG8_SCHED __builtin_amdgcn_sched_barrier(0)
; template <class Epi, class Sched, bool ALIGN_EPI = false, bool SP2 = false>
; __device__ __forceinline__ void gemm_phase(PG8_LAS unsigned char* lds, const Gemm g, const Sched& S, const Epi& E) {
;     ...
;             const bool last = (t == nt - 2);
;             const char* a1 = cA + (size_t)(t + 1) * kstep;
;             const char* a2 = last ? nA : cA + (size_t)(t + 2) * kstep; const char* b2 = last ? nB : cB + (size_t)(t + 2) * kstep;
;             const char* a3 = a2 + kstep; const char* b3 = b2 + kstep;
;             if (last && has_next) S.a_ready(nxt);
;             if constexpr (SP2) {
;             PG8_LDB(B0, 0, 0); PG8_LDB(B1, 0, 1); PG8_SCHED; PG8_LDA(At, 0, 0); PG8_STAGE(PG8_SA(1, 1), a1 + hstep, voffA);
;             PG8_WAIT_V(8); PG8_WAIT_L(0); PG8_BAR; PG8_MMA(0, 0, At, B0); PG8_MMA(0, 1, At, B1); PG8_BAR; PG8_SCHED;
	s_add_u32 s53, s18, 0xfffc0080
	s_addc_u32 s60, s19, -1
	s_add_i32 s64, 0, 0x10000
	s_cmp_eq_u32 s52, 12
	s_cselect_b32 s63, s30, s60
	s_cselect_b32 s62, s31, s53
	s_cselect_b32 s61, s34, s47
	s_cselect_b32 s60, s35, s45
	s_add_i32 s53, 0, 0x14000
	v_add_u32_e32 v134, s64, v239
	v_add_u32_e32 v158, s53, v239
	ds_read_b128 v[122:125], v134
	ds_read_b128 v[126:129], v134 offset:1024
	ds_read_b128 v[130:133], v134 offset:2048
	ds_read_b128 v[134:137], v134 offset:3072
	ds_read_b128 v[138:141], v158
	ds_read_b128 v[142:145], v158 offset:1024
	ds_read_b128 v[146:149], v158 offset:2048
	ds_read_b128 v[158:161], v158 offset:3072
	v_lshl_add_u64 v[212:213], s[18:19], 0, v[204:205]
	s_add_i32 m0, s25, 0xc000
	ds_read_b128 v[162:165], v241
	ds_read_b128 v[166:169], v241 offset:1024
	ds_read_b128 v[170:173], v241 offset:2048
	ds_read_b128 v[174:177], v241 offset:3072
	ds_read_b128 v[178:181], v241 offset:4096
	ds_read_b128 v[182:185], v241 offset:5120
	ds_read_b128 v[186:189], v241 offset:6144
	ds_read_b128 v[208:211], v241 offset:7168
	global_load_lds_dwordx4 v[212:213], off
	v_lshl_add_u64 v[212:213], s[18:19], 0, v[206:207]
	s_add_i32 m0, s25, 0xe000
	s_nop 0
	global_load_lds_dwordx4 v[212:213], off
	s_waitcnt vmcnt(8)
	s_waitcnt lgkmcnt(0)
	s_barrier
	s_setprio 1
	s_waitcnt lgkmcnt(0)
	v_mfma_f32_16x16x32_bf16 v[154:157], v[122:125], v[162:165], 0
	v_mfma_f32_16x16x32_bf16 v[150:153], v[130:133], v[162:165], 0
	v_mfma_f32_16x16x32_bf16 v[110:113], v[122:125], v[170:173], 0
	v_mfma_f32_16x16x32_bf16 v[106:109], v[130:133], v[170:173], 0
	v_mfma_f32_16x16x32_bf16 v[94:97], v[122:125], v[178:181], 0
	v_mfma_f32_16x16x32_bf16 v[90:93], v[130:133], v[178:181], 0
	v_mfma_f32_16x16x32_bf16 v[78:81], v[122:125], v[186:189], 0
	v_mfma_f32_16x16x32_bf16 v[74:77], v[130:133], v[186:189], 0
	v_mfma_f32_16x16x32_bf16 v[154:157], v[126:129], v[166:169], v[154:157]
	v_mfma_f32_16x16x32_bf16 v[150:153], v[134:137], v[166:169], v[150:153]
	v_mfma_f32_16x16x32_bf16 v[110:113], v[126:129], v[174:177], v[110:113]
	v_mfma_f32_16x16x32_bf16 v[106:109], v[134:137], v[174:177], v[106:109]
	v_mfma_f32_16x16x32_bf16 v[94:97], v[126:129], v[182:185], v[94:97]
	v_mfma_f32_16x16x32_bf16 v[90:93], v[134:137], v[182:185], v[90:93]
	v_mfma_f32_16x16x32_bf16 v[78:81], v[126:129], v[208:211], v[78:81]
	v_mfma_f32_16x16x32_bf16 v[74:77], v[134:137], v[208:211], v[74:77]


; #define PG8_STAGE(bufoff, gbase, voff) do { _Pragma("unroll") for (int _i = 0; _i < 2; ++_i) \
;         __builtin_amdgcn_global_load_lds((const unsigned*)((const char*)(gbase) + (voff)[_i]), (PG8_LAS unsigned*)(lds + (bufoff) + ldsw + _i * 8192), 16, 0, 0); } while (0)
; #define PG8_LDA(dst, b, h) do { _Pragma("unroll") for (int m = 0; m < 4; ++m) _Pragma("unroll") for (int k = 0; k < 2; ++k) dst[m][k] = *(const PG8_LAS bf16x8*)(lds + PG8_SA(b, h) + aoff + m * 2048 + k * 1024); } while (0)
; #define PG8_MMA(ai, bj, At, Bt) do { __builtin_amdgcn_s_setprio(1); _Pragma("unroll") for (int m = 0; m < 4; ++m) _Pragma("unroll") for (int n = 0; n < 2; ++n) _Pragma("unroll") for (int k = 0; k < 2; ++k) \
;         acc[ai][bj][m][n] = __builtin_amdgcn_mfma_f32_16x16x32_bf16(Bt[n][k], At[m][k], acc[ai][bj][m][n], 0, 0, 0); __builtin_amdgcn_s_setprio(0); } while (0)
; #define PG8_WAIT_V(n) asm volatile("s_waitcnt vmcnt(" #n ")" ::: "memory")
; #define PG8_WAIT_L(n) asm volatile("s_waitcnt lgkmcnt(" #n ")" ::: "memory")
; #define PG8_BAR __builtin_amdgcn_s_barrier()
; #define PG8_SCHED __builtin_amdgcn_sched_barrier(0)
; template <class Epi, class Sched, bool ALIGN_EPI = false, bool SP2 = false>
; __device__ __forceinline__ void gemm_phase(PG8_LAS unsigned char* lds, const Gemm g, const Sched& S, const Epi& E) {
;     ...
;             PG8_WAIT_V(8); PG8_WAIT_L(0); PG8_BAR; PG8_MMA(0, 0, At, B0); PG8_MMA(0, 1, At, B1); PG8_BAR; PG8_SCHED;
;             PG8_LDA(At, 0, 1); PG8_STAGE(PG8_SB(0, 0), b2, voffB); PG8_STAGE(PG8_SB(0, 1), b2 + hstep, voffB); PG8_STAGE(PG8_SA(0, 0), a2, voffA);
;             PG8_WAIT_V(8); PG8_WAIT_L(0); PG8_BAR; PG8_MMA(1, 0, At, B0); PG8_MMA(1, 1, At, B1); PG8_BAR; PG8_SCHED;
	v_mfma_f32_16x16x32_bf16 v[118:121], v[138:141], v[162:165], 0
	v_mfma_f32_16x16x32_bf16 v[114:117], v[146:149], v[162:165], 0
	v_mfma_f32_16x16x32_bf16 v[102:105], v[138:141], v[170:173], 0
	v_mfma_f32_16x16x32_bf16 v[98:101], v[146:149], v[170:173], 0
	v_mfma_f32_16x16x32_bf16 v[86:89], v[138:141], v[178:181], 0
	v_mfma_f32_16x16x32_bf16 v[82:85], v[146:149], v[178:181], 0
	v_mfma_f32_16x16x32_bf16 v[70:73], v[138:141], v[186:189], 0
	v_mfma_f32_16x16x32_bf16 v[66:69], v[146:149], v[186:189], 0
	v_mfma_f32_16x16x32_bf16 v[118:121], v[142:145], v[166:169], v[118:121]
	v_mfma_f32_16x16x32_bf16 v[114:117], v[158:161], v[166:169], v[114:117]
	v_mfma_f32_16x16x32_bf16 v[102:105], v[142:145], v[174:177], v[102:105]
	v_mfma_f32_16x16x32_bf16 v[98:101], v[158:161], v[174:177], v[98:101]
	v_mfma_f32_16x16x32_bf16 v[86:89], v[142:145], v[182:185], v[86:89]
	v_mfma_f32_16x16x32_bf16 v[82:85], v[158:161], v[182:185], v[82:85]
	v_mfma_f32_16x16x32_bf16 v[70:73], v[142:145], v[208:211], v[70:73]
	v_mfma_f32_16x16x32_bf16 v[66:69], v[158:161], v[208:211], v[66:69]
	s_setprio 0
	s_barrier
	s_add_i32 s64, s64, s24
	v_lshl_add_u64 v[212:213], s[60:61], 0, v[0:1]
	s_mov_b32 m0, s64
	ds_read_b128 v[162:165], v241 offset:16384
	ds_read_b128 v[166:169], v241 offset:17408
	ds_read_b128 v[170:173], v241 offset:18432
	ds_read_b128 v[174:177], v241 offset:19456
	ds_read_b128 v[178:181], v241 offset:20480
	ds_read_b128 v[182:185], v241 offset:21504
	ds_read_b128 v[186:189], v241 offset:22528
	ds_read_b128 v[208:211], v241 offset:23552
	global_load_lds_dwordx4 v[212:213], off
	s_add_i32 m0, s64, 0x2000
	s_add_u32 s64, s60, 0x40000
	v_lshl_add_u64 v[214:215], s[60:61], 0, v[198:199]
	s_addc_u32 s65, s61, 0
	s_add_i32 s53, s53, s24
	global_load_lds_dwordx4 v[214:215], off
	v_lshl_add_u64 v[216:217], s[64:65], 0, v[0:1]
	s_mov_b32 m0, s53
	v_lshl_add_u64 v[218:219], s[62:63], 0, v[196:197]
	global_load_lds_dwordx4 v[216:217], off
	v_lshl_add_u64 v[216:217], s[64:65], 0, v[198:199]
	s_add_i32 m0, s53, 0x2000
	s_nop 0
	global_load_lds_dwordx4 v[216:217], off
	v_lshl_add_u64 v[216:217], s[62:63], 0, v[194:195]
	s_mov_b32 m0, s25
	s_nop 0
	global_load_lds_dwordx4 v[216:217], off
	s_mov_b32 m0, s26
	s_nop 0
	global_load_lds_dwordx4 v[218:219], off
	s_waitcnt vmcnt(8)
	s_waitcnt lgkmcnt(0)
	s_barrier
	s_setprio 1
	s_waitcnt lgkmcnt(0)
	v_mfma_f32_16x16x32_bf16 v[62:65], v[122:125], v[162:165], 0
	v_mfma_f32_16x16x32_bf16 v[58:61], v[130:133], v[162:165], 0
	v_mfma_f32_16x16x32_bf16 v[46:49], v[122:125], v[170:173], 0
	v_mfma_f32_16x16x32_bf16 v[42:45], v[130:133], v[170:173], 0
	v_mfma_f32_16x16x32_bf16 v[30:33], v[122:125], v[178:181], 0
	v_mfma_f32_16x16x32_bf16 v[26:29], v[130:133], v[178:181], 0
	v_mfma_f32_16x16x32_bf16 v[14:17], v[122:125], v[186:189], 0
	v_mfma_f32_16x16x32_bf16 v[10:13], v[130:133], v[186:189], 0
	v_mfma_f32_16x16x32_bf16 v[62:65], v[126:129], v[166:169], v[62:65]
	v_mfma_f32_16x16x32_bf16 v[58:61], v[134:137], v[166:169], v[58:61]
	v_mfma_f32_16x16x32_bf16 v[46:49], v[126:129], v[174:177], v[46:49]
	v_mfma_f32_16x16x32_bf16 v[42:45], v[134:137], v[174:177], v[42:45]
	v_mfma_f32_16x16x32_bf16 v[30:33], v[126:129], v[182:185], v[30:33]
	v_mfma_f32_16x16x32_bf16 v[26:29], v[134:137], v[182:185], v[26:29]
	v_mfma_f32_16x16x32_bf16 v[14:17], v[126:129], v[208:211], v[14:17]
	v_mfma_f32_16x16x32_bf16 v[10:13], v[134:137], v[208:211], v[10:13]


; #define PG8_STAGE(bufoff, gbase, voff) do { _Pragma("unroll") for (int _i = 0; _i < 2; ++_i) \
;         __builtin_amdgcn_global_load_lds((const unsigned*)((const char*)(gbase) + (voff)[_i]), (PG8_LAS unsigned*)(lds + (bufoff) + ldsw + _i * 8192), 16, 0, 0); } while (0)
; #define PG8_LDA(dst, b, h) do { _Pragma("unroll") for (int m = 0; m < 4; ++m) _Pragma("unroll") for (int k = 0; k < 2; ++k) dst[m][k] = *(const PG8_LAS bf16x8*)(lds + PG8_SA(b, h) + aoff + m * 2048 + k * 1024); } while (0)
; #define PG8_LDB(dst, b, h) do { _Pragma("unroll") for (int n = 0; n < 2; ++n) _Pragma("unroll") for (int k = 0; k < 2; ++k) dst[n][k] = *(const PG8_LAS bf16x8*)(lds + PG8_SB(b, h) + boff + n * 2048 + k * 1024); } while (0)
; #define PG8_MMA(ai, bj, At, Bt) do { __builtin_amdgcn_s_setprio(1); _Pragma("unroll") for (int m = 0; m < 4; ++m) _Pragma("unroll") for (int n = 0; n < 2; ++n) _Pragma("unroll") for (int k = 0; k < 2; ++k) \
;         acc[ai][bj][m][n] = __builtin_amdgcn_mfma_f32_16x16x32_bf16(Bt[n][k], At[m][k], acc[ai][bj][m][n], 0, 0, 0); __builtin_amdgcn_s_setprio(0); } while (0)
; #define PG8_WAIT_V(n) asm volatile("s_waitcnt vmcnt(" #n ")" ::: "memory")
; #define PG8_WAIT_L(n) asm volatile("s_waitcnt lgkmcnt(" #n ")" ::: "memory")
; #define PG8_BAR __builtin_amdgcn_s_barrier()
; #define PG8_SCHED __builtin_amdgcn_sched_barrier(0)
; template <class Epi, class Sched, bool ALIGN_EPI = false, bool SP2 = false>
; __device__ __forceinline__ void gemm_phase(PG8_LAS unsigned char* lds, const Gemm g, const Sched& S, const Epi& E) {
;     ...
;             PG8_WAIT_V(8); PG8_WAIT_L(0); PG8_BAR; PG8_MMA(1, 0, At, B0); PG8_MMA(1, 1, At, B1); PG8_BAR; PG8_SCHED;
;             PG8_LDB(B0, 1, 0); PG8_LDB(B1, 1, 1); PG8_SCHED; PG8_LDA(At, 1, 0); PG8_STAGE(PG8_SA(0, 1), a2 + hstep, voffA);
;             PG8_WAIT_V(8); PG8_WAIT_L(0); PG8_BAR; PG8_MMA(0, 0, At, B0); PG8_MMA(0, 1, At, B1); PG8_BAR; PG8_SCHED;
	v_mfma_f32_16x16x32_bf16 v[54:57], v[138:141], v[162:165], 0
	v_mfma_f32_16x16x32_bf16 v[50:53], v[146:149], v[162:165], 0
	v_mfma_f32_16x16x32_bf16 v[38:41], v[138:141], v[170:173], 0
	v_mfma_f32_16x16x32_bf16 v[34:37], v[146:149], v[170:173], 0
	v_mfma_f32_16x16x32_bf16 v[22:25], v[138:141], v[178:181], 0
	v_mfma_f32_16x16x32_bf16 v[18:21], v[146:149], v[178:181], 0
	v_mfma_f32_16x16x32_bf16 v[6:9], v[138:141], v[186:189], 0
	v_mfma_f32_16x16x32_bf16 v[2:5], v[146:149], v[186:189], 0
	v_mfma_f32_16x16x32_bf16 v[54:57], v[142:145], v[166:169], v[54:57]
	v_mfma_f32_16x16x32_bf16 v[50:53], v[158:161], v[166:169], v[50:53]
	v_mfma_f32_16x16x32_bf16 v[38:41], v[142:145], v[174:177], v[38:41]
	v_mfma_f32_16x16x32_bf16 v[34:37], v[158:161], v[174:177], v[34:37]
	v_mfma_f32_16x16x32_bf16 v[22:25], v[142:145], v[182:185], v[22:25]
	v_mfma_f32_16x16x32_bf16 v[18:21], v[158:161], v[182:185], v[18:21]
	v_mfma_f32_16x16x32_bf16 v[6:9], v[142:145], v[208:211], v[6:9]
	v_mfma_f32_16x16x32_bf16 v[2:5], v[158:161], v[208:211], v[2:5]
	s_setprio 0
	s_barrier
	s_add_i32 s53, 0, 0x18000
	s_add_i32 s64, 0, 0x1c000
	v_add_u32_e32 v134, s53, v239
	v_add_u32_e32 v158, s64, v239
	ds_read_b128 v[122:125], v134
	ds_read_b128 v[126:129], v134 offset:1024
	ds_read_b128 v[130:133], v134 offset:2048
	ds_read_b128 v[134:137], v134 offset:3072
	ds_read_b128 v[138:141], v158
	ds_read_b128 v[142:145], v158 offset:1024
	ds_read_b128 v[146:149], v158 offset:2048
	ds_read_b128 v[158:161], v158 offset:3072
	s_add_u32 s62, s62, 0x40000
	s_addc_u32 s63, s63, 0
	s_mov_b32 m0, s27
	v_lshl_add_u64 v[220:221], s[62:63], 0, v[194:195]
	ds_read_b128 v[162:165], v241 offset:32768
	ds_read_b128 v[166:169], v241 offset:33792
	ds_read_b128 v[170:173], v241 offset:34816
	ds_read_b128 v[174:177], v241 offset:35840
	ds_read_b128 v[178:181], v241 offset:36864
	ds_read_b128 v[182:185], v241 offset:37888
	ds_read_b128 v[186:189], v241 offset:38912
	ds_read_b128 v[208:211], v241 offset:39936
	global_load_lds_dwordx4 v[220:221], off
	v_lshl_add_u64 v[220:221], s[62:63], 0, v[196:197]
	s_mov_b32 m0, s28
	s_nop 0
	global_load_lds_dwordx4 v[220:221], off
	s_waitcnt vmcnt(8)
	s_waitcnt lgkmcnt(0)
	s_barrier
	s_setprio 1
	s_waitcnt lgkmcnt(0)
	v_mfma_f32_16x16x32_bf16 v[154:157], v[122:125], v[162:165], v[154:157]
	v_mfma_f32_16x16x32_bf16 v[150:153], v[130:133], v[162:165], v[150:153]
	v_mfma_f32_16x16x32_bf16 v[110:113], v[122:125], v[170:173], v[110:113]
	v_mfma_f32_16x16x32_bf16 v[106:109], v[130:133], v[170:173], v[106:109]
	v_mfma_f32_16x16x32_bf16 v[94:97], v[122:125], v[178:181], v[94:97]
	v_mfma_f32_16x16x32_bf16 v[90:93], v[130:133], v[178:181], v[90:93]
	v_mfma_f32_16x16x32_bf16 v[78:81], v[122:125], v[186:189], v[78:81]
	v_mfma_f32_16x16x32_bf16 v[74:77], v[130:133], v[186:189], v[74:77]
	v_mfma_f32_16x16x32_bf16 v[154:157], v[126:129], v[166:169], v[154:157]
	v_mfma_f32_16x16x32_bf16 v[150:153], v[134:137], v[166:169], v[150:153]
	v_mfma_f32_16x16x32_bf16 v[110:113], v[126:129], v[174:177], v[110:113]
	v_mfma_f32_16x16x32_bf16 v[106:109], v[134:137], v[174:177], v[106:109]
	v_mfma_f32_16x16x32_bf16 v[94:97], v[126:129], v[182:185], v[94:97]
	v_mfma_f32_16x16x32_bf16 v[90:93], v[134:137], v[182:185], v[90:93]
	v_mfma_f32_16x16x32_bf16 v[78:81], v[126:129], v[208:211], v[78:81]
	v_mfma_f32_16x16x32_bf16 v[74:77], v[134:137], v[208:211], v[74:77]


; #define PG8_STAGE(bufoff, gbase, voff) do { _Pragma("unroll") for (int _i = 0; _i < 2; ++_i) \
;         __builtin_amdgcn_global_load_lds((const unsigned*)((const char*)(gbase) + (voff)[_i]), (PG8_LAS unsigned*)(lds + (bufoff) + ldsw + _i * 8192), 16, 0, 0); } while (0)
; #define PG8_LDA(dst, b, h) do { _Pragma("unroll") for (int m = 0; m < 4; ++m) _Pragma("unroll") for (int k = 0; k < 2; ++k) dst[m][k] = *(const PG8_LAS bf16x8*)(lds + PG8_SA(b, h) + aoff + m * 2048 + k * 1024); } while (0)
; #define PG8_MMA(ai, bj, At, Bt) do { __builtin_amdgcn_s_setprio(1); _Pragma("unroll") for (int m = 0; m < 4; ++m) _Pragma("unroll") for (int n = 0; n < 2; ++n) _Pragma("unroll") for (int k = 0; k < 2; ++k) \
;         acc[ai][bj][m][n] = __builtin_amdgcn_mfma_f32_16x16x32_bf16(Bt[n][k], At[m][k], acc[ai][bj][m][n], 0, 0, 0); __builtin_amdgcn_s_setprio(0); } while (0)
; #define PG8_WAIT_V(n) asm volatile("s_waitcnt vmcnt(" #n ")" ::: "memory")
; #define PG8_WAIT_L(n) asm volatile("s_waitcnt lgkmcnt(" #n ")" ::: "memory")
; #define PG8_BAR __builtin_amdgcn_s_barrier()
; #define PG8_SCHED __builtin_amdgcn_sched_barrier(0)
; template <class Epi, class Sched, bool ALIGN_EPI = false, bool SP2 = false>
; __device__ __forceinline__ void gemm_phase(PG8_LAS unsigned char* lds, const Gemm g, const Sched& S, const Epi& E) {
;     ...
;             PG8_WAIT_V(8); PG8_WAIT_L(0); PG8_BAR; PG8_MMA(0, 0, At, B0); PG8_MMA(0, 1, At, B1); PG8_BAR; PG8_SCHED;
;             PG8_LDA(At, 1, 1); PG8_STAGE(PG8_SB(1, 0), b3, voffB); PG8_STAGE(PG8_SB(1, 1), b3 + hstep, voffB); PG8_STAGE(PG8_SA(1, 0), a3, voffA);
;             PG8_WAIT_V(8); PG8_WAIT_L(0); PG8_BAR; PG8_MMA(1, 0, At, B0); PG8_MMA(1, 1, At, B1); PG8_BAR; PG8_SCHED;
	v_mfma_f32_16x16x32_bf16 v[118:121], v[138:141], v[162:165], v[118:121]
	v_mfma_f32_16x16x32_bf16 v[114:117], v[146:149], v[162:165], v[114:117]
	v_mfma_f32_16x16x32_bf16 v[102:105], v[138:141], v[170:173], v[102:105]
	v_mfma_f32_16x16x32_bf16 v[98:101], v[146:149], v[170:173], v[98:101]
	v_mfma_f32_16x16x32_bf16 v[86:89], v[138:141], v[178:181], v[86:89]
	v_mfma_f32_16x16x32_bf16 v[82:85], v[146:149], v[178:181], v[82:85]
	v_mfma_f32_16x16x32_bf16 v[70:73], v[138:141], v[186:189], v[70:73]
	v_mfma_f32_16x16x32_bf16 v[66:69], v[146:149], v[186:189], v[66:69]
	v_mfma_f32_16x16x32_bf16 v[118:121], v[142:145], v[166:169], v[118:121]
	v_mfma_f32_16x16x32_bf16 v[114:117], v[158:161], v[166:169], v[114:117]
	v_mfma_f32_16x16x32_bf16 v[102:105], v[142:145], v[174:177], v[102:105]
	v_mfma_f32_16x16x32_bf16 v[98:101], v[158:161], v[174:177], v[98:101]
	v_mfma_f32_16x16x32_bf16 v[86:89], v[142:145], v[182:185], v[86:89]
	v_mfma_f32_16x16x32_bf16 v[82:85], v[158:161], v[182:185], v[82:85]
	v_mfma_f32_16x16x32_bf16 v[70:73], v[142:145], v[208:211], v[70:73]
	v_mfma_f32_16x16x32_bf16 v[66:69], v[158:161], v[208:211], v[66:69]
	s_setprio 0
	s_barrier
	s_add_i32 s53, s53, s24
	v_lshl_add_u64 v[212:213], v[212:213], 0, s[8:9]
	s_mov_b32 m0, s53
	ds_read_b128 v[162:165], v241 offset:49152
	ds_read_b128 v[166:169], v241 offset:50176
	ds_read_b128 v[170:173], v241 offset:51200
	ds_read_b128 v[174:177], v241 offset:52224
	ds_read_b128 v[178:181], v241 offset:53248
	ds_read_b128 v[182:185], v241 offset:54272
	ds_read_b128 v[186:189], v241 offset:55296
	ds_read_b128 v[208:211], v241 offset:56320
	global_load_lds_dwordx4 v[212:213], off
	s_add_i32 m0, s53, 0x2000
	s_add_u32 s60, s60, 0x40080
	v_lshl_add_u64 v[212:213], v[214:215], 0, s[8:9]
	s_addc_u32 s61, s61, 0
	s_add_i32 s53, s64, s24
	global_load_lds_dwordx4 v[212:213], off
	v_lshl_add_u64 v[212:213], s[60:61], 0, v[0:1]
	s_mov_b32 m0, s53
	s_nop 0
	global_load_lds_dwordx4 v[212:213], off
	v_lshl_add_u64 v[212:213], s[60:61], 0, v[198:199]
	s_add_i32 m0, s53, 0x2000
	s_nop 0
	global_load_lds_dwordx4 v[212:213], off
	v_lshl_add_u64 v[212:213], v[216:217], 0, s[8:9]
	s_mov_b32 m0, s29
	s_nop 0
	global_load_lds_dwordx4 v[212:213], off
	v_lshl_add_u64 v[212:213], v[218:219], 0, s[8:9]
	s_mov_b32 m0, s57
	s_nop 0
	global_load_lds_dwordx4 v[212:213], off
	s_waitcnt vmcnt(8)
	s_waitcnt lgkmcnt(0)
	s_barrier
	s_setprio 1
	s_waitcnt lgkmcnt(0)
	v_mfma_f32_16x16x32_bf16 v[62:65], v[122:125], v[162:165], v[62:65]
	v_mfma_f32_16x16x32_bf16 v[58:61], v[130:133], v[162:165], v[58:61]
	v_mfma_f32_16x16x32_bf16 v[46:49], v[122:125], v[170:173], v[46:49]
	v_mfma_f32_16x16x32_bf16 v[42:45], v[130:133], v[170:173], v[42:45]
	v_mfma_f32_16x16x32_bf16 v[30:33], v[122:125], v[178:181], v[30:33]
	v_mfma_f32_16x16x32_bf16 v[26:29], v[130:133], v[178:181], v[26:29]
	v_mfma_f32_16x16x32_bf16 v[14:17], v[122:125], v[186:189], v[14:17]
	v_mfma_f32_16x16x32_bf16 v[10:13], v[130:133], v[186:189], v[10:13]
	v_mfma_f32_16x16x32_bf16 v[62:65], v[126:129], v[166:169], v[62:65]
	v_mfma_f32_16x16x32_bf16 v[58:61], v[134:137], v[166:169], v[58:61]
	v_mfma_f32_16x16x32_bf16 v[46:49], v[126:129], v[174:177], v[46:49]
	v_mfma_f32_16x16x32_bf16 v[42:45], v[134:137], v[174:177], v[42:45]
	v_mfma_f32_16x16x32_bf16 v[30:33], v[126:129], v[182:185], v[30:33]
	v_mfma_f32_16x16x32_bf16 v[26:29], v[134:137], v[182:185], v[26:29]
	v_mfma_f32_16x16x32_bf16 v[14:17], v[126:129], v[208:211], v[14:17]
	v_mfma_f32_16x16x32_bf16 v[10:13], v[134:137], v[208:211], v[10:13]


; #define PG8_STAGE(bufoff, gbase, voff) do { _Pragma("unroll") for (int _i = 0; _i < 2; ++_i) \
;         __builtin_amdgcn_global_load_lds((const unsigned*)((const char*)(gbase) + (voff)[_i]), (PG8_LAS unsigned*)(lds + (bufoff) + ldsw + _i * 8192), 16, 0, 0); } while (0)
; #define PG8_LDA(dst, b, h) do { _Pragma("unroll") for (int m = 0; m < 4; ++m) _Pragma("unroll") for (int k = 0; k < 2; ++k) dst[m][k] = *(const PG8_LAS bf16x8*)(lds + PG8_SA(b, h) + aoff + m * 2048 + k * 1024); } while (0)
; #define PG8_LDB(dst, b, h) do { _Pragma("unroll") for (int n = 0; n < 2; ++n) _Pragma("unroll") for (int k = 0; k < 2; ++k) dst[n][k] = *(const PG8_LAS bf16x8*)(lds + PG8_SB(b, h) + boff + n * 2048 + k * 1024); } while (0)
; #define PG8_MMA(ai, bj, At, Bt) do { __builtin_amdgcn_s_setprio(1); _Pragma("unroll") for (int m = 0; m < 4; ++m) _Pragma("unroll") for (int n = 0; n < 2; ++n) _Pragma("unroll") for (int k = 0; k < 2; ++k) \
;         acc[ai][bj][m][n] = __builtin_amdgcn_mfma_f32_16x16x32_bf16(Bt[n][k], At[m][k], acc[ai][bj][m][n], 0, 0, 0); __builtin_amdgcn_s_setprio(0); } while (0)
; #define PG8_WAIT_V(n) asm volatile("s_waitcnt vmcnt(" #n ")" ::: "memory")
; #define PG8_WAIT_L(n) asm volatile("s_waitcnt lgkmcnt(" #n ")" ::: "memory")
; #define PG8_BAR __builtin_amdgcn_s_barrier()
; #define PG8_SCHED __builtin_amdgcn_sched_barrier(0)
; template <class Epi, class Sched, bool ALIGN_EPI = false, bool SP2 = false>
; __device__ __forceinline__ void gemm_phase(PG8_LAS unsigned char* lds, const Gemm g, const Sched& S, const Epi& E) {
;     ...
;             const bool last = (t == nt - 2);
;             const char* a1 = cA + (size_t)(t + 1) * kstep;
;             const char* a2 = last ? nA : cA + (size_t)(t + 2) * kstep; const char* b2 = last ? nB : cB + (size_t)(t + 2) * kstep;
;             const char* a3 = a2 + kstep; const char* b3 = b2 + kstep;
;             if (last && has_next) S.a_ready(nxt);
;             if constexpr (SP2) {
;             PG8_LDB(B0, 0, 0); PG8_LDB(B1, 0, 1); PG8_SCHED; PG8_LDA(At, 0, 0); PG8_STAGE(PG8_SA(1, 1), a1 + hstep, voffA);
;             PG8_WAIT_V(8); PG8_WAIT_L(0); PG8_BAR; PG8_MMA(0, 0, At, B0); PG8_MMA(0, 1, At, B1); PG8_BAR; PG8_SCHED;
	v_mfma_f32_16x16x32_bf16 v[54:57], v[138:141], v[162:165], v[54:57]
	v_mfma_f32_16x16x32_bf16 v[50:53], v[146:149], v[162:165], v[50:53]
	v_mfma_f32_16x16x32_bf16 v[38:41], v[138:141], v[170:173], v[38:41]
	v_mfma_f32_16x16x32_bf16 v[34:37], v[146:149], v[170:173], v[34:37]
	v_mfma_f32_16x16x32_bf16 v[22:25], v[138:141], v[178:181], v[22:25]
	v_mfma_f32_16x16x32_bf16 v[18:21], v[146:149], v[178:181], v[18:21]
	v_mfma_f32_16x16x32_bf16 v[6:9], v[138:141], v[186:189], v[6:9]
	v_mfma_f32_16x16x32_bf16 v[2:5], v[146:149], v[186:189], v[2:5]
	v_mfma_f32_16x16x32_bf16 v[54:57], v[142:145], v[166:169], v[54:57]
	v_mfma_f32_16x16x32_bf16 v[50:53], v[158:161], v[166:169], v[50:53]
	v_mfma_f32_16x16x32_bf16 v[38:41], v[142:145], v[174:177], v[38:41]
	v_mfma_f32_16x16x32_bf16 v[34:37], v[158:161], v[174:177], v[34:37]
	v_mfma_f32_16x16x32_bf16 v[22:25], v[142:145], v[182:185], v[22:25]
	v_mfma_f32_16x16x32_bf16 v[18:21], v[158:161], v[182:185], v[18:21]
	v_mfma_f32_16x16x32_bf16 v[6:9], v[142:145], v[208:211], v[6:9]
	v_mfma_f32_16x16x32_bf16 v[2:5], v[158:161], v[208:211], v[2:5]
	s_setprio 0
	s_barrier
	s_add_i32 s52, s52, 2
	s_add_u32 s18, s18, 0x100
	s_addc_u32 s19, s19, 0
	s_add_u32 s45, s45, 0x100
	s_addc_u32 s47, s47, 0
	s_cmp_gt_u32 s52, 13
.LBB0_487:
	s_add_u32 s53, s18, 0xfffc0080
	s_addc_u32 s60, s19, -1
	s_add_i32 s64, 0, 0x10000
	s_cmp_eq_u32 s52, 12
	s_cselect_b32 s63, s30, s60
	s_cselect_b32 s62, s31, s53
	s_cselect_b32 s61, s34, s47
	s_cselect_b32 s60, s35, s45
	s_add_i32 s53, 0, 0x14000
	v_add_u32_e32 v134, s64, v239
	v_add_u32_e32 v158, s53, v239
	ds_read_b128 v[122:125], v134
	ds_read_b128 v[126:129], v134 offset:1024
	ds_read_b128 v[130:133], v134 offset:2048
	ds_read_b128 v[134:137], v134 offset:3072
	ds_read_b128 v[138:141], v158
	ds_read_b128 v[142:145], v158 offset:1024
	ds_read_b128 v[146:149], v158 offset:2048
	ds_read_b128 v[158:161], v158 offset:3072
	v_lshl_add_u64 v[212:213], s[18:19], 0, v[204:205]
	s_add_i32 m0, s25, 0xc000
	ds_read_b128 v[162:165], v241
	ds_read_b128 v[166:169], v241 offset:1024
	ds_read_b128 v[170:173], v241 offset:2048
	ds_read_b128 v[174:177], v241 offset:3072
	ds_read_b128 v[178:181], v241 offset:4096
	ds_read_b128 v[182:185], v241 offset:5120
	ds_read_b128 v[186:189], v241 offset:6144
	ds_read_b128 v[208:211], v241 offset:7168
	global_load_lds_dwordx4 v[212:213], off
	v_lshl_add_u64 v[212:213], s[18:19], 0, v[206:207]
	s_add_i32 m0, s25, 0xe000
	s_nop 0
	global_load_lds_dwordx4 v[212:213], off
	s_waitcnt vmcnt(8)
	s_waitcnt lgkmcnt(0)
	s_barrier
	s_setprio 1
	s_waitcnt lgkmcnt(0)
	v_mfma_f32_16x16x32_bf16 v[154:157], v[122:125], v[162:165], v[154:157]
	v_mfma_f32_16x16x32_bf16 v[150:153], v[130:133], v[162:165], v[150:153]
	v_mfma_f32_16x16x32_bf16 v[110:113], v[122:125], v[170:173], v[110:113]
	v_mfma_f32_16x16x32_bf16 v[106:109], v[130:133], v[170:173], v[106:109]
	v_mfma_f32_16x16x32_bf16 v[94:97], v[122:125], v[178:181], v[94:97]
	v_mfma_f32_16x16x32_bf16 v[90:93], v[130:133], v[178:181], v[90:93]
	v_mfma_f32_16x16x32_bf16 v[78:81], v[122:125], v[186:189], v[78:81]
	v_mfma_f32_16x16x32_bf16 v[74:77], v[130:133], v[186:189], v[74:77]
	v_mfma_f32_16x16x32_bf16 v[154:157], v[126:129], v[166:169], v[154:157]
	v_mfma_f32_16x16x32_bf16 v[150:153], v[134:137], v[166:169], v[150:153]
	v_mfma_f32_16x16x32_bf16 v[110:113], v[126:129], v[174:177], v[110:113]
	v_mfma_f32_16x16x32_bf16 v[106:109], v[134:137], v[174:177], v[106:109]
	v_mfma_f32_16x16x32_bf16 v[94:97], v[126:129], v[182:185], v[94:97]
	v_mfma_f32_16x16x32_bf16 v[90:93], v[134:137], v[182:185], v[90:93]
	v_mfma_f32_16x16x32_bf16 v[78:81], v[126:129], v[208:211], v[78:81]
	v_mfma_f32_16x16x32_bf16 v[74:77], v[134:137], v[208:211], v[74:77]


; #define PG8_STAGE(bufoff, gbase, voff) do { _Pragma("unroll") for (int _i = 0; _i < 2; ++_i) \
;         __builtin_amdgcn_global_load_lds((const unsigned*)((const char*)(gbase) + (voff)[_i]), (PG8_LAS unsigned*)(lds + (bufoff) + ldsw + _i * 8192), 16, 0, 0); } while (0)
; #define PG8_LDA(dst, b, h) do { _Pragma("unroll") for (int m = 0; m < 4; ++m) _Pragma("unroll") for (int k = 0; k < 2; ++k) dst[m][k] = *(const PG8_LAS bf16x8*)(lds + PG8_SA(b, h) + aoff + m * 2048 + k * 1024); } while (0)
; #define PG8_MMA(ai, bj, At, Bt) do { __builtin_amdgcn_s_setprio(1); _Pragma("unroll") for (int m = 0; m < 4; ++m) _Pragma("unroll") for (int n = 0; n < 2; ++n) _Pragma("unroll") for (int k = 0; k < 2; ++k) \
;         acc[ai][bj][m][n] = __builtin_amdgcn_mfma_f32_16x16x32_bf16(Bt[n][k], At[m][k], acc[ai][bj][m][n], 0, 0, 0); __builtin_amdgcn_s_setprio(0); } while (0)
; #define PG8_WAIT_V(n) asm volatile("s_waitcnt vmcnt(" #n ")" ::: "memory")
; #define PG8_WAIT_L(n) asm volatile("s_waitcnt lgkmcnt(" #n ")" ::: "memory")
; #define PG8_BAR __builtin_amdgcn_s_barrier()
; #define PG8_SCHED __builtin_amdgcn_sched_barrier(0)
; template <class Epi, class Sched, bool ALIGN_EPI = false, bool SP2 = false>
; __device__ __forceinline__ void gemm_phase(PG8_LAS unsigned char* lds, const Gemm g, const Sched& S, const Epi& E) {
;     ...
;             PG8_WAIT_V(8); PG8_WAIT_L(0); PG8_BAR; PG8_MMA(0, 0, At, B0); PG8_MMA(0, 1, At, B1); PG8_BAR; PG8_SCHED;
;             PG8_LDA(At, 0, 1); PG8_STAGE(PG8_SB(0, 0), b2, voffB); PG8_STAGE(PG8_SB(0, 1), b2 + hstep, voffB); PG8_STAGE(PG8_SA(0, 0), a2, voffA);
;             PG8_WAIT_V(8); PG8_WAIT_L(0); PG8_BAR; PG8_MMA(1, 0, At, B0); PG8_MMA(1, 1, At, B1); PG8_BAR; PG8_SCHED;
	v_mfma_f32_16x16x32_bf16 v[118:121], v[138:141], v[162:165], v[118:121]
	v_mfma_f32_16x16x32_bf16 v[114:117], v[146:149], v[162:165], v[114:117]
	v_mfma_f32_16x16x32_bf16 v[102:105], v[138:141], v[170:173], v[102:105]
	v_mfma_f32_16x16x32_bf16 v[98:101], v[146:149], v[170:173], v[98:101]
	v_mfma_f32_16x16x32_bf16 v[86:89], v[138:141], v[178:181], v[86:89]
	v_mfma_f32_16x16x32_bf16 v[82:85], v[146:149], v[178:181], v[82:85]
	v_mfma_f32_16x16x32_bf16 v[70:73], v[138:141], v[186:189], v[70:73]
	v_mfma_f32_16x16x32_bf16 v[66:69], v[146:149], v[186:189], v[66:69]
	v_mfma_f32_16x16x32_bf16 v[118:121], v[142:145], v[166:169], v[118:121]
	v_mfma_f32_16x16x32_bf16 v[114:117], v[158:161], v[166:169], v[114:117]
	v_mfma_f32_16x16x32_bf16 v[102:105], v[142:145], v[174:177], v[102:105]
	v_mfma_f32_16x16x32_bf16 v[98:101], v[158:161], v[174:177], v[98:101]
	v_mfma_f32_16x16x32_bf16 v[86:89], v[142:145], v[182:185], v[86:89]
	v_mfma_f32_16x16x32_bf16 v[82:85], v[158:161], v[182:185], v[82:85]
	v_mfma_f32_16x16x32_bf16 v[70:73], v[142:145], v[208:211], v[70:73]
	v_mfma_f32_16x16x32_bf16 v[66:69], v[158:161], v[208:211], v[66:69]
	s_setprio 0
	s_barrier
	s_add_i32 s64, s64, s24
	v_lshl_add_u64 v[212:213], s[60:61], 0, v[0:1]
	s_mov_b32 m0, s64
	ds_read_b128 v[162:165], v241 offset:16384
	ds_read_b128 v[166:169], v241 offset:17408
	ds_read_b128 v[170:173], v241 offset:18432
	ds_read_b128 v[174:177], v241 offset:19456
	ds_read_b128 v[178:181], v241 offset:20480
	ds_read_b128 v[182:185], v241 offset:21504
	ds_read_b128 v[186:189], v241 offset:22528
	ds_read_b128 v[208:211], v241 offset:23552
	global_load_lds_dwordx4 v[212:213], off
	s_add_i32 m0, s64, 0x2000
	s_add_u32 s64, s60, 0x40000
	v_lshl_add_u64 v[214:215], s[60:61], 0, v[198:199]
	s_addc_u32 s65, s61, 0
	s_add_i32 s53, s53, s24
	global_load_lds_dwordx4 v[214:215], off
	v_lshl_add_u64 v[216:217], s[64:65], 0, v[0:1]
	s_mov_b32 m0, s53
	v_lshl_add_u64 v[218:219], s[62:63], 0, v[196:197]
	global_load_lds_dwordx4 v[216:217], off
	v_lshl_add_u64 v[216:217], s[64:65], 0, v[198:199]
	s_add_i32 m0, s53, 0x2000
	s_nop 0
	global_load_lds_dwordx4 v[216:217], off
	v_lshl_add_u64 v[216:217], s[62:63], 0, v[194:195]
	s_mov_b32 m0, s25
	s_nop 0
	global_load_lds_dwordx4 v[216:217], off
	s_mov_b32 m0, s26
	s_nop 0
	global_load_lds_dwordx4 v[218:219], off
	s_waitcnt vmcnt(8)
	s_waitcnt lgkmcnt(0)
	s_barrier
	s_setprio 1
	s_waitcnt lgkmcnt(0)
	v_mfma_f32_16x16x32_bf16 v[62:65], v[122:125], v[162:165], v[62:65]
	v_mfma_f32_16x16x32_bf16 v[58:61], v[130:133], v[162:165], v[58:61]
	v_mfma_f32_16x16x32_bf16 v[46:49], v[122:125], v[170:173], v[46:49]
	v_mfma_f32_16x16x32_bf16 v[42:45], v[130:133], v[170:173], v[42:45]
	v_mfma_f32_16x16x32_bf16 v[30:33], v[122:125], v[178:181], v[30:33]
	v_mfma_f32_16x16x32_bf16 v[26:29], v[130:133], v[178:181], v[26:29]
	v_mfma_f32_16x16x32_bf16 v[14:17], v[122:125], v[186:189], v[14:17]
	v_mfma_f32_16x16x32_bf16 v[10:13], v[130:133], v[186:189], v[10:13]
	v_mfma_f32_16x16x32_bf16 v[62:65], v[126:129], v[166:169], v[62:65]
	v_mfma_f32_16x16x32_bf16 v[58:61], v[134:137], v[166:169], v[58:61]
	v_mfma_f32_16x16x32_bf16 v[46:49], v[126:129], v[174:177], v[46:49]
	v_mfma_f32_16x16x32_bf16 v[42:45], v[134:137], v[174:177], v[42:45]
	v_mfma_f32_16x16x32_bf16 v[30:33], v[126:129], v[182:185], v[30:33]
	v_mfma_f32_16x16x32_bf16 v[26:29], v[134:137], v[182:185], v[26:29]
	v_mfma_f32_16x16x32_bf16 v[14:17], v[126:129], v[208:211], v[14:17]
	v_mfma_f32_16x16x32_bf16 v[10:13], v[134:137], v[208:211], v[10:13]


; #define PG8_STAGE(bufoff, gbase, voff) do { _Pragma("unroll") for (int _i = 0; _i < 2; ++_i) \
;         __builtin_amdgcn_global_load_lds((const unsigned*)((const char*)(gbase) + (voff)[_i]), (PG8_LAS unsigned*)(lds + (bufoff) + ldsw + _i * 8192), 16, 0, 0); } while (0)
; #define PG8_LDA(dst, b, h) do { _Pragma("unroll") for (int m = 0; m < 4; ++m) _Pragma("unroll") for (int k = 0; k < 2; ++k) dst[m][k] = *(const PG8_LAS bf16x8*)(lds + PG8_SA(b, h) + aoff + m * 2048 + k * 1024); } while (0)
; #define PG8_LDB(dst, b, h) do { _Pragma("unroll") for (int n = 0; n < 2; ++n) _Pragma("unroll") for (int k = 0; k < 2; ++k) dst[n][k] = *(const PG8_LAS bf16x8*)(lds + PG8_SB(b, h) + boff + n * 2048 + k * 1024); } while (0)
; #define PG8_MMA(ai, bj, At, Bt) do { __builtin_amdgcn_s_setprio(1); _Pragma("unroll") for (int m = 0; m < 4; ++m) _Pragma("unroll") for (int n = 0; n < 2; ++n) _Pragma("unroll") for (int k = 0; k < 2; ++k) \
;         acc[ai][bj][m][n] = __builtin_amdgcn_mfma_f32_16x16x32_bf16(Bt[n][k], At[m][k], acc[ai][bj][m][n], 0, 0, 0); __builtin_amdgcn_s_setprio(0); } while (0)
; #define PG8_WAIT_V(n) asm volatile("s_waitcnt vmcnt(" #n ")" ::: "memory")
; #define PG8_WAIT_L(n) asm volatile("s_waitcnt lgkmcnt(" #n ")" ::: "memory")
; #define PG8_BAR __builtin_amdgcn_s_barrier()
; #define PG8_SCHED __builtin_amdgcn_sched_barrier(0)
; template <class Epi, class Sched, bool ALIGN_EPI = false, bool SP2 = false>
; __device__ __forceinline__ void gemm_phase(PG8_LAS unsigned char* lds, const Gemm g, const Sched& S, const Epi& E) {
;     ...
;             PG8_WAIT_V(8); PG8_WAIT_L(0); PG8_BAR; PG8_MMA(1, 0, At, B0); PG8_MMA(1, 1, At, B1); PG8_BAR; PG8_SCHED;
;             PG8_LDB(B0, 1, 0); PG8_LDB(B1, 1, 1); PG8_SCHED; PG8_LDA(At, 1, 0); PG8_STAGE(PG8_SA(0, 1), a2 + hstep, voffA);
;             PG8_WAIT_V(8); PG8_WAIT_L(0); PG8_BAR; PG8_MMA(0, 0, At, B0); PG8_MMA(0, 1, At, B1); PG8_BAR; PG8_SCHED;
	v_mfma_f32_16x16x32_bf16 v[54:57], v[138:141], v[162:165], v[54:57]
	v_mfma_f32_16x16x32_bf16 v[50:53], v[146:149], v[162:165], v[50:53]
	v_mfma_f32_16x16x32_bf16 v[38:41], v[138:141], v[170:173], v[38:41]
	v_mfma_f32_16x16x32_bf16 v[34:37], v[146:149], v[170:173], v[34:37]
	v_mfma_f32_16x16x32_bf16 v[22:25], v[138:141], v[178:181], v[22:25]
	v_mfma_f32_16x16x32_bf16 v[18:21], v[146:149], v[178:181], v[18:21]
	v_mfma_f32_16x16x32_bf16 v[6:9], v[138:141], v[186:189], v[6:9]
	v_mfma_f32_16x16x32_bf16 v[2:5], v[146:149], v[186:189], v[2:5]
	v_mfma_f32_16x16x32_bf16 v[54:57], v[142:145], v[166:169], v[54:57]
	v_mfma_f32_16x16x32_bf16 v[50:53], v[158:161], v[166:169], v[50:53]
	v_mfma_f32_16x16x32_bf16 v[38:41], v[142:145], v[174:177], v[38:41]
	v_mfma_f32_16x16x32_bf16 v[34:37], v[158:161], v[174:177], v[34:37]
	v_mfma_f32_16x16x32_bf16 v[22:25], v[142:145], v[182:185], v[22:25]
	v_mfma_f32_16x16x32_bf16 v[18:21], v[158:161], v[182:185], v[18:21]
	v_mfma_f32_16x16x32_bf16 v[6:9], v[142:145], v[208:211], v[6:9]
	v_mfma_f32_16x16x32_bf16 v[2:5], v[158:161], v[208:211], v[2:5]
	s_setprio 0
	s_barrier
	s_add_i32 s53, 0, 0x18000
	s_add_i32 s64, 0, 0x1c000
	v_add_u32_e32 v134, s53, v239
	v_add_u32_e32 v158, s64, v239
	ds_read_b128 v[122:125], v134
	ds_read_b128 v[126:129], v134 offset:1024
	ds_read_b128 v[130:133], v134 offset:2048
	ds_read_b128 v[134:137], v134 offset:3072
	ds_read_b128 v[138:141], v158
	ds_read_b128 v[142:145], v158 offset:1024
	ds_read_b128 v[146:149], v158 offset:2048
	ds_read_b128 v[158:161], v158 offset:3072
	s_add_u32 s62, s62, 0x40000
	s_addc_u32 s63, s63, 0
	s_mov_b32 m0, s27
	v_lshl_add_u64 v[220:221], s[62:63], 0, v[194:195]
	ds_read_b128 v[162:165], v241 offset:32768
	ds_read_b128 v[166:169], v241 offset:33792
	ds_read_b128 v[170:173], v241 offset:34816
	ds_read_b128 v[174:177], v241 offset:35840
	ds_read_b128 v[178:181], v241 offset:36864
	ds_read_b128 v[182:185], v241 offset:37888
	ds_read_b128 v[186:189], v241 offset:38912
	ds_read_b128 v[208:211], v241 offset:39936
	global_load_lds_dwordx4 v[220:221], off
	v_lshl_add_u64 v[220:221], s[62:63], 0, v[196:197]
	s_mov_b32 m0, s28
	s_nop 0
	global_load_lds_dwordx4 v[220:221], off
	s_waitcnt vmcnt(8)
	s_waitcnt lgkmcnt(0)
	s_barrier
	s_setprio 1
	s_waitcnt lgkmcnt(0)
	v_mfma_f32_16x16x32_bf16 v[154:157], v[122:125], v[162:165], v[154:157]
	v_mfma_f32_16x16x32_bf16 v[150:153], v[130:133], v[162:165], v[150:153]
	v_mfma_f32_16x16x32_bf16 v[110:113], v[122:125], v[170:173], v[110:113]
	v_mfma_f32_16x16x32_bf16 v[106:109], v[130:133], v[170:173], v[106:109]
	v_mfma_f32_16x16x32_bf16 v[94:97], v[122:125], v[178:181], v[94:97]
	v_mfma_f32_16x16x32_bf16 v[90:93], v[130:133], v[178:181], v[90:93]
	v_mfma_f32_16x16x32_bf16 v[78:81], v[122:125], v[186:189], v[78:81]
	v_mfma_f32_16x16x32_bf16 v[74:77], v[130:133], v[186:189], v[74:77]
	v_mfma_f32_16x16x32_bf16 v[154:157], v[126:129], v[166:169], v[154:157]
	v_mfma_f32_16x16x32_bf16 v[150:153], v[134:137], v[166:169], v[150:153]
	v_mfma_f32_16x16x32_bf16 v[110:113], v[126:129], v[174:177], v[110:113]
	v_mfma_f32_16x16x32_bf16 v[106:109], v[134:137], v[174:177], v[106:109]
	v_mfma_f32_16x16x32_bf16 v[94:97], v[126:129], v[182:185], v[94:97]
	v_mfma_f32_16x16x32_bf16 v[90:93], v[134:137], v[182:185], v[90:93]
	v_mfma_f32_16x16x32_bf16 v[78:81], v[126:129], v[208:211], v[78:81]
	v_mfma_f32_16x16x32_bf16 v[74:77], v[134:137], v[208:211], v[74:77]


; #define PG8_STAGE(bufoff, gbase, voff) do { _Pragma("unroll") for (int _i = 0; _i < 2; ++_i) \
;         __builtin_amdgcn_global_load_lds((const unsigned*)((const char*)(gbase) + (voff)[_i]), (PG8_LAS unsigned*)(lds + (bufoff) + ldsw + _i * 8192), 16, 0, 0); } while (0)
; #define PG8_LDA(dst, b, h) do { _Pragma("unroll") for (int m = 0; m < 4; ++m) _Pragma("unroll") for (int k = 0; k < 2; ++k) dst[m][k] = *(const PG8_LAS bf16x8*)(lds + PG8_SA(b, h) + aoff + m * 2048 + k * 1024); } while (0)
; #define PG8_MMA(ai, bj, At, Bt) do { __builtin_amdgcn_s_setprio(1); _Pragma("unroll") for (int m = 0; m < 4; ++m) _Pragma("unroll") for (int n = 0; n < 2; ++n) _Pragma("unroll") for (int k = 0; k < 2; ++k) \
;         acc[ai][bj][m][n] = __builtin_amdgcn_mfma_f32_16x16x32_bf16(Bt[n][k], At[m][k], acc[ai][bj][m][n], 0, 0, 0); __builtin_amdgcn_s_setprio(0); } while (0)
; #define PG8_WAIT_V(n) asm volatile("s_waitcnt vmcnt(" #n ")" ::: "memory")
; #define PG8_WAIT_L(n) asm volatile("s_waitcnt lgkmcnt(" #n ")" ::: "memory")
; #define PG8_BAR __builtin_amdgcn_s_barrier()
; #define PG8_SCHED __builtin_amdgcn_sched_barrier(0)
; template <class Epi, class Sched, bool ALIGN_EPI = false, bool SP2 = false>
; __device__ __forceinline__ void gemm_phase(PG8_LAS unsigned char* lds, const Gemm g, const Sched& S, const Epi& E) {
;     ...
;             PG8_WAIT_V(8); PG8_WAIT_L(0); PG8_BAR; PG8_MMA(0, 0, At, B0); PG8_MMA(0, 1, At, B1); PG8_BAR; PG8_SCHED;
;             PG8_LDA(At, 1, 1); PG8_STAGE(PG8_SB(1, 0), b3, voffB); PG8_STAGE(PG8_SB(1, 1), b3 + hstep, voffB); PG8_STAGE(PG8_SA(1, 0), a3, voffA);
;             PG8_WAIT_V(8); PG8_WAIT_L(0); PG8_BAR; PG8_MMA(1, 0, At, B0); PG8_MMA(1, 1, At, B1); PG8_BAR; PG8_SCHED;
	v_mfma_f32_16x16x32_bf16 v[118:121], v[138:141], v[162:165], v[118:121]
	v_mfma_f32_16x16x32_bf16 v[114:117], v[146:149], v[162:165], v[114:117]
	v_mfma_f32_16x16x32_bf16 v[102:105], v[138:141], v[170:173], v[102:105]
	v_mfma_f32_16x16x32_bf16 v[98:101], v[146:149], v[170:173], v[98:101]
	v_mfma_f32_16x16x32_bf16 v[86:89], v[138:141], v[178:181], v[86:89]
	v_mfma_f32_16x16x32_bf16 v[82:85], v[146:149], v[178:181], v[82:85]
	v_mfma_f32_16x16x32_bf16 v[70:73], v[138:141], v[186:189], v[70:73]
	v_mfma_f32_16x16x32_bf16 v[66:69], v[146:149], v[186:189], v[66:69]
	v_mfma_f32_16x16x32_bf16 v[118:121], v[142:145], v[166:169], v[118:121]
	v_mfma_f32_16x16x32_bf16 v[114:117], v[158:161], v[166:169], v[114:117]
	v_mfma_f32_16x16x32_bf16 v[102:105], v[142:145], v[174:177], v[102:105]
	v_mfma_f32_16x16x32_bf16 v[98:101], v[158:161], v[174:177], v[98:101]
	v_mfma_f32_16x16x32_bf16 v[86:89], v[142:145], v[182:185], v[86:89]
	v_mfma_f32_16x16x32_bf16 v[82:85], v[158:161], v[182:185], v[82:85]
	v_mfma_f32_16x16x32_bf16 v[70:73], v[142:145], v[208:211], v[70:73]
	v_mfma_f32_16x16x32_bf16 v[66:69], v[158:161], v[208:211], v[66:69]
	s_setprio 0
	s_barrier
	s_add_i32 s53, s53, s24
	v_lshl_add_u64 v[212:213], v[212:213], 0, s[8:9]
	s_mov_b32 m0, s53
	ds_read_b128 v[162:165], v241 offset:49152
	ds_read_b128 v[166:169], v241 offset:50176
	ds_read_b128 v[170:173], v241 offset:51200
	ds_read_b128 v[174:177], v241 offset:52224
	ds_read_b128 v[178:181], v241 offset:53248
	ds_read_b128 v[182:185], v241 offset:54272
	ds_read_b128 v[186:189], v241 offset:55296
	ds_read_b128 v[208:211], v241 offset:56320
	global_load_lds_dwordx4 v[212:213], off
	s_add_i32 m0, s53, 0x2000
	s_add_u32 s60, s60, 0x40080
	v_lshl_add_u64 v[212:213], v[214:215], 0, s[8:9]
	s_addc_u32 s61, s61, 0
	s_add_i32 s53, s64, s24
	global_load_lds_dwordx4 v[212:213], off
	v_lshl_add_u64 v[212:213], s[60:61], 0, v[0:1]
	s_mov_b32 m0, s53
	s_nop 0
	global_load_lds_dwordx4 v[212:213], off
	v_lshl_add_u64 v[212:213], s[60:61], 0, v[198:199]
	s_add_i32 m0, s53, 0x2000
	s_nop 0
	global_load_lds_dwordx4 v[212:213], off
	v_lshl_add_u64 v[212:213], v[216:217], 0, s[8:9]
	s_mov_b32 m0, s29
	s_nop 0
	global_load_lds_dwordx4 v[212:213], off
	v_lshl_add_u64 v[212:213], v[218:219], 0, s[8:9]
	s_mov_b32 m0, s57
	s_nop 0
	global_load_lds_dwordx4 v[212:213], off
	s_waitcnt vmcnt(8)
	s_waitcnt lgkmcnt(0)
	s_barrier
	s_setprio 1
	s_waitcnt lgkmcnt(0)
	v_mfma_f32_16x16x32_bf16 v[62:65], v[122:125], v[162:165], v[62:65]
	v_mfma_f32_16x16x32_bf16 v[58:61], v[130:133], v[162:165], v[58:61]
	v_mfma_f32_16x16x32_bf16 v[46:49], v[122:125], v[170:173], v[46:49]
	v_mfma_f32_16x16x32_bf16 v[42:45], v[130:133], v[170:173], v[42:45]
	v_mfma_f32_16x16x32_bf16 v[30:33], v[122:125], v[178:181], v[30:33]
	v_mfma_f32_16x16x32_bf16 v[26:29], v[130:133], v[178:181], v[26:29]
	v_mfma_f32_16x16x32_bf16 v[14:17], v[122:125], v[186:189], v[14:17]
	v_mfma_f32_16x16x32_bf16 v[10:13], v[130:133], v[186:189], v[10:13]
	v_mfma_f32_16x16x32_bf16 v[62:65], v[126:129], v[166:169], v[62:65]
	v_mfma_f32_16x16x32_bf16 v[58:61], v[134:137], v[166:169], v[58:61]
	v_mfma_f32_16x16x32_bf16 v[46:49], v[126:129], v[174:177], v[46:49]
	v_mfma_f32_16x16x32_bf16 v[42:45], v[134:137], v[174:177], v[42:45]
	v_mfma_f32_16x16x32_bf16 v[30:33], v[126:129], v[182:185], v[30:33]
	v_mfma_f32_16x16x32_bf16 v[26:29], v[134:137], v[182:185], v[26:29]
	v_mfma_f32_16x16x32_bf16 v[14:17], v[126:129], v[208:211], v[14:17]
	v_mfma_f32_16x16x32_bf16 v[10:13], v[134:137], v[208:211], v[10:13]


; template <class Epi, class Sched, bool ALIGN_EPI = false, bool SP2 = false>
; __device__ __forceinline__ void gemm_phase(PG8_LAS unsigned char* lds, const Gemm g, const Sched& S, const Epi& E) {
;     ...
;         for (int t = 0; t < nt; t += 2) {
;             const bool last = (t == nt - 2);
;             const char* a1 = cA + (size_t)(t + 1) * kstep;
;             const char* a2 = last ? nA : cA + (size_t)(t + 2) * kstep; const char* b2 = last ? nB : cB + (size_t)(t + 2) * kstep;
	v_mfma_f32_16x16x32_bf16 v[54:57], v[138:141], v[162:165], v[54:57]
	v_mfma_f32_16x16x32_bf16 v[50:53], v[146:149], v[162:165], v[50:53]
	v_mfma_f32_16x16x32_bf16 v[38:41], v[138:141], v[170:173], v[38:41]
	v_mfma_f32_16x16x32_bf16 v[34:37], v[146:149], v[170:173], v[34:37]
	v_mfma_f32_16x16x32_bf16 v[22:25], v[138:141], v[178:181], v[22:25]
	v_mfma_f32_16x16x32_bf16 v[18:21], v[146:149], v[178:181], v[18:21]
	v_mfma_f32_16x16x32_bf16 v[6:9], v[138:141], v[186:189], v[6:9]
	v_mfma_f32_16x16x32_bf16 v[2:5], v[146:149], v[186:189], v[2:5]
	v_mfma_f32_16x16x32_bf16 v[54:57], v[142:145], v[166:169], v[54:57]
	v_mfma_f32_16x16x32_bf16 v[50:53], v[158:161], v[166:169], v[50:53]
	v_mfma_f32_16x16x32_bf16 v[38:41], v[142:145], v[174:177], v[38:41]
	v_mfma_f32_16x16x32_bf16 v[34:37], v[158:161], v[174:177], v[34:37]
	v_mfma_f32_16x16x32_bf16 v[22:25], v[142:145], v[182:185], v[22:25]
	v_mfma_f32_16x16x32_bf16 v[18:21], v[158:161], v[182:185], v[18:21]
	v_mfma_f32_16x16x32_bf16 v[6:9], v[142:145], v[208:211], v[6:9]
	v_mfma_f32_16x16x32_bf16 v[2:5], v[158:161], v[208:211], v[2:5]
	s_setprio 0
	s_barrier
	s_add_i32 s52, s52, 2
	s_add_u32 s18, s18, 0x100
	s_addc_u32 s19, s19, 0
	s_add_u32 s45, s45, 0x100
	s_addc_u32 s47, s47, 0
	s_cmp_gt_u32 s52, 13
	s_cbranch_scc0 .LBB0_487



; template <class Epi, class Sched, bool ALIGN_EPI = false, bool SP2 = false>
; __device__ __forceinline__ void gemm_phase(PG8_LAS unsigned char* lds, const Gemm g, const Sched& S, const Epi& E) {
;     ...
;         const bool has_next = S.next(ui + 1, nxt);
;         const char* nA = has_next ? (const char*)g.A + (size_t)nxt.pm * tstep : cA; const char* nB = has_next ? (const char*)g.Bt + (size_t)nxt.pn * tstep : cB;
;         for (int t = 0; t < nt; t += 2) {
;             const bool last = (t == nt - 2);
;             const char* a1 = cA + (size_t)(t + 1) * kstep;
;             const char* a2 = last ? nA : cA + (size_t)(t + 2) * kstep; const char* b2 = last ? nB : cB + (size_t)(t + 2) * kstep;
.LBB0_521:
	s_ashr_i32 s45, s44, 31
	s_lshl_b64 s[30:31], s[44:45], 19
	s_add_u32 s48, s98, s30
	s_addc_u32 s49, s99, s31
	s_and_b64 s[30:31], s[46:47], exec
	s_cselect_b32 s30, s49, s19
	s_cselect_b32 s31, s48, s18
	s_ashr_i32 s43, s42, 31
	s_lshl_b64 s[34:35], s[42:43], 19
	s_add_u32 s50, s68, s34
	s_addc_u32 s51, s69, s35
	s_and_b64 s[34:35], s[46:47], exec
	s_cselect_b32 s34, s51, s59
	s_cselect_b32 s35, s50, s58
	s_add_u32 s18, s18, 0x40080
	s_addc_u32 s19, s19, 0
	s_add_u32 s43, s58, 0x100

; template <class Epi, class Sched, bool ALIGN_EPI = false, bool SP2 = false>
; __device__ __forceinline__ void gemm_phase(PG8_LAS unsigned char* lds, const Gemm g, const Sched& S, const Epi& E) {
;     ...
;         const bool has_next = S.next(ui + 1, nxt);
;         const char* nA = has_next ? (const char*)g.A + (size_t)nxt.pm * tstep : cA; const char* nB = has_next ? (const char*)g.Bt + (size_t)nxt.pn * tstep : cB;
;         for (int t = 0; t < nt; t += 2) {
;             const bool last = (t == nt - 2);
;             const char* a1 = cA + (size_t)(t + 1) * kstep;
;             const char* a2 = last ? nA : cA + (size_t)(t + 2) * kstep; const char* b2 = last ? nB : cB + (size_t)(t + 2) * kstep;
	s_addc_u32 s45, s59, 0
	s_mov_b32 s52, -2


; #define PG8_STAGE(bufoff, gbase, voff) do { _Pragma("unroll") for (int _i = 0; _i < 2; ++_i) \
;         __builtin_amdgcn_global_load_lds((const unsigned*)((const char*)(gbase) + (voff)[_i]), (PG8_LAS unsigned*)(lds + (bufoff) + ldsw + _i * 8192), 16, 0, 0); } while (0)
; #define PG8_LDA(dst, b, h) do { _Pragma("unroll") for (int m = 0; m < 4; ++m) _Pragma("unroll") for (int k = 0; k < 2; ++k) dst[m][k] = *(const PG8_LAS bf16x8*)(lds + PG8_SA(b, h) + aoff + m * 2048 + k * 1024); } while (0)
; #define PG8_LDB(dst, b, h) do { _Pragma("unroll") for (int n = 0; n < 2; ++n) _Pragma("unroll") for (int k = 0; k < 2; ++k) dst[n][k] = *(const PG8_LAS bf16x8*)(lds + PG8_SB(b, h) + boff + n * 2048 + k * 1024); } while (0)
; #define PG8_MMA(ai, bj, At, Bt) do { __builtin_amdgcn_s_setprio(1); _Pragma("unroll") for (int m = 0; m < 4; ++m) _Pragma("unroll") for (int n = 0; n < 2; ++n) _Pragma("unroll") for (int k = 0; k < 2; ++k) \
;         acc[ai][bj][m][n] = __builtin_amdgcn_mfma_f32_16x16x32_bf16(Bt[n][k], At[m][k], acc[ai][bj][m][n], 0, 0, 0); __builtin_amdgcn_s_setprio(0); } while (0)
; #define PG8_WAIT_V(n) asm volatile("s_waitcnt vmcnt(" #n ")" ::: "memory")
; #define PG8_WAIT_L(n) asm volatile("s_waitcnt lgkmcnt(" #n ")" ::: "memory")
; #define PG8_BAR __builtin_amdgcn_s_barrier()
; #define PG8_SCHED __builtin_amdgcn_sched_barrier(0)
; template <class Epi, class Sched, bool ALIGN_EPI = false, bool SP2 = false>
; __device__ __forceinline__ void gemm_phase(PG8_LAS unsigned char* lds, const Gemm g, const Sched& S, const Epi& E) {
;     ...
;             PG8_LDB(B0, 0, 0); PG8_LDB(B1, 0, 1); PG8_SCHED; PG8_LDA(At, 0, 0); PG8_STAGE(PG8_SA(1, 1), a1 + hstep, voffA);
;             PG8_WAIT_V(8); PG8_WAIT_L(0); PG8_BAR; PG8_MMA(0, 0, At, B0); PG8_MMA(0, 1, At, B1); PG8_BAR; PG8_SCHED;
	s_waitcnt lgkmcnt(0)


; #define PG8_STAGE(bufoff, gbase, voff) do { _Pragma("unroll") for (int _i = 0; _i < 2; ++_i) \
;         __builtin_amdgcn_global_load_lds((const unsigned*)((const char*)(gbase) + (voff)[_i]), (PG8_LAS unsigned*)(lds + (bufoff) + ldsw + _i * 8192), 16, 0, 0); } while (0)
; #define PG8_LDA(dst, b, h) do { _Pragma("unroll") for (int m = 0; m < 4; ++m) _Pragma("unroll") for (int k = 0; k < 2; ++k) dst[m][k] = *(const PG8_LAS bf16x8*)(lds + PG8_SA(b, h) + aoff + m * 2048 + k * 1024); } while (0)
; #define PG8_LDB(dst, b, h) do { _Pragma("unroll") for (int n = 0; n < 2; ++n) _Pragma("unroll") for (int k = 0; k < 2; ++k) dst[n][k] = *(const PG8_LAS bf16x8*)(lds + PG8_SB(b, h) + boff + n * 2048 + k * 1024); } while (0)
; #define PG8_MMA(ai, bj, At, Bt) do { __builtin_amdgcn_s_setprio(1); _Pragma("unroll") for (int m = 0; m < 4; ++m) _Pragma("unroll") for (int n = 0; n < 2; ++n) _Pragma("unroll") for (int k = 0; k < 2; ++k) \
;         acc[ai][bj][m][n] = __builtin_amdgcn_mfma_f32_16x16x32_bf16(Bt[n][k], At[m][k], acc[ai][bj][m][n], 0, 0, 0); __builtin_amdgcn_s_setprio(0); } while (0)
; #define PG8_WAIT_V(n) asm volatile("s_waitcnt vmcnt(" #n ")" ::: "memory")
; #define PG8_WAIT_L(n) asm volatile("s_waitcnt lgkmcnt(" #n ")" ::: "memory")
; #define PG8_BAR __builtin_amdgcn_s_barrier()
; #define PG8_SCHED __builtin_amdgcn_sched_barrier(0)
; template <class Epi, class Sched, bool ALIGN_EPI = false, bool SP2 = false>
; __device__ __forceinline__ void gemm_phase(PG8_LAS unsigned char* lds, const Gemm g, const Sched& S, const Epi& E) {
;     ...
;             const bool last = (t == nt - 2);
;             const char* a1 = cA + (size_t)(t + 1) * kstep;
;             const char* a2 = last ? nA : cA + (size_t)(t + 2) * kstep; const char* b2 = last ? nB : cB + (size_t)(t + 2) * kstep;
;             const char* a3 = a2 + kstep; const char* b3 = b2 + kstep;
;             if (last && has_next) S.a_ready(nxt);
;             if constexpr (SP2) {
;             PG8_LDB(B0, 0, 0); PG8_LDB(B1, 0, 1); PG8_SCHED; PG8_LDA(At, 0, 0); PG8_STAGE(PG8_SA(1, 1), a1 + hstep, voffA);
;             PG8_WAIT_V(8); PG8_WAIT_L(0); PG8_BAR; PG8_MMA(0, 0, At, B0); PG8_MMA(0, 1, At, B1); PG8_BAR; PG8_SCHED;
	s_add_u32 s53, s18, 0xfffc0080
	s_addc_u32 s58, s19, -1
	s_add_i32 s62, 0, 0x10000
	s_cmp_eq_u32 s52, 12
	s_cselect_b32 s61, s30, s58
	s_cselect_b32 s60, s31, s53
	s_cselect_b32 s59, s34, s45
	s_cselect_b32 s58, s35, s43
	s_add_i32 s53, 0, 0x14000
	v_add_u32_e32 v156, s62, v149
	v_add_u32_e32 v172, s53, v149
	ds_read_b128 v[140:143], v156
	ds_read_b128 v[144:147], v156 offset:1024
	ds_read_b128 v[152:155], v156 offset:2048
	ds_read_b128 v[156:159], v156 offset:3072
	ds_read_b128 v[160:163], v172
	ds_read_b128 v[164:167], v172 offset:1024
	ds_read_b128 v[168:171], v172 offset:2048
	ds_read_b128 v[172:175], v172 offset:3072
	v_lshl_add_u64 v[188:189], s[18:19], 0, v[136:137]
	s_add_i32 m0, s25, 0xc000
	ds_read_b128 v[176:179], v151
	ds_read_b128 v[180:183], v151 offset:1024
	ds_read_b128 v[184:187], v151 offset:2048
	ds_read_b128 v[194:197], v151 offset:3072
	ds_read_b128 v[198:201], v151 offset:4096
	ds_read_b128 v[202:205], v151 offset:5120
	ds_read_b128 v[206:209], v151 offset:6144
	ds_read_b128 v[210:213], v151 offset:7168
	global_load_lds_dwordx4 v[188:189], off
	v_lshl_add_u64 v[188:189], s[18:19], 0, v[138:139]
	s_add_i32 m0, s25, 0xe000
	s_nop 0
	global_load_lds_dwordx4 v[188:189], off
	s_waitcnt vmcnt(8)
	s_waitcnt lgkmcnt(0)
	s_barrier
	s_setprio 1
	s_waitcnt lgkmcnt(0)
	v_mfma_f32_16x16x32_bf16 v[126:129], v[140:143], v[176:179], 0
	v_mfma_f32_16x16x32_bf16 v[122:125], v[152:155], v[176:179], 0
	v_mfma_f32_16x16x32_bf16 v[118:121], v[140:143], v[184:187], 0
	v_mfma_f32_16x16x32_bf16 v[110:113], v[152:155], v[184:187], 0
	v_mfma_f32_16x16x32_bf16 v[94:97], v[140:143], v[198:201], 0
	v_mfma_f32_16x16x32_bf16 v[90:93], v[152:155], v[198:201], 0
	v_mfma_f32_16x16x32_bf16 v[78:81], v[140:143], v[206:209], 0
	v_mfma_f32_16x16x32_bf16 v[74:77], v[152:155], v[206:209], 0
	v_mfma_f32_16x16x32_bf16 v[126:129], v[144:147], v[180:183], v[126:129]
	v_mfma_f32_16x16x32_bf16 v[122:125], v[156:159], v[180:183], v[122:125]
	v_mfma_f32_16x16x32_bf16 v[118:121], v[144:147], v[194:197], v[118:121]
	v_mfma_f32_16x16x32_bf16 v[110:113], v[156:159], v[194:197], v[110:113]
	v_mfma_f32_16x16x32_bf16 v[94:97], v[144:147], v[202:205], v[94:97]
	v_mfma_f32_16x16x32_bf16 v[90:93], v[156:159], v[202:205], v[90:93]
	v_mfma_f32_16x16x32_bf16 v[78:81], v[144:147], v[210:213], v[78:81]
	v_mfma_f32_16x16x32_bf16 v[74:77], v[156:159], v[210:213], v[74:77]


; #define PG8_STAGE(bufoff, gbase, voff) do { _Pragma("unroll") for (int _i = 0; _i < 2; ++_i) \
;         __builtin_amdgcn_global_load_lds((const unsigned*)((const char*)(gbase) + (voff)[_i]), (PG8_LAS unsigned*)(lds + (bufoff) + ldsw + _i * 8192), 16, 0, 0); } while (0)
; #define PG8_LDA(dst, b, h) do { _Pragma("unroll") for (int m = 0; m < 4; ++m) _Pragma("unroll") for (int k = 0; k < 2; ++k) dst[m][k] = *(const PG8_LAS bf16x8*)(lds + PG8_SA(b, h) + aoff + m * 2048 + k * 1024); } while (0)
; #define PG8_MMA(ai, bj, At, Bt) do { __builtin_amdgcn_s_setprio(1); _Pragma("unroll") for (int m = 0; m < 4; ++m) _Pragma("unroll") for (int n = 0; n < 2; ++n) _Pragma("unroll") for (int k = 0; k < 2; ++k) \
;         acc[ai][bj][m][n] = __builtin_amdgcn_mfma_f32_16x16x32_bf16(Bt[n][k], At[m][k], acc[ai][bj][m][n], 0, 0, 0); __builtin_amdgcn_s_setprio(0); } while (0)
; #define PG8_WAIT_V(n) asm volatile("s_waitcnt vmcnt(" #n ")" ::: "memory")
; #define PG8_WAIT_L(n) asm volatile("s_waitcnt lgkmcnt(" #n ")" ::: "memory")
; #define PG8_BAR __builtin_amdgcn_s_barrier()
; #define PG8_SCHED __builtin_amdgcn_sched_barrier(0)
; template <class Epi, class Sched, bool ALIGN_EPI = false, bool SP2 = false>
; __device__ __forceinline__ void gemm_phase(PG8_LAS unsigned char* lds, const Gemm g, const Sched& S, const Epi& E) {
;     ...
;             PG8_WAIT_V(8); PG8_WAIT_L(0); PG8_BAR; PG8_MMA(0, 0, At, B0); PG8_MMA(0, 1, At, B1); PG8_BAR; PG8_SCHED;
;             PG8_LDA(At, 0, 1); PG8_STAGE(PG8_SB(0, 0), b2, voffB); PG8_STAGE(PG8_SB(0, 1), b2 + hstep, voffB); PG8_STAGE(PG8_SA(0, 0), a2, voffA);
;             PG8_WAIT_V(8); PG8_WAIT_L(0); PG8_BAR; PG8_MMA(1, 0, At, B0); PG8_MMA(1, 1, At, B1); PG8_BAR; PG8_SCHED;
	v_mfma_f32_16x16x32_bf16 v[114:117], v[160:163], v[176:179], 0
	v_mfma_f32_16x16x32_bf16 v[106:109], v[168:171], v[176:179], 0
	v_mfma_f32_16x16x32_bf16 v[102:105], v[160:163], v[184:187], 0
	v_mfma_f32_16x16x32_bf16 v[98:101], v[168:171], v[184:187], 0
	v_mfma_f32_16x16x32_bf16 v[86:89], v[160:163], v[198:201], 0
	v_mfma_f32_16x16x32_bf16 v[82:85], v[168:171], v[198:201], 0
	v_mfma_f32_16x16x32_bf16 v[70:73], v[160:163], v[206:209], 0
	v_mfma_f32_16x16x32_bf16 v[66:69], v[168:171], v[206:209], 0
	v_mfma_f32_16x16x32_bf16 v[114:117], v[164:167], v[180:183], v[114:117]
	v_mfma_f32_16x16x32_bf16 v[106:109], v[172:175], v[180:183], v[106:109]
	v_mfma_f32_16x16x32_bf16 v[102:105], v[164:167], v[194:197], v[102:105]
	v_mfma_f32_16x16x32_bf16 v[98:101], v[172:175], v[194:197], v[98:101]
	v_mfma_f32_16x16x32_bf16 v[86:89], v[164:167], v[202:205], v[86:89]
	v_mfma_f32_16x16x32_bf16 v[82:85], v[172:175], v[202:205], v[82:85]
	v_mfma_f32_16x16x32_bf16 v[70:73], v[164:167], v[210:213], v[70:73]
	v_mfma_f32_16x16x32_bf16 v[66:69], v[172:175], v[210:213], v[66:69]
	s_setprio 0
	s_barrier
	s_add_i32 s62, s62, s24
	v_lshl_add_u64 v[188:189], s[58:59], 0, v[0:1]
	s_mov_b32 m0, s62
	ds_read_b128 v[176:179], v151 offset:16384
	ds_read_b128 v[180:183], v151 offset:17408
	ds_read_b128 v[184:187], v151 offset:18432
	ds_read_b128 v[194:197], v151 offset:19456
	ds_read_b128 v[198:201], v151 offset:20480
	ds_read_b128 v[202:205], v151 offset:21504
	ds_read_b128 v[206:209], v151 offset:22528
	ds_read_b128 v[210:213], v151 offset:23552
	global_load_lds_dwordx4 v[188:189], off
	s_add_i32 m0, s62, 0x2000
	s_add_u32 s62, s58, 0x40000
	v_lshl_add_u64 v[214:215], s[58:59], 0, v[134:135]
	s_addc_u32 s63, s59, 0
	s_add_i32 s53, s53, s24
	global_load_lds_dwordx4 v[214:215], off
	v_lshl_add_u64 v[216:217], s[62:63], 0, v[0:1]
	s_mov_b32 m0, s53
	v_lshl_add_u64 v[218:219], s[60:61], 0, v[132:133]
	global_load_lds_dwordx4 v[216:217], off
	v_lshl_add_u64 v[216:217], s[62:63], 0, v[134:135]
	s_add_i32 m0, s53, 0x2000
	s_nop 0
	global_load_lds_dwordx4 v[216:217], off
	v_lshl_add_u64 v[216:217], s[60:61], 0, v[130:131]
	s_mov_b32 m0, s25
	s_nop 0
	global_load_lds_dwordx4 v[216:217], off
	s_mov_b32 m0, s26
	s_nop 0
	global_load_lds_dwordx4 v[218:219], off
	s_waitcnt vmcnt(8)
	s_waitcnt lgkmcnt(0)
	s_barrier
	s_setprio 1
	s_waitcnt lgkmcnt(0)
	v_mfma_f32_16x16x32_bf16 v[62:65], v[140:143], v[176:179], 0
	v_mfma_f32_16x16x32_bf16 v[58:61], v[152:155], v[176:179], 0
	v_mfma_f32_16x16x32_bf16 v[46:49], v[140:143], v[184:187], 0
	v_mfma_f32_16x16x32_bf16 v[42:45], v[152:155], v[184:187], 0
	v_mfma_f32_16x16x32_bf16 v[30:33], v[140:143], v[198:201], 0
	v_mfma_f32_16x16x32_bf16 v[26:29], v[152:155], v[198:201], 0
	v_mfma_f32_16x16x32_bf16 v[14:17], v[140:143], v[206:209], 0
	v_mfma_f32_16x16x32_bf16 v[10:13], v[152:155], v[206:209], 0
	v_mfma_f32_16x16x32_bf16 v[62:65], v[144:147], v[180:183], v[62:65]
	v_mfma_f32_16x16x32_bf16 v[58:61], v[156:159], v[180:183], v[58:61]
	v_mfma_f32_16x16x32_bf16 v[46:49], v[144:147], v[194:197], v[46:49]
	v_mfma_f32_16x16x32_bf16 v[42:45], v[156:159], v[194:197], v[42:45]
	v_mfma_f32_16x16x32_bf16 v[30:33], v[144:147], v[202:205], v[30:33]
	v_mfma_f32_16x16x32_bf16 v[26:29], v[156:159], v[202:205], v[26:29]
	v_mfma_f32_16x16x32_bf16 v[14:17], v[144:147], v[210:213], v[14:17]
	v_mfma_f32_16x16x32_bf16 v[10:13], v[156:159], v[210:213], v[10:13]


; #define PG8_STAGE(bufoff, gbase, voff) do { _Pragma("unroll") for (int _i = 0; _i < 2; ++_i) \
;         __builtin_amdgcn_global_load_lds((const unsigned*)((const char*)(gbase) + (voff)[_i]), (PG8_LAS unsigned*)(lds + (bufoff) + ldsw + _i * 8192), 16, 0, 0); } while (0)
; #define PG8_LDA(dst, b, h) do { _Pragma("unroll") for (int m = 0; m < 4; ++m) _Pragma("unroll") for (int k = 0; k < 2; ++k) dst[m][k] = *(const PG8_LAS bf16x8*)(lds + PG8_SA(b, h) + aoff + m * 2048 + k * 1024); } while (0)
; #define PG8_LDB(dst, b, h) do { _Pragma("unroll") for (int n = 0; n < 2; ++n) _Pragma("unroll") for (int k = 0; k < 2; ++k) dst[n][k] = *(const PG8_LAS bf16x8*)(lds + PG8_SB(b, h) + boff + n * 2048 + k * 1024); } while (0)
; #define PG8_MMA(ai, bj, At, Bt) do { __builtin_amdgcn_s_setprio(1); _Pragma("unroll") for (int m = 0; m < 4; ++m) _Pragma("unroll") for (int n = 0; n < 2; ++n) _Pragma("unroll") for (int k = 0; k < 2; ++k) \
;         acc[ai][bj][m][n] = __builtin_amdgcn_mfma_f32_16x16x32_bf16(Bt[n][k], At[m][k], acc[ai][bj][m][n], 0, 0, 0); __builtin_amdgcn_s_setprio(0); } while (0)
; #define PG8_WAIT_V(n) asm volatile("s_waitcnt vmcnt(" #n ")" ::: "memory")
; #define PG8_WAIT_L(n) asm volatile("s_waitcnt lgkmcnt(" #n ")" ::: "memory")
; #define PG8_BAR __builtin_amdgcn_s_barrier()
; #define PG8_SCHED __builtin_amdgcn_sched_barrier(0)
; template <class Epi, class Sched, bool ALIGN_EPI = false, bool SP2 = false>
; __device__ __forceinline__ void gemm_phase(PG8_LAS unsigned char* lds, const Gemm g, const Sched& S, const Epi& E) {
;     ...
;             PG8_WAIT_V(8); PG8_WAIT_L(0); PG8_BAR; PG8_MMA(1, 0, At, B0); PG8_MMA(1, 1, At, B1); PG8_BAR; PG8_SCHED;
;             PG8_LDB(B0, 1, 0); PG8_LDB(B1, 1, 1); PG8_SCHED; PG8_LDA(At, 1, 0); PG8_STAGE(PG8_SA(0, 1), a2 + hstep, voffA);
;             PG8_WAIT_V(8); PG8_WAIT_L(0); PG8_BAR; PG8_MMA(0, 0, At, B0); PG8_MMA(0, 1, At, B1); PG8_BAR; PG8_SCHED;
	v_mfma_f32_16x16x32_bf16 v[54:57], v[160:163], v[176:179], 0
	v_mfma_f32_16x16x32_bf16 v[50:53], v[168:171], v[176:179], 0
	v_mfma_f32_16x16x32_bf16 v[38:41], v[160:163], v[184:187], 0
	v_mfma_f32_16x16x32_bf16 v[34:37], v[168:171], v[184:187], 0
	v_mfma_f32_16x16x32_bf16 v[22:25], v[160:163], v[198:201], 0
	v_mfma_f32_16x16x32_bf16 v[18:21], v[168:171], v[198:201], 0
	v_mfma_f32_16x16x32_bf16 v[6:9], v[160:163], v[206:209], 0
	v_mfma_f32_16x16x32_bf16 v[2:5], v[168:171], v[206:209], 0
	v_mfma_f32_16x16x32_bf16 v[54:57], v[164:167], v[180:183], v[54:57]
	v_mfma_f32_16x16x32_bf16 v[50:53], v[172:175], v[180:183], v[50:53]
	v_mfma_f32_16x16x32_bf16 v[38:41], v[164:167], v[194:197], v[38:41]
	v_mfma_f32_16x16x32_bf16 v[34:37], v[172:175], v[194:197], v[34:37]
	v_mfma_f32_16x16x32_bf16 v[22:25], v[164:167], v[202:205], v[22:25]
	v_mfma_f32_16x16x32_bf16 v[18:21], v[172:175], v[202:205], v[18:21]
	v_mfma_f32_16x16x32_bf16 v[6:9], v[164:167], v[210:213], v[6:9]
	v_mfma_f32_16x16x32_bf16 v[2:5], v[172:175], v[210:213], v[2:5]
	s_setprio 0
	s_barrier
	s_add_i32 s53, 0, 0x18000
	s_add_i32 s62, 0, 0x1c000
	v_add_u32_e32 v156, s53, v149
	v_add_u32_e32 v172, s62, v149
	ds_read_b128 v[140:143], v156
	ds_read_b128 v[144:147], v156 offset:1024
	ds_read_b128 v[152:155], v156 offset:2048
	ds_read_b128 v[156:159], v156 offset:3072
	ds_read_b128 v[160:163], v172
	ds_read_b128 v[164:167], v172 offset:1024
	ds_read_b128 v[168:171], v172 offset:2048
	ds_read_b128 v[172:175], v172 offset:3072
	s_add_u32 s60, s60, 0x40000
	s_addc_u32 s61, s61, 0
	s_mov_b32 m0, s27
	v_lshl_add_u64 v[220:221], s[60:61], 0, v[130:131]
	ds_read_b128 v[176:179], v151 offset:32768
	ds_read_b128 v[180:183], v151 offset:33792
	ds_read_b128 v[184:187], v151 offset:34816
	ds_read_b128 v[194:197], v151 offset:35840
	ds_read_b128 v[198:201], v151 offset:36864
	ds_read_b128 v[202:205], v151 offset:37888
	ds_read_b128 v[206:209], v151 offset:38912
	ds_read_b128 v[210:213], v151 offset:39936
	global_load_lds_dwordx4 v[220:221], off
	v_lshl_add_u64 v[220:221], s[60:61], 0, v[132:133]
	s_mov_b32 m0, s28
	s_nop 0
	global_load_lds_dwordx4 v[220:221], off
	s_waitcnt vmcnt(8)
	s_waitcnt lgkmcnt(0)
	s_barrier
	s_setprio 1
	s_waitcnt lgkmcnt(0)
	v_mfma_f32_16x16x32_bf16 v[126:129], v[140:143], v[176:179], v[126:129]
	v_mfma_f32_16x16x32_bf16 v[122:125], v[152:155], v[176:179], v[122:125]
	v_mfma_f32_16x16x32_bf16 v[118:121], v[140:143], v[184:187], v[118:121]
	v_mfma_f32_16x16x32_bf16 v[110:113], v[152:155], v[184:187], v[110:113]
	v_mfma_f32_16x16x32_bf16 v[94:97], v[140:143], v[198:201], v[94:97]
	v_mfma_f32_16x16x32_bf16 v[90:93], v[152:155], v[198:201], v[90:93]
	v_mfma_f32_16x16x32_bf16 v[78:81], v[140:143], v[206:209], v[78:81]
	v_mfma_f32_16x16x32_bf16 v[74:77], v[152:155], v[206:209], v[74:77]
	v_mfma_f32_16x16x32_bf16 v[126:129], v[144:147], v[180:183], v[126:129]
	v_mfma_f32_16x16x32_bf16 v[122:125], v[156:159], v[180:183], v[122:125]
	v_mfma_f32_16x16x32_bf16 v[118:121], v[144:147], v[194:197], v[118:121]
	v_mfma_f32_16x16x32_bf16 v[110:113], v[156:159], v[194:197], v[110:113]
	v_mfma_f32_16x16x32_bf16 v[94:97], v[144:147], v[202:205], v[94:97]
	v_mfma_f32_16x16x32_bf16 v[90:93], v[156:159], v[202:205], v[90:93]
	v_mfma_f32_16x16x32_bf16 v[78:81], v[144:147], v[210:213], v[78:81]
	v_mfma_f32_16x16x32_bf16 v[74:77], v[156:159], v[210:213], v[74:77]


; #define PG8_STAGE(bufoff, gbase, voff) do { _Pragma("unroll") for (int _i = 0; _i < 2; ++_i) \
;         __builtin_amdgcn_global_load_lds((const unsigned*)((const char*)(gbase) + (voff)[_i]), (PG8_LAS unsigned*)(lds + (bufoff) + ldsw + _i * 8192), 16, 0, 0); } while (0)
; #define PG8_LDA(dst, b, h) do { _Pragma("unroll") for (int m = 0; m < 4; ++m) _Pragma("unroll") for (int k = 0; k < 2; ++k) dst[m][k] = *(const PG8_LAS bf16x8*)(lds + PG8_SA(b, h) + aoff + m * 2048 + k * 1024); } while (0)
; #define PG8_MMA(ai, bj, At, Bt) do { __builtin_amdgcn_s_setprio(1); _Pragma("unroll") for (int m = 0; m < 4; ++m) _Pragma("unroll") for (int n = 0; n < 2; ++n) _Pragma("unroll") for (int k = 0; k < 2; ++k) \
;         acc[ai][bj][m][n] = __builtin_amdgcn_mfma_f32_16x16x32_bf16(Bt[n][k], At[m][k], acc[ai][bj][m][n], 0, 0, 0); __builtin_amdgcn_s_setprio(0); } while (0)
; #define PG8_WAIT_V(n) asm volatile("s_waitcnt vmcnt(" #n ")" ::: "memory")
; #define PG8_WAIT_L(n) asm volatile("s_waitcnt lgkmcnt(" #n ")" ::: "memory")
; #define PG8_BAR __builtin_amdgcn_s_barrier()
; #define PG8_SCHED __builtin_amdgcn_sched_barrier(0)
; template <class Epi, class Sched, bool ALIGN_EPI = false, bool SP2 = false>
; __device__ __forceinline__ void gemm_phase(PG8_LAS unsigned char* lds, const Gemm g, const Sched& S, const Epi& E) {
;     ...
;             PG8_WAIT_V(8); PG8_WAIT_L(0); PG8_BAR; PG8_MMA(0, 0, At, B0); PG8_MMA(0, 1, At, B1); PG8_BAR; PG8_SCHED;
;             PG8_LDA(At, 1, 1); PG8_STAGE(PG8_SB(1, 0), b3, voffB); PG8_STAGE(PG8_SB(1, 1), b3 + hstep, voffB); PG8_STAGE(PG8_SA(1, 0), a3, voffA);
;             PG8_WAIT_V(8); PG8_WAIT_L(0); PG8_BAR; PG8_MMA(1, 0, At, B0); PG8_MMA(1, 1, At, B1); PG8_BAR; PG8_SCHED;
	v_mfma_f32_16x16x32_bf16 v[114:117], v[160:163], v[176:179], v[114:117]
	v_mfma_f32_16x16x32_bf16 v[106:109], v[168:171], v[176:179], v[106:109]
	v_mfma_f32_16x16x32_bf16 v[102:105], v[160:163], v[184:187], v[102:105]
	v_mfma_f32_16x16x32_bf16 v[98:101], v[168:171], v[184:187], v[98:101]
	v_mfma_f32_16x16x32_bf16 v[86:89], v[160:163], v[198:201], v[86:89]
	v_mfma_f32_16x16x32_bf16 v[82:85], v[168:171], v[198:201], v[82:85]
	v_mfma_f32_16x16x32_bf16 v[70:73], v[160:163], v[206:209], v[70:73]
	v_mfma_f32_16x16x32_bf16 v[66:69], v[168:171], v[206:209], v[66:69]
	v_mfma_f32_16x16x32_bf16 v[114:117], v[164:167], v[180:183], v[114:117]
	v_mfma_f32_16x16x32_bf16 v[106:109], v[172:175], v[180:183], v[106:109]
	v_mfma_f32_16x16x32_bf16 v[102:105], v[164:167], v[194:197], v[102:105]
	v_mfma_f32_16x16x32_bf16 v[98:101], v[172:175], v[194:197], v[98:101]
	v_mfma_f32_16x16x32_bf16 v[86:89], v[164:167], v[202:205], v[86:89]
	v_mfma_f32_16x16x32_bf16 v[82:85], v[172:175], v[202:205], v[82:85]
	v_mfma_f32_16x16x32_bf16 v[70:73], v[164:167], v[210:213], v[70:73]
	v_mfma_f32_16x16x32_bf16 v[66:69], v[172:175], v[210:213], v[66:69]
	s_setprio 0
	s_barrier
	s_add_i32 s53, s53, s24
	v_lshl_add_u64 v[188:189], v[188:189], 0, s[8:9]
	s_mov_b32 m0, s53
	ds_read_b128 v[176:179], v151 offset:49152
	ds_read_b128 v[180:183], v151 offset:50176
	ds_read_b128 v[184:187], v151 offset:51200
	ds_read_b128 v[194:197], v151 offset:52224
	ds_read_b128 v[198:201], v151 offset:53248
	ds_read_b128 v[202:205], v151 offset:54272
	ds_read_b128 v[206:209], v151 offset:55296
	ds_read_b128 v[210:213], v151 offset:56320
	global_load_lds_dwordx4 v[188:189], off
	s_add_i32 m0, s53, 0x2000
	s_add_u32 s58, s58, 0x40080
	v_lshl_add_u64 v[188:189], v[214:215], 0, s[8:9]
	s_addc_u32 s59, s59, 0
	s_add_i32 s53, s62, s24
	global_load_lds_dwordx4 v[188:189], off
	v_lshl_add_u64 v[188:189], s[58:59], 0, v[0:1]
	s_mov_b32 m0, s53
	s_nop 0
	global_load_lds_dwordx4 v[188:189], off
	v_lshl_add_u64 v[188:189], s[58:59], 0, v[134:135]
	s_add_i32 m0, s53, 0x2000
	s_nop 0
	global_load_lds_dwordx4 v[188:189], off
	v_lshl_add_u64 v[188:189], v[216:217], 0, s[8:9]
	s_mov_b32 m0, s29
	s_nop 0
	global_load_lds_dwordx4 v[188:189], off
	v_lshl_add_u64 v[188:189], v[218:219], 0, s[8:9]
	s_mov_b32 m0, s55
	s_nop 0
	global_load_lds_dwordx4 v[188:189], off
	s_waitcnt vmcnt(8)
	s_waitcnt lgkmcnt(0)
	s_barrier
	s_setprio 1
	s_waitcnt lgkmcnt(0)
	v_mfma_f32_16x16x32_bf16 v[62:65], v[140:143], v[176:179], v[62:65]
	v_mfma_f32_16x16x32_bf16 v[58:61], v[152:155], v[176:179], v[58:61]
	v_mfma_f32_16x16x32_bf16 v[46:49], v[140:143], v[184:187], v[46:49]
	v_mfma_f32_16x16x32_bf16 v[42:45], v[152:155], v[184:187], v[42:45]
	v_mfma_f32_16x16x32_bf16 v[30:33], v[140:143], v[198:201], v[30:33]
	v_mfma_f32_16x16x32_bf16 v[26:29], v[152:155], v[198:201], v[26:29]
	v_mfma_f32_16x16x32_bf16 v[14:17], v[140:143], v[206:209], v[14:17]
	v_mfma_f32_16x16x32_bf16 v[10:13], v[152:155], v[206:209], v[10:13]
	v_mfma_f32_16x16x32_bf16 v[62:65], v[144:147], v[180:183], v[62:65]
	v_mfma_f32_16x16x32_bf16 v[58:61], v[156:159], v[180:183], v[58:61]
	v_mfma_f32_16x16x32_bf16 v[46:49], v[144:147], v[194:197], v[46:49]
	v_mfma_f32_16x16x32_bf16 v[42:45], v[156:159], v[194:197], v[42:45]
	v_mfma_f32_16x16x32_bf16 v[30:33], v[144:147], v[202:205], v[30:33]
	v_mfma_f32_16x16x32_bf16 v[26:29], v[156:159], v[202:205], v[26:29]
	v_mfma_f32_16x16x32_bf16 v[14:17], v[144:147], v[210:213], v[14:17]
	v_mfma_f32_16x16x32_bf16 v[10:13], v[156:159], v[210:213], v[10:13]


; #define PG8_STAGE(bufoff, gbase, voff) do { _Pragma("unroll") for (int _i = 0; _i < 2; ++_i) \
;         __builtin_amdgcn_global_load_lds((const unsigned*)((const char*)(gbase) + (voff)[_i]), (PG8_LAS unsigned*)(lds + (bufoff) + ldsw + _i * 8192), 16, 0, 0); } while (0)
; #define PG8_LDA(dst, b, h) do { _Pragma("unroll") for (int m = 0; m < 4; ++m) _Pragma("unroll") for (int k = 0; k < 2; ++k) dst[m][k] = *(const PG8_LAS bf16x8*)(lds + PG8_SA(b, h) + aoff + m * 2048 + k * 1024); } while (0)
; #define PG8_LDB(dst, b, h) do { _Pragma("unroll") for (int n = 0; n < 2; ++n) _Pragma("unroll") for (int k = 0; k < 2; ++k) dst[n][k] = *(const PG8_LAS bf16x8*)(lds + PG8_SB(b, h) + boff + n * 2048 + k * 1024); } while (0)
; #define PG8_MMA(ai, bj, At, Bt) do { __builtin_amdgcn_s_setprio(1); _Pragma("unroll") for (int m = 0; m < 4; ++m) _Pragma("unroll") for (int n = 0; n < 2; ++n) _Pragma("unroll") for (int k = 0; k < 2; ++k) \
;         acc[ai][bj][m][n] = __builtin_amdgcn_mfma_f32_16x16x32_bf16(Bt[n][k], At[m][k], acc[ai][bj][m][n], 0, 0, 0); __builtin_amdgcn_s_setprio(0); } while (0)
; #define PG8_WAIT_V(n) asm volatile("s_waitcnt vmcnt(" #n ")" ::: "memory")
; #define PG8_WAIT_L(n) asm volatile("s_waitcnt lgkmcnt(" #n ")" ::: "memory")
; #define PG8_BAR __builtin_amdgcn_s_barrier()
; #define PG8_SCHED __builtin_amdgcn_sched_barrier(0)
; template <class Epi, class Sched, bool ALIGN_EPI = false, bool SP2 = false>
; __device__ __forceinline__ void gemm_phase(PG8_LAS unsigned char* lds, const Gemm g, const Sched& S, const Epi& E) {
;     ...
;             const bool last = (t == nt - 2);
;             const char* a1 = cA + (size_t)(t + 1) * kstep;
;             const char* a2 = last ? nA : cA + (size_t)(t + 2) * kstep; const char* b2 = last ? nB : cB + (size_t)(t + 2) * kstep;
;             const char* a3 = a2 + kstep; const char* b3 = b2 + kstep;
;             if (last && has_next) S.a_ready(nxt);
;             if constexpr (SP2) {
;             PG8_LDB(B0, 0, 0); PG8_LDB(B1, 0, 1); PG8_SCHED; PG8_LDA(At, 0, 0); PG8_STAGE(PG8_SA(1, 1), a1 + hstep, voffA);
;             PG8_WAIT_V(8); PG8_WAIT_L(0); PG8_BAR; PG8_MMA(0, 0, At, B0); PG8_MMA(0, 1, At, B1); PG8_BAR; PG8_SCHED;
	v_mfma_f32_16x16x32_bf16 v[54:57], v[160:163], v[176:179], v[54:57]
	v_mfma_f32_16x16x32_bf16 v[50:53], v[168:171], v[176:179], v[50:53]
	v_mfma_f32_16x16x32_bf16 v[38:41], v[160:163], v[184:187], v[38:41]
	v_mfma_f32_16x16x32_bf16 v[34:37], v[168:171], v[184:187], v[34:37]
	v_mfma_f32_16x16x32_bf16 v[22:25], v[160:163], v[198:201], v[22:25]
	v_mfma_f32_16x16x32_bf16 v[18:21], v[168:171], v[198:201], v[18:21]
	v_mfma_f32_16x16x32_bf16 v[6:9], v[160:163], v[206:209], v[6:9]
	v_mfma_f32_16x16x32_bf16 v[2:5], v[168:171], v[206:209], v[2:5]
	v_mfma_f32_16x16x32_bf16 v[54:57], v[164:167], v[180:183], v[54:57]
	v_mfma_f32_16x16x32_bf16 v[50:53], v[172:175], v[180:183], v[50:53]
	v_mfma_f32_16x16x32_bf16 v[38:41], v[164:167], v[194:197], v[38:41]
	v_mfma_f32_16x16x32_bf16 v[34:37], v[172:175], v[194:197], v[34:37]
	v_mfma_f32_16x16x32_bf16 v[22:25], v[164:167], v[202:205], v[22:25]
	v_mfma_f32_16x16x32_bf16 v[18:21], v[172:175], v[202:205], v[18:21]
	v_mfma_f32_16x16x32_bf16 v[6:9], v[164:167], v[210:213], v[6:9]
	v_mfma_f32_16x16x32_bf16 v[2:5], v[172:175], v[210:213], v[2:5]
	s_setprio 0
	s_barrier
	s_add_i32 s52, s52, 2
	s_add_u32 s18, s18, 0x100
	s_addc_u32 s19, s19, 0
	s_add_u32 s43, s43, 0x100
	s_addc_u32 s45, s45, 0
	s_cmp_gt_u32 s52, 13
.LBB0_522:
	s_add_u32 s53, s18, 0xfffc0080
	s_addc_u32 s58, s19, -1
	s_add_i32 s62, 0, 0x10000
	s_cmp_eq_u32 s52, 12
	s_cselect_b32 s61, s30, s58
	s_cselect_b32 s60, s31, s53
	s_cselect_b32 s59, s34, s45
	s_cselect_b32 s58, s35, s43
	s_add_i32 s53, 0, 0x14000
	v_add_u32_e32 v156, s62, v149
	v_add_u32_e32 v172, s53, v149
	ds_read_b128 v[140:143], v156
	ds_read_b128 v[144:147], v156 offset:1024
	ds_read_b128 v[152:155], v156 offset:2048
	ds_read_b128 v[156:159], v156 offset:3072
	ds_read_b128 v[160:163], v172
	ds_read_b128 v[164:167], v172 offset:1024
	ds_read_b128 v[168:171], v172 offset:2048
	ds_read_b128 v[172:175], v172 offset:3072
	v_lshl_add_u64 v[188:189], s[18:19], 0, v[136:137]
	s_add_i32 m0, s25, 0xc000
	ds_read_b128 v[176:179], v151
	ds_read_b128 v[180:183], v151 offset:1024
	ds_read_b128 v[184:187], v151 offset:2048
	ds_read_b128 v[194:197], v151 offset:3072
	ds_read_b128 v[198:201], v151 offset:4096
	ds_read_b128 v[202:205], v151 offset:5120
	ds_read_b128 v[206:209], v151 offset:6144
	ds_read_b128 v[210:213], v151 offset:7168
	global_load_lds_dwordx4 v[188:189], off
	v_lshl_add_u64 v[188:189], s[18:19], 0, v[138:139]
	s_add_i32 m0, s25, 0xe000
	s_nop 0
	global_load_lds_dwordx4 v[188:189], off
	s_waitcnt vmcnt(8)
	s_waitcnt lgkmcnt(0)
	s_barrier
	s_setprio 1
	s_waitcnt lgkmcnt(0)
	v_mfma_f32_16x16x32_bf16 v[126:129], v[140:143], v[176:179], v[126:129]
	v_mfma_f32_16x16x32_bf16 v[122:125], v[152:155], v[176:179], v[122:125]
	v_mfma_f32_16x16x32_bf16 v[118:121], v[140:143], v[184:187], v[118:121]
	v_mfma_f32_16x16x32_bf16 v[110:113], v[152:155], v[184:187], v[110:113]
	v_mfma_f32_16x16x32_bf16 v[94:97], v[140:143], v[198:201], v[94:97]
	v_mfma_f32_16x16x32_bf16 v[90:93], v[152:155], v[198:201], v[90:93]
	v_mfma_f32_16x16x32_bf16 v[78:81], v[140:143], v[206:209], v[78:81]
	v_mfma_f32_16x16x32_bf16 v[74:77], v[152:155], v[206:209], v[74:77]
	v_mfma_f32_16x16x32_bf16 v[126:129], v[144:147], v[180:183], v[126:129]
	v_mfma_f32_16x16x32_bf16 v[122:125], v[156:159], v[180:183], v[122:125]
	v_mfma_f32_16x16x32_bf16 v[118:121], v[144:147], v[194:197], v[118:121]
	v_mfma_f32_16x16x32_bf16 v[110:113], v[156:159], v[194:197], v[110:113]
	v_mfma_f32_16x16x32_bf16 v[94:97], v[144:147], v[202:205], v[94:97]
	v_mfma_f32_16x16x32_bf16 v[90:93], v[156:159], v[202:205], v[90:93]
	v_mfma_f32_16x16x32_bf16 v[78:81], v[144:147], v[210:213], v[78:81]
	v_mfma_f32_16x16x32_bf16 v[74:77], v[156:159], v[210:213], v[74:77]


; #define PG8_STAGE(bufoff, gbase, voff) do { _Pragma("unroll") for (int _i = 0; _i < 2; ++_i) \
;         __builtin_amdgcn_global_load_lds((const unsigned*)((const char*)(gbase) + (voff)[_i]), (PG8_LAS unsigned*)(lds + (bufoff) + ldsw + _i * 8192), 16, 0, 0); } while (0)
; #define PG8_LDA(dst, b, h) do { _Pragma("unroll") for (int m = 0; m < 4; ++m) _Pragma("unroll") for (int k = 0; k < 2; ++k) dst[m][k] = *(const PG8_LAS bf16x8*)(lds + PG8_SA(b, h) + aoff + m * 2048 + k * 1024); } while (0)
; #define PG8_MMA(ai, bj, At, Bt) do { __builtin_amdgcn_s_setprio(1); _Pragma("unroll") for (int m = 0; m < 4; ++m) _Pragma("unroll") for (int n = 0; n < 2; ++n) _Pragma("unroll") for (int k = 0; k < 2; ++k) \
;         acc[ai][bj][m][n] = __builtin_amdgcn_mfma_f32_16x16x32_bf16(Bt[n][k], At[m][k], acc[ai][bj][m][n], 0, 0, 0); __builtin_amdgcn_s_setprio(0); } while (0)
; #define PG8_WAIT_V(n) asm volatile("s_waitcnt vmcnt(" #n ")" ::: "memory")
; #define PG8_WAIT_L(n) asm volatile("s_waitcnt lgkmcnt(" #n ")" ::: "memory")
; #define PG8_BAR __builtin_amdgcn_s_barrier()
; #define PG8_SCHED __builtin_amdgcn_sched_barrier(0)
; template <class Epi, class Sched, bool ALIGN_EPI = false, bool SP2 = false>
; __device__ __forceinline__ void gemm_phase(PG8_LAS unsigned char* lds, const Gemm g, const Sched& S, const Epi& E) {
;     ...
;             PG8_WAIT_V(8); PG8_WAIT_L(0); PG8_BAR; PG8_MMA(0, 0, At, B0); PG8_MMA(0, 1, At, B1); PG8_BAR; PG8_SCHED;
;             PG8_LDA(At, 0, 1); PG8_STAGE(PG8_SB(0, 0), b2, voffB); PG8_STAGE(PG8_SB(0, 1), b2 + hstep, voffB); PG8_STAGE(PG8_SA(0, 0), a2, voffA);
;             PG8_WAIT_V(8); PG8_WAIT_L(0); PG8_BAR; PG8_MMA(1, 0, At, B0); PG8_MMA(1, 1, At, B1); PG8_BAR; PG8_SCHED;
	v_mfma_f32_16x16x32_bf16 v[114:117], v[160:163], v[176:179], v[114:117]
	v_mfma_f32_16x16x32_bf16 v[106:109], v[168:171], v[176:179], v[106:109]
	v_mfma_f32_16x16x32_bf16 v[102:105], v[160:163], v[184:187], v[102:105]
	v_mfma_f32_16x16x32_bf16 v[98:101], v[168:171], v[184:187], v[98:101]
	v_mfma_f32_16x16x32_bf16 v[86:89], v[160:163], v[198:201], v[86:89]
	v_mfma_f32_16x16x32_bf16 v[82:85], v[168:171], v[198:201], v[82:85]
	v_mfma_f32_16x16x32_bf16 v[70:73], v[160:163], v[206:209], v[70:73]
	v_mfma_f32_16x16x32_bf16 v[66:69], v[168:171], v[206:209], v[66:69]
	v_mfma_f32_16x16x32_bf16 v[114:117], v[164:167], v[180:183], v[114:117]
	v_mfma_f32_16x16x32_bf16 v[106:109], v[172:175], v[180:183], v[106:109]
	v_mfma_f32_16x16x32_bf16 v[102:105], v[164:167], v[194:197], v[102:105]
	v_mfma_f32_16x16x32_bf16 v[98:101], v[172:175], v[194:197], v[98:101]
	v_mfma_f32_16x16x32_bf16 v[86:89], v[164:167], v[202:205], v[86:89]
	v_mfma_f32_16x16x32_bf16 v[82:85], v[172:175], v[202:205], v[82:85]
	v_mfma_f32_16x16x32_bf16 v[70:73], v[164:167], v[210:213], v[70:73]
	v_mfma_f32_16x16x32_bf16 v[66:69], v[172:175], v[210:213], v[66:69]
	s_setprio 0
	s_barrier
	s_add_i32 s62, s62, s24
	v_lshl_add_u64 v[188:189], s[58:59], 0, v[0:1]
	s_mov_b32 m0, s62
	ds_read_b128 v[176:179], v151 offset:16384
	ds_read_b128 v[180:183], v151 offset:17408
	ds_read_b128 v[184:187], v151 offset:18432
	ds_read_b128 v[194:197], v151 offset:19456
	ds_read_b128 v[198:201], v151 offset:20480
	ds_read_b128 v[202:205], v151 offset:21504
	ds_read_b128 v[206:209], v151 offset:22528
	ds_read_b128 v[210:213], v151 offset:23552
	global_load_lds_dwordx4 v[188:189], off
	s_add_i32 m0, s62, 0x2000
	s_add_u32 s62, s58, 0x40000
	v_lshl_add_u64 v[214:215], s[58:59], 0, v[134:135]
	s_addc_u32 s63, s59, 0
	s_add_i32 s53, s53, s24
	global_load_lds_dwordx4 v[214:215], off
	v_lshl_add_u64 v[216:217], s[62:63], 0, v[0:1]
	s_mov_b32 m0, s53
	v_lshl_add_u64 v[218:219], s[60:61], 0, v[132:133]
	global_load_lds_dwordx4 v[216:217], off
	v_lshl_add_u64 v[216:217], s[62:63], 0, v[134:135]
	s_add_i32 m0, s53, 0x2000
	s_nop 0
	global_load_lds_dwordx4 v[216:217], off
	v_lshl_add_u64 v[216:217], s[60:61], 0, v[130:131]
	s_mov_b32 m0, s25
	s_nop 0
	global_load_lds_dwordx4 v[216:217], off
	s_mov_b32 m0, s26
	s_nop 0
	global_load_lds_dwordx4 v[218:219], off
	s_waitcnt vmcnt(8)
	s_waitcnt lgkmcnt(0)
	s_barrier
	s_setprio 1
	s_waitcnt lgkmcnt(0)
	v_mfma_f32_16x16x32_bf16 v[62:65], v[140:143], v[176:179], v[62:65]
	v_mfma_f32_16x16x32_bf16 v[58:61], v[152:155], v[176:179], v[58:61]
	v_mfma_f32_16x16x32_bf16 v[46:49], v[140:143], v[184:187], v[46:49]
	v_mfma_f32_16x16x32_bf16 v[42:45], v[152:155], v[184:187], v[42:45]
	v_mfma_f32_16x16x32_bf16 v[30:33], v[140:143], v[198:201], v[30:33]
	v_mfma_f32_16x16x32_bf16 v[26:29], v[152:155], v[198:201], v[26:29]
	v_mfma_f32_16x16x32_bf16 v[14:17], v[140:143], v[206:209], v[14:17]
	v_mfma_f32_16x16x32_bf16 v[10:13], v[152:155], v[206:209], v[10:13]
	v_mfma_f32_16x16x32_bf16 v[62:65], v[144:147], v[180:183], v[62:65]
	v_mfma_f32_16x16x32_bf16 v[58:61], v[156:159], v[180:183], v[58:61]
	v_mfma_f32_16x16x32_bf16 v[46:49], v[144:147], v[194:197], v[46:49]
	v_mfma_f32_16x16x32_bf16 v[42:45], v[156:159], v[194:197], v[42:45]
	v_mfma_f32_16x16x32_bf16 v[30:33], v[144:147], v[202:205], v[30:33]
	v_mfma_f32_16x16x32_bf16 v[26:29], v[156:159], v[202:205], v[26:29]
	v_mfma_f32_16x16x32_bf16 v[14:17], v[144:147], v[210:213], v[14:17]
	v_mfma_f32_16x16x32_bf16 v[10:13], v[156:159], v[210:213], v[10:13]


; #define PG8_STAGE(bufoff, gbase, voff) do { _Pragma("unroll") for (int _i = 0; _i < 2; ++_i) \
;         __builtin_amdgcn_global_load_lds((const unsigned*)((const char*)(gbase) + (voff)[_i]), (PG8_LAS unsigned*)(lds + (bufoff) + ldsw + _i * 8192), 16, 0, 0); } while (0)
; #define PG8_LDA(dst, b, h) do { _Pragma("unroll") for (int m = 0; m < 4; ++m) _Pragma("unroll") for (int k = 0; k < 2; ++k) dst[m][k] = *(const PG8_LAS bf16x8*)(lds + PG8_SA(b, h) + aoff + m * 2048 + k * 1024); } while (0)
; #define PG8_LDB(dst, b, h) do { _Pragma("unroll") for (int n = 0; n < 2; ++n) _Pragma("unroll") for (int k = 0; k < 2; ++k) dst[n][k] = *(const PG8_LAS bf16x8*)(lds + PG8_SB(b, h) + boff + n * 2048 + k * 1024); } while (0)
; #define PG8_MMA(ai, bj, At, Bt) do { __builtin_amdgcn_s_setprio(1); _Pragma("unroll") for (int m = 0; m < 4; ++m) _Pragma("unroll") for (int n = 0; n < 2; ++n) _Pragma("unroll") for (int k = 0; k < 2; ++k) \
;         acc[ai][bj][m][n] = __builtin_amdgcn_mfma_f32_16x16x32_bf16(Bt[n][k], At[m][k], acc[ai][bj][m][n], 0, 0, 0); __builtin_amdgcn_s_setprio(0); } while (0)
; #define PG8_WAIT_V(n) asm volatile("s_waitcnt vmcnt(" #n ")" ::: "memory")
; #define PG8_WAIT_L(n) asm volatile("s_waitcnt lgkmcnt(" #n ")" ::: "memory")
; #define PG8_BAR __builtin_amdgcn_s_barrier()
; #define PG8_SCHED __builtin_amdgcn_sched_barrier(0)
; template <class Epi, class Sched, bool ALIGN_EPI = false, bool SP2 = false>
; __device__ __forceinline__ void gemm_phase(PG8_LAS unsigned char* lds, const Gemm g, const Sched& S, const Epi& E) {
;     ...
;             PG8_WAIT_V(8); PG8_WAIT_L(0); PG8_BAR; PG8_MMA(1, 0, At, B0); PG8_MMA(1, 1, At, B1); PG8_BAR; PG8_SCHED;
;             PG8_LDB(B0, 1, 0); PG8_LDB(B1, 1, 1); PG8_SCHED; PG8_LDA(At, 1, 0); PG8_STAGE(PG8_SA(0, 1), a2 + hstep, voffA);
;             PG8_WAIT_V(8); PG8_WAIT_L(0); PG8_BAR; PG8_MMA(0, 0, At, B0); PG8_MMA(0, 1, At, B1); PG8_BAR; PG8_SCHED;
	v_mfma_f32_16x16x32_bf16 v[54:57], v[160:163], v[176:179], v[54:57]
	v_mfma_f32_16x16x32_bf16 v[50:53], v[168:171], v[176:179], v[50:53]
	v_mfma_f32_16x16x32_bf16 v[38:41], v[160:163], v[184:187], v[38:41]
	v_mfma_f32_16x16x32_bf16 v[34:37], v[168:171], v[184:187], v[34:37]
	v_mfma_f32_16x16x32_bf16 v[22:25], v[160:163], v[198:201], v[22:25]
	v_mfma_f32_16x16x32_bf16 v[18:21], v[168:171], v[198:201], v[18:21]
	v_mfma_f32_16x16x32_bf16 v[6:9], v[160:163], v[206:209], v[6:9]
	v_mfma_f32_16x16x32_bf16 v[2:5], v[168:171], v[206:209], v[2:5]
	v_mfma_f32_16x16x32_bf16 v[54:57], v[164:167], v[180:183], v[54:57]
	v_mfma_f32_16x16x32_bf16 v[50:53], v[172:175], v[180:183], v[50:53]
	v_mfma_f32_16x16x32_bf16 v[38:41], v[164:167], v[194:197], v[38:41]
	v_mfma_f32_16x16x32_bf16 v[34:37], v[172:175], v[194:197], v[34:37]
	v_mfma_f32_16x16x32_bf16 v[22:25], v[164:167], v[202:205], v[22:25]
	v_mfma_f32_16x16x32_bf16 v[18:21], v[172:175], v[202:205], v[18:21]
	v_mfma_f32_16x16x32_bf16 v[6:9], v[164:167], v[210:213], v[6:9]
	v_mfma_f32_16x16x32_bf16 v[2:5], v[172:175], v[210:213], v[2:5]
	s_setprio 0
	s_barrier
	s_add_i32 s53, 0, 0x18000
	s_add_i32 s62, 0, 0x1c000
	v_add_u32_e32 v156, s53, v149
	v_add_u32_e32 v172, s62, v149
	ds_read_b128 v[140:143], v156
	ds_read_b128 v[144:147], v156 offset:1024
	ds_read_b128 v[152:155], v156 offset:2048
	ds_read_b128 v[156:159], v156 offset:3072
	ds_read_b128 v[160:163], v172
	ds_read_b128 v[164:167], v172 offset:1024
	ds_read_b128 v[168:171], v172 offset:2048
	ds_read_b128 v[172:175], v172 offset:3072
	s_add_u32 s60, s60, 0x40000
	s_addc_u32 s61, s61, 0
	s_mov_b32 m0, s27
	v_lshl_add_u64 v[220:221], s[60:61], 0, v[130:131]
	ds_read_b128 v[176:179], v151 offset:32768
	ds_read_b128 v[180:183], v151 offset:33792
	ds_read_b128 v[184:187], v151 offset:34816
	ds_read_b128 v[194:197], v151 offset:35840
	ds_read_b128 v[198:201], v151 offset:36864
	ds_read_b128 v[202:205], v151 offset:37888
	ds_read_b128 v[206:209], v151 offset:38912
	ds_read_b128 v[210:213], v151 offset:39936
	global_load_lds_dwordx4 v[220:221], off
	v_lshl_add_u64 v[220:221], s[60:61], 0, v[132:133]
	s_mov_b32 m0, s28
	s_nop 0
	global_load_lds_dwordx4 v[220:221], off
	s_waitcnt vmcnt(8)
	s_waitcnt lgkmcnt(0)
	s_barrier
	s_setprio 1
	s_waitcnt lgkmcnt(0)
	v_mfma_f32_16x16x32_bf16 v[126:129], v[140:143], v[176:179], v[126:129]
	v_mfma_f32_16x16x32_bf16 v[122:125], v[152:155], v[176:179], v[122:125]
	v_mfma_f32_16x16x32_bf16 v[118:121], v[140:143], v[184:187], v[118:121]
	v_mfma_f32_16x16x32_bf16 v[110:113], v[152:155], v[184:187], v[110:113]
	v_mfma_f32_16x16x32_bf16 v[94:97], v[140:143], v[198:201], v[94:97]
	v_mfma_f32_16x16x32_bf16 v[90:93], v[152:155], v[198:201], v[90:93]
	v_mfma_f32_16x16x32_bf16 v[78:81], v[140:143], v[206:209], v[78:81]
	v_mfma_f32_16x16x32_bf16 v[74:77], v[152:155], v[206:209], v[74:77]
	v_mfma_f32_16x16x32_bf16 v[126:129], v[144:147], v[180:183], v[126:129]
	v_mfma_f32_16x16x32_bf16 v[122:125], v[156:159], v[180:183], v[122:125]
	v_mfma_f32_16x16x32_bf16 v[118:121], v[144:147], v[194:197], v[118:121]
	v_mfma_f32_16x16x32_bf16 v[110:113], v[156:159], v[194:197], v[110:113]
	v_mfma_f32_16x16x32_bf16 v[94:97], v[144:147], v[202:205], v[94:97]
	v_mfma_f32_16x16x32_bf16 v[90:93], v[156:159], v[202:205], v[90:93]
	v_mfma_f32_16x16x32_bf16 v[78:81], v[144:147], v[210:213], v[78:81]
	v_mfma_f32_16x16x32_bf16 v[74:77], v[156:159], v[210:213], v[74:77]


; #define PG8_STAGE(bufoff, gbase, voff) do { _Pragma("unroll") for (int _i = 0; _i < 2; ++_i) \
;         __builtin_amdgcn_global_load_lds((const unsigned*)((const char*)(gbase) + (voff)[_i]), (PG8_LAS unsigned*)(lds + (bufoff) + ldsw + _i * 8192), 16, 0, 0); } while (0)
; #define PG8_LDA(dst, b, h) do { _Pragma("unroll") for (int m = 0; m < 4; ++m) _Pragma("unroll") for (int k = 0; k < 2; ++k) dst[m][k] = *(const PG8_LAS bf16x8*)(lds + PG8_SA(b, h) + aoff + m * 2048 + k * 1024); } while (0)
; #define PG8_MMA(ai, bj, At, Bt) do { __builtin_amdgcn_s_setprio(1); _Pragma("unroll") for (int m = 0; m < 4; ++m) _Pragma("unroll") for (int n = 0; n < 2; ++n) _Pragma("unroll") for (int k = 0; k < 2; ++k) \
;         acc[ai][bj][m][n] = __builtin_amdgcn_mfma_f32_16x16x32_bf16(Bt[n][k], At[m][k], acc[ai][bj][m][n], 0, 0, 0); __builtin_amdgcn_s_setprio(0); } while (0)
; #define PG8_WAIT_V(n) asm volatile("s_waitcnt vmcnt(" #n ")" ::: "memory")
; #define PG8_WAIT_L(n) asm volatile("s_waitcnt lgkmcnt(" #n ")" ::: "memory")
; #define PG8_BAR __builtin_amdgcn_s_barrier()
; #define PG8_SCHED __builtin_amdgcn_sched_barrier(0)
; template <class Epi, class Sched, bool ALIGN_EPI = false, bool SP2 = false>
; __device__ __forceinline__ void gemm_phase(PG8_LAS unsigned char* lds, const Gemm g, const Sched& S, const Epi& E) {
;     ...
;             PG8_WAIT_V(8); PG8_WAIT_L(0); PG8_BAR; PG8_MMA(0, 0, At, B0); PG8_MMA(0, 1, At, B1); PG8_BAR; PG8_SCHED;
;             PG8_LDA(At, 1, 1); PG8_STAGE(PG8_SB(1, 0), b3, voffB); PG8_STAGE(PG8_SB(1, 1), b3 + hstep, voffB); PG8_STAGE(PG8_SA(1, 0), a3, voffA);
;             PG8_WAIT_V(8); PG8_WAIT_L(0); PG8_BAR; PG8_MMA(1, 0, At, B0); PG8_MMA(1, 1, At, B1); PG8_BAR; PG8_SCHED;
	v_mfma_f32_16x16x32_bf16 v[114:117], v[160:163], v[176:179], v[114:117]
	v_mfma_f32_16x16x32_bf16 v[106:109], v[168:171], v[176:179], v[106:109]
	v_mfma_f32_16x16x32_bf16 v[102:105], v[160:163], v[184:187], v[102:105]
	v_mfma_f32_16x16x32_bf16 v[98:101], v[168:171], v[184:187], v[98:101]
	v_mfma_f32_16x16x32_bf16 v[86:89], v[160:163], v[198:201], v[86:89]
	v_mfma_f32_16x16x32_bf16 v[82:85], v[168:171], v[198:201], v[82:85]
	v_mfma_f32_16x16x32_bf16 v[70:73], v[160:163], v[206:209], v[70:73]
	v_mfma_f32_16x16x32_bf16 v[66:69], v[168:171], v[206:209], v[66:69]
	v_mfma_f32_16x16x32_bf16 v[114:117], v[164:167], v[180:183], v[114:117]
	v_mfma_f32_16x16x32_bf16 v[106:109], v[172:175], v[180:183], v[106:109]
	v_mfma_f32_16x16x32_bf16 v[102:105], v[164:167], v[194:197], v[102:105]
	v_mfma_f32_16x16x32_bf16 v[98:101], v[172:175], v[194:197], v[98:101]
	v_mfma_f32_16x16x32_bf16 v[86:89], v[164:167], v[202:205], v[86:89]
	v_mfma_f32_16x16x32_bf16 v[82:85], v[172:175], v[202:205], v[82:85]
	v_mfma_f32_16x16x32_bf16 v[70:73], v[164:167], v[210:213], v[70:73]
	v_mfma_f32_16x16x32_bf16 v[66:69], v[172:175], v[210:213], v[66:69]
	s_setprio 0
	s_barrier
	s_add_i32 s53, s53, s24
	v_lshl_add_u64 v[188:189], v[188:189], 0, s[8:9]
	s_mov_b32 m0, s53
	ds_read_b128 v[176:179], v151 offset:49152
	ds_read_b128 v[180:183], v151 offset:50176
	ds_read_b128 v[184:187], v151 offset:51200
	ds_read_b128 v[194:197], v151 offset:52224
	ds_read_b128 v[198:201], v151 offset:53248
	ds_read_b128 v[202:205], v151 offset:54272
	ds_read_b128 v[206:209], v151 offset:55296
	ds_read_b128 v[210:213], v151 offset:56320
	global_load_lds_dwordx4 v[188:189], off
	s_add_i32 m0, s53, 0x2000
	s_add_u32 s58, s58, 0x40080
	v_lshl_add_u64 v[188:189], v[214:215], 0, s[8:9]
	s_addc_u32 s59, s59, 0
	s_add_i32 s53, s62, s24
	global_load_lds_dwordx4 v[188:189], off
	v_lshl_add_u64 v[188:189], s[58:59], 0, v[0:1]
	s_mov_b32 m0, s53
	s_nop 0
	global_load_lds_dwordx4 v[188:189], off
	v_lshl_add_u64 v[188:189], s[58:59], 0, v[134:135]
	s_add_i32 m0, s53, 0x2000
	s_nop 0
	global_load_lds_dwordx4 v[188:189], off
	v_lshl_add_u64 v[188:189], v[216:217], 0, s[8:9]
	s_mov_b32 m0, s29
	s_nop 0
	global_load_lds_dwordx4 v[188:189], off
	v_lshl_add_u64 v[188:189], v[218:219], 0, s[8:9]
	s_mov_b32 m0, s55
	s_nop 0
	global_load_lds_dwordx4 v[188:189], off
	s_waitcnt vmcnt(8)
	s_waitcnt lgkmcnt(0)
	s_barrier
	s_setprio 1
	s_waitcnt lgkmcnt(0)
	v_mfma_f32_16x16x32_bf16 v[62:65], v[140:143], v[176:179], v[62:65]
	v_mfma_f32_16x16x32_bf16 v[58:61], v[152:155], v[176:179], v[58:61]
	v_mfma_f32_16x16x32_bf16 v[46:49], v[140:143], v[184:187], v[46:49]
	v_mfma_f32_16x16x32_bf16 v[42:45], v[152:155], v[184:187], v[42:45]
	v_mfma_f32_16x16x32_bf16 v[30:33], v[140:143], v[198:201], v[30:33]
	v_mfma_f32_16x16x32_bf16 v[26:29], v[152:155], v[198:201], v[26:29]
	v_mfma_f32_16x16x32_bf16 v[14:17], v[140:143], v[206:209], v[14:17]
	v_mfma_f32_16x16x32_bf16 v[10:13], v[152:155], v[206:209], v[10:13]
	v_mfma_f32_16x16x32_bf16 v[62:65], v[144:147], v[180:183], v[62:65]
	v_mfma_f32_16x16x32_bf16 v[58:61], v[156:159], v[180:183], v[58:61]
	v_mfma_f32_16x16x32_bf16 v[46:49], v[144:147], v[194:197], v[46:49]
	v_mfma_f32_16x16x32_bf16 v[42:45], v[156:159], v[194:197], v[42:45]
	v_mfma_f32_16x16x32_bf16 v[30:33], v[144:147], v[202:205], v[30:33]
	v_mfma_f32_16x16x32_bf16 v[26:29], v[156:159], v[202:205], v[26:29]
	v_mfma_f32_16x16x32_bf16 v[14:17], v[144:147], v[210:213], v[14:17]
	v_mfma_f32_16x16x32_bf16 v[10:13], v[156:159], v[210:213], v[10:13]


; template <class Epi, class Sched, bool ALIGN_EPI = false, bool SP2 = false>
; __device__ __forceinline__ void gemm_phase(PG8_LAS unsigned char* lds, const Gemm g, const Sched& S, const Epi& E) {
;     ...
;         for (int t = 0; t < nt; t += 2) {
;             const bool last = (t == nt - 2);
;             const char* a1 = cA + (size_t)(t + 1) * kstep;
;             const char* a2 = last ? nA : cA + (size_t)(t + 2) * kstep; const char* b2 = last ? nB : cB + (size_t)(t + 2) * kstep;
	v_mfma_f32_16x16x32_bf16 v[54:57], v[160:163], v[176:179], v[54:57]
	v_mfma_f32_16x16x32_bf16 v[50:53], v[168:171], v[176:179], v[50:53]
	v_mfma_f32_16x16x32_bf16 v[38:41], v[160:163], v[184:187], v[38:41]
	v_mfma_f32_16x16x32_bf16 v[34:37], v[168:171], v[184:187], v[34:37]
	v_mfma_f32_16x16x32_bf16 v[22:25], v[160:163], v[198:201], v[22:25]
	v_mfma_f32_16x16x32_bf16 v[18:21], v[168:171], v[198:201], v[18:21]
	v_mfma_f32_16x16x32_bf16 v[6:9], v[160:163], v[206:209], v[6:9]
	v_mfma_f32_16x16x32_bf16 v[2:5], v[168:171], v[206:209], v[2:5]
	v_mfma_f32_16x16x32_bf16 v[54:57], v[164:167], v[180:183], v[54:57]
	v_mfma_f32_16x16x32_bf16 v[50:53], v[172:175], v[180:183], v[50:53]
	v_mfma_f32_16x16x32_bf16 v[38:41], v[164:167], v[194:197], v[38:41]
	v_mfma_f32_16x16x32_bf16 v[34:37], v[172:175], v[194:197], v[34:37]
	v_mfma_f32_16x16x32_bf16 v[22:25], v[164:167], v[202:205], v[22:25]
	v_mfma_f32_16x16x32_bf16 v[18:21], v[172:175], v[202:205], v[18:21]
	v_mfma_f32_16x16x32_bf16 v[6:9], v[164:167], v[210:213], v[6:9]
	v_mfma_f32_16x16x32_bf16 v[2:5], v[172:175], v[210:213], v[2:5]
	s_setprio 0
	s_barrier
	s_add_i32 s52, s52, 2
	s_add_u32 s18, s18, 0x100
	s_addc_u32 s19, s19, 0
	s_add_u32 s43, s43, 0x100
	s_addc_u32 s45, s45, 0
	s_cmp_gt_u32 s52, 13
	s_cbranch_scc0 .LBB0_522



; template <class Epi, class Sched, bool ALIGN_EPI = false, bool SP2 = false>
; __device__ __forceinline__ void gemm_phase(PG8_LAS unsigned char* lds, const Gemm g, const Sched& S, const Epi& E) {
;     ...
;         const bool has_next = S.next(ui + 1, nxt);
;         const char* nA = has_next ? (const char*)g.A + (size_t)nxt.pm * tstep : cA; const char* nB = has_next ? (const char*)g.Bt + (size_t)nxt.pn * tstep : cB;
;         for (int t = 0; t < nt; t += 2) {
;             const bool last = (t == nt - 2);
;             const char* a1 = cA + (size_t)(t + 1) * kstep;
;             const char* a2 = last ? nA : cA + (size_t)(t + 2) * kstep; const char* b2 = last ? nB : cB + (size_t)(t + 2) * kstep;
.LBB0_556:
	s_ashr_i32 s43, s42, 31
	s_lshl_b64 s[30:31], s[42:43], 19
	s_add_u32 s46, s96, s30
	s_addc_u32 s47, s97, s31
	s_and_b64 s[30:31], s[44:45], exec
	s_cselect_b32 s30, s47, s19
	s_cselect_b32 s31, s46, s18
	s_ashr_i32 s41, s40, 31
	s_lshl_b64 s[34:35], s[40:41], 19
	s_add_u32 s48, s24, s34
	s_addc_u32 s49, s25, s35
	s_and_b64 s[34:35], s[44:45], exec
	s_cselect_b32 s34, s49, s57
	s_cselect_b32 s35, s48, s56
	s_add_u32 s18, s18, 0x40080
	s_addc_u32 s19, s19, 0
	s_add_u32 s41, s56, 0x100

; template <class Epi, class Sched, bool ALIGN_EPI = false, bool SP2 = false>
; __device__ __forceinline__ void gemm_phase(PG8_LAS unsigned char* lds, const Gemm g, const Sched& S, const Epi& E) {
;     ...
;         const bool has_next = S.next(ui + 1, nxt);
;         const char* nA = has_next ? (const char*)g.A + (size_t)nxt.pm * tstep : cA; const char* nB = has_next ? (const char*)g.Bt + (size_t)nxt.pn * tstep : cB;
;         for (int t = 0; t < nt; t += 2) {
;             const bool last = (t == nt - 2);
;             const char* a1 = cA + (size_t)(t + 1) * kstep;
;             const char* a2 = last ? nA : cA + (size_t)(t + 2) * kstep; const char* b2 = last ? nB : cB + (size_t)(t + 2) * kstep;
	s_addc_u32 s43, s57, 0
	s_mov_b32 s52, -2


; #define PG8_STAGE(bufoff, gbase, voff) do { _Pragma("unroll") for (int _i = 0; _i < 2; ++_i) \
;         __builtin_amdgcn_global_load_lds((const unsigned*)((const char*)(gbase) + (voff)[_i]), (PG8_LAS unsigned*)(lds + (bufoff) + ldsw + _i * 8192), 16, 0, 0); } while (0)
; #define PG8_LDA(dst, b, h) do { _Pragma("unroll") for (int m = 0; m < 4; ++m) _Pragma("unroll") for (int k = 0; k < 2; ++k) dst[m][k] = *(const PG8_LAS bf16x8*)(lds + PG8_SA(b, h) + aoff + m * 2048 + k * 1024); } while (0)
; #define PG8_LDB(dst, b, h) do { _Pragma("unroll") for (int n = 0; n < 2; ++n) _Pragma("unroll") for (int k = 0; k < 2; ++k) dst[n][k] = *(const PG8_LAS bf16x8*)(lds + PG8_SB(b, h) + boff + n * 2048 + k * 1024); } while (0)
; #define PG8_MMA(ai, bj, At, Bt) do { __builtin_amdgcn_s_setprio(1); _Pragma("unroll") for (int m = 0; m < 4; ++m) _Pragma("unroll") for (int n = 0; n < 2; ++n) _Pragma("unroll") for (int k = 0; k < 2; ++k) \
;         acc[ai][bj][m][n] = __builtin_amdgcn_mfma_f32_16x16x32_bf16(Bt[n][k], At[m][k], acc[ai][bj][m][n], 0, 0, 0); __builtin_amdgcn_s_setprio(0); } while (0)
; #define PG8_WAIT_V(n) asm volatile("s_waitcnt vmcnt(" #n ")" ::: "memory")
; #define PG8_WAIT_L(n) asm volatile("s_waitcnt lgkmcnt(" #n ")" ::: "memory")
; #define PG8_BAR __builtin_amdgcn_s_barrier()
; #define PG8_SCHED __builtin_amdgcn_sched_barrier(0)
; template <class Epi, class Sched, bool ALIGN_EPI = false, bool SP2 = false>
; __device__ __forceinline__ void gemm_phase(PG8_LAS unsigned char* lds, const Gemm g, const Sched& S, const Epi& E) {
;     ...
;             const bool last = (t == nt - 2);
;             const char* a1 = cA + (size_t)(t + 1) * kstep;
;             const char* a2 = last ? nA : cA + (size_t)(t + 2) * kstep; const char* b2 = last ? nB : cB + (size_t)(t + 2) * kstep;
;             const char* a3 = a2 + kstep; const char* b3 = b2 + kstep;
;             if (last && has_next) S.a_ready(nxt);
;             if constexpr (SP2) {
;             PG8_LDB(B0, 0, 0); PG8_LDB(B1, 0, 1); PG8_SCHED; PG8_LDA(At, 0, 0); PG8_STAGE(PG8_SA(1, 1), a1 + hstep, voffA);
;             PG8_WAIT_V(8); PG8_WAIT_L(0); PG8_BAR; PG8_MMA(0, 0, At, B0); PG8_MMA(0, 1, At, B1); PG8_BAR; PG8_SCHED;
	s_add_u32 s53, s18, 0xfffc0080
	s_addc_u32 s56, s19, -1
	s_add_i32 s60, 0, 0x10000
	s_cmp_eq_u32 s52, 12
	s_cselect_b32 s59, s30, s56
	s_cselect_b32 s58, s31, s53
	s_cselect_b32 s57, s34, s43
	s_cselect_b32 s56, s35, s41
	s_add_i32 s53, 0, 0x14000
	v_add_u32_e32 v152, s60, v161
	v_add_u32_e32 v172, s53, v161
	ds_read_b128 v[140:143], v152
	ds_read_b128 v[144:147], v152 offset:1024
	ds_read_b128 v[148:151], v152 offset:2048
	ds_read_b128 v[152:155], v152 offset:3072
	ds_read_b128 v[156:159], v172
	ds_read_b128 v[164:167], v172 offset:1024
	ds_read_b128 v[168:171], v172 offset:2048
	ds_read_b128 v[172:175], v172 offset:3072
	v_lshl_add_u64 v[188:189], s[18:19], 0, v[136:137]
	s_add_i32 m0, s26, 0xc000
	ds_read_b128 v[176:179], v163
	ds_read_b128 v[180:183], v163 offset:1024
	ds_read_b128 v[184:187], v163 offset:2048
	ds_read_b128 v[194:197], v163 offset:3072
	ds_read_b128 v[198:201], v163 offset:4096
	ds_read_b128 v[202:205], v163 offset:5120
	ds_read_b128 v[206:209], v163 offset:6144
	ds_read_b128 v[210:213], v163 offset:7168
	global_load_lds_dwordx4 v[188:189], off
	v_lshl_add_u64 v[188:189], s[18:19], 0, v[138:139]
	s_add_i32 m0, s26, 0xe000
	s_nop 0
	global_load_lds_dwordx4 v[188:189], off
	s_waitcnt vmcnt(8)
	s_waitcnt lgkmcnt(0)
	s_barrier
	s_setprio 1
	s_waitcnt lgkmcnt(0)
	v_mfma_f32_16x16x32_bf16 v[126:129], v[140:143], v[176:179], 0
	v_mfma_f32_16x16x32_bf16 v[122:125], v[148:151], v[176:179], 0
	v_mfma_f32_16x16x32_bf16 v[118:121], v[140:143], v[184:187], 0
	v_mfma_f32_16x16x32_bf16 v[106:109], v[148:151], v[184:187], 0
	v_mfma_f32_16x16x32_bf16 v[94:97], v[140:143], v[198:201], 0
	v_mfma_f32_16x16x32_bf16 v[90:93], v[148:151], v[198:201], 0
	v_mfma_f32_16x16x32_bf16 v[78:81], v[140:143], v[206:209], 0
	v_mfma_f32_16x16x32_bf16 v[74:77], v[148:151], v[206:209], 0
	v_mfma_f32_16x16x32_bf16 v[126:129], v[144:147], v[180:183], v[126:129]
	v_mfma_f32_16x16x32_bf16 v[122:125], v[152:155], v[180:183], v[122:125]
	v_mfma_f32_16x16x32_bf16 v[118:121], v[144:147], v[194:197], v[118:121]
	v_mfma_f32_16x16x32_bf16 v[106:109], v[152:155], v[194:197], v[106:109]
	v_mfma_f32_16x16x32_bf16 v[94:97], v[144:147], v[202:205], v[94:97]
	v_mfma_f32_16x16x32_bf16 v[90:93], v[152:155], v[202:205], v[90:93]
	v_mfma_f32_16x16x32_bf16 v[78:81], v[144:147], v[210:213], v[78:81]
	v_mfma_f32_16x16x32_bf16 v[74:77], v[152:155], v[210:213], v[74:77]


; #define PG8_STAGE(bufoff, gbase, voff) do { _Pragma("unroll") for (int _i = 0; _i < 2; ++_i) \
;         __builtin_amdgcn_global_load_lds((const unsigned*)((const char*)(gbase) + (voff)[_i]), (PG8_LAS unsigned*)(lds + (bufoff) + ldsw + _i * 8192), 16, 0, 0); } while (0)
; #define PG8_LDA(dst, b, h) do { _Pragma("unroll") for (int m = 0; m < 4; ++m) _Pragma("unroll") for (int k = 0; k < 2; ++k) dst[m][k] = *(const PG8_LAS bf16x8*)(lds + PG8_SA(b, h) + aoff + m * 2048 + k * 1024); } while (0)
; #define PG8_MMA(ai, bj, At, Bt) do { __builtin_amdgcn_s_setprio(1); _Pragma("unroll") for (int m = 0; m < 4; ++m) _Pragma("unroll") for (int n = 0; n < 2; ++n) _Pragma("unroll") for (int k = 0; k < 2; ++k) \
;         acc[ai][bj][m][n] = __builtin_amdgcn_mfma_f32_16x16x32_bf16(Bt[n][k], At[m][k], acc[ai][bj][m][n], 0, 0, 0); __builtin_amdgcn_s_setprio(0); } while (0)
; #define PG8_WAIT_V(n) asm volatile("s_waitcnt vmcnt(" #n ")" ::: "memory")
; #define PG8_WAIT_L(n) asm volatile("s_waitcnt lgkmcnt(" #n ")" ::: "memory")
; #define PG8_BAR __builtin_amdgcn_s_barrier()
; #define PG8_SCHED __builtin_amdgcn_sched_barrier(0)
; template <class Epi, class Sched, bool ALIGN_EPI = false, bool SP2 = false>
; __device__ __forceinline__ void gemm_phase(PG8_LAS unsigned char* lds, const Gemm g, const Sched& S, const Epi& E) {
;     ...
;             PG8_WAIT_V(8); PG8_WAIT_L(0); PG8_BAR; PG8_MMA(0, 0, At, B0); PG8_MMA(0, 1, At, B1); PG8_BAR; PG8_SCHED;
;             PG8_LDA(At, 0, 1); PG8_STAGE(PG8_SB(0, 0), b2, voffB); PG8_STAGE(PG8_SB(0, 1), b2 + hstep, voffB); PG8_STAGE(PG8_SA(0, 0), a2, voffA);
;             PG8_WAIT_V(8); PG8_WAIT_L(0); PG8_BAR; PG8_MMA(1, 0, At, B0); PG8_MMA(1, 1, At, B1); PG8_BAR; PG8_SCHED;
	v_mfma_f32_16x16x32_bf16 v[114:117], v[156:159], v[176:179], 0
	v_mfma_f32_16x16x32_bf16 v[110:113], v[168:171], v[176:179], 0
	v_mfma_f32_16x16x32_bf16 v[102:105], v[156:159], v[184:187], 0
	v_mfma_f32_16x16x32_bf16 v[98:101], v[168:171], v[184:187], 0
	v_mfma_f32_16x16x32_bf16 v[86:89], v[156:159], v[198:201], 0
	v_mfma_f32_16x16x32_bf16 v[82:85], v[168:171], v[198:201], 0
	v_mfma_f32_16x16x32_bf16 v[70:73], v[156:159], v[206:209], 0
	v_mfma_f32_16x16x32_bf16 v[66:69], v[168:171], v[206:209], 0
	v_mfma_f32_16x16x32_bf16 v[114:117], v[164:167], v[180:183], v[114:117]
	v_mfma_f32_16x16x32_bf16 v[110:113], v[172:175], v[180:183], v[110:113]
	v_mfma_f32_16x16x32_bf16 v[102:105], v[164:167], v[194:197], v[102:105]
	v_mfma_f32_16x16x32_bf16 v[98:101], v[172:175], v[194:197], v[98:101]
	v_mfma_f32_16x16x32_bf16 v[86:89], v[164:167], v[202:205], v[86:89]
	v_mfma_f32_16x16x32_bf16 v[82:85], v[172:175], v[202:205], v[82:85]
	v_mfma_f32_16x16x32_bf16 v[70:73], v[164:167], v[210:213], v[70:73]
	v_mfma_f32_16x16x32_bf16 v[66:69], v[172:175], v[210:213], v[66:69]
	s_setprio 0
	s_barrier
	s_add_i32 s60, s60, s23
	v_lshl_add_u64 v[188:189], s[56:57], 0, v[0:1]
	s_mov_b32 m0, s60
	ds_read_b128 v[176:179], v163 offset:16384
	ds_read_b128 v[180:183], v163 offset:17408
	ds_read_b128 v[184:187], v163 offset:18432
	ds_read_b128 v[194:197], v163 offset:19456
	ds_read_b128 v[198:201], v163 offset:20480
	ds_read_b128 v[202:205], v163 offset:21504
	ds_read_b128 v[206:209], v163 offset:22528
	ds_read_b128 v[210:213], v163 offset:23552
	global_load_lds_dwordx4 v[188:189], off
	s_add_i32 m0, s60, 0x2000
	s_add_u32 s60, s56, 0x40000
	v_lshl_add_u64 v[214:215], s[56:57], 0, v[134:135]
	s_addc_u32 s61, s57, 0
	s_add_i32 s53, s53, s23
	global_load_lds_dwordx4 v[214:215], off
	v_lshl_add_u64 v[216:217], s[60:61], 0, v[0:1]
	s_mov_b32 m0, s53
	v_lshl_add_u64 v[218:219], s[58:59], 0, v[132:133]
	global_load_lds_dwordx4 v[216:217], off
	v_lshl_add_u64 v[216:217], s[60:61], 0, v[134:135]
	s_add_i32 m0, s53, 0x2000
	s_nop 0
	global_load_lds_dwordx4 v[216:217], off
	v_lshl_add_u64 v[216:217], s[58:59], 0, v[130:131]
	s_mov_b32 m0, s26
	s_nop 0
	global_load_lds_dwordx4 v[216:217], off
	s_mov_b32 m0, s27
	s_nop 0
	global_load_lds_dwordx4 v[218:219], off
	s_waitcnt vmcnt(8)
	s_waitcnt lgkmcnt(0)
	s_barrier
	s_setprio 1
	s_waitcnt lgkmcnt(0)
	v_mfma_f32_16x16x32_bf16 v[62:65], v[140:143], v[176:179], 0
	v_mfma_f32_16x16x32_bf16 v[58:61], v[148:151], v[176:179], 0
	v_mfma_f32_16x16x32_bf16 v[46:49], v[140:143], v[184:187], 0
	v_mfma_f32_16x16x32_bf16 v[42:45], v[148:151], v[184:187], 0
	v_mfma_f32_16x16x32_bf16 v[30:33], v[140:143], v[198:201], 0
	v_mfma_f32_16x16x32_bf16 v[26:29], v[148:151], v[198:201], 0
	v_mfma_f32_16x16x32_bf16 v[14:17], v[140:143], v[206:209], 0
	v_mfma_f32_16x16x32_bf16 v[10:13], v[148:151], v[206:209], 0
	v_mfma_f32_16x16x32_bf16 v[62:65], v[144:147], v[180:183], v[62:65]
	v_mfma_f32_16x16x32_bf16 v[58:61], v[152:155], v[180:183], v[58:61]
	v_mfma_f32_16x16x32_bf16 v[46:49], v[144:147], v[194:197], v[46:49]
	v_mfma_f32_16x16x32_bf16 v[42:45], v[152:155], v[194:197], v[42:45]
	v_mfma_f32_16x16x32_bf16 v[30:33], v[144:147], v[202:205], v[30:33]
	v_mfma_f32_16x16x32_bf16 v[26:29], v[152:155], v[202:205], v[26:29]
	v_mfma_f32_16x16x32_bf16 v[14:17], v[144:147], v[210:213], v[14:17]
	v_mfma_f32_16x16x32_bf16 v[10:13], v[152:155], v[210:213], v[10:13]


; #define PG8_STAGE(bufoff, gbase, voff) do { _Pragma("unroll") for (int _i = 0; _i < 2; ++_i) \
;         __builtin_amdgcn_global_load_lds((const unsigned*)((const char*)(gbase) + (voff)[_i]), (PG8_LAS unsigned*)(lds + (bufoff) + ldsw + _i * 8192), 16, 0, 0); } while (0)
; #define PG8_LDA(dst, b, h) do { _Pragma("unroll") for (int m = 0; m < 4; ++m) _Pragma("unroll") for (int k = 0; k < 2; ++k) dst[m][k] = *(const PG8_LAS bf16x8*)(lds + PG8_SA(b, h) + aoff + m * 2048 + k * 1024); } while (0)
; #define PG8_LDB(dst, b, h) do { _Pragma("unroll") for (int n = 0; n < 2; ++n) _Pragma("unroll") for (int k = 0; k < 2; ++k) dst[n][k] = *(const PG8_LAS bf16x8*)(lds + PG8_SB(b, h) + boff + n * 2048 + k * 1024); } while (0)
; #define PG8_MMA(ai, bj, At, Bt) do { __builtin_amdgcn_s_setprio(1); _Pragma("unroll") for (int m = 0; m < 4; ++m) _Pragma("unroll") for (int n = 0; n < 2; ++n) _Pragma("unroll") for (int k = 0; k < 2; ++k) \
;         acc[ai][bj][m][n] = __builtin_amdgcn_mfma_f32_16x16x32_bf16(Bt[n][k], At[m][k], acc[ai][bj][m][n], 0, 0, 0); __builtin_amdgcn_s_setprio(0); } while (0)
; #define PG8_WAIT_V(n) asm volatile("s_waitcnt vmcnt(" #n ")" ::: "memory")
; #define PG8_WAIT_L(n) asm volatile("s_waitcnt lgkmcnt(" #n ")" ::: "memory")
; #define PG8_BAR __builtin_amdgcn_s_barrier()
; #define PG8_SCHED __builtin_amdgcn_sched_barrier(0)
; template <class Epi, class Sched, bool ALIGN_EPI = false, bool SP2 = false>
; __device__ __forceinline__ void gemm_phase(PG8_LAS unsigned char* lds, const Gemm g, const Sched& S, const Epi& E) {
;     ...
;             PG8_WAIT_V(8); PG8_WAIT_L(0); PG8_BAR; PG8_MMA(1, 0, At, B0); PG8_MMA(1, 1, At, B1); PG8_BAR; PG8_SCHED;
;             PG8_LDB(B0, 1, 0); PG8_LDB(B1, 1, 1); PG8_SCHED; PG8_LDA(At, 1, 0); PG8_STAGE(PG8_SA(0, 1), a2 + hstep, voffA);
;             PG8_WAIT_V(8); PG8_WAIT_L(0); PG8_BAR; PG8_MMA(0, 0, At, B0); PG8_MMA(0, 1, At, B1); PG8_BAR; PG8_SCHED;
	v_mfma_f32_16x16x32_bf16 v[54:57], v[156:159], v[176:179], 0
	v_mfma_f32_16x16x32_bf16 v[50:53], v[168:171], v[176:179], 0
	v_mfma_f32_16x16x32_bf16 v[38:41], v[156:159], v[184:187], 0
	v_mfma_f32_16x16x32_bf16 v[34:37], v[168:171], v[184:187], 0
	v_mfma_f32_16x16x32_bf16 v[22:25], v[156:159], v[198:201], 0
	v_mfma_f32_16x16x32_bf16 v[18:21], v[168:171], v[198:201], 0
	v_mfma_f32_16x16x32_bf16 v[6:9], v[156:159], v[206:209], 0
	v_mfma_f32_16x16x32_bf16 v[2:5], v[168:171], v[206:209], 0
	v_mfma_f32_16x16x32_bf16 v[54:57], v[164:167], v[180:183], v[54:57]
	v_mfma_f32_16x16x32_bf16 v[50:53], v[172:175], v[180:183], v[50:53]
	v_mfma_f32_16x16x32_bf16 v[38:41], v[164:167], v[194:197], v[38:41]
	v_mfma_f32_16x16x32_bf16 v[34:37], v[172:175], v[194:197], v[34:37]
	v_mfma_f32_16x16x32_bf16 v[22:25], v[164:167], v[202:205], v[22:25]
	v_mfma_f32_16x16x32_bf16 v[18:21], v[172:175], v[202:205], v[18:21]
	v_mfma_f32_16x16x32_bf16 v[6:9], v[164:167], v[210:213], v[6:9]
	v_mfma_f32_16x16x32_bf16 v[2:5], v[172:175], v[210:213], v[2:5]
	s_setprio 0
	s_barrier
	s_add_i32 s53, 0, 0x18000
	s_add_i32 s60, 0, 0x1c000
	v_add_u32_e32 v152, s53, v161
	v_add_u32_e32 v172, s60, v161
	ds_read_b128 v[140:143], v152
	ds_read_b128 v[144:147], v152 offset:1024
	ds_read_b128 v[148:151], v152 offset:2048
	ds_read_b128 v[152:155], v152 offset:3072
	ds_read_b128 v[156:159], v172
	ds_read_b128 v[164:167], v172 offset:1024
	ds_read_b128 v[168:171], v172 offset:2048
	ds_read_b128 v[172:175], v172 offset:3072
	s_add_u32 s58, s58, 0x40000
	s_addc_u32 s59, s59, 0
	s_mov_b32 m0, s28
	v_lshl_add_u64 v[220:221], s[58:59], 0, v[130:131]
	ds_read_b128 v[176:179], v163 offset:32768
	ds_read_b128 v[180:183], v163 offset:33792
	ds_read_b128 v[184:187], v163 offset:34816
	ds_read_b128 v[194:197], v163 offset:35840
	ds_read_b128 v[198:201], v163 offset:36864
	ds_read_b128 v[202:205], v163 offset:37888
	ds_read_b128 v[206:209], v163 offset:38912
	ds_read_b128 v[210:213], v163 offset:39936
	global_load_lds_dwordx4 v[220:221], off
	v_lshl_add_u64 v[220:221], s[58:59], 0, v[132:133]
	s_mov_b32 m0, s29
	s_nop 0
	global_load_lds_dwordx4 v[220:221], off
	s_waitcnt vmcnt(8)
	s_waitcnt lgkmcnt(0)
	s_barrier
	s_setprio 1
	s_waitcnt lgkmcnt(0)
	v_mfma_f32_16x16x32_bf16 v[126:129], v[140:143], v[176:179], v[126:129]
	v_mfma_f32_16x16x32_bf16 v[122:125], v[148:151], v[176:179], v[122:125]
	v_mfma_f32_16x16x32_bf16 v[118:121], v[140:143], v[184:187], v[118:121]
	v_mfma_f32_16x16x32_bf16 v[106:109], v[148:151], v[184:187], v[106:109]
	v_mfma_f32_16x16x32_bf16 v[94:97], v[140:143], v[198:201], v[94:97]
	v_mfma_f32_16x16x32_bf16 v[90:93], v[148:151], v[198:201], v[90:93]
	v_mfma_f32_16x16x32_bf16 v[78:81], v[140:143], v[206:209], v[78:81]
	v_mfma_f32_16x16x32_bf16 v[74:77], v[148:151], v[206:209], v[74:77]
	v_mfma_f32_16x16x32_bf16 v[126:129], v[144:147], v[180:183], v[126:129]
	v_mfma_f32_16x16x32_bf16 v[122:125], v[152:155], v[180:183], v[122:125]
	v_mfma_f32_16x16x32_bf16 v[118:121], v[144:147], v[194:197], v[118:121]
	v_mfma_f32_16x16x32_bf16 v[106:109], v[152:155], v[194:197], v[106:109]
	v_mfma_f32_16x16x32_bf16 v[94:97], v[144:147], v[202:205], v[94:97]
	v_mfma_f32_16x16x32_bf16 v[90:93], v[152:155], v[202:205], v[90:93]
	v_mfma_f32_16x16x32_bf16 v[78:81], v[144:147], v[210:213], v[78:81]
	v_mfma_f32_16x16x32_bf16 v[74:77], v[152:155], v[210:213], v[74:77]


; #define PG8_STAGE(bufoff, gbase, voff) do { _Pragma("unroll") for (int _i = 0; _i < 2; ++_i) \
;         __builtin_amdgcn_global_load_lds((const unsigned*)((const char*)(gbase) + (voff)[_i]), (PG8_LAS unsigned*)(lds + (bufoff) + ldsw + _i * 8192), 16, 0, 0); } while (0)
; #define PG8_LDA(dst, b, h) do { _Pragma("unroll") for (int m = 0; m < 4; ++m) _Pragma("unroll") for (int k = 0; k < 2; ++k) dst[m][k] = *(const PG8_LAS bf16x8*)(lds + PG8_SA(b, h) + aoff + m * 2048 + k * 1024); } while (0)
; #define PG8_MMA(ai, bj, At, Bt) do { __builtin_amdgcn_s_setprio(1); _Pragma("unroll") for (int m = 0; m < 4; ++m) _Pragma("unroll") for (int n = 0; n < 2; ++n) _Pragma("unroll") for (int k = 0; k < 2; ++k) \
;         acc[ai][bj][m][n] = __builtin_amdgcn_mfma_f32_16x16x32_bf16(Bt[n][k], At[m][k], acc[ai][bj][m][n], 0, 0, 0); __builtin_amdgcn_s_setprio(0); } while (0)
; #define PG8_WAIT_V(n) asm volatile("s_waitcnt vmcnt(" #n ")" ::: "memory")
; #define PG8_WAIT_L(n) asm volatile("s_waitcnt lgkmcnt(" #n ")" ::: "memory")
; #define PG8_BAR __builtin_amdgcn_s_barrier()
; #define PG8_SCHED __builtin_amdgcn_sched_barrier(0)
; template <class Epi, class Sched, bool ALIGN_EPI = false, bool SP2 = false>
; __device__ __forceinline__ void gemm_phase(PG8_LAS unsigned char* lds, const Gemm g, const Sched& S, const Epi& E) {
;     ...
;             PG8_WAIT_V(8); PG8_WAIT_L(0); PG8_BAR; PG8_MMA(0, 0, At, B0); PG8_MMA(0, 1, At, B1); PG8_BAR; PG8_SCHED;
;             PG8_LDA(At, 1, 1); PG8_STAGE(PG8_SB(1, 0), b3, voffB); PG8_STAGE(PG8_SB(1, 1), b3 + hstep, voffB); PG8_STAGE(PG8_SA(1, 0), a3, voffA);
;             PG8_WAIT_V(8); PG8_WAIT_L(0); PG8_BAR; PG8_MMA(1, 0, At, B0); PG8_MMA(1, 1, At, B1); PG8_BAR; PG8_SCHED;
	v_mfma_f32_16x16x32_bf16 v[114:117], v[156:159], v[176:179], v[114:117]
	v_mfma_f32_16x16x32_bf16 v[110:113], v[168:171], v[176:179], v[110:113]
	v_mfma_f32_16x16x32_bf16 v[102:105], v[156:159], v[184:187], v[102:105]
	v_mfma_f32_16x16x32_bf16 v[98:101], v[168:171], v[184:187], v[98:101]
	v_mfma_f32_16x16x32_bf16 v[86:89], v[156:159], v[198:201], v[86:89]
	v_mfma_f32_16x16x32_bf16 v[82:85], v[168:171], v[198:201], v[82:85]
	v_mfma_f32_16x16x32_bf16 v[70:73], v[156:159], v[206:209], v[70:73]
	v_mfma_f32_16x16x32_bf16 v[66:69], v[168:171], v[206:209], v[66:69]
	v_mfma_f32_16x16x32_bf16 v[114:117], v[164:167], v[180:183], v[114:117]
	v_mfma_f32_16x16x32_bf16 v[110:113], v[172:175], v[180:183], v[110:113]
	v_mfma_f32_16x16x32_bf16 v[102:105], v[164:167], v[194:197], v[102:105]
	v_mfma_f32_16x16x32_bf16 v[98:101], v[172:175], v[194:197], v[98:101]
	v_mfma_f32_16x16x32_bf16 v[86:89], v[164:167], v[202:205], v[86:89]
	v_mfma_f32_16x16x32_bf16 v[82:85], v[172:175], v[202:205], v[82:85]
	v_mfma_f32_16x16x32_bf16 v[70:73], v[164:167], v[210:213], v[70:73]
	v_mfma_f32_16x16x32_bf16 v[66:69], v[172:175], v[210:213], v[66:69]
	s_setprio 0
	s_barrier
	s_add_i32 s53, s53, s23
	v_lshl_add_u64 v[188:189], v[188:189], 0, s[8:9]
	s_mov_b32 m0, s53
	ds_read_b128 v[176:179], v163 offset:49152
	ds_read_b128 v[180:183], v163 offset:50176
	ds_read_b128 v[184:187], v163 offset:51200
	ds_read_b128 v[194:197], v163 offset:52224
	ds_read_b128 v[198:201], v163 offset:53248
	ds_read_b128 v[202:205], v163 offset:54272
	ds_read_b128 v[206:209], v163 offset:55296
	ds_read_b128 v[210:213], v163 offset:56320
	global_load_lds_dwordx4 v[188:189], off
	s_add_i32 m0, s53, 0x2000
	s_add_u32 s56, s56, 0x40080
	v_lshl_add_u64 v[188:189], v[214:215], 0, s[8:9]
	s_addc_u32 s57, s57, 0
	s_add_i32 s53, s60, s23
	global_load_lds_dwordx4 v[188:189], off
	v_lshl_add_u64 v[188:189], s[56:57], 0, v[0:1]
	s_mov_b32 m0, s53
	s_nop 0
	global_load_lds_dwordx4 v[188:189], off
	v_lshl_add_u64 v[188:189], s[56:57], 0, v[134:135]
	s_add_i32 m0, s53, 0x2000
	s_nop 0
	global_load_lds_dwordx4 v[188:189], off
	v_lshl_add_u64 v[188:189], v[216:217], 0, s[8:9]
	s_mov_b32 m0, s22
	s_nop 0
	global_load_lds_dwordx4 v[188:189], off
	v_lshl_add_u64 v[188:189], v[218:219], 0, s[8:9]
	s_mov_b32 m0, s51
	s_nop 0
	global_load_lds_dwordx4 v[188:189], off
	s_waitcnt vmcnt(8)
	s_waitcnt lgkmcnt(0)
	s_barrier
	s_setprio 1
	s_waitcnt lgkmcnt(0)
	v_mfma_f32_16x16x32_bf16 v[62:65], v[140:143], v[176:179], v[62:65]
	v_mfma_f32_16x16x32_bf16 v[58:61], v[148:151], v[176:179], v[58:61]
	v_mfma_f32_16x16x32_bf16 v[46:49], v[140:143], v[184:187], v[46:49]
	v_mfma_f32_16x16x32_bf16 v[42:45], v[148:151], v[184:187], v[42:45]
	v_mfma_f32_16x16x32_bf16 v[30:33], v[140:143], v[198:201], v[30:33]
	v_mfma_f32_16x16x32_bf16 v[26:29], v[148:151], v[198:201], v[26:29]
	v_mfma_f32_16x16x32_bf16 v[14:17], v[140:143], v[206:209], v[14:17]
	v_mfma_f32_16x16x32_bf16 v[10:13], v[148:151], v[206:209], v[10:13]
	v_mfma_f32_16x16x32_bf16 v[62:65], v[144:147], v[180:183], v[62:65]
	v_mfma_f32_16x16x32_bf16 v[58:61], v[152:155], v[180:183], v[58:61]
	v_mfma_f32_16x16x32_bf16 v[46:49], v[144:147], v[194:197], v[46:49]
	v_mfma_f32_16x16x32_bf16 v[42:45], v[152:155], v[194:197], v[42:45]
	v_mfma_f32_16x16x32_bf16 v[30:33], v[144:147], v[202:205], v[30:33]
	v_mfma_f32_16x16x32_bf16 v[26:29], v[152:155], v[202:205], v[26:29]
	v_mfma_f32_16x16x32_bf16 v[14:17], v[144:147], v[210:213], v[14:17]
	v_mfma_f32_16x16x32_bf16 v[10:13], v[152:155], v[210:213], v[10:13]


; #define PG8_STAGE(bufoff, gbase, voff) do { _Pragma("unroll") for (int _i = 0; _i < 2; ++_i) \
;         __builtin_amdgcn_global_load_lds((const unsigned*)((const char*)(gbase) + (voff)[_i]), (PG8_LAS unsigned*)(lds + (bufoff) + ldsw + _i * 8192), 16, 0, 0); } while (0)
; #define PG8_LDA(dst, b, h) do { _Pragma("unroll") for (int m = 0; m < 4; ++m) _Pragma("unroll") for (int k = 0; k < 2; ++k) dst[m][k] = *(const PG8_LAS bf16x8*)(lds + PG8_SA(b, h) + aoff + m * 2048 + k * 1024); } while (0)
; #define PG8_LDB(dst, b, h) do { _Pragma("unroll") for (int n = 0; n < 2; ++n) _Pragma("unroll") for (int k = 0; k < 2; ++k) dst[n][k] = *(const PG8_LAS bf16x8*)(lds + PG8_SB(b, h) + boff + n * 2048 + k * 1024); } while (0)
; #define PG8_MMA(ai, bj, At, Bt) do { __builtin_amdgcn_s_setprio(1); _Pragma("unroll") for (int m = 0; m < 4; ++m) _Pragma("unroll") for (int n = 0; n < 2; ++n) _Pragma("unroll") for (int k = 0; k < 2; ++k) \
;         acc[ai][bj][m][n] = __builtin_amdgcn_mfma_f32_16x16x32_bf16(Bt[n][k], At[m][k], acc[ai][bj][m][n], 0, 0, 0); __builtin_amdgcn_s_setprio(0); } while (0)
; #define PG8_WAIT_V(n) asm volatile("s_waitcnt vmcnt(" #n ")" ::: "memory")
; #define PG8_WAIT_L(n) asm volatile("s_waitcnt lgkmcnt(" #n ")" ::: "memory")
; #define PG8_BAR __builtin_amdgcn_s_barrier()
; #define PG8_SCHED __builtin_amdgcn_sched_barrier(0)
; template <class Epi, class Sched, bool ALIGN_EPI = false, bool SP2 = false>
; __device__ __forceinline__ void gemm_phase(PG8_LAS unsigned char* lds, const Gemm g, const Sched& S, const Epi& E) {
;     ...
;             const bool last = (t == nt - 2);
;             const char* a1 = cA + (size_t)(t + 1) * kstep;
;             const char* a2 = last ? nA : cA + (size_t)(t + 2) * kstep; const char* b2 = last ? nB : cB + (size_t)(t + 2) * kstep;
;             const char* a3 = a2 + kstep; const char* b3 = b2 + kstep;
;             if (last && has_next) S.a_ready(nxt);
;             if constexpr (SP2) {
;             PG8_LDB(B0, 0, 0); PG8_LDB(B1, 0, 1); PG8_SCHED; PG8_LDA(At, 0, 0); PG8_STAGE(PG8_SA(1, 1), a1 + hstep, voffA);
;             PG8_WAIT_V(8); PG8_WAIT_L(0); PG8_BAR; PG8_MMA(0, 0, At, B0); PG8_MMA(0, 1, At, B1); PG8_BAR; PG8_SCHED;
	v_mfma_f32_16x16x32_bf16 v[54:57], v[156:159], v[176:179], v[54:57]
	v_mfma_f32_16x16x32_bf16 v[50:53], v[168:171], v[176:179], v[50:53]
	v_mfma_f32_16x16x32_bf16 v[38:41], v[156:159], v[184:187], v[38:41]
	v_mfma_f32_16x16x32_bf16 v[34:37], v[168:171], v[184:187], v[34:37]
	v_mfma_f32_16x16x32_bf16 v[22:25], v[156:159], v[198:201], v[22:25]
	v_mfma_f32_16x16x32_bf16 v[18:21], v[168:171], v[198:201], v[18:21]
	v_mfma_f32_16x16x32_bf16 v[6:9], v[156:159], v[206:209], v[6:9]
	v_mfma_f32_16x16x32_bf16 v[2:5], v[168:171], v[206:209], v[2:5]
	v_mfma_f32_16x16x32_bf16 v[54:57], v[164:167], v[180:183], v[54:57]
	v_mfma_f32_16x16x32_bf16 v[50:53], v[172:175], v[180:183], v[50:53]
	v_mfma_f32_16x16x32_bf16 v[38:41], v[164:167], v[194:197], v[38:41]
	v_mfma_f32_16x16x32_bf16 v[34:37], v[172:175], v[194:197], v[34:37]
	v_mfma_f32_16x16x32_bf16 v[22:25], v[164:167], v[202:205], v[22:25]
	v_mfma_f32_16x16x32_bf16 v[18:21], v[172:175], v[202:205], v[18:21]
	v_mfma_f32_16x16x32_bf16 v[6:9], v[164:167], v[210:213], v[6:9]
	v_mfma_f32_16x16x32_bf16 v[2:5], v[172:175], v[210:213], v[2:5]
	s_setprio 0
	s_barrier
	s_add_i32 s52, s52, 2
	s_add_u32 s18, s18, 0x100
	s_addc_u32 s19, s19, 0
	s_add_u32 s41, s41, 0x100
	s_addc_u32 s43, s43, 0
	s_cmp_gt_u32 s52, 13
.LBB0_557:
	s_add_u32 s53, s18, 0xfffc0080
	s_addc_u32 s56, s19, -1
	s_add_i32 s60, 0, 0x10000
	s_cmp_eq_u32 s52, 12
	s_cselect_b32 s59, s30, s56
	s_cselect_b32 s58, s31, s53
	s_cselect_b32 s57, s34, s43
	s_cselect_b32 s56, s35, s41
	s_add_i32 s53, 0, 0x14000
	v_add_u32_e32 v152, s60, v161
	v_add_u32_e32 v172, s53, v161
	ds_read_b128 v[140:143], v152
	ds_read_b128 v[144:147], v152 offset:1024
	ds_read_b128 v[148:151], v152 offset:2048
	ds_read_b128 v[152:155], v152 offset:3072
	ds_read_b128 v[156:159], v172
	ds_read_b128 v[164:167], v172 offset:1024
	ds_read_b128 v[168:171], v172 offset:2048
	ds_read_b128 v[172:175], v172 offset:3072
	v_lshl_add_u64 v[188:189], s[18:19], 0, v[136:137]
	s_add_i32 m0, s26, 0xc000
	ds_read_b128 v[176:179], v163
	ds_read_b128 v[180:183], v163 offset:1024
	ds_read_b128 v[184:187], v163 offset:2048
	ds_read_b128 v[194:197], v163 offset:3072
	ds_read_b128 v[198:201], v163 offset:4096
	ds_read_b128 v[202:205], v163 offset:5120
	ds_read_b128 v[206:209], v163 offset:6144
	ds_read_b128 v[210:213], v163 offset:7168
	global_load_lds_dwordx4 v[188:189], off
	v_lshl_add_u64 v[188:189], s[18:19], 0, v[138:139]
	s_add_i32 m0, s26, 0xe000
	s_nop 0
	global_load_lds_dwordx4 v[188:189], off
	s_waitcnt vmcnt(8)
	s_waitcnt lgkmcnt(0)
	s_barrier
	s_setprio 1
	s_waitcnt lgkmcnt(0)
	v_mfma_f32_16x16x32_bf16 v[126:129], v[140:143], v[176:179], v[126:129]
	v_mfma_f32_16x16x32_bf16 v[122:125], v[148:151], v[176:179], v[122:125]
	v_mfma_f32_16x16x32_bf16 v[118:121], v[140:143], v[184:187], v[118:121]
	v_mfma_f32_16x16x32_bf16 v[106:109], v[148:151], v[184:187], v[106:109]
	v_mfma_f32_16x16x32_bf16 v[94:97], v[140:143], v[198:201], v[94:97]
	v_mfma_f32_16x16x32_bf16 v[90:93], v[148:151], v[198:201], v[90:93]
	v_mfma_f32_16x16x32_bf16 v[78:81], v[140:143], v[206:209], v[78:81]
	v_mfma_f32_16x16x32_bf16 v[74:77], v[148:151], v[206:209], v[74:77]
	v_mfma_f32_16x16x32_bf16 v[126:129], v[144:147], v[180:183], v[126:129]
	v_mfma_f32_16x16x32_bf16 v[122:125], v[152:155], v[180:183], v[122:125]
	v_mfma_f32_16x16x32_bf16 v[118:121], v[144:147], v[194:197], v[118:121]
	v_mfma_f32_16x16x32_bf16 v[106:109], v[152:155], v[194:197], v[106:109]
	v_mfma_f32_16x16x32_bf16 v[94:97], v[144:147], v[202:205], v[94:97]
	v_mfma_f32_16x16x32_bf16 v[90:93], v[152:155], v[202:205], v[90:93]
	v_mfma_f32_16x16x32_bf16 v[78:81], v[144:147], v[210:213], v[78:81]
	v_mfma_f32_16x16x32_bf16 v[74:77], v[152:155], v[210:213], v[74:77]


; #define PG8_STAGE(bufoff, gbase, voff) do { _Pragma("unroll") for (int _i = 0; _i < 2; ++_i) \
;         __builtin_amdgcn_global_load_lds((const unsigned*)((const char*)(gbase) + (voff)[_i]), (PG8_LAS unsigned*)(lds + (bufoff) + ldsw + _i * 8192), 16, 0, 0); } while (0)
; #define PG8_LDA(dst, b, h) do { _Pragma("unroll") for (int m = 0; m < 4; ++m) _Pragma("unroll") for (int k = 0; k < 2; ++k) dst[m][k] = *(const PG8_LAS bf16x8*)(lds + PG8_SA(b, h) + aoff + m * 2048 + k * 1024); } while (0)
; #define PG8_MMA(ai, bj, At, Bt) do { __builtin_amdgcn_s_setprio(1); _Pragma("unroll") for (int m = 0; m < 4; ++m) _Pragma("unroll") for (int n = 0; n < 2; ++n) _Pragma("unroll") for (int k = 0; k < 2; ++k) \
;         acc[ai][bj][m][n] = __builtin_amdgcn_mfma_f32_16x16x32_bf16(Bt[n][k], At[m][k], acc[ai][bj][m][n], 0, 0, 0); __builtin_amdgcn_s_setprio(0); } while (0)
; #define PG8_WAIT_V(n) asm volatile("s_waitcnt vmcnt(" #n ")" ::: "memory")
; #define PG8_WAIT_L(n) asm volatile("s_waitcnt lgkmcnt(" #n ")" ::: "memory")
; #define PG8_BAR __builtin_amdgcn_s_barrier()
; #define PG8_SCHED __builtin_amdgcn_sched_barrier(0)
; template <class Epi, class Sched, bool ALIGN_EPI = false, bool SP2 = false>
; __device__ __forceinline__ void gemm_phase(PG8_LAS unsigned char* lds, const Gemm g, const Sched& S, const Epi& E) {
;     ...
;             PG8_WAIT_V(8); PG8_WAIT_L(0); PG8_BAR; PG8_MMA(0, 0, At, B0); PG8_MMA(0, 1, At, B1); PG8_BAR; PG8_SCHED;
;             PG8_LDA(At, 0, 1); PG8_STAGE(PG8_SB(0, 0), b2, voffB); PG8_STAGE(PG8_SB(0, 1), b2 + hstep, voffB); PG8_STAGE(PG8_SA(0, 0), a2, voffA);
;             PG8_WAIT_V(8); PG8_WAIT_L(0); PG8_BAR; PG8_MMA(1, 0, At, B0); PG8_MMA(1, 1, At, B1); PG8_BAR; PG8_SCHED;
	v_mfma_f32_16x16x32_bf16 v[114:117], v[156:159], v[176:179], v[114:117]
	v_mfma_f32_16x16x32_bf16 v[110:113], v[168:171], v[176:179], v[110:113]
	v_mfma_f32_16x16x32_bf16 v[102:105], v[156:159], v[184:187], v[102:105]
	v_mfma_f32_16x16x32_bf16 v[98:101], v[168:171], v[184:187], v[98:101]
	v_mfma_f32_16x16x32_bf16 v[86:89], v[156:159], v[198:201], v[86:89]
	v_mfma_f32_16x16x32_bf16 v[82:85], v[168:171], v[198:201], v[82:85]
	v_mfma_f32_16x16x32_bf16 v[70:73], v[156:159], v[206:209], v[70:73]
	v_mfma_f32_16x16x32_bf16 v[66:69], v[168:171], v[206:209], v[66:69]
	v_mfma_f32_16x16x32_bf16 v[114:117], v[164:167], v[180:183], v[114:117]
	v_mfma_f32_16x16x32_bf16 v[110:113], v[172:175], v[180:183], v[110:113]
	v_mfma_f32_16x16x32_bf16 v[102:105], v[164:167], v[194:197], v[102:105]
	v_mfma_f32_16x16x32_bf16 v[98:101], v[172:175], v[194:197], v[98:101]
	v_mfma_f32_16x16x32_bf16 v[86:89], v[164:167], v[202:205], v[86:89]
	v_mfma_f32_16x16x32_bf16 v[82:85], v[172:175], v[202:205], v[82:85]
	v_mfma_f32_16x16x32_bf16 v[70:73], v[164:167], v[210:213], v[70:73]
	v_mfma_f32_16x16x32_bf16 v[66:69], v[172:175], v[210:213], v[66:69]
	s_setprio 0
	s_barrier
	s_add_i32 s60, s60, s23
	v_lshl_add_u64 v[188:189], s[56:57], 0, v[0:1]
	s_mov_b32 m0, s60
	ds_read_b128 v[176:179], v163 offset:16384
	ds_read_b128 v[180:183], v163 offset:17408
	ds_read_b128 v[184:187], v163 offset:18432
	ds_read_b128 v[194:197], v163 offset:19456
	ds_read_b128 v[198:201], v163 offset:20480
	ds_read_b128 v[202:205], v163 offset:21504
	ds_read_b128 v[206:209], v163 offset:22528
	ds_read_b128 v[210:213], v163 offset:23552
	global_load_lds_dwordx4 v[188:189], off
	s_add_i32 m0, s60, 0x2000
	s_add_u32 s60, s56, 0x40000
	v_lshl_add_u64 v[214:215], s[56:57], 0, v[134:135]
	s_addc_u32 s61, s57, 0
	s_add_i32 s53, s53, s23
	global_load_lds_dwordx4 v[214:215], off
	v_lshl_add_u64 v[216:217], s[60:61], 0, v[0:1]
	s_mov_b32 m0, s53
	v_lshl_add_u64 v[218:219], s[58:59], 0, v[132:133]
	global_load_lds_dwordx4 v[216:217], off
	v_lshl_add_u64 v[216:217], s[60:61], 0, v[134:135]
	s_add_i32 m0, s53, 0x2000
	s_nop 0
	global_load_lds_dwordx4 v[216:217], off
	v_lshl_add_u64 v[216:217], s[58:59], 0, v[130:131]
	s_mov_b32 m0, s26
	s_nop 0
	global_load_lds_dwordx4 v[216:217], off
	s_mov_b32 m0, s27
	s_nop 0
	global_load_lds_dwordx4 v[218:219], off
	s_waitcnt vmcnt(8)
	s_waitcnt lgkmcnt(0)
	s_barrier
	s_setprio 1
	s_waitcnt lgkmcnt(0)
	v_mfma_f32_16x16x32_bf16 v[62:65], v[140:143], v[176:179], v[62:65]
	v_mfma_f32_16x16x32_bf16 v[58:61], v[148:151], v[176:179], v[58:61]
	v_mfma_f32_16x16x32_bf16 v[46:49], v[140:143], v[184:187], v[46:49]
	v_mfma_f32_16x16x32_bf16 v[42:45], v[148:151], v[184:187], v[42:45]
	v_mfma_f32_16x16x32_bf16 v[30:33], v[140:143], v[198:201], v[30:33]
	v_mfma_f32_16x16x32_bf16 v[26:29], v[148:151], v[198:201], v[26:29]
	v_mfma_f32_16x16x32_bf16 v[14:17], v[140:143], v[206:209], v[14:17]
	v_mfma_f32_16x16x32_bf16 v[10:13], v[148:151], v[206:209], v[10:13]
	v_mfma_f32_16x16x32_bf16 v[62:65], v[144:147], v[180:183], v[62:65]
	v_mfma_f32_16x16x32_bf16 v[58:61], v[152:155], v[180:183], v[58:61]
	v_mfma_f32_16x16x32_bf16 v[46:49], v[144:147], v[194:197], v[46:49]
	v_mfma_f32_16x16x32_bf16 v[42:45], v[152:155], v[194:197], v[42:45]
	v_mfma_f32_16x16x32_bf16 v[30:33], v[144:147], v[202:205], v[30:33]
	v_mfma_f32_16x16x32_bf16 v[26:29], v[152:155], v[202:205], v[26:29]
	v_mfma_f32_16x16x32_bf16 v[14:17], v[144:147], v[210:213], v[14:17]
	v_mfma_f32_16x16x32_bf16 v[10:13], v[152:155], v[210:213], v[10:13]


; #define PG8_STAGE(bufoff, gbase, voff) do { _Pragma("unroll") for (int _i = 0; _i < 2; ++_i) \
;         __builtin_amdgcn_global_load_lds((const unsigned*)((const char*)(gbase) + (voff)[_i]), (PG8_LAS unsigned*)(lds + (bufoff) + ldsw + _i * 8192), 16, 0, 0); } while (0)
; #define PG8_LDA(dst, b, h) do { _Pragma("unroll") for (int m = 0; m < 4; ++m) _Pragma("unroll") for (int k = 0; k < 2; ++k) dst[m][k] = *(const PG8_LAS bf16x8*)(lds + PG8_SA(b, h) + aoff + m * 2048 + k * 1024); } while (0)
; #define PG8_LDB(dst, b, h) do { _Pragma("unroll") for (int n = 0; n < 2; ++n) _Pragma("unroll") for (int k = 0; k < 2; ++k) dst[n][k] = *(const PG8_LAS bf16x8*)(lds + PG8_SB(b, h) + boff + n * 2048 + k * 1024); } while (0)
; #define PG8_MMA(ai, bj, At, Bt) do { __builtin_amdgcn_s_setprio(1); _Pragma("unroll") for (int m = 0; m < 4; ++m) _Pragma("unroll") for (int n = 0; n < 2; ++n) _Pragma("unroll") for (int k = 0; k < 2; ++k) \
;         acc[ai][bj][m][n] = __builtin_amdgcn_mfma_f32_16x16x32_bf16(Bt[n][k], At[m][k], acc[ai][bj][m][n], 0, 0, 0); __builtin_amdgcn_s_setprio(0); } while (0)
; #define PG8_WAIT_V(n) asm volatile("s_waitcnt vmcnt(" #n ")" ::: "memory")
; #define PG8_WAIT_L(n) asm volatile("s_waitcnt lgkmcnt(" #n ")" ::: "memory")
; #define PG8_BAR __builtin_amdgcn_s_barrier()
; #define PG8_SCHED __builtin_amdgcn_sched_barrier(0)
; template <class Epi, class Sched, bool ALIGN_EPI = false, bool SP2 = false>
; __device__ __forceinline__ void gemm_phase(PG8_LAS unsigned char* lds, const Gemm g, const Sched& S, const Epi& E) {
;     ...
;             PG8_WAIT_V(8); PG8_WAIT_L(0); PG8_BAR; PG8_MMA(1, 0, At, B0); PG8_MMA(1, 1, At, B1); PG8_BAR; PG8_SCHED;
;             PG8_LDB(B0, 1, 0); PG8_LDB(B1, 1, 1); PG8_SCHED; PG8_LDA(At, 1, 0); PG8_STAGE(PG8_SA(0, 1), a2 + hstep, voffA);
;             PG8_WAIT_V(8); PG8_WAIT_L(0); PG8_BAR; PG8_MMA(0, 0, At, B0); PG8_MMA(0, 1, At, B1); PG8_BAR; PG8_SCHED;
	v_mfma_f32_16x16x32_bf16 v[54:57], v[156:159], v[176:179], v[54:57]
	v_mfma_f32_16x16x32_bf16 v[50:53], v[168:171], v[176:179], v[50:53]
	v_mfma_f32_16x16x32_bf16 v[38:41], v[156:159], v[184:187], v[38:41]
	v_mfma_f32_16x16x32_bf16 v[34:37], v[168:171], v[184:187], v[34:37]
	v_mfma_f32_16x16x32_bf16 v[22:25], v[156:159], v[198:201], v[22:25]
	v_mfma_f32_16x16x32_bf16 v[18:21], v[168:171], v[198:201], v[18:21]
	v_mfma_f32_16x16x32_bf16 v[6:9], v[156:159], v[206:209], v[6:9]
	v_mfma_f32_16x16x32_bf16 v[2:5], v[168:171], v[206:209], v[2:5]
	v_mfma_f32_16x16x32_bf16 v[54:57], v[164:167], v[180:183], v[54:57]
	v_mfma_f32_16x16x32_bf16 v[50:53], v[172:175], v[180:183], v[50:53]
	v_mfma_f32_16x16x32_bf16 v[38:41], v[164:167], v[194:197], v[38:41]
	v_mfma_f32_16x16x32_bf16 v[34:37], v[172:175], v[194:197], v[34:37]
	v_mfma_f32_16x16x32_bf16 v[22:25], v[164:167], v[202:205], v[22:25]
	v_mfma_f32_16x16x32_bf16 v[18:21], v[172:175], v[202:205], v[18:21]
	v_mfma_f32_16x16x32_bf16 v[6:9], v[164:167], v[210:213], v[6:9]
	v_mfma_f32_16x16x32_bf16 v[2:5], v[172:175], v[210:213], v[2:5]
	s_setprio 0
	s_barrier
	s_add_i32 s53, 0, 0x18000
	s_add_i32 s60, 0, 0x1c000
	v_add_u32_e32 v152, s53, v161
	v_add_u32_e32 v172, s60, v161
	ds_read_b128 v[140:143], v152
	ds_read_b128 v[144:147], v152 offset:1024
	ds_read_b128 v[148:151], v152 offset:2048
	ds_read_b128 v[152:155], v152 offset:3072
	ds_read_b128 v[156:159], v172
	ds_read_b128 v[164:167], v172 offset:1024
	ds_read_b128 v[168:171], v172 offset:2048
	ds_read_b128 v[172:175], v172 offset:3072
	s_add_u32 s58, s58, 0x40000
	s_addc_u32 s59, s59, 0
	s_mov_b32 m0, s28
	v_lshl_add_u64 v[220:221], s[58:59], 0, v[130:131]
	ds_read_b128 v[176:179], v163 offset:32768
	ds_read_b128 v[180:183], v163 offset:33792
	ds_read_b128 v[184:187], v163 offset:34816
	ds_read_b128 v[194:197], v163 offset:35840
	ds_read_b128 v[198:201], v163 offset:36864
	ds_read_b128 v[202:205], v163 offset:37888
	ds_read_b128 v[206:209], v163 offset:38912
	ds_read_b128 v[210:213], v163 offset:39936
	global_load_lds_dwordx4 v[220:221], off
	v_lshl_add_u64 v[220:221], s[58:59], 0, v[132:133]
	s_mov_b32 m0, s29
	s_nop 0
	global_load_lds_dwordx4 v[220:221], off
	s_waitcnt vmcnt(8)
	s_waitcnt lgkmcnt(0)
	s_barrier
	s_setprio 1
	s_waitcnt lgkmcnt(0)
	v_mfma_f32_16x16x32_bf16 v[126:129], v[140:143], v[176:179], v[126:129]
	v_mfma_f32_16x16x32_bf16 v[122:125], v[148:151], v[176:179], v[122:125]
	v_mfma_f32_16x16x32_bf16 v[118:121], v[140:143], v[184:187], v[118:121]
	v_mfma_f32_16x16x32_bf16 v[106:109], v[148:151], v[184:187], v[106:109]
	v_mfma_f32_16x16x32_bf16 v[94:97], v[140:143], v[198:201], v[94:97]
	v_mfma_f32_16x16x32_bf16 v[90:93], v[148:151], v[198:201], v[90:93]
	v_mfma_f32_16x16x32_bf16 v[78:81], v[140:143], v[206:209], v[78:81]
	v_mfma_f32_16x16x32_bf16 v[74:77], v[148:151], v[206:209], v[74:77]
	v_mfma_f32_16x16x32_bf16 v[126:129], v[144:147], v[180:183], v[126:129]
	v_mfma_f32_16x16x32_bf16 v[122:125], v[152:155], v[180:183], v[122:125]
	v_mfma_f32_16x16x32_bf16 v[118:121], v[144:147], v[194:197], v[118:121]
	v_mfma_f32_16x16x32_bf16 v[106:109], v[152:155], v[194:197], v[106:109]
	v_mfma_f32_16x16x32_bf16 v[94:97], v[144:147], v[202:205], v[94:97]
	v_mfma_f32_16x16x32_bf16 v[90:93], v[152:155], v[202:205], v[90:93]
	v_mfma_f32_16x16x32_bf16 v[78:81], v[144:147], v[210:213], v[78:81]
	v_mfma_f32_16x16x32_bf16 v[74:77], v[152:155], v[210:213], v[74:77]


; #define PG8_STAGE(bufoff, gbase, voff) do { _Pragma("unroll") for (int _i = 0; _i < 2; ++_i) \
;         __builtin_amdgcn_global_load_lds((const unsigned*)((const char*)(gbase) + (voff)[_i]), (PG8_LAS unsigned*)(lds + (bufoff) + ldsw + _i * 8192), 16, 0, 0); } while (0)
; #define PG8_LDA(dst, b, h) do { _Pragma("unroll") for (int m = 0; m < 4; ++m) _Pragma("unroll") for (int k = 0; k < 2; ++k) dst[m][k] = *(const PG8_LAS bf16x8*)(lds + PG8_SA(b, h) + aoff + m * 2048 + k * 1024); } while (0)
; #define PG8_MMA(ai, bj, At, Bt) do { __builtin_amdgcn_s_setprio(1); _Pragma("unroll") for (int m = 0; m < 4; ++m) _Pragma("unroll") for (int n = 0; n < 2; ++n) _Pragma("unroll") for (int k = 0; k < 2; ++k) \
;         acc[ai][bj][m][n] = __builtin_amdgcn_mfma_f32_16x16x32_bf16(Bt[n][k], At[m][k], acc[ai][bj][m][n], 0, 0, 0); __builtin_amdgcn_s_setprio(0); } while (0)
; #define PG8_WAIT_V(n) asm volatile("s_waitcnt vmcnt(" #n ")" ::: "memory")
; #define PG8_WAIT_L(n) asm volatile("s_waitcnt lgkmcnt(" #n ")" ::: "memory")
; #define PG8_BAR __builtin_amdgcn_s_barrier()
; #define PG8_SCHED __builtin_amdgcn_sched_barrier(0)
; template <class Epi, class Sched, bool ALIGN_EPI = false, bool SP2 = false>
; __device__ __forceinline__ void gemm_phase(PG8_LAS unsigned char* lds, const Gemm g, const Sched& S, const Epi& E) {
;     ...
;             PG8_WAIT_V(8); PG8_WAIT_L(0); PG8_BAR; PG8_MMA(0, 0, At, B0); PG8_MMA(0, 1, At, B1); PG8_BAR; PG8_SCHED;
;             PG8_LDA(At, 1, 1); PG8_STAGE(PG8_SB(1, 0), b3, voffB); PG8_STAGE(PG8_SB(1, 1), b3 + hstep, voffB); PG8_STAGE(PG8_SA(1, 0), a3, voffA);
;             PG8_WAIT_V(8); PG8_WAIT_L(0); PG8_BAR; PG8_MMA(1, 0, At, B0); PG8_MMA(1, 1, At, B1); PG8_BAR; PG8_SCHED;
	v_mfma_f32_16x16x32_bf16 v[114:117], v[156:159], v[176:179], v[114:117]
	v_mfma_f32_16x16x32_bf16 v[110:113], v[168:171], v[176:179], v[110:113]
	v_mfma_f32_16x16x32_bf16 v[102:105], v[156:159], v[184:187], v[102:105]
	v_mfma_f32_16x16x32_bf16 v[98:101], v[168:171], v[184:187], v[98:101]
	v_mfma_f32_16x16x32_bf16 v[86:89], v[156:159], v[198:201], v[86:89]
	v_mfma_f32_16x16x32_bf16 v[82:85], v[168:171], v[198:201], v[82:85]
	v_mfma_f32_16x16x32_bf16 v[70:73], v[156:159], v[206:209], v[70:73]
	v_mfma_f32_16x16x32_bf16 v[66:69], v[168:171], v[206:209], v[66:69]
	v_mfma_f32_16x16x32_bf16 v[114:117], v[164:167], v[180:183], v[114:117]
	v_mfma_f32_16x16x32_bf16 v[110:113], v[172:175], v[180:183], v[110:113]
	v_mfma_f32_16x16x32_bf16 v[102:105], v[164:167], v[194:197], v[102:105]
	v_mfma_f32_16x16x32_bf16 v[98:101], v[172:175], v[194:197], v[98:101]
	v_mfma_f32_16x16x32_bf16 v[86:89], v[164:167], v[202:205], v[86:89]
	v_mfma_f32_16x16x32_bf16 v[82:85], v[172:175], v[202:205], v[82:85]
	v_mfma_f32_16x16x32_bf16 v[70:73], v[164:167], v[210:213], v[70:73]
	v_mfma_f32_16x16x32_bf16 v[66:69], v[172:175], v[210:213], v[66:69]
	s_setprio 0
	s_barrier
	s_add_i32 s53, s53, s23
	v_lshl_add_u64 v[188:189], v[188:189], 0, s[8:9]
	s_mov_b32 m0, s53
	ds_read_b128 v[176:179], v163 offset:49152
	ds_read_b128 v[180:183], v163 offset:50176
	ds_read_b128 v[184:187], v163 offset:51200
	ds_read_b128 v[194:197], v163 offset:52224
	ds_read_b128 v[198:201], v163 offset:53248
	ds_read_b128 v[202:205], v163 offset:54272
	ds_read_b128 v[206:209], v163 offset:55296
	ds_read_b128 v[210:213], v163 offset:56320
	global_load_lds_dwordx4 v[188:189], off
	s_add_i32 m0, s53, 0x2000
	s_add_u32 s56, s56, 0x40080
	v_lshl_add_u64 v[188:189], v[214:215], 0, s[8:9]
	s_addc_u32 s57, s57, 0
	s_add_i32 s53, s60, s23
	global_load_lds_dwordx4 v[188:189], off
	v_lshl_add_u64 v[188:189], s[56:57], 0, v[0:1]
	s_mov_b32 m0, s53
	s_nop 0
	global_load_lds_dwordx4 v[188:189], off
	v_lshl_add_u64 v[188:189], s[56:57], 0, v[134:135]
	s_add_i32 m0, s53, 0x2000
	s_nop 0
	global_load_lds_dwordx4 v[188:189], off
	v_lshl_add_u64 v[188:189], v[216:217], 0, s[8:9]
	s_mov_b32 m0, s22
	s_nop 0
	global_load_lds_dwordx4 v[188:189], off
	v_lshl_add_u64 v[188:189], v[218:219], 0, s[8:9]
	s_mov_b32 m0, s51
	s_nop 0
	global_load_lds_dwordx4 v[188:189], off
	s_waitcnt vmcnt(8)
	s_waitcnt lgkmcnt(0)
	s_barrier
	s_setprio 1
	s_waitcnt lgkmcnt(0)
	v_mfma_f32_16x16x32_bf16 v[62:65], v[140:143], v[176:179], v[62:65]
	v_mfma_f32_16x16x32_bf16 v[58:61], v[148:151], v[176:179], v[58:61]
	v_mfma_f32_16x16x32_bf16 v[46:49], v[140:143], v[184:187], v[46:49]
	v_mfma_f32_16x16x32_bf16 v[42:45], v[148:151], v[184:187], v[42:45]
	v_mfma_f32_16x16x32_bf16 v[30:33], v[140:143], v[198:201], v[30:33]
	v_mfma_f32_16x16x32_bf16 v[26:29], v[148:151], v[198:201], v[26:29]
	v_mfma_f32_16x16x32_bf16 v[14:17], v[140:143], v[206:209], v[14:17]
	v_mfma_f32_16x16x32_bf16 v[10:13], v[148:151], v[206:209], v[10:13]
	v_mfma_f32_16x16x32_bf16 v[62:65], v[144:147], v[180:183], v[62:65]
	v_mfma_f32_16x16x32_bf16 v[58:61], v[152:155], v[180:183], v[58:61]
	v_mfma_f32_16x16x32_bf16 v[46:49], v[144:147], v[194:197], v[46:49]
	v_mfma_f32_16x16x32_bf16 v[42:45], v[152:155], v[194:197], v[42:45]
	v_mfma_f32_16x16x32_bf16 v[30:33], v[144:147], v[202:205], v[30:33]
	v_mfma_f32_16x16x32_bf16 v[26:29], v[152:155], v[202:205], v[26:29]
	v_mfma_f32_16x16x32_bf16 v[14:17], v[144:147], v[210:213], v[14:17]
	v_mfma_f32_16x16x32_bf16 v[10:13], v[152:155], v[210:213], v[10:13]


; template <class Epi, class Sched, bool ALIGN_EPI = false, bool SP2 = false>
; __device__ __forceinline__ void gemm_phase(PG8_LAS unsigned char* lds, const Gemm g, const Sched& S, const Epi& E) {
;     ...
;         for (int t = 0; t < nt; t += 2) {
;             const bool last = (t == nt - 2);
;             const char* a1 = cA + (size_t)(t + 1) * kstep;
;             const char* a2 = last ? nA : cA + (size_t)(t + 2) * kstep; const char* b2 = last ? nB : cB + (size_t)(t + 2) * kstep;
	v_mfma_f32_16x16x32_bf16 v[54:57], v[156:159], v[176:179], v[54:57]
	v_mfma_f32_16x16x32_bf16 v[50:53], v[168:171], v[176:179], v[50:53]
	v_mfma_f32_16x16x32_bf16 v[38:41], v[156:159], v[184:187], v[38:41]
	v_mfma_f32_16x16x32_bf16 v[34:37], v[168:171], v[184:187], v[34:37]
	v_mfma_f32_16x16x32_bf16 v[22:25], v[156:159], v[198:201], v[22:25]
	v_mfma_f32_16x16x32_bf16 v[18:21], v[168:171], v[198:201], v[18:21]
	v_mfma_f32_16x16x32_bf16 v[6:9], v[156:159], v[206:209], v[6:9]
	v_mfma_f32_16x16x32_bf16 v[2:5], v[168:171], v[206:209], v[2:5]
	v_mfma_f32_16x16x32_bf16 v[54:57], v[164:167], v[180:183], v[54:57]
	v_mfma_f32_16x16x32_bf16 v[50:53], v[172:175], v[180:183], v[50:53]
	v_mfma_f32_16x16x32_bf16 v[38:41], v[164:167], v[194:197], v[38:41]
	v_mfma_f32_16x16x32_bf16 v[34:37], v[172:175], v[194:197], v[34:37]
	v_mfma_f32_16x16x32_bf16 v[22:25], v[164:167], v[202:205], v[22:25]
	v_mfma_f32_16x16x32_bf16 v[18:21], v[172:175], v[202:205], v[18:21]
	v_mfma_f32_16x16x32_bf16 v[6:9], v[164:167], v[210:213], v[6:9]
	v_mfma_f32_16x16x32_bf16 v[2:5], v[172:175], v[210:213], v[2:5]
	s_setprio 0
	s_barrier
	s_add_i32 s52, s52, 2
	s_add_u32 s18, s18, 0x100
	s_addc_u32 s19, s19, 0
	s_add_u32 s41, s41, 0x100
	s_addc_u32 s43, s43, 0
	s_cmp_gt_u32 s52, 13
	s_cbranch_scc0 .LBB0_557


